# baseline (speedup 1.0000x reference)
; __device__ __forceinline__ unsigned pack2(float a, float b) { return (unsigned)f2bf(a) | ((unsigned)f2bf(b) << 16); }
; #define WAIT_V(n) asm volatile("s_waitcnt vmcnt(" #n ")" ::: "memory")
; template <int EPI, bool HS = false>
; __device__ __forceinline__ void gemm_phase(const Params& p, const GemmCfg& g, char* shm, const int wave_s) {
;     ...
;       const float* xin_t = g.xin + (size_t)orow0 * 1024 + pn * 256;
;       float* xout_t = g.xout + (size_t)orow0 * 1024 + pn * 256;
;       u16* xg_t = p.h + (size_t)orow0 * 1024 + pn * 256;
;       float* rss_t = p.rowss + (size_t)orow0 * 16 + pn * 4 + wc;
;       const unsigned tb = (unsigned)((wr * 64 + fq * 4) * 1024 + wc * 32 + 2 * fr);
;       const unsigned ldsb = (unsigned)(size_t)(__attribute__((address_space(3))) char*)shm;
;       const int wv_s = __builtin_amdgcn_readfirstlane(wid);
;       constexpr int XROW = 1040;
;       const char* xl = shm + (wr * 64 + fq * 4) * XROW + (wc * 32 + 2 * fr) * 4;
; #pragma unroll
;       for (int ai = 0; ai < 2; ++ai) {
; #pragma unroll
;         for (int i = 0; i < 16; ++i) {
;           const int r = wv_s * 16 + i;
;           glds_row(xin_t + (size_t)(ai * 128 + r) * 1024, (unsigned)lane * 16u, ldsb + (unsigned)(r * XROW));
;         }
;         WAIT_V(0);
;         __syncthreads();
; #pragma unroll
;         for (int m = 0; m < 4; ++m) {
;           float2 xv[4][2];
; #pragma unroll
;           for (int j = 0; j < 4; ++j)
; #pragma unroll
;             for (int bj = 0; bj < 2; ++bj) xv[j][bj] = *(const float2*)(xl + (m * 16 + j) * XROW + bj * 512);
; #pragma unroll
;           for (int j = 0; j < 4; ++j) {
;             float ss = 0.f;
; #pragma unroll
;             for (int bj = 0; bj < 2; ++bj) {
;               float2 xn;
;               xn.x = xv[j][bj].x + gt[bj][0] * acc[ai][bj][m][0][j];
;               xn.y = xv[j][bj].y + gt[bj][1] * acc[ai][bj][m][1][j];
;               const unsigned o = tb + (unsigned)((ai * 128 + m * 16 + j) * 1024 + bj * 128);
;               *(float2*)(xout_t + o) = xn;
;               if (g.has_next) *(unsigned*)(xg_t + o) = pack2(xn.x * gn[bj][0], xn.y * gn[bj][1]);
.LBB0_102:
	s_mov_b32 s85, s43
	s_mov_b32 s77, s41
	s_or_b64 exec, exec, s[2:3]
	s_mov_b32 s2, s82
	s_mov_b32 s3, -1
	v_readlane_b32 s9, v254, 56
	v_mbcnt_lo_u32_b32 v0, s3, 0
	v_mbcnt_hi_u32_b32 v0, s3, v0
	v_lshl_add_u32 v0, s2, 6, v0
	s_lshl_b64 s[2:3], s[4:5], 12
	s_add_u32 s14, s9, s2
	v_readlane_b32 s9, v254, 55
	s_addc_u32 s15, s9, s3
	s_ashr_i32 s9, s8, 31
	s_lshl_b64 s[12:13], s[8:9], 2
	s_add_u32 s71, s14, s12
	v_readlane_b32 s52, v253, 25
	s_addc_u32 s75, s15, s13
	v_readlane_b32 s64, v253, 37
	v_readlane_b32 s65, v253, 38
	s_add_u32 s2, s64, s2
	s_addc_u32 s3, s65, s3
	s_add_u32 s2, s2, s12
	s_addc_u32 s3, s3, s13
	s_add_u32 s10, s88, s10
	s_addc_u32 s11, s89, s11
	v_lshrrev_b32_e32 v132, 2, v0
	s_lshl_b64 s[8:9], s[8:9], 1
	v_ashrrev_i32_e32 v130, 6, v0
	v_ashrrev_i32_e32 v131, 2, v0
	v_and_b32_e32 v132, 12, v132
	s_add_u32 s8, s10, s8
	s_movk_i32 s10, 0xffc0
	v_and_or_b32 v160, v131, s10, v132
	v_readfirstlane_b32 s10, v130
	s_addc_u32 s9, s11, s9
	s_movk_i32 s11, 0x410
	s_lshl_b32 s10, s10, 4
	v_and_b32_e32 v166, 3, v130
	v_mul_lo_u32 v130, v160, s11
	s_ashr_i32 s11, s10, 31
	s_lshl_b64 s[12:13], s[10:11], 12
	v_and_b32_e32 v165, 15, v0
	v_lshlrev_b32_e32 v0, 4, v0
	s_add_u32 s12, s71, s12
	s_mul_i32 s70, s10, 0x410
	v_and_b32_e32 v164, 0x3f0, v0
	s_addc_u32 s13, s75, s13
	s_add_i32 s70, s70, 0
	s_mov_b32 m0, s70
	s_nop 0
	global_load_lds_dwordx4 v164, s[12:13]
	s_or_b32 s12, s10, 1
	s_ashr_i32 s13, s12, 31
	s_lshl_b64 s[14:15], s[12:13], 12
	s_add_u32 s14, s71, s14
	s_mul_i32 s76, s12, 0x410
	s_addc_u32 s15, s75, s15
	s_add_i32 s76, s76, 0
	s_mov_b32 m0, s76
	s_nop 0
	global_load_lds_dwordx4 v164, s[14:15]
	s_or_b32 s12, s10, 2
	s_ashr_i32 s13, s12, 31
	s_lshl_b64 s[14:15], s[12:13], 12
	s_add_u32 s14, s71, s14
	s_mulk_i32 s12, 0x410
	s_addc_u32 s15, s75, s15
	s_add_i32 s12, s12, 0
	s_mov_b32 m0, s12
	s_nop 0
	global_load_lds_dwordx4 v164, s[14:15]
	s_or_b32 s14, s10, 3
	s_ashr_i32 s15, s14, 31
	s_lshl_b64 s[16:17], s[14:15], 12
	s_add_u32 s16, s71, s16
	s_mul_i32 s13, s14, 0x410
	s_addc_u32 s17, s75, s17
	s_add_i32 s13, s13, 0
	s_mov_b32 m0, s13
	s_nop 0
	global_load_lds_dwordx4 v164, s[16:17]
	s_or_b32 s14, s10, 4
	s_ashr_i32 s15, s14, 31
	s_lshl_b64 s[16:17], s[14:15], 12
	s_add_u32 s16, s71, s16
	s_mulk_i32 s14, 0x410
	s_addc_u32 s17, s75, s17
	s_add_i32 s14, s14, 0
	s_mov_b32 m0, s14
	s_nop 0
	global_load_lds_dwordx4 v164, s[16:17]
	s_or_b32 s16, s10, 5
	s_ashr_i32 s17, s16, 31
	s_lshl_b64 s[18:19], s[16:17], 12
	s_add_u32 s18, s71, s18
	s_mul_i32 s15, s16, 0x410
	s_addc_u32 s19, s75, s19
	s_add_i32 s15, s15, 0
	s_mov_b32 m0, s15
	s_nop 0
	global_load_lds_dwordx4 v164, s[18:19]
	s_or_b32 s16, s10, 6
	s_ashr_i32 s17, s16, 31
	s_lshl_b64 s[18:19], s[16:17], 12
	s_add_u32 s18, s71, s18
	s_mulk_i32 s16, 0x410
	s_addc_u32 s19, s75, s19
	s_add_i32 s16, s16, 0
	s_mov_b32 m0, s16
	s_nop 0
	global_load_lds_dwordx4 v164, s[18:19]
	s_or_b32 s18, s10, 7
	s_ashr_i32 s19, s18, 31
	s_lshl_b64 s[20:21], s[18:19], 12
	s_add_u32 s20, s71, s20
	s_mul_i32 s17, s18, 0x410
	s_addc_u32 s21, s75, s21
	s_add_i32 s17, s17, 0
	s_mov_b32 m0, s17
	s_nop 0
	global_load_lds_dwordx4 v164, s[20:21]
	s_or_b32 s18, s10, 8
	s_ashr_i32 s19, s18, 31
	s_lshl_b64 s[20:21], s[18:19], 12
	s_add_u32 s20, s71, s20
	s_mulk_i32 s18, 0x410
	s_addc_u32 s21, s75, s21
	s_add_i32 s18, s18, 0
	s_mov_b32 m0, s18
	s_nop 0
	global_load_lds_dwordx4 v164, s[20:21]
	s_or_b32 s20, s10, 9
	s_ashr_i32 s21, s20, 31
	s_lshl_b64 s[22:23], s[20:21], 12
	s_add_u32 s22, s71, s22
	s_mul_i32 s19, s20, 0x410
	s_addc_u32 s23, s75, s23
	s_add_i32 s19, s19, 0
	s_mov_b32 m0, s19
	s_nop 0
	global_load_lds_dwordx4 v164, s[22:23]
	s_or_b32 s20, s10, 10
	s_ashr_i32 s21, s20, 31
	s_lshl_b64 s[22:23], s[20:21], 12
	s_add_u32 s22, s71, s22
	s_mulk_i32 s20, 0x410
	s_addc_u32 s23, s75, s23
	s_add_i32 s20, s20, 0
	s_mov_b32 m0, s20
	s_nop 0
	global_load_lds_dwordx4 v164, s[22:23]
	s_or_b32 s22, s10, 11
	s_ashr_i32 s23, s22, 31
	s_lshl_b64 s[24:25], s[22:23], 12
	s_add_u32 s24, s71, s24
	s_mul_i32 s21, s22, 0x410
	s_addc_u32 s25, s75, s25
	s_add_i32 s21, s21, 0
	s_mov_b32 m0, s21
	s_nop 0
	global_load_lds_dwordx4 v164, s[24:25]
	s_or_b32 s22, s10, 12
	s_ashr_i32 s23, s22, 31
	s_lshl_b64 s[24:25], s[22:23], 12
	s_add_u32 s24, s71, s24
	s_mulk_i32 s22, 0x410
	s_addc_u32 s25, s75, s25
	s_add_i32 s22, s22, 0
	s_mov_b32 m0, s22
	s_nop 0
	global_load_lds_dwordx4 v164, s[24:25]
	s_or_b32 s24, s10, 13
	s_ashr_i32 s25, s24, 31
	s_lshl_b64 s[26:27], s[24:25], 12
	s_add_u32 s26, s71, s26
	s_mul_i32 s23, s24, 0x410
	s_addc_u32 s27, s75, s27
	s_add_i32 s23, s23, 0
	s_mov_b32 m0, s23
	s_nop 0
	global_load_lds_dwordx4 v164, s[26:27]
	s_or_b32 s24, s10, 14
	s_ashr_i32 s25, s24, 31
	s_lshl_b64 s[26:27], s[24:25], 12
	s_add_u32 s26, s71, s26
	s_mulk_i32 s24, 0x410
	v_lshlrev_b32_e32 v132, 5, v166
	v_lshlrev_b32_e32 v133, 1, v165
	s_addc_u32 s27, s75, s27
	s_add_i32 s24, s24, 0
	s_mov_b32 m0, s24
	s_nop 0
	global_load_lds_dwordx4 v164, s[26:27]
	s_or_b32 s26, s10, 15
	v_or_b32_e32 v134, v132, v133
	s_ashr_i32 s27, s26, 31
	v_add_u32_e32 v130, 0, v130
	v_lshlrev_b32_e32 v134, 2, v134
	s_lshl_b64 s[36:37], s[26:27], 12
	v_add_u32_e32 v161, v130, v134
	s_add_u32 s36, s71, s36
	s_mul_i32 s25, s26, 0x410
	v_lshlrev_b32_e32 v131, 10, v160
	s_addc_u32 s37, s75, s37
	s_add_i32 s25, s25, 0
	s_mov_b32 m0, s25
	s_nop 0
	global_load_lds_dwordx4 v164, s[36:37]
	v_add_u32_e32 v162, 32, v161
	v_add_u32_e32 v163, 48, v161
	v_or3_b32 v0, v131, v133, v132
	s_waitcnt vmcnt(0)
	s_barrier
	ds_read2st64_b64 v[142:145], v161 offset1:1
	ds_read2_b64 v[138:141], v161 offset0:130 offset1:194
	ds_read2st64_b64 v[134:137], v162 offset0:4 offset1:5
	ds_read2st64_b64 v[130:133], v163 offset0:6 offset1:7
	v_readlane_b32 s26, v254, 60
	v_mov_b32_e32 v154, v122
	v_mov_b32_e32 v155, v126
	v_readlane_b32 s27, v254, 61
	s_waitcnt lgkmcnt(3)
	v_pk_fma_f32 v[156:157], v[150:151], v[154:155], v[142:143]
	v_lshl_add_u64 v[158:159], v[0:1], 2, s[2:3]
	s_and_b64 vcc, exec, s[26:27]
	v_lshl_add_u64 v[154:155], v[0:1], 1, s[8:9]
	v_readlane_b32 s53, v253, 26
	v_readlane_b32 s54, v253, 27
	v_readlane_b32 s55, v253, 28
	v_readlane_b32 s56, v253, 29
	v_readlane_b32 s57, v253, 30
	v_readlane_b32 s58, v253, 31
	v_readlane_b32 s59, v253, 32
	v_readlane_b32 s60, v253, 33
	v_readlane_b32 s61, v253, 34
	v_readlane_b32 s62, v253, 35
	v_readlane_b32 s63, v253, 36
	v_readlane_b32 s66, v253, 39
	v_readlane_b32 s67, v253, 40
	global_store_dwordx2 v[158:159], v[156:157], off
	s_cbranch_vccz .LBB0_104
	v_pk_mul_f32 v[142:143], v[148:149], v[156:157]
	s_nop 0
	s_nop 0
	s_nop 0
	v_cvt_pk_bf16_f32 v126, v142, v142
	v_cvt_pk_bf16_f32 v122, v143, v143
	v_lshrrev_b32_e32 v126, 16, v126
	v_and_or_b32 v122, v122, s28, v126
	global_store_dword v[154:155], v122, off
; __device__ __forceinline__ unsigned pack2(float a, float b) { return (unsigned)f2bf(a) | ((unsigned)f2bf(b) << 16); }
; template <int EPI, bool HS = false>
; __device__ __forceinline__ void gemm_phase(const Params& p, const GemmCfg& g, char* shm, const int wave_s) {
;     ...
;           for (int j = 0; j < 4; ++j) {
;             float ss = 0.f;
; #pragma unroll
;             for (int bj = 0; bj < 2; ++bj) {
;               float2 xn;
;               xn.x = xv[j][bj].x + gt[bj][0] * acc[ai][bj][m][0][j];
;               xn.y = xv[j][bj].y + gt[bj][1] * acc[ai][bj][m][1][j];
;               const unsigned o = tb + (unsigned)((ai * 128 + m * 16 + j) * 1024 + bj * 128);
;               *(float2*)(xout_t + o) = xn;
;               if (g.has_next) *(unsigned*)(xg_t + o) = pack2(xn.x * gn[bj][0], xn.y * gn[bj][1]);
;               ss += xn.x * xn.x + xn.y * xn.y;
;             }
;             if (g.has_next) {
;               ss = dpp_row_sum16(ss);
;               if (fr == 0) rss_t[(wr * 64 + fq * 4 + ai * 128 + m * 16 + j) * 16] = ss;
;             }
.LBB0_104:
	v_readlane_b32 s36, v252, 0
	s_lshl_b64 s[4:5], s[4:5], 6
	v_readlane_b32 s42, v252, 6
	v_readlane_b32 s43, v252, 7
	s_add_u32 s26, s42, s4
	s_addc_u32 s27, s43, s5
	s_lshl_b32 s4, s68, 2
	s_ashr_i32 s5, s4, 31
	s_lshl_b64 s[4:5], s[4:5], 2
	s_add_u32 s4, s26, s4
	s_addc_u32 s5, s27, s5
	v_lshlrev_b32_e32 v142, 2, v166
	v_mov_b32_e32 v143, v1
	v_mov_b32_e32 v166, v114
	v_mov_b32_e32 v167, v118
	v_lshl_add_u64 v[142:143], s[4:5], 0, v[142:143]
	v_cmp_eq_u32_e64 s[4:5], 0, v165
	v_pk_fma_f32 v[144:145], v[146:147], v[166:167], v[144:145]
	s_and_b64 vcc, exec, s[6:7]
	s_mov_b64 s[68:69], -1
	v_readlane_b32 s37, v252, 1
	v_readlane_b32 s38, v252, 2
	v_readlane_b32 s39, v252, 3
	v_readlane_b32 s40, v252, 4
	v_readlane_b32 s41, v252, 5
	global_store_dwordx2 v[158:159], v[144:145], off offset:512
	s_cbranch_vccnz .LBB0_110
	v_pk_mul_f32 v[158:159], v[152:153], v[144:145]
	v_pk_mul_f32 v[156:157], v[156:157], v[156:157]
	s_nop 0
	s_nop 0
	v_cvt_pk_bf16_f32 v118, v158, v158
	v_cvt_pk_bf16_f32 v114, v159, v159
	v_lshrrev_b32_e32 v118, 16, v118
	v_and_or_b32 v114, v114, s28, v118
	v_pk_mul_f32 v[144:145], v[144:145], v[144:145]
	global_store_dword v[154:155], v114, off offset:256
	v_add_f32_e32 v114, v144, v145
	v_add_f32_e32 v118, v156, v157
	v_add_f32_e32 v114, v118, v114
	s_nop 1
	v_add_f32_dpp v114, v114, v114 quad_perm:[1,0,3,2] row_mask:0xf bank_mask:0xf bound_ctrl:1
	s_nop 1
	v_add_f32_dpp v114, v114, v114 quad_perm:[2,3,0,1] row_mask:0xf bank_mask:0xf bound_ctrl:1
	s_nop 1
	v_add_f32_dpp v114, v114, v114 row_half_mirror row_mask:0xf bank_mask:0xf bound_ctrl:1
	s_nop 1
	v_mov_b32_dpp v118, v114 row_mirror row_mask:0xf bank_mask:0xf bound_ctrl:1
	s_and_saveexec_b64 s[68:69], s[4:5]
	s_cbranch_execz .LBB0_107
	v_lshlrev_b32_e32 v144, 4, v160
	v_ashrrev_i32_e32 v145, 31, v144
	v_add_f32_e32 v114, v114, v118
	v_lshl_add_u64 v[144:145], v[144:145], 2, v[142:143]
	global_store_dword v[144:145], v114, off
.LBB0_107:
	s_or_b64 exec, exec, s[68:69]
	v_or_b32_e32 v144, 0x400, v0
	v_mov_b32_e32 v126, v123
	v_mov_b32_e32 v145, v1
	s_waitcnt lgkmcnt(2)
	v_pk_fma_f32 v[156:157], v[150:151], v[126:127], v[138:139]
	v_lshl_add_u64 v[144:145], v[144:145], 2, s[2:3]
	global_store_dwordx2 v[144:145], v[156:157], off
	v_pk_mul_f32 v[144:145], v[148:149], v[156:157]
	v_or_b32_e32 v158, 0x480, v0
	s_nop 0
	s_nop 0
	v_cvt_pk_bf16_f32 v118, v144, v144
	v_cvt_pk_bf16_f32 v114, v145, v145
	v_lshrrev_b32_e32 v118, 16, v118
	v_and_or_b32 v114, v114, s28, v118
	v_mov_b32_e32 v118, v115
	v_mov_b32_e32 v159, v1
	v_pk_fma_f32 v[144:145], v[146:147], v[118:119], v[140:141]
	v_lshl_add_u64 v[158:159], v[158:159], 2, s[2:3]
	global_store_dword v[154:155], v114, off offset:2048
	global_store_dwordx2 v[158:159], v[144:145], off
	v_pk_mul_f32 v[158:159], v[152:153], v[144:145]
	v_pk_mul_f32 v[156:157], v[156:157], v[156:157]
	s_nop 0
	s_nop 0
	v_cvt_pk_bf16_f32 v118, v158, v158
	v_cvt_pk_bf16_f32 v114, v159, v159
	v_lshrrev_b32_e32 v118, 16, v118
	v_and_or_b32 v114, v114, s28, v118
	v_pk_mul_f32 v[144:145], v[144:145], v[144:145]
	global_store_dword v[154:155], v114, off offset:2304
	v_add_f32_e32 v114, v144, v145
	v_add_f32_e32 v118, v156, v157
	v_add_f32_e32 v114, v118, v114
	s_nop 1
	v_add_f32_dpp v114, v114, v114 quad_perm:[1,0,3,2] row_mask:0xf bank_mask:0xf bound_ctrl:1
	s_nop 1
	v_add_f32_dpp v114, v114, v114 quad_perm:[2,3,0,1] row_mask:0xf bank_mask:0xf bound_ctrl:1
	s_nop 1
	v_add_f32_dpp v114, v114, v114 row_half_mirror row_mask:0xf bank_mask:0xf bound_ctrl:1
	s_nop 1
	v_mov_b32_dpp v118, v114 row_mirror row_mask:0xf bank_mask:0xf bound_ctrl:1
	s_and_saveexec_b64 s[68:69], s[4:5]
	s_cbranch_execz .LBB0_109
	v_lshlrev_b32_e32 v144, 4, v160
	v_ashrrev_i32_e32 v145, 31, v144
	v_add_f32_e32 v114, v114, v118
	v_lshl_add_u64 v[144:145], v[144:145], 2, v[142:143]
	global_store_dword v[144:145], v114, off offset:64

; __device__ __forceinline__ unsigned pack2(float a, float b) { return (unsigned)f2bf(a) | ((unsigned)f2bf(b) << 16); }
; template <int EPI, bool HS = false>
; __device__ __forceinline__ void gemm_phase(const Params& p, const GemmCfg& g, char* shm, const int wave_s) {
;     ...
;           for (int j = 0; j < 4; ++j) {
;             float ss = 0.f;
; #pragma unroll
;             for (int bj = 0; bj < 2; ++bj) {
;               float2 xn;
;               xn.x = xv[j][bj].x + gt[bj][0] * acc[ai][bj][m][0][j];
;               xn.y = xv[j][bj].y + gt[bj][1] * acc[ai][bj][m][1][j];
;               const unsigned o = tb + (unsigned)((ai * 128 + m * 16 + j) * 1024 + bj * 128);
;               *(float2*)(xout_t + o) = xn;
;               if (g.has_next) *(unsigned*)(xg_t + o) = pack2(xn.x * gn[bj][0], xn.y * gn[bj][1]);
;               ss += xn.x * xn.x + xn.y * xn.y;
;             }
;             if (g.has_next) {
;               ss = dpp_row_sum16(ss);
;               if (fr == 0) rss_t[(wr * 64 + fq * 4 + ai * 128 + m * 16 + j) * 16] = ss;
;             }
.LBB0_112:
	v_or_b32_e32 v122, 0x800, v0
	v_mov_b32_e32 v114, v124
	v_mov_b32_e32 v115, v128
	v_mov_b32_e32 v123, v1
	s_waitcnt lgkmcnt(1)
	v_pk_fma_f32 v[118:119], v[150:151], v[114:115], v[134:135]
	v_lshl_add_u64 v[114:115], v[122:123], 2, s[2:3]
	global_store_dwordx2 v[114:115], v[118:119], off
	s_mov_b64 s[68:69], -1
	s_and_b64 vcc, exec, s[6:7]
	v_or_b32_e32 v114, 0x880, v0
	s_mov_b32 s42, 0x800000
	s_mov_b32 s41, s77
	s_mov_b32 s43, s85
	s_cbranch_vccnz .LBB0_116
	v_pk_mul_f32 v[126:127], v[148:149], v[118:119]
	v_lshl_add_u64 v[122:123], v[122:123], 1, s[8:9]
	s_nop 0
	s_nop 0
	v_cvt_pk_bf16_f32 v124, v126, v126
	v_cvt_pk_bf16_f32 v115, v127, v127
	v_lshrrev_b32_e32 v124, 16, v124
	v_and_or_b32 v115, v115, s28, v124
	global_store_dword v[122:123], v115, off
	v_mov_b32_e32 v122, v116
	v_mov_b32_e32 v123, v120
	v_mov_b32_e32 v115, v1
	v_pk_fma_f32 v[122:123], v[146:147], v[122:123], v[136:137]
	v_lshl_add_u64 v[126:127], v[114:115], 2, s[2:3]
	global_store_dwordx2 v[126:127], v[122:123], off
	v_pk_mul_f32 v[126:127], v[152:153], v[122:123]
	v_pk_mul_f32 v[118:119], v[118:119], v[118:119]
	v_and_b32_sdwa v128, v126, v178 dst_sel:DWORD dst_unused:UNUSED_PAD src0_sel:WORD_1 src1_sel:DWORD
	s_nop 0
	v_add3_u32 v126, v126, v128, s81
	v_cvt_pk_bf16_f32 v124, v127, v127
	v_lshrrev_b32_e32 v126, 16, v126
	v_pk_mul_f32 v[122:123], v[122:123], v[122:123]
	v_and_or_b32 v124, v124, s28, v126
	v_lshl_add_u64 v[126:127], v[114:115], 1, s[8:9]
	v_add_f32_e32 v115, v122, v123
	v_add_f32_e32 v118, v118, v119
	v_add_f32_e32 v115, v118, v115
	global_store_dword v[126:127], v124, off
	s_nop 0
	v_add_f32_dpp v115, v115, v115 quad_perm:[1,0,3,2] row_mask:0xf bank_mask:0xf bound_ctrl:1
	s_nop 1
	v_add_f32_dpp v115, v115, v115 quad_perm:[2,3,0,1] row_mask:0xf bank_mask:0xf bound_ctrl:1
	s_nop 1
	v_add_f32_dpp v115, v115, v115 row_half_mirror row_mask:0xf bank_mask:0xf bound_ctrl:1
	s_nop 1
	v_mov_b32_dpp v118, v115 row_mirror row_mask:0xf bank_mask:0xf bound_ctrl:1
	s_and_saveexec_b64 s[68:69], s[4:5]
	s_cbranch_execz .LBB0_115
	v_add_f32_e32 v115, v115, v118
	v_lshlrev_b32_e32 v118, 4, v160
	v_ashrrev_i32_e32 v119, 31, v118
	v_lshl_add_u64 v[118:119], v[118:119], 2, v[142:143]
	global_store_dword v[118:119], v115, off offset:128

; __device__ __forceinline__ unsigned pack2(float a, float b) { return (unsigned)f2bf(a) | ((unsigned)f2bf(b) << 16); }
; template <int EPI, bool HS = false>
; __device__ __forceinline__ void gemm_phase(const Params& p, const GemmCfg& g, char* shm, const int wave_s) {
;     ...
;           for (int j = 0; j < 4; ++j) {
;             float ss = 0.f;
; #pragma unroll
;             for (int bj = 0; bj < 2; ++bj) {
;               float2 xn;
;               xn.x = xv[j][bj].x + gt[bj][0] * acc[ai][bj][m][0][j];
;               xn.y = xv[j][bj].y + gt[bj][1] * acc[ai][bj][m][1][j];
;               const unsigned o = tb + (unsigned)((ai * 128 + m * 16 + j) * 1024 + bj * 128);
;               *(float2*)(xout_t + o) = xn;
;               if (g.has_next) *(unsigned*)(xg_t + o) = pack2(xn.x * gn[bj][0], xn.y * gn[bj][1]);
;               ss += xn.x * xn.x + xn.y * xn.y;
;             }
;             if (g.has_next) {
;               ss = dpp_row_sum16(ss);
;               if (fr == 0) rss_t[(wr * 64 + fq * 4 + ai * 128 + m * 16 + j) * 16] = ss;
;             }
.LBB0_118:
	v_or_b32_e32 v122, 0xc00, v0
	v_mov_b32_e32 v128, v125
	v_mov_b32_e32 v123, v1
	s_waitcnt lgkmcnt(0)
	v_pk_fma_f32 v[118:119], v[150:151], v[128:129], v[130:131]
	v_lshl_add_u64 v[114:115], v[122:123], 2, s[2:3]
	global_store_dwordx2 v[114:115], v[118:119], off
	s_mov_b64 s[68:69], -1
	s_and_b64 vcc, exec, s[6:7]
	v_or_b32_e32 v114, 0xc80, v0
	s_cbranch_vccnz .LBB0_122
	v_pk_mul_f32 v[124:125], v[148:149], v[118:119]
	v_lshl_add_u64 v[122:123], v[122:123], 1, s[8:9]
	s_nop 0
	s_nop 0
	v_cvt_pk_bf16_f32 v116, v124, v124
	v_cvt_pk_bf16_f32 v115, v125, v125
	v_lshrrev_b32_e32 v116, 16, v116
	v_and_or_b32 v115, v115, s28, v116
	global_store_dword v[122:123], v115, off
	v_mov_b32_e32 v120, v117
	v_mov_b32_e32 v115, v1
	v_pk_fma_f32 v[122:123], v[146:147], v[120:121], v[132:133]
	v_lshl_add_u64 v[124:125], v[114:115], 2, s[2:3]
	global_store_dwordx2 v[124:125], v[122:123], off
	v_pk_mul_f32 v[124:125], v[152:153], v[122:123]
	v_pk_mul_f32 v[118:119], v[118:119], v[118:119]
	s_nop 0
	s_nop 0
	v_cvt_pk_bf16_f32 v120, v124, v124
	v_cvt_pk_bf16_f32 v116, v125, v125
	v_lshrrev_b32_e32 v120, 16, v120
	v_and_or_b32 v116, v116, s28, v120
	v_lshl_add_u64 v[124:125], v[114:115], 1, s[8:9]
	v_pk_mul_f32 v[122:123], v[122:123], v[122:123]
	global_store_dword v[124:125], v116, off
	v_add_f32_e32 v115, v122, v123
	v_add_f32_e32 v116, v118, v119
	v_add_f32_e32 v115, v116, v115
	s_nop 1
	v_add_f32_dpp v115, v115, v115 quad_perm:[1,0,3,2] row_mask:0xf bank_mask:0xf bound_ctrl:1
	s_nop 1
	v_add_f32_dpp v115, v115, v115 quad_perm:[2,3,0,1] row_mask:0xf bank_mask:0xf bound_ctrl:1
	s_nop 1
	v_add_f32_dpp v115, v115, v115 row_half_mirror row_mask:0xf bank_mask:0xf bound_ctrl:1
	s_nop 1
	v_mov_b32_dpp v116, v115 row_mirror row_mask:0xf bank_mask:0xf bound_ctrl:1
	s_and_saveexec_b64 s[68:69], s[4:5]
	s_cbranch_execz .LBB0_121
	v_lshlrev_b32_e32 v118, 4, v160
	v_ashrrev_i32_e32 v119, 31, v118
	v_add_f32_e32 v115, v115, v116
	v_lshl_add_u64 v[118:119], v[118:119], 2, v[142:143]
	global_store_dword v[118:119], v115, off offset:192

; __device__ __forceinline__ unsigned pack2(float a, float b) { return (unsigned)f2bf(a) | ((unsigned)f2bf(b) << 16); }
; template <int EPI, bool HS = false>
; __device__ __forceinline__ void gemm_phase(const Params& p, const GemmCfg& g, char* shm, const int wave_s) {
;     ...
;             for (int bj = 0; bj < 2; ++bj) xv[j][bj] = *(const float2*)(xl + (m * 16 + j) * XROW + bj * 512);
; #pragma unroll
;           for (int j = 0; j < 4; ++j) {
;             float ss = 0.f;
; #pragma unroll
;             for (int bj = 0; bj < 2; ++bj) {
;               float2 xn;
;               xn.x = xv[j][bj].x + gt[bj][0] * acc[ai][bj][m][0][j];
;               xn.y = xv[j][bj].y + gt[bj][1] * acc[ai][bj][m][1][j];
;               const unsigned o = tb + (unsigned)((ai * 128 + m * 16 + j) * 1024 + bj * 128);
;               *(float2*)(xout_t + o) = xn;
;               if (g.has_next) *(unsigned*)(xg_t + o) = pack2(xn.x * gn[bj][0], xn.y * gn[bj][1]);
;               ss += xn.x * xn.x + xn.y * xn.y;
;             }
;             if (g.has_next) {
;               ss = dpp_row_sum16(ss);
;               if (fr == 0) rss_t[(wr * 64 + fq * 4 + ai * 128 + m * 16 + j) * 16] = ss;
;             }
.LBB0_124:
	v_add_u32_e32 v134, 0x100, v161
	ds_read2st64_b64 v[126:129], v134 offset0:32 offset1:33
	v_add_u32_e32 v135, 0x110, v161
	v_add_u32_e32 v136, 0x120, v161
	v_add_u32_e32 v137, 0x130, v161
	ds_read2st64_b64 v[122:125], v135 offset0:34 offset1:35
	ds_read2st64_b64 v[118:121], v136 offset0:36 offset1:37
	ds_read2st64_b64 v[114:117], v137 offset0:38 offset1:39
	v_or_b32_e32 v132, 0x4000, v0
	v_mov_b32_e32 v130, v106
	v_mov_b32_e32 v131, v110
	v_mov_b32_e32 v133, v1
	s_waitcnt lgkmcnt(3)
	v_pk_fma_f32 v[130:131], v[150:151], v[130:131], v[126:127]
	v_lshl_add_u64 v[126:127], v[132:133], 2, s[2:3]
	global_store_dwordx2 v[126:127], v[130:131], off
	s_mov_b64 s[68:69], -1
	s_and_b64 vcc, exec, s[6:7]
	v_or_b32_e32 v126, 0x4080, v0
	s_cbranch_vccnz .LBB0_128
	v_pk_mul_f32 v[138:139], v[148:149], v[130:131]
	v_lshl_add_u64 v[132:133], v[132:133], 1, s[8:9]
	s_nop 0
	s_nop 0
	v_cvt_pk_bf16_f32 v110, v138, v138
	v_cvt_pk_bf16_f32 v106, v139, v139
	v_lshrrev_b32_e32 v110, 16, v110
	v_and_or_b32 v106, v106, s28, v110
	global_store_dword v[132:133], v106, off
	v_mov_b32_e32 v132, v98
	v_mov_b32_e32 v133, v102
	v_mov_b32_e32 v127, v1
	v_pk_fma_f32 v[132:133], v[146:147], v[132:133], v[128:129]
	v_lshl_add_u64 v[138:139], v[126:127], 2, s[2:3]
	global_store_dwordx2 v[138:139], v[132:133], off
	v_pk_mul_f32 v[138:139], v[152:153], v[132:133]
	v_pk_mul_f32 v[130:131], v[130:131], v[130:131]
	s_nop 0
	s_nop 0
	v_cvt_pk_bf16_f32 v110, v138, v138
	v_cvt_pk_bf16_f32 v106, v139, v139
	v_lshrrev_b32_e32 v110, 16, v110
	v_and_or_b32 v106, v106, s28, v110
	v_lshl_add_u64 v[138:139], v[126:127], 1, s[8:9]
	v_pk_mul_f32 v[132:133], v[132:133], v[132:133]
	global_store_dword v[138:139], v106, off
	v_add_f32_e32 v106, v132, v133
	v_add_f32_e32 v110, v130, v131
	v_add_f32_e32 v106, v110, v106
	s_nop 1
	v_add_f32_dpp v106, v106, v106 quad_perm:[1,0,3,2] row_mask:0xf bank_mask:0xf bound_ctrl:1
	s_nop 1
	v_add_f32_dpp v106, v106, v106 quad_perm:[2,3,0,1] row_mask:0xf bank_mask:0xf bound_ctrl:1
	s_nop 1
	v_add_f32_dpp v106, v106, v106 row_half_mirror row_mask:0xf bank_mask:0xf bound_ctrl:1
	s_nop 1
	v_mov_b32_dpp v110, v106 row_mirror row_mask:0xf bank_mask:0xf bound_ctrl:1
	s_and_saveexec_b64 s[68:69], s[4:5]
	s_cbranch_execz .LBB0_127
	v_lshlrev_b32_e32 v130, 4, v160
	v_ashrrev_i32_e32 v131, 31, v130
	v_add_f32_e32 v106, v106, v110
	v_lshl_add_u64 v[130:131], v[130:131], 2, v[142:143]
	global_store_dword v[130:131], v106, off offset:1024

; __device__ __forceinline__ unsigned pack2(float a, float b) { return (unsigned)f2bf(a) | ((unsigned)f2bf(b) << 16); }
; template <int EPI, bool HS = false>
; __device__ __forceinline__ void gemm_phase(const Params& p, const GemmCfg& g, char* shm, const int wave_s) {
;     ...
;           for (int j = 0; j < 4; ++j) {
;             float ss = 0.f;
; #pragma unroll
;             for (int bj = 0; bj < 2; ++bj) {
;               float2 xn;
;               xn.x = xv[j][bj].x + gt[bj][0] * acc[ai][bj][m][0][j];
;               xn.y = xv[j][bj].y + gt[bj][1] * acc[ai][bj][m][1][j];
;               const unsigned o = tb + (unsigned)((ai * 128 + m * 16 + j) * 1024 + bj * 128);
;               *(float2*)(xout_t + o) = xn;
;               if (g.has_next) *(unsigned*)(xg_t + o) = pack2(xn.x * gn[bj][0], xn.y * gn[bj][1]);
;               ss += xn.x * xn.x + xn.y * xn.y;
;             }
;             if (g.has_next) {
;               ss = dpp_row_sum16(ss);
;               if (fr == 0) rss_t[(wr * 64 + fq * 4 + ai * 128 + m * 16 + j) * 16] = ss;
;             }
.LBB0_130:
	v_or_b32_e32 v126, 0x4400, v0
	v_mov_b32_e32 v110, v107
	v_mov_b32_e32 v127, v1
	s_waitcnt lgkmcnt(2)
	v_pk_fma_f32 v[110:111], v[150:151], v[110:111], v[122:123]
	v_lshl_add_u64 v[106:107], v[126:127], 2, s[2:3]
	global_store_dwordx2 v[106:107], v[110:111], off
	s_mov_b64 s[68:69], -1
	s_and_b64 vcc, exec, s[6:7]
	v_or_b32_e32 v106, 0x4480, v0
	s_cbranch_vccnz .LBB0_134
	v_pk_mul_f32 v[122:123], v[148:149], v[110:111]
	v_mov_b32_e32 v107, v1
	s_nop 0
	s_nop 0
	v_cvt_pk_bf16_f32 v102, v122, v122
	v_cvt_pk_bf16_f32 v98, v123, v123
	v_lshrrev_b32_e32 v102, 16, v102
	v_and_or_b32 v98, v98, s28, v102
	v_lshl_add_u64 v[122:123], v[126:127], 1, s[8:9]
	v_mov_b32_e32 v102, v99
	global_store_dword v[122:123], v98, off
	v_pk_fma_f32 v[122:123], v[146:147], v[102:103], v[124:125]
	v_lshl_add_u64 v[126:127], v[106:107], 2, s[2:3]
	global_store_dwordx2 v[126:127], v[122:123], off
	v_pk_mul_f32 v[126:127], v[152:153], v[122:123]
	v_pk_mul_f32 v[110:111], v[110:111], v[110:111]
	s_nop 0
	s_nop 0
	v_cvt_pk_bf16_f32 v102, v126, v126
	v_cvt_pk_bf16_f32 v98, v127, v127
	v_lshrrev_b32_e32 v102, 16, v102
	v_and_or_b32 v98, v98, s28, v102
	v_lshl_add_u64 v[126:127], v[106:107], 1, s[8:9]
	v_pk_mul_f32 v[122:123], v[122:123], v[122:123]
	global_store_dword v[126:127], v98, off
	v_add_f32_e32 v98, v122, v123
	v_add_f32_e32 v102, v110, v111
	v_add_f32_e32 v98, v102, v98
	s_nop 1
	v_add_f32_dpp v98, v98, v98 quad_perm:[1,0,3,2] row_mask:0xf bank_mask:0xf bound_ctrl:1
	s_nop 1
	v_add_f32_dpp v98, v98, v98 quad_perm:[2,3,0,1] row_mask:0xf bank_mask:0xf bound_ctrl:1
	s_nop 1
	v_add_f32_dpp v98, v98, v98 row_half_mirror row_mask:0xf bank_mask:0xf bound_ctrl:1
	s_nop 1
	v_mov_b32_dpp v102, v98 row_mirror row_mask:0xf bank_mask:0xf bound_ctrl:1
	s_and_saveexec_b64 s[68:69], s[4:5]
	s_cbranch_execz .LBB0_133
	v_lshlrev_b32_e32 v110, 4, v160
	v_ashrrev_i32_e32 v111, 31, v110
	v_add_f32_e32 v98, v98, v102
	v_lshl_add_u64 v[110:111], v[110:111], 2, v[142:143]
	global_store_dword v[110:111], v98, off offset:1088

; __device__ __forceinline__ unsigned pack2(float a, float b) { return (unsigned)f2bf(a) | ((unsigned)f2bf(b) << 16); }
; template <int EPI, bool HS = false>
; __device__ __forceinline__ void gemm_phase(const Params& p, const GemmCfg& g, char* shm, const int wave_s) {
;     ...
;           for (int j = 0; j < 4; ++j) {
;             float ss = 0.f;
; #pragma unroll
;             for (int bj = 0; bj < 2; ++bj) {
;               float2 xn;
;               xn.x = xv[j][bj].x + gt[bj][0] * acc[ai][bj][m][0][j];
;               xn.y = xv[j][bj].y + gt[bj][1] * acc[ai][bj][m][1][j];
;               const unsigned o = tb + (unsigned)((ai * 128 + m * 16 + j) * 1024 + bj * 128);
;               *(float2*)(xout_t + o) = xn;
;               if (g.has_next) *(unsigned*)(xg_t + o) = pack2(xn.x * gn[bj][0], xn.y * gn[bj][1]);
;               ss += xn.x * xn.x + xn.y * xn.y;
;             }
;             if (g.has_next) {
;               ss = dpp_row_sum16(ss);
;               if (fr == 0) rss_t[(wr * 64 + fq * 4 + ai * 128 + m * 16 + j) * 16] = ss;
;             }
.LBB0_136:
	v_or_b32_e32 v106, 0x4800, v0
	v_mov_b32_e32 v98, v108
	v_mov_b32_e32 v99, v112
	v_mov_b32_e32 v107, v1
	s_waitcnt lgkmcnt(1)
	v_pk_fma_f32 v[102:103], v[150:151], v[98:99], v[118:119]
	v_lshl_add_u64 v[98:99], v[106:107], 2, s[2:3]
	global_store_dwordx2 v[98:99], v[102:103], off
	s_mov_b64 s[68:69], -1
	s_and_b64 vcc, exec, s[6:7]
	v_or_b32_e32 v98, 0x4880, v0
	s_cbranch_vccnz .LBB0_140
	v_pk_mul_f32 v[110:111], v[148:149], v[102:103]
	v_lshl_add_u64 v[106:107], v[106:107], 1, s[8:9]
	s_nop 0
	s_nop 0
	v_cvt_pk_bf16_f32 v108, v110, v110
	v_cvt_pk_bf16_f32 v99, v111, v111
	v_lshrrev_b32_e32 v108, 16, v108
	v_and_or_b32 v99, v99, s28, v108
	global_store_dword v[106:107], v99, off
	v_mov_b32_e32 v106, v100
	v_mov_b32_e32 v107, v104
	v_mov_b32_e32 v99, v1
	v_pk_fma_f32 v[106:107], v[146:147], v[106:107], v[120:121]
	v_lshl_add_u64 v[110:111], v[98:99], 2, s[2:3]
	global_store_dwordx2 v[110:111], v[106:107], off
	v_pk_mul_f32 v[110:111], v[152:153], v[106:107]
	v_pk_mul_f32 v[102:103], v[102:103], v[102:103]
	v_and_b32_sdwa v112, v110, v178 dst_sel:DWORD dst_unused:UNUSED_PAD src0_sel:WORD_1 src1_sel:DWORD
	s_nop 0
	v_add3_u32 v110, v110, v112, s81
	v_cvt_pk_bf16_f32 v108, v111, v111
	v_lshrrev_b32_e32 v110, 16, v110
	v_pk_mul_f32 v[106:107], v[106:107], v[106:107]
	v_and_or_b32 v108, v108, s28, v110
	v_lshl_add_u64 v[110:111], v[98:99], 1, s[8:9]
	v_add_f32_e32 v99, v106, v107
	v_add_f32_e32 v102, v102, v103
	v_add_f32_e32 v99, v102, v99
	global_store_dword v[110:111], v108, off
	s_nop 0
	v_add_f32_dpp v99, v99, v99 quad_perm:[1,0,3,2] row_mask:0xf bank_mask:0xf bound_ctrl:1
	s_nop 1
	v_add_f32_dpp v99, v99, v99 quad_perm:[2,3,0,1] row_mask:0xf bank_mask:0xf bound_ctrl:1
	s_nop 1
	v_add_f32_dpp v99, v99, v99 row_half_mirror row_mask:0xf bank_mask:0xf bound_ctrl:1
	s_nop 1
	v_mov_b32_dpp v102, v99 row_mirror row_mask:0xf bank_mask:0xf bound_ctrl:1
	s_and_saveexec_b64 s[68:69], s[4:5]
	s_cbranch_execz .LBB0_139
	v_add_f32_e32 v99, v99, v102
	v_lshlrev_b32_e32 v102, 4, v160
	v_ashrrev_i32_e32 v103, 31, v102
	v_lshl_add_u64 v[102:103], v[102:103], 2, v[142:143]
	global_store_dword v[102:103], v99, off offset:1152

; __device__ __forceinline__ unsigned pack2(float a, float b) { return (unsigned)f2bf(a) | ((unsigned)f2bf(b) << 16); }
; template <int EPI, bool HS = false>
; __device__ __forceinline__ void gemm_phase(const Params& p, const GemmCfg& g, char* shm, const int wave_s) {
;     ...
;           for (int j = 0; j < 4; ++j) {
;             float ss = 0.f;
; #pragma unroll
;             for (int bj = 0; bj < 2; ++bj) {
;               float2 xn;
;               xn.x = xv[j][bj].x + gt[bj][0] * acc[ai][bj][m][0][j];
;               xn.y = xv[j][bj].y + gt[bj][1] * acc[ai][bj][m][1][j];
;               const unsigned o = tb + (unsigned)((ai * 128 + m * 16 + j) * 1024 + bj * 128);
;               *(float2*)(xout_t + o) = xn;
;               if (g.has_next) *(unsigned*)(xg_t + o) = pack2(xn.x * gn[bj][0], xn.y * gn[bj][1]);
;               ss += xn.x * xn.x + xn.y * xn.y;
;             }
;             if (g.has_next) {
;               ss = dpp_row_sum16(ss);
;               if (fr == 0) rss_t[(wr * 64 + fq * 4 + ai * 128 + m * 16 + j) * 16] = ss;
;             }
.LBB0_142:
	v_or_b32_e32 v106, 0x4c00, v0
	v_mov_b32_e32 v112, v109
	v_mov_b32_e32 v107, v1
	s_waitcnt lgkmcnt(0)
	v_pk_fma_f32 v[102:103], v[150:151], v[112:113], v[114:115]
	v_lshl_add_u64 v[98:99], v[106:107], 2, s[2:3]
	global_store_dwordx2 v[98:99], v[102:103], off
	s_mov_b64 s[68:69], -1
	s_and_b64 vcc, exec, s[6:7]
	v_or_b32_e32 v98, 0x4c80, v0
	s_cbranch_vccnz .LBB0_146
	v_pk_mul_f32 v[108:109], v[148:149], v[102:103]
	v_lshl_add_u64 v[106:107], v[106:107], 1, s[8:9]
	s_nop 0
	s_nop 0
	v_cvt_pk_bf16_f32 v100, v108, v108
	v_cvt_pk_bf16_f32 v99, v109, v109
	v_lshrrev_b32_e32 v100, 16, v100
	v_and_or_b32 v99, v99, s28, v100
	global_store_dword v[106:107], v99, off
	v_mov_b32_e32 v104, v101
	v_mov_b32_e32 v99, v1
	v_pk_fma_f32 v[106:107], v[146:147], v[104:105], v[116:117]
	v_lshl_add_u64 v[108:109], v[98:99], 2, s[2:3]
	global_store_dwordx2 v[108:109], v[106:107], off
	v_pk_mul_f32 v[108:109], v[152:153], v[106:107]
	v_pk_mul_f32 v[102:103], v[102:103], v[102:103]
	s_nop 0
	s_nop 0
	v_cvt_pk_bf16_f32 v104, v108, v108
	v_cvt_pk_bf16_f32 v100, v109, v109
	v_lshrrev_b32_e32 v104, 16, v104
	v_and_or_b32 v100, v100, s28, v104
	v_lshl_add_u64 v[108:109], v[98:99], 1, s[8:9]
	v_pk_mul_f32 v[106:107], v[106:107], v[106:107]
	global_store_dword v[108:109], v100, off
	v_add_f32_e32 v99, v106, v107
	v_add_f32_e32 v100, v102, v103
	v_add_f32_e32 v99, v100, v99
	s_nop 1
	v_add_f32_dpp v99, v99, v99 quad_perm:[1,0,3,2] row_mask:0xf bank_mask:0xf bound_ctrl:1
	s_nop 1
	v_add_f32_dpp v99, v99, v99 quad_perm:[2,3,0,1] row_mask:0xf bank_mask:0xf bound_ctrl:1
	s_nop 1
	v_add_f32_dpp v99, v99, v99 row_half_mirror row_mask:0xf bank_mask:0xf bound_ctrl:1
	s_nop 1
	v_mov_b32_dpp v100, v99 row_mirror row_mask:0xf bank_mask:0xf bound_ctrl:1
	s_and_saveexec_b64 s[68:69], s[4:5]
	s_cbranch_execz .LBB0_145
	v_lshlrev_b32_e32 v102, 4, v160
	v_ashrrev_i32_e32 v103, 31, v102
	v_add_f32_e32 v99, v99, v100
	v_lshl_add_u64 v[102:103], v[102:103], 2, v[142:143]
	global_store_dword v[102:103], v99, off offset:1216

; __device__ __forceinline__ unsigned pack2(float a, float b) { return (unsigned)f2bf(a) | ((unsigned)f2bf(b) << 16); }
; template <int EPI, bool HS = false>
; __device__ __forceinline__ void gemm_phase(const Params& p, const GemmCfg& g, char* shm, const int wave_s) {
;     ...
;             for (int bj = 0; bj < 2; ++bj) xv[j][bj] = *(const float2*)(xl + (m * 16 + j) * XROW + bj * 512);
; #pragma unroll
;           for (int j = 0; j < 4; ++j) {
;             float ss = 0.f;
; #pragma unroll
;             for (int bj = 0; bj < 2; ++bj) {
;               float2 xn;
;               xn.x = xv[j][bj].x + gt[bj][0] * acc[ai][bj][m][0][j];
;               xn.y = xv[j][bj].y + gt[bj][1] * acc[ai][bj][m][1][j];
;               const unsigned o = tb + (unsigned)((ai * 128 + m * 16 + j) * 1024 + bj * 128);
;               *(float2*)(xout_t + o) = xn;
;               if (g.has_next) *(unsigned*)(xg_t + o) = pack2(xn.x * gn[bj][0], xn.y * gn[bj][1]);
;               ss += xn.x * xn.x + xn.y * xn.y;
;             }
;             if (g.has_next) {
;               ss = dpp_row_sum16(ss);
;               if (fr == 0) rss_t[(wr * 64 + fq * 4 + ai * 128 + m * 16 + j) * 16] = ss;
;             }
.LBB0_148:
	ds_read2st64_b64 v[110:113], v161 offset0:65 offset1:66
	v_add_u32_e32 v118, 16, v161
	ds_read2st64_b64 v[106:109], v118 offset0:67 offset1:68
	ds_read2st64_b64 v[102:105], v162 offset0:69 offset1:70
	ds_read2st64_b64 v[98:101], v163 offset0:71 offset1:72
	v_or_b32_e32 v116, 0x8000, v0
	v_mov_b32_e32 v114, v90
	v_mov_b32_e32 v115, v94
	v_mov_b32_e32 v117, v1
	s_waitcnt lgkmcnt(3)
	v_pk_fma_f32 v[114:115], v[150:151], v[114:115], v[110:111]
	v_lshl_add_u64 v[110:111], v[116:117], 2, s[2:3]
	global_store_dwordx2 v[110:111], v[114:115], off
	s_mov_b64 s[68:69], -1
	s_and_b64 vcc, exec, s[6:7]
	v_or_b32_e32 v110, 0x8080, v0
	s_cbranch_vccnz .LBB0_152
	v_pk_mul_f32 v[120:121], v[148:149], v[114:115]
	v_lshl_add_u64 v[116:117], v[116:117], 1, s[8:9]
	s_nop 0
	s_nop 0
	v_cvt_pk_bf16_f32 v94, v120, v120
	v_cvt_pk_bf16_f32 v90, v121, v121
	v_lshrrev_b32_e32 v94, 16, v94
	v_and_or_b32 v90, v90, s28, v94
	global_store_dword v[116:117], v90, off
	v_mov_b32_e32 v116, v82
	v_mov_b32_e32 v117, v86
	v_mov_b32_e32 v111, v1
	v_pk_fma_f32 v[116:117], v[146:147], v[116:117], v[112:113]
	v_lshl_add_u64 v[120:121], v[110:111], 2, s[2:3]
	global_store_dwordx2 v[120:121], v[116:117], off
	v_pk_mul_f32 v[120:121], v[152:153], v[116:117]
	v_pk_mul_f32 v[114:115], v[114:115], v[114:115]
	s_nop 0
	s_nop 0
	v_cvt_pk_bf16_f32 v94, v120, v120
	v_cvt_pk_bf16_f32 v90, v121, v121
	v_lshrrev_b32_e32 v94, 16, v94
	v_and_or_b32 v90, v90, s28, v94
	v_lshl_add_u64 v[120:121], v[110:111], 1, s[8:9]
	v_pk_mul_f32 v[116:117], v[116:117], v[116:117]
	global_store_dword v[120:121], v90, off
	v_add_f32_e32 v90, v116, v117
	v_add_f32_e32 v94, v114, v115
	v_add_f32_e32 v90, v94, v90
	s_nop 1
	v_add_f32_dpp v90, v90, v90 quad_perm:[1,0,3,2] row_mask:0xf bank_mask:0xf bound_ctrl:1
	s_nop 1
	v_add_f32_dpp v90, v90, v90 quad_perm:[2,3,0,1] row_mask:0xf bank_mask:0xf bound_ctrl:1
	s_nop 1
	v_add_f32_dpp v90, v90, v90 row_half_mirror row_mask:0xf bank_mask:0xf bound_ctrl:1
	s_nop 1
	v_mov_b32_dpp v94, v90 row_mirror row_mask:0xf bank_mask:0xf bound_ctrl:1
	s_and_saveexec_b64 s[68:69], s[4:5]
	s_cbranch_execz .LBB0_151
	v_lshlrev_b32_e32 v114, 4, v160
	v_ashrrev_i32_e32 v115, 31, v114
	v_add_f32_e32 v90, v90, v94
	v_lshl_add_u64 v[114:115], v[114:115], 2, v[142:143]
	global_store_dword v[114:115], v90, off offset:2048

; __device__ __forceinline__ unsigned pack2(float a, float b) { return (unsigned)f2bf(a) | ((unsigned)f2bf(b) << 16); }
; template <int EPI, bool HS = false>
; __device__ __forceinline__ void gemm_phase(const Params& p, const GemmCfg& g, char* shm, const int wave_s) {
;     ...
;           for (int j = 0; j < 4; ++j) {
;             float ss = 0.f;
; #pragma unroll
;             for (int bj = 0; bj < 2; ++bj) {
;               float2 xn;
;               xn.x = xv[j][bj].x + gt[bj][0] * acc[ai][bj][m][0][j];
;               xn.y = xv[j][bj].y + gt[bj][1] * acc[ai][bj][m][1][j];
;               const unsigned o = tb + (unsigned)((ai * 128 + m * 16 + j) * 1024 + bj * 128);
;               *(float2*)(xout_t + o) = xn;
;               if (g.has_next) *(unsigned*)(xg_t + o) = pack2(xn.x * gn[bj][0], xn.y * gn[bj][1]);
;               ss += xn.x * xn.x + xn.y * xn.y;
;             }
;             if (g.has_next) {
;               ss = dpp_row_sum16(ss);
;               if (fr == 0) rss_t[(wr * 64 + fq * 4 + ai * 128 + m * 16 + j) * 16] = ss;
;             }
.LBB0_154:
	v_or_b32_e32 v110, 0x8400, v0
	v_mov_b32_e32 v94, v91
	v_mov_b32_e32 v111, v1
	s_waitcnt lgkmcnt(2)
	v_pk_fma_f32 v[94:95], v[150:151], v[94:95], v[106:107]
	v_lshl_add_u64 v[90:91], v[110:111], 2, s[2:3]
	global_store_dwordx2 v[90:91], v[94:95], off
	s_mov_b64 s[68:69], -1
	s_and_b64 vcc, exec, s[6:7]
	v_or_b32_e32 v90, 0x8480, v0
	s_cbranch_vccnz .LBB0_158
	v_pk_mul_f32 v[106:107], v[148:149], v[94:95]
	v_mov_b32_e32 v91, v1
	s_nop 0
	s_nop 0
	v_cvt_pk_bf16_f32 v86, v106, v106
	v_cvt_pk_bf16_f32 v82, v107, v107
	v_lshrrev_b32_e32 v86, 16, v86
	v_and_or_b32 v82, v82, s28, v86
	v_lshl_add_u64 v[106:107], v[110:111], 1, s[8:9]
	v_mov_b32_e32 v86, v83
	global_store_dword v[106:107], v82, off
	v_pk_fma_f32 v[106:107], v[146:147], v[86:87], v[108:109]
	v_lshl_add_u64 v[110:111], v[90:91], 2, s[2:3]
	global_store_dwordx2 v[110:111], v[106:107], off
	v_pk_mul_f32 v[110:111], v[152:153], v[106:107]
	v_pk_mul_f32 v[94:95], v[94:95], v[94:95]
	s_nop 0
	s_nop 0
	v_cvt_pk_bf16_f32 v86, v110, v110
	v_cvt_pk_bf16_f32 v82, v111, v111
	v_lshrrev_b32_e32 v86, 16, v86
	v_and_or_b32 v82, v82, s28, v86
	v_lshl_add_u64 v[110:111], v[90:91], 1, s[8:9]
	v_pk_mul_f32 v[106:107], v[106:107], v[106:107]
	global_store_dword v[110:111], v82, off
	v_add_f32_e32 v82, v106, v107
	v_add_f32_e32 v86, v94, v95
	v_add_f32_e32 v82, v86, v82
	s_nop 1
	v_add_f32_dpp v82, v82, v82 quad_perm:[1,0,3,2] row_mask:0xf bank_mask:0xf bound_ctrl:1
	s_nop 1
	v_add_f32_dpp v82, v82, v82 quad_perm:[2,3,0,1] row_mask:0xf bank_mask:0xf bound_ctrl:1
	s_nop 1
	v_add_f32_dpp v82, v82, v82 row_half_mirror row_mask:0xf bank_mask:0xf bound_ctrl:1
	s_nop 1
	v_mov_b32_dpp v86, v82 row_mirror row_mask:0xf bank_mask:0xf bound_ctrl:1
	s_and_saveexec_b64 s[68:69], s[4:5]
	s_cbranch_execz .LBB0_157
	v_lshlrev_b32_e32 v94, 4, v160
	v_ashrrev_i32_e32 v95, 31, v94
	v_add_f32_e32 v82, v82, v86
	v_lshl_add_u64 v[94:95], v[94:95], 2, v[142:143]
	global_store_dword v[94:95], v82, off offset:2112

; __device__ __forceinline__ unsigned pack2(float a, float b) { return (unsigned)f2bf(a) | ((unsigned)f2bf(b) << 16); }
; template <int EPI, bool HS = false>
; __device__ __forceinline__ void gemm_phase(const Params& p, const GemmCfg& g, char* shm, const int wave_s) {
;     ...
;           for (int j = 0; j < 4; ++j) {
;             float ss = 0.f;
; #pragma unroll
;             for (int bj = 0; bj < 2; ++bj) {
;               float2 xn;
;               xn.x = xv[j][bj].x + gt[bj][0] * acc[ai][bj][m][0][j];
;               xn.y = xv[j][bj].y + gt[bj][1] * acc[ai][bj][m][1][j];
;               const unsigned o = tb + (unsigned)((ai * 128 + m * 16 + j) * 1024 + bj * 128);
;               *(float2*)(xout_t + o) = xn;
;               if (g.has_next) *(unsigned*)(xg_t + o) = pack2(xn.x * gn[bj][0], xn.y * gn[bj][1]);
;               ss += xn.x * xn.x + xn.y * xn.y;
;             }
;             if (g.has_next) {
;               ss = dpp_row_sum16(ss);
;               if (fr == 0) rss_t[(wr * 64 + fq * 4 + ai * 128 + m * 16 + j) * 16] = ss;
;             }
.LBB0_160:
	v_or_b32_e32 v90, 0x8800, v0
	v_mov_b32_e32 v82, v92
	v_mov_b32_e32 v83, v96
	v_mov_b32_e32 v91, v1
	s_waitcnt lgkmcnt(1)
	v_pk_fma_f32 v[86:87], v[150:151], v[82:83], v[102:103]
	v_lshl_add_u64 v[82:83], v[90:91], 2, s[2:3]
	global_store_dwordx2 v[82:83], v[86:87], off
	s_mov_b64 s[68:69], -1
	s_and_b64 vcc, exec, s[6:7]
	v_or_b32_e32 v82, 0x8880, v0
	s_cbranch_vccnz .LBB0_164
	v_pk_mul_f32 v[94:95], v[148:149], v[86:87]
	v_lshl_add_u64 v[90:91], v[90:91], 1, s[8:9]
	s_nop 0
	s_nop 0
	v_cvt_pk_bf16_f32 v92, v94, v94
	v_cvt_pk_bf16_f32 v83, v95, v95
	v_lshrrev_b32_e32 v92, 16, v92
	v_and_or_b32 v83, v83, s28, v92
	global_store_dword v[90:91], v83, off
	v_mov_b32_e32 v90, v84
	v_mov_b32_e32 v91, v88
	v_mov_b32_e32 v83, v1
	v_pk_fma_f32 v[90:91], v[146:147], v[90:91], v[104:105]
	v_lshl_add_u64 v[94:95], v[82:83], 2, s[2:3]
	global_store_dwordx2 v[94:95], v[90:91], off
	v_pk_mul_f32 v[94:95], v[152:153], v[90:91]
	v_pk_mul_f32 v[86:87], v[86:87], v[86:87]
	v_and_b32_sdwa v96, v94, v178 dst_sel:DWORD dst_unused:UNUSED_PAD src0_sel:WORD_1 src1_sel:DWORD
	s_nop 0
	v_add3_u32 v94, v94, v96, s81
	v_cvt_pk_bf16_f32 v92, v95, v95
	v_lshrrev_b32_e32 v94, 16, v94
	v_pk_mul_f32 v[90:91], v[90:91], v[90:91]
	v_and_or_b32 v92, v92, s28, v94
	v_lshl_add_u64 v[94:95], v[82:83], 1, s[8:9]
	v_add_f32_e32 v83, v90, v91
	v_add_f32_e32 v86, v86, v87
	v_add_f32_e32 v83, v86, v83
	global_store_dword v[94:95], v92, off
	s_nop 0
	v_add_f32_dpp v83, v83, v83 quad_perm:[1,0,3,2] row_mask:0xf bank_mask:0xf bound_ctrl:1
	s_nop 1
	v_add_f32_dpp v83, v83, v83 quad_perm:[2,3,0,1] row_mask:0xf bank_mask:0xf bound_ctrl:1
	s_nop 1
	v_add_f32_dpp v83, v83, v83 row_half_mirror row_mask:0xf bank_mask:0xf bound_ctrl:1
	s_nop 1
	v_mov_b32_dpp v86, v83 row_mirror row_mask:0xf bank_mask:0xf bound_ctrl:1
	s_and_saveexec_b64 s[68:69], s[4:5]
	s_cbranch_execz .LBB0_163
	v_add_f32_e32 v83, v83, v86
	v_lshlrev_b32_e32 v86, 4, v160
	v_ashrrev_i32_e32 v87, 31, v86
	v_lshl_add_u64 v[86:87], v[86:87], 2, v[142:143]
	global_store_dword v[86:87], v83, off offset:2176

; __device__ __forceinline__ unsigned pack2(float a, float b) { return (unsigned)f2bf(a) | ((unsigned)f2bf(b) << 16); }
; template <int EPI, bool HS = false>
; __device__ __forceinline__ void gemm_phase(const Params& p, const GemmCfg& g, char* shm, const int wave_s) {
;     ...
;           for (int j = 0; j < 4; ++j) {
;             float ss = 0.f;
; #pragma unroll
;             for (int bj = 0; bj < 2; ++bj) {
;               float2 xn;
;               xn.x = xv[j][bj].x + gt[bj][0] * acc[ai][bj][m][0][j];
;               xn.y = xv[j][bj].y + gt[bj][1] * acc[ai][bj][m][1][j];
;               const unsigned o = tb + (unsigned)((ai * 128 + m * 16 + j) * 1024 + bj * 128);
;               *(float2*)(xout_t + o) = xn;
;               if (g.has_next) *(unsigned*)(xg_t + o) = pack2(xn.x * gn[bj][0], xn.y * gn[bj][1]);
;               ss += xn.x * xn.x + xn.y * xn.y;
;             }
;             if (g.has_next) {
;               ss = dpp_row_sum16(ss);
;               if (fr == 0) rss_t[(wr * 64 + fq * 4 + ai * 128 + m * 16 + j) * 16] = ss;
;             }
.LBB0_166:
	v_or_b32_e32 v90, 0x8c00, v0
	v_mov_b32_e32 v96, v93
	v_mov_b32_e32 v91, v1
	s_waitcnt lgkmcnt(0)
	v_pk_fma_f32 v[86:87], v[150:151], v[96:97], v[98:99]
	v_lshl_add_u64 v[82:83], v[90:91], 2, s[2:3]
	global_store_dwordx2 v[82:83], v[86:87], off
	s_mov_b64 s[68:69], -1
	s_and_b64 vcc, exec, s[6:7]
	v_or_b32_e32 v82, 0x8c80, v0
	s_cbranch_vccnz .LBB0_170
	v_pk_mul_f32 v[92:93], v[148:149], v[86:87]
	v_lshl_add_u64 v[90:91], v[90:91], 1, s[8:9]
	s_nop 0
	s_nop 0
	v_cvt_pk_bf16_f32 v84, v92, v92
	v_cvt_pk_bf16_f32 v83, v93, v93
	v_lshrrev_b32_e32 v84, 16, v84
	v_and_or_b32 v83, v83, s28, v84
	global_store_dword v[90:91], v83, off
	v_mov_b32_e32 v88, v85
	v_mov_b32_e32 v83, v1
	v_pk_fma_f32 v[90:91], v[146:147], v[88:89], v[100:101]
	v_lshl_add_u64 v[92:93], v[82:83], 2, s[2:3]
	global_store_dwordx2 v[92:93], v[90:91], off
	v_pk_mul_f32 v[92:93], v[152:153], v[90:91]
	v_pk_mul_f32 v[86:87], v[86:87], v[86:87]
	s_nop 0
	s_nop 0
	v_cvt_pk_bf16_f32 v88, v92, v92
	v_cvt_pk_bf16_f32 v84, v93, v93
	v_lshrrev_b32_e32 v88, 16, v88
	v_and_or_b32 v84, v84, s28, v88
	v_lshl_add_u64 v[92:93], v[82:83], 1, s[8:9]
	v_pk_mul_f32 v[90:91], v[90:91], v[90:91]
	global_store_dword v[92:93], v84, off
	v_add_f32_e32 v83, v90, v91
	v_add_f32_e32 v84, v86, v87
	v_add_f32_e32 v83, v84, v83
	s_nop 1
	v_add_f32_dpp v83, v83, v83 quad_perm:[1,0,3,2] row_mask:0xf bank_mask:0xf bound_ctrl:1
	s_nop 1
	v_add_f32_dpp v83, v83, v83 quad_perm:[2,3,0,1] row_mask:0xf bank_mask:0xf bound_ctrl:1
	s_nop 1
	v_add_f32_dpp v83, v83, v83 row_half_mirror row_mask:0xf bank_mask:0xf bound_ctrl:1
	s_nop 1
	v_mov_b32_dpp v84, v83 row_mirror row_mask:0xf bank_mask:0xf bound_ctrl:1
	s_and_saveexec_b64 s[68:69], s[4:5]
	s_cbranch_execz .LBB0_169
	v_lshlrev_b32_e32 v86, 4, v160
	v_ashrrev_i32_e32 v87, 31, v86
	v_add_f32_e32 v83, v83, v84
	v_lshl_add_u64 v[86:87], v[86:87], 2, v[142:143]
	global_store_dword v[86:87], v83, off offset:2240

; __device__ __forceinline__ unsigned pack2(float a, float b) { return (unsigned)f2bf(a) | ((unsigned)f2bf(b) << 16); }
; template <int EPI, bool HS = false>
; __device__ __forceinline__ void gemm_phase(const Params& p, const GemmCfg& g, char* shm, const int wave_s) {
;     ...
;             for (int bj = 0; bj < 2; ++bj) xv[j][bj] = *(const float2*)(xl + (m * 16 + j) * XROW + bj * 512);
; #pragma unroll
;           for (int j = 0; j < 4; ++j) {
;             float ss = 0.f;
; #pragma unroll
;             for (int bj = 0; bj < 2; ++bj) {
;               float2 xn;
;               xn.x = xv[j][bj].x + gt[bj][0] * acc[ai][bj][m][0][j];
;               xn.y = xv[j][bj].y + gt[bj][1] * acc[ai][bj][m][1][j];
;               const unsigned o = tb + (unsigned)((ai * 128 + m * 16 + j) * 1024 + bj * 128);
;               *(float2*)(xout_t + o) = xn;
;               if (g.has_next) *(unsigned*)(xg_t + o) = pack2(xn.x * gn[bj][0], xn.y * gn[bj][1]);
;               ss += xn.x * xn.x + xn.y * xn.y;
;             }
;             if (g.has_next) {
;               ss = dpp_row_sum16(ss);
;               if (fr == 0) rss_t[(wr * 64 + fq * 4 + ai * 128 + m * 16 + j) * 16] = ss;
;             }
.LBB0_172:
	ds_read2st64_b64 v[94:97], v134 offset0:97 offset1:98
	ds_read2st64_b64 v[90:93], v135 offset0:99 offset1:100
	ds_read2st64_b64 v[86:89], v136 offset0:101 offset1:102
	ds_read2st64_b64 v[82:85], v137 offset0:103 offset1:104
	v_or_b32_e32 v100, 0xc000, v0
	v_mov_b32_e32 v98, v74
	v_mov_b32_e32 v99, v78
	v_mov_b32_e32 v101, v1
	s_waitcnt lgkmcnt(3)
	v_pk_fma_f32 v[98:99], v[150:151], v[98:99], v[94:95]
	v_lshl_add_u64 v[94:95], v[100:101], 2, s[2:3]
	global_store_dwordx2 v[94:95], v[98:99], off
	s_mov_b64 s[68:69], -1
	s_and_b64 vcc, exec, s[6:7]
	v_or_b32_e32 v94, 0xc080, v0
	s_cbranch_vccnz .LBB0_176
	v_pk_mul_f32 v[102:103], v[148:149], v[98:99]
	v_lshl_add_u64 v[100:101], v[100:101], 1, s[8:9]
	s_nop 0
	s_nop 0
	v_cvt_pk_bf16_f32 v78, v102, v102
	v_cvt_pk_bf16_f32 v74, v103, v103
	v_lshrrev_b32_e32 v78, 16, v78
	v_and_or_b32 v74, v74, s28, v78
	global_store_dword v[100:101], v74, off
	v_mov_b32_e32 v100, v66
	v_mov_b32_e32 v101, v70
	v_mov_b32_e32 v95, v1
	v_pk_fma_f32 v[100:101], v[146:147], v[100:101], v[96:97]
	v_lshl_add_u64 v[102:103], v[94:95], 2, s[2:3]
	global_store_dwordx2 v[102:103], v[100:101], off
	v_pk_mul_f32 v[102:103], v[152:153], v[100:101]
	v_pk_mul_f32 v[98:99], v[98:99], v[98:99]
	s_nop 0
	s_nop 0
	v_cvt_pk_bf16_f32 v78, v102, v102
	v_cvt_pk_bf16_f32 v74, v103, v103
	v_lshrrev_b32_e32 v78, 16, v78
	v_and_or_b32 v74, v74, s28, v78
	v_lshl_add_u64 v[102:103], v[94:95], 1, s[8:9]
	v_pk_mul_f32 v[100:101], v[100:101], v[100:101]
	global_store_dword v[102:103], v74, off
	v_add_f32_e32 v74, v100, v101
	v_add_f32_e32 v78, v98, v99
	v_add_f32_e32 v74, v78, v74
	s_nop 1
	v_add_f32_dpp v74, v74, v74 quad_perm:[1,0,3,2] row_mask:0xf bank_mask:0xf bound_ctrl:1
	s_nop 1
	v_add_f32_dpp v74, v74, v74 quad_perm:[2,3,0,1] row_mask:0xf bank_mask:0xf bound_ctrl:1
	s_nop 1
	v_add_f32_dpp v74, v74, v74 row_half_mirror row_mask:0xf bank_mask:0xf bound_ctrl:1
	s_nop 1
	v_mov_b32_dpp v78, v74 row_mirror row_mask:0xf bank_mask:0xf bound_ctrl:1
	s_and_saveexec_b64 s[68:69], s[4:5]
	s_cbranch_execz .LBB0_175
	v_lshlrev_b32_e32 v98, 4, v160
	v_ashrrev_i32_e32 v99, 31, v98
	v_add_f32_e32 v74, v74, v78
	v_lshl_add_u64 v[98:99], v[98:99], 2, v[142:143]
	global_store_dword v[98:99], v74, off offset:3072

; __device__ __forceinline__ unsigned pack2(float a, float b) { return (unsigned)f2bf(a) | ((unsigned)f2bf(b) << 16); }
; template <int EPI, bool HS = false>
; __device__ __forceinline__ void gemm_phase(const Params& p, const GemmCfg& g, char* shm, const int wave_s) {
;     ...
;           for (int j = 0; j < 4; ++j) {
;             float ss = 0.f;
; #pragma unroll
;             for (int bj = 0; bj < 2; ++bj) {
;               float2 xn;
;               xn.x = xv[j][bj].x + gt[bj][0] * acc[ai][bj][m][0][j];
;               xn.y = xv[j][bj].y + gt[bj][1] * acc[ai][bj][m][1][j];
;               const unsigned o = tb + (unsigned)((ai * 128 + m * 16 + j) * 1024 + bj * 128);
;               *(float2*)(xout_t + o) = xn;
;               if (g.has_next) *(unsigned*)(xg_t + o) = pack2(xn.x * gn[bj][0], xn.y * gn[bj][1]);
;               ss += xn.x * xn.x + xn.y * xn.y;
;             }
;             if (g.has_next) {
;               ss = dpp_row_sum16(ss);
;               if (fr == 0) rss_t[(wr * 64 + fq * 4 + ai * 128 + m * 16 + j) * 16] = ss;
;             }
.LBB0_178:
	v_or_b32_e32 v94, 0xc400, v0
	v_mov_b32_e32 v78, v75
	v_mov_b32_e32 v95, v1
	s_waitcnt lgkmcnt(2)
	v_pk_fma_f32 v[78:79], v[150:151], v[78:79], v[90:91]
	v_lshl_add_u64 v[74:75], v[94:95], 2, s[2:3]
	global_store_dwordx2 v[74:75], v[78:79], off
	s_mov_b64 s[68:69], -1
	s_and_b64 vcc, exec, s[6:7]
	v_or_b32_e32 v74, 0xc480, v0
	s_cbranch_vccnz .LBB0_182
	v_pk_mul_f32 v[90:91], v[148:149], v[78:79]
	v_mov_b32_e32 v75, v1
	s_nop 0
	s_nop 0
	v_cvt_pk_bf16_f32 v70, v90, v90
	v_cvt_pk_bf16_f32 v66, v91, v91
	v_lshrrev_b32_e32 v70, 16, v70
	v_and_or_b32 v66, v66, s28, v70
	v_lshl_add_u64 v[90:91], v[94:95], 1, s[8:9]
	v_mov_b32_e32 v70, v67
	global_store_dword v[90:91], v66, off
	v_pk_fma_f32 v[90:91], v[146:147], v[70:71], v[92:93]
	v_lshl_add_u64 v[94:95], v[74:75], 2, s[2:3]
	global_store_dwordx2 v[94:95], v[90:91], off
	v_pk_mul_f32 v[94:95], v[152:153], v[90:91]
	v_pk_mul_f32 v[78:79], v[78:79], v[78:79]
	s_nop 0
	s_nop 0
	v_cvt_pk_bf16_f32 v70, v94, v94
	v_cvt_pk_bf16_f32 v66, v95, v95
	v_lshrrev_b32_e32 v70, 16, v70
	v_and_or_b32 v66, v66, s28, v70
	v_lshl_add_u64 v[94:95], v[74:75], 1, s[8:9]
	v_pk_mul_f32 v[90:91], v[90:91], v[90:91]
	global_store_dword v[94:95], v66, off
	v_add_f32_e32 v66, v90, v91
	v_add_f32_e32 v70, v78, v79
	v_add_f32_e32 v66, v70, v66
	s_nop 1
	v_add_f32_dpp v66, v66, v66 quad_perm:[1,0,3,2] row_mask:0xf bank_mask:0xf bound_ctrl:1
	s_nop 1
	v_add_f32_dpp v66, v66, v66 quad_perm:[2,3,0,1] row_mask:0xf bank_mask:0xf bound_ctrl:1
	s_nop 1
	v_add_f32_dpp v66, v66, v66 row_half_mirror row_mask:0xf bank_mask:0xf bound_ctrl:1
	s_nop 1
	v_mov_b32_dpp v70, v66 row_mirror row_mask:0xf bank_mask:0xf bound_ctrl:1
	s_and_saveexec_b64 s[68:69], s[4:5]
	s_cbranch_execz .LBB0_181
	v_lshlrev_b32_e32 v78, 4, v160
	v_ashrrev_i32_e32 v79, 31, v78
	v_add_f32_e32 v66, v66, v70
	v_lshl_add_u64 v[78:79], v[78:79], 2, v[142:143]
	global_store_dword v[78:79], v66, off offset:3136

; __device__ __forceinline__ unsigned pack2(float a, float b) { return (unsigned)f2bf(a) | ((unsigned)f2bf(b) << 16); }
; template <int EPI, bool HS = false>
; __device__ __forceinline__ void gemm_phase(const Params& p, const GemmCfg& g, char* shm, const int wave_s) {
;     ...
;           for (int j = 0; j < 4; ++j) {
;             float ss = 0.f;
; #pragma unroll
;             for (int bj = 0; bj < 2; ++bj) {
;               float2 xn;
;               xn.x = xv[j][bj].x + gt[bj][0] * acc[ai][bj][m][0][j];
;               xn.y = xv[j][bj].y + gt[bj][1] * acc[ai][bj][m][1][j];
;               const unsigned o = tb + (unsigned)((ai * 128 + m * 16 + j) * 1024 + bj * 128);
;               *(float2*)(xout_t + o) = xn;
;               if (g.has_next) *(unsigned*)(xg_t + o) = pack2(xn.x * gn[bj][0], xn.y * gn[bj][1]);
;               ss += xn.x * xn.x + xn.y * xn.y;
;             }
;             if (g.has_next) {
;               ss = dpp_row_sum16(ss);
;               if (fr == 0) rss_t[(wr * 64 + fq * 4 + ai * 128 + m * 16 + j) * 16] = ss;
;             }
.LBB0_184:
	v_or_b32_e32 v74, 0xc800, v0
	v_mov_b32_e32 v66, v76
	v_mov_b32_e32 v67, v80
	v_mov_b32_e32 v75, v1
	s_waitcnt lgkmcnt(1)
	v_pk_fma_f32 v[70:71], v[150:151], v[66:67], v[86:87]
	v_lshl_add_u64 v[66:67], v[74:75], 2, s[2:3]
	global_store_dwordx2 v[66:67], v[70:71], off
	s_mov_b64 s[68:69], -1
	s_and_b64 vcc, exec, s[6:7]
	v_or_b32_e32 v66, 0xc880, v0
	s_cbranch_vccnz .LBB0_188
	v_pk_mul_f32 v[78:79], v[148:149], v[70:71]
	v_lshl_add_u64 v[74:75], v[74:75], 1, s[8:9]
	s_nop 0
	s_nop 0
	v_cvt_pk_bf16_f32 v76, v78, v78
	v_cvt_pk_bf16_f32 v67, v79, v79
	v_lshrrev_b32_e32 v76, 16, v76
	v_and_or_b32 v67, v67, s28, v76
	global_store_dword v[74:75], v67, off
	v_mov_b32_e32 v74, v68
	v_mov_b32_e32 v75, v72
	v_mov_b32_e32 v67, v1
	v_pk_fma_f32 v[74:75], v[146:147], v[74:75], v[88:89]
	v_lshl_add_u64 v[78:79], v[66:67], 2, s[2:3]
	global_store_dwordx2 v[78:79], v[74:75], off
	v_pk_mul_f32 v[78:79], v[152:153], v[74:75]
	v_pk_mul_f32 v[70:71], v[70:71], v[70:71]
	v_and_b32_sdwa v80, v78, v178 dst_sel:DWORD dst_unused:UNUSED_PAD src0_sel:WORD_1 src1_sel:DWORD
	s_nop 0
	v_add3_u32 v78, v78, v80, s81
	v_cvt_pk_bf16_f32 v76, v79, v79
	v_lshrrev_b32_e32 v78, 16, v78
	v_pk_mul_f32 v[74:75], v[74:75], v[74:75]
	v_and_or_b32 v76, v76, s28, v78
	v_lshl_add_u64 v[78:79], v[66:67], 1, s[8:9]
	v_add_f32_e32 v67, v74, v75
	v_add_f32_e32 v70, v70, v71
	v_add_f32_e32 v67, v70, v67
	global_store_dword v[78:79], v76, off
	s_nop 0
	v_add_f32_dpp v67, v67, v67 quad_perm:[1,0,3,2] row_mask:0xf bank_mask:0xf bound_ctrl:1
	s_nop 1
	v_add_f32_dpp v67, v67, v67 quad_perm:[2,3,0,1] row_mask:0xf bank_mask:0xf bound_ctrl:1
	s_nop 1
	v_add_f32_dpp v67, v67, v67 row_half_mirror row_mask:0xf bank_mask:0xf bound_ctrl:1
	s_nop 1
	v_mov_b32_dpp v70, v67 row_mirror row_mask:0xf bank_mask:0xf bound_ctrl:1
	s_and_saveexec_b64 s[68:69], s[4:5]
	s_cbranch_execz .LBB0_187
	v_add_f32_e32 v67, v67, v70
	v_lshlrev_b32_e32 v70, 4, v160
	v_ashrrev_i32_e32 v71, 31, v70
	v_lshl_add_u64 v[70:71], v[70:71], 2, v[142:143]
	global_store_dword v[70:71], v67, off offset:3200

; __device__ __forceinline__ unsigned pack2(float a, float b) { return (unsigned)f2bf(a) | ((unsigned)f2bf(b) << 16); }
; template <int EPI, bool HS = false>
; __device__ __forceinline__ void gemm_phase(const Params& p, const GemmCfg& g, char* shm, const int wave_s) {
;     ...
;           for (int j = 0; j < 4; ++j) {
;             float ss = 0.f;
; #pragma unroll
;             for (int bj = 0; bj < 2; ++bj) {
;               float2 xn;
;               xn.x = xv[j][bj].x + gt[bj][0] * acc[ai][bj][m][0][j];
;               xn.y = xv[j][bj].y + gt[bj][1] * acc[ai][bj][m][1][j];
;               const unsigned o = tb + (unsigned)((ai * 128 + m * 16 + j) * 1024 + bj * 128);
;               *(float2*)(xout_t + o) = xn;
;               if (g.has_next) *(unsigned*)(xg_t + o) = pack2(xn.x * gn[bj][0], xn.y * gn[bj][1]);
;               ss += xn.x * xn.x + xn.y * xn.y;
;             }
;             if (g.has_next) {
;               ss = dpp_row_sum16(ss);
;               if (fr == 0) rss_t[(wr * 64 + fq * 4 + ai * 128 + m * 16 + j) * 16] = ss;
;             }
.LBB0_190:
	v_or_b32_e32 v74, 0xcc00, v0
	v_mov_b32_e32 v80, v77
	v_mov_b32_e32 v75, v1
	s_waitcnt lgkmcnt(0)
	v_pk_fma_f32 v[70:71], v[150:151], v[80:81], v[82:83]
	v_lshl_add_u64 v[66:67], v[74:75], 2, s[2:3]
	global_store_dwordx2 v[66:67], v[70:71], off
	s_mov_b64 s[68:69], -1
	s_and_b64 vcc, exec, s[6:7]
	v_or_b32_e32 v66, 0xcc80, v0
	s_cbranch_vccnz .LBB0_194
	v_pk_mul_f32 v[76:77], v[148:149], v[70:71]
	v_lshl_add_u64 v[74:75], v[74:75], 1, s[8:9]
	s_nop 0
	s_nop 0
	v_cvt_pk_bf16_f32 v68, v76, v76
	v_cvt_pk_bf16_f32 v67, v77, v77
	v_lshrrev_b32_e32 v68, 16, v68
	v_and_or_b32 v67, v67, s28, v68
	global_store_dword v[74:75], v67, off
	v_mov_b32_e32 v72, v69
	v_mov_b32_e32 v67, v1
	v_pk_fma_f32 v[74:75], v[146:147], v[72:73], v[84:85]
	v_lshl_add_u64 v[76:77], v[66:67], 2, s[2:3]
	global_store_dwordx2 v[76:77], v[74:75], off
	v_pk_mul_f32 v[76:77], v[152:153], v[74:75]
	v_pk_mul_f32 v[70:71], v[70:71], v[70:71]
	s_nop 0
	s_nop 0
	v_cvt_pk_bf16_f32 v72, v76, v76
	v_cvt_pk_bf16_f32 v68, v77, v77
	v_lshrrev_b32_e32 v72, 16, v72
	v_and_or_b32 v68, v68, s28, v72
	v_lshl_add_u64 v[76:77], v[66:67], 1, s[8:9]
	v_pk_mul_f32 v[74:75], v[74:75], v[74:75]
	global_store_dword v[76:77], v68, off
	v_add_f32_e32 v67, v74, v75
	v_add_f32_e32 v68, v70, v71
	v_add_f32_e32 v67, v68, v67
	s_nop 1
	v_add_f32_dpp v67, v67, v67 quad_perm:[1,0,3,2] row_mask:0xf bank_mask:0xf bound_ctrl:1
	s_nop 1
	v_add_f32_dpp v67, v67, v67 quad_perm:[2,3,0,1] row_mask:0xf bank_mask:0xf bound_ctrl:1
	s_nop 1
	v_add_f32_dpp v67, v67, v67 row_half_mirror row_mask:0xf bank_mask:0xf bound_ctrl:1
	s_nop 1
	v_mov_b32_dpp v68, v67 row_mirror row_mask:0xf bank_mask:0xf bound_ctrl:1
	s_and_saveexec_b64 s[68:69], s[4:5]
	s_cbranch_execz .LBB0_193
	v_lshlrev_b32_e32 v70, 4, v160
	v_ashrrev_i32_e32 v71, 31, v70
	v_add_f32_e32 v67, v67, v68
	v_lshl_add_u64 v[70:71], v[70:71], 2, v[142:143]
	global_store_dword v[70:71], v67, off offset:3264

; __device__ __forceinline__ unsigned pack2(float a, float b) { return (unsigned)f2bf(a) | ((unsigned)f2bf(b) << 16); }
; #define WAIT_V(n) asm volatile("s_waitcnt vmcnt(" #n ")" ::: "memory")
; template <int EPI, bool HS = false>
; __device__ __forceinline__ void gemm_phase(const Params& p, const GemmCfg& g, char* shm, const int wave_s) {
;     ...
;         for (int i = 0; i < 16; ++i) {
;           const int r = wv_s * 16 + i;
;           glds_row(xin_t + (size_t)(ai * 128 + r) * 1024, (unsigned)lane * 16u, ldsb + (unsigned)(r * XROW));
;         }
;         WAIT_V(0);
;         __syncthreads();
; #pragma unroll
;         for (int m = 0; m < 4; ++m) {
;           float2 xv[4][2];
; #pragma unroll
;           for (int j = 0; j < 4; ++j)
; #pragma unroll
;             for (int bj = 0; bj < 2; ++bj) xv[j][bj] = *(const float2*)(xl + (m * 16 + j) * XROW + bj * 512);
; #pragma unroll
;           for (int j = 0; j < 4; ++j) {
;             float ss = 0.f;
; #pragma unroll
;             for (int bj = 0; bj < 2; ++bj) {
;               float2 xn;
;               xn.x = xv[j][bj].x + gt[bj][0] * acc[ai][bj][m][0][j];
;               xn.y = xv[j][bj].y + gt[bj][1] * acc[ai][bj][m][1][j];
;               const unsigned o = tb + (unsigned)((ai * 128 + m * 16 + j) * 1024 + bj * 128);
;               *(float2*)(xout_t + o) = xn;
;               if (g.has_next) *(unsigned*)(xg_t + o) = pack2(xn.x * gn[bj][0], xn.y * gn[bj][1]);
;               ss += xn.x * xn.x + xn.y * xn.y;
;             }
;             if (g.has_next) {
;               ss = dpp_row_sum16(ss);
;               if (fr == 0) rss_t[(wr * 64 + fq * 4 + ai * 128 + m * 16 + j) * 16] = ss;
;             }
.LBB0_196:
	s_lshl_b64 s[10:11], s[10:11], 12
	s_add_u32 s26, s71, s10
	s_addc_u32 s27, s75, s11
	s_add_u32 s10, s26, 0x80000
	s_addc_u32 s11, s27, 0
	s_waitcnt vmcnt(63) expcnt(7) lgkmcnt(15)
	s_barrier
	s_mov_b32 m0, s70
	s_nop 0
	global_load_lds_dwordx4 v164, s[10:11]
	s_add_u32 s10, s26, 0x81000
	s_addc_u32 s11, s27, 0
	s_mov_b32 m0, s76
	s_nop 0
	global_load_lds_dwordx4 v164, s[10:11]
	s_add_u32 s10, s26, 0x82000
	s_addc_u32 s11, s27, 0
	s_mov_b32 m0, s12
	s_nop 0
	global_load_lds_dwordx4 v164, s[10:11]
	s_add_u32 s10, s26, 0x83000
	s_addc_u32 s11, s27, 0
	s_mov_b32 m0, s13
	s_nop 0
	global_load_lds_dwordx4 v164, s[10:11]
	s_add_u32 s10, s26, 0x84000
	s_addc_u32 s11, s27, 0
	s_mov_b32 m0, s14
	s_nop 0
	global_load_lds_dwordx4 v164, s[10:11]
	s_add_u32 s10, s26, 0x85000
	s_addc_u32 s11, s27, 0
	s_mov_b32 m0, s15
	s_nop 0
	global_load_lds_dwordx4 v164, s[10:11]
	s_add_u32 s10, s26, 0x86000
	s_addc_u32 s11, s27, 0
	s_mov_b32 m0, s16
	s_nop 0
	global_load_lds_dwordx4 v164, s[10:11]
	s_add_u32 s10, s26, 0x87000
	s_addc_u32 s11, s27, 0
	s_mov_b32 m0, s17
	s_nop 0
	global_load_lds_dwordx4 v164, s[10:11]
	s_add_u32 s10, s26, 0x88000
	s_addc_u32 s11, s27, 0
	s_mov_b32 m0, s18
	s_nop 0
	global_load_lds_dwordx4 v164, s[10:11]
	s_add_u32 s10, s26, 0x89000
	s_addc_u32 s11, s27, 0
	s_mov_b32 m0, s19
	s_nop 0
	global_load_lds_dwordx4 v164, s[10:11]
	s_add_u32 s10, s26, 0x8a000
	s_addc_u32 s11, s27, 0
	s_mov_b32 m0, s20
	s_nop 0
	global_load_lds_dwordx4 v164, s[10:11]
	s_add_u32 s10, s26, 0x8b000
	s_addc_u32 s11, s27, 0
	s_mov_b32 m0, s21
	s_nop 0
	global_load_lds_dwordx4 v164, s[10:11]
	s_add_u32 s10, s26, 0x8c000
	s_addc_u32 s11, s27, 0
	s_mov_b32 m0, s22
	s_nop 0
	global_load_lds_dwordx4 v164, s[10:11]
	s_add_u32 s10, s26, 0x8d000
	s_addc_u32 s11, s27, 0
	s_mov_b32 m0, s23
	s_nop 0
	global_load_lds_dwordx4 v164, s[10:11]
	s_add_u32 s10, s26, 0x8e000
	s_addc_u32 s11, s27, 0
	s_mov_b32 m0, s24
	s_nop 0
	global_load_lds_dwordx4 v164, s[10:11]
	s_add_u32 s10, s26, 0x8f000
	s_addc_u32 s11, s27, 0
	s_mov_b32 m0, s25
	s_nop 0
	global_load_lds_dwordx4 v164, s[10:11]
	s_waitcnt vmcnt(0)
	s_barrier
	ds_read2st64_b64 v[78:81], v161 offset1:1
	ds_read2_b64 v[74:77], v161 offset0:130 offset1:194
	ds_read2st64_b64 v[70:73], v162 offset0:4 offset1:5
	ds_read2st64_b64 v[66:69], v163 offset0:6 offset1:7
	v_add_u32_e32 v84, 0x20000, v0
	v_mov_b32_e32 v82, v58
	v_mov_b32_e32 v83, v62
	v_mov_b32_e32 v85, v1
	s_waitcnt lgkmcnt(3)
	v_pk_fma_f32 v[82:83], v[150:151], v[82:83], v[78:79]
	v_lshl_add_u64 v[78:79], v[84:85], 2, s[2:3]
	global_store_dwordx2 v[78:79], v[82:83], off
	s_mov_b64 s[10:11], -1
	s_and_b64 vcc, exec, s[6:7]
	v_add_u32_e32 v78, 0x20080, v0
	s_cbranch_vccnz .LBB0_200
	v_pk_mul_f32 v[86:87], v[148:149], v[82:83]
	v_lshl_add_u64 v[84:85], v[84:85], 1, s[8:9]
	s_nop 0
	s_nop 0
	v_cvt_pk_bf16_f32 v62, v86, v86
	v_cvt_pk_bf16_f32 v58, v87, v87
	v_lshrrev_b32_e32 v62, 16, v62
	v_and_or_b32 v58, v58, s28, v62
	global_store_dword v[84:85], v58, off
	v_mov_b32_e32 v84, v50
	v_mov_b32_e32 v85, v54
	v_mov_b32_e32 v79, v1
	v_pk_fma_f32 v[84:85], v[146:147], v[84:85], v[80:81]
	v_lshl_add_u64 v[86:87], v[78:79], 2, s[2:3]
	global_store_dwordx2 v[86:87], v[84:85], off
	v_pk_mul_f32 v[86:87], v[152:153], v[84:85]
	v_pk_mul_f32 v[82:83], v[82:83], v[82:83]
	s_nop 0
	s_nop 0
	v_cvt_pk_bf16_f32 v62, v86, v86
	v_cvt_pk_bf16_f32 v58, v87, v87
	v_lshrrev_b32_e32 v62, 16, v62
	v_and_or_b32 v58, v58, s28, v62
	v_lshl_add_u64 v[86:87], v[78:79], 1, s[8:9]
	v_pk_mul_f32 v[84:85], v[84:85], v[84:85]
	global_store_dword v[86:87], v58, off
	v_add_f32_e32 v58, v84, v85
	v_add_f32_e32 v62, v82, v83
	v_add_f32_e32 v58, v62, v58
	s_nop 1
	v_add_f32_dpp v58, v58, v58 quad_perm:[1,0,3,2] row_mask:0xf bank_mask:0xf bound_ctrl:1
	s_nop 1
	v_add_f32_dpp v58, v58, v58 quad_perm:[2,3,0,1] row_mask:0xf bank_mask:0xf bound_ctrl:1
	s_nop 1
	v_add_f32_dpp v58, v58, v58 row_half_mirror row_mask:0xf bank_mask:0xf bound_ctrl:1
	s_nop 1
	v_mov_b32_dpp v62, v58 row_mirror row_mask:0xf bank_mask:0xf bound_ctrl:1
	s_and_saveexec_b64 s[10:11], s[4:5]
	s_cbranch_execz .LBB0_199
	v_add_f32_e32 v58, v58, v62
	v_mov_b32_e32 v62, 0x800
	v_lshl_add_u32 v82, v160, 4, v62
	v_ashrrev_i32_e32 v83, 31, v82
	v_lshl_add_u64 v[82:83], v[82:83], 2, v[142:143]
	global_store_dword v[82:83], v58, off

; __device__ __forceinline__ unsigned pack2(float a, float b) { return (unsigned)f2bf(a) | ((unsigned)f2bf(b) << 16); }
; template <int EPI, bool HS = false>
; __device__ __forceinline__ void gemm_phase(const Params& p, const GemmCfg& g, char* shm, const int wave_s) {
;     ...
;           for (int j = 0; j < 4; ++j) {
;             float ss = 0.f;
; #pragma unroll
;             for (int bj = 0; bj < 2; ++bj) {
;               float2 xn;
;               xn.x = xv[j][bj].x + gt[bj][0] * acc[ai][bj][m][0][j];
;               xn.y = xv[j][bj].y + gt[bj][1] * acc[ai][bj][m][1][j];
;               const unsigned o = tb + (unsigned)((ai * 128 + m * 16 + j) * 1024 + bj * 128);
;               *(float2*)(xout_t + o) = xn;
;               if (g.has_next) *(unsigned*)(xg_t + o) = pack2(xn.x * gn[bj][0], xn.y * gn[bj][1]);
;               ss += xn.x * xn.x + xn.y * xn.y;
;             }
;             if (g.has_next) {
;               ss = dpp_row_sum16(ss);
;               if (fr == 0) rss_t[(wr * 64 + fq * 4 + ai * 128 + m * 16 + j) * 16] = ss;
;             }
.LBB0_202:
	v_add_u32_e32 v78, 0x20400, v0
	v_mov_b32_e32 v62, v59
	v_mov_b32_e32 v79, v1
	s_waitcnt lgkmcnt(2)
	v_pk_fma_f32 v[62:63], v[150:151], v[62:63], v[74:75]
	v_lshl_add_u64 v[58:59], v[78:79], 2, s[2:3]
	global_store_dwordx2 v[58:59], v[62:63], off
	s_mov_b64 s[10:11], -1
	s_and_b64 vcc, exec, s[6:7]
	v_add_u32_e32 v58, 0x20480, v0
	s_cbranch_vccnz .LBB0_206
	v_pk_mul_f32 v[74:75], v[148:149], v[62:63]
	v_mov_b32_e32 v59, v1
	s_nop 0
	s_nop 0
	v_cvt_pk_bf16_f32 v54, v74, v74
	v_cvt_pk_bf16_f32 v50, v75, v75
	v_lshrrev_b32_e32 v54, 16, v54
	v_and_or_b32 v50, v50, s28, v54
	v_lshl_add_u64 v[74:75], v[78:79], 1, s[8:9]
	v_mov_b32_e32 v54, v51
	global_store_dword v[74:75], v50, off
	v_pk_fma_f32 v[74:75], v[146:147], v[54:55], v[76:77]
	v_lshl_add_u64 v[78:79], v[58:59], 2, s[2:3]
	global_store_dwordx2 v[78:79], v[74:75], off
	v_pk_mul_f32 v[78:79], v[152:153], v[74:75]
	v_pk_mul_f32 v[62:63], v[62:63], v[62:63]
	s_nop 0
	s_nop 0
	v_cvt_pk_bf16_f32 v54, v78, v78
	v_cvt_pk_bf16_f32 v50, v79, v79
	v_lshrrev_b32_e32 v54, 16, v54
	v_and_or_b32 v50, v50, s28, v54
	v_lshl_add_u64 v[78:79], v[58:59], 1, s[8:9]
	v_pk_mul_f32 v[74:75], v[74:75], v[74:75]
	global_store_dword v[78:79], v50, off
	v_add_f32_e32 v50, v74, v75
	v_add_f32_e32 v54, v62, v63
	v_add_f32_e32 v50, v54, v50
	s_nop 1
	v_add_f32_dpp v50, v50, v50 quad_perm:[1,0,3,2] row_mask:0xf bank_mask:0xf bound_ctrl:1
	s_nop 1
	v_add_f32_dpp v50, v50, v50 quad_perm:[2,3,0,1] row_mask:0xf bank_mask:0xf bound_ctrl:1
	s_nop 1
	v_add_f32_dpp v50, v50, v50 row_half_mirror row_mask:0xf bank_mask:0xf bound_ctrl:1
	s_nop 1
	v_mov_b32_dpp v54, v50 row_mirror row_mask:0xf bank_mask:0xf bound_ctrl:1
	s_and_saveexec_b64 s[10:11], s[4:5]
	s_cbranch_execz .LBB0_205
	v_add_f32_e32 v50, v50, v54
	v_mov_b32_e32 v54, 0x810
	v_lshl_add_u32 v62, v160, 4, v54
	v_ashrrev_i32_e32 v63, 31, v62
	v_lshl_add_u64 v[62:63], v[62:63], 2, v[142:143]
	global_store_dword v[62:63], v50, off

; __device__ __forceinline__ unsigned pack2(float a, float b) { return (unsigned)f2bf(a) | ((unsigned)f2bf(b) << 16); }
; template <int EPI, bool HS = false>
; __device__ __forceinline__ void gemm_phase(const Params& p, const GemmCfg& g, char* shm, const int wave_s) {
;     ...
;           for (int j = 0; j < 4; ++j) {
;             float ss = 0.f;
; #pragma unroll
;             for (int bj = 0; bj < 2; ++bj) {
;               float2 xn;
;               xn.x = xv[j][bj].x + gt[bj][0] * acc[ai][bj][m][0][j];
;               xn.y = xv[j][bj].y + gt[bj][1] * acc[ai][bj][m][1][j];
;               const unsigned o = tb + (unsigned)((ai * 128 + m * 16 + j) * 1024 + bj * 128);
;               *(float2*)(xout_t + o) = xn;
;               if (g.has_next) *(unsigned*)(xg_t + o) = pack2(xn.x * gn[bj][0], xn.y * gn[bj][1]);
;               ss += xn.x * xn.x + xn.y * xn.y;
;             }
;             if (g.has_next) {
;               ss = dpp_row_sum16(ss);
;               if (fr == 0) rss_t[(wr * 64 + fq * 4 + ai * 128 + m * 16 + j) * 16] = ss;
;             }
.LBB0_208:
	v_add_u32_e32 v58, 0x20800, v0
	v_mov_b32_e32 v50, v60
	v_mov_b32_e32 v51, v64
	v_mov_b32_e32 v59, v1
	s_waitcnt lgkmcnt(1)
	v_pk_fma_f32 v[54:55], v[150:151], v[50:51], v[70:71]
	v_lshl_add_u64 v[50:51], v[58:59], 2, s[2:3]
	global_store_dwordx2 v[50:51], v[54:55], off
	s_mov_b64 s[10:11], -1
	s_and_b64 vcc, exec, s[6:7]
	v_add_u32_e32 v50, 0x20880, v0
	s_cbranch_vccnz .LBB0_212
	v_pk_mul_f32 v[62:63], v[148:149], v[54:55]
	v_lshl_add_u64 v[58:59], v[58:59], 1, s[8:9]
	s_nop 0
	s_nop 0
	v_cvt_pk_bf16_f32 v60, v62, v62
	v_cvt_pk_bf16_f32 v51, v63, v63
	v_lshrrev_b32_e32 v60, 16, v60
	v_and_or_b32 v51, v51, s28, v60
	global_store_dword v[58:59], v51, off
	v_mov_b32_e32 v58, v52
	v_mov_b32_e32 v59, v56
	v_mov_b32_e32 v51, v1
	v_pk_fma_f32 v[58:59], v[146:147], v[58:59], v[72:73]
	v_lshl_add_u64 v[62:63], v[50:51], 2, s[2:3]
	global_store_dwordx2 v[62:63], v[58:59], off
	v_pk_mul_f32 v[62:63], v[152:153], v[58:59]
	v_pk_mul_f32 v[54:55], v[54:55], v[54:55]
	v_and_b32_sdwa v64, v62, v178 dst_sel:DWORD dst_unused:UNUSED_PAD src0_sel:WORD_1 src1_sel:DWORD
	s_nop 0
	v_add3_u32 v62, v62, v64, s81
	v_cvt_pk_bf16_f32 v60, v63, v63
	v_lshrrev_b32_e32 v62, 16, v62
	v_pk_mul_f32 v[58:59], v[58:59], v[58:59]
	v_and_or_b32 v60, v60, s28, v62
	v_lshl_add_u64 v[62:63], v[50:51], 1, s[8:9]
	v_add_f32_e32 v51, v58, v59
	v_add_f32_e32 v54, v54, v55
	v_add_f32_e32 v51, v54, v51
	global_store_dword v[62:63], v60, off
	s_nop 0
	v_add_f32_dpp v51, v51, v51 quad_perm:[1,0,3,2] row_mask:0xf bank_mask:0xf bound_ctrl:1
	s_nop 1
	v_add_f32_dpp v51, v51, v51 quad_perm:[2,3,0,1] row_mask:0xf bank_mask:0xf bound_ctrl:1
	s_nop 1
	v_add_f32_dpp v51, v51, v51 row_half_mirror row_mask:0xf bank_mask:0xf bound_ctrl:1
	s_nop 1
	v_mov_b32_dpp v54, v51 row_mirror row_mask:0xf bank_mask:0xf bound_ctrl:1
	s_and_saveexec_b64 s[10:11], s[4:5]
	s_cbranch_execz .LBB0_211
	v_add_f32_e32 v51, v51, v54
	v_mov_b32_e32 v54, 0x820
	v_lshl_add_u32 v54, v160, 4, v54
	v_ashrrev_i32_e32 v55, 31, v54
	v_lshl_add_u64 v[54:55], v[54:55], 2, v[142:143]
	global_store_dword v[54:55], v51, off

; __device__ __forceinline__ unsigned pack2(float a, float b) { return (unsigned)f2bf(a) | ((unsigned)f2bf(b) << 16); }
; template <int EPI, bool HS = false>
; __device__ __forceinline__ void gemm_phase(const Params& p, const GemmCfg& g, char* shm, const int wave_s) {
;     ...
;           for (int j = 0; j < 4; ++j) {
;             float ss = 0.f;
; #pragma unroll
;             for (int bj = 0; bj < 2; ++bj) {
;               float2 xn;
;               xn.x = xv[j][bj].x + gt[bj][0] * acc[ai][bj][m][0][j];
;               xn.y = xv[j][bj].y + gt[bj][1] * acc[ai][bj][m][1][j];
;               const unsigned o = tb + (unsigned)((ai * 128 + m * 16 + j) * 1024 + bj * 128);
;               *(float2*)(xout_t + o) = xn;
;               if (g.has_next) *(unsigned*)(xg_t + o) = pack2(xn.x * gn[bj][0], xn.y * gn[bj][1]);
;               ss += xn.x * xn.x + xn.y * xn.y;
;             }
;             if (g.has_next) {
;               ss = dpp_row_sum16(ss);
;               if (fr == 0) rss_t[(wr * 64 + fq * 4 + ai * 128 + m * 16 + j) * 16] = ss;
;             }
.LBB0_214:
	v_add_u32_e32 v58, 0x20c00, v0
	v_mov_b32_e32 v64, v61
	v_mov_b32_e32 v59, v1
	s_waitcnt lgkmcnt(0)
	v_pk_fma_f32 v[54:55], v[150:151], v[64:65], v[66:67]
	v_lshl_add_u64 v[50:51], v[58:59], 2, s[2:3]
	global_store_dwordx2 v[50:51], v[54:55], off
	s_mov_b64 s[10:11], -1
	s_and_b64 vcc, exec, s[6:7]
	v_add_u32_e32 v50, 0x20c80, v0
	s_cbranch_vccnz .LBB0_218
	v_pk_mul_f32 v[60:61], v[148:149], v[54:55]
	v_lshl_add_u64 v[58:59], v[58:59], 1, s[8:9]
	s_nop 0
	s_nop 0
	v_cvt_pk_bf16_f32 v52, v60, v60
	v_cvt_pk_bf16_f32 v51, v61, v61
	v_lshrrev_b32_e32 v52, 16, v52
	v_and_or_b32 v51, v51, s28, v52
	global_store_dword v[58:59], v51, off
	v_mov_b32_e32 v56, v53
	v_mov_b32_e32 v51, v1
	v_pk_fma_f32 v[58:59], v[146:147], v[56:57], v[68:69]
	v_lshl_add_u64 v[60:61], v[50:51], 2, s[2:3]
	global_store_dwordx2 v[60:61], v[58:59], off
	v_pk_mul_f32 v[60:61], v[152:153], v[58:59]
	v_pk_mul_f32 v[54:55], v[54:55], v[54:55]
	s_nop 0
	s_nop 0
	v_cvt_pk_bf16_f32 v56, v60, v60
	v_cvt_pk_bf16_f32 v52, v61, v61
	v_lshrrev_b32_e32 v56, 16, v56
	v_and_or_b32 v52, v52, s28, v56
	v_lshl_add_u64 v[60:61], v[50:51], 1, s[8:9]
	v_pk_mul_f32 v[58:59], v[58:59], v[58:59]
	global_store_dword v[60:61], v52, off
	v_add_f32_e32 v51, v58, v59
	v_add_f32_e32 v52, v54, v55
	v_add_f32_e32 v51, v52, v51
	s_nop 1
	v_add_f32_dpp v51, v51, v51 quad_perm:[1,0,3,2] row_mask:0xf bank_mask:0xf bound_ctrl:1
	s_nop 1
	v_add_f32_dpp v51, v51, v51 quad_perm:[2,3,0,1] row_mask:0xf bank_mask:0xf bound_ctrl:1
	s_nop 1
	v_add_f32_dpp v51, v51, v51 row_half_mirror row_mask:0xf bank_mask:0xf bound_ctrl:1
	s_nop 1
	v_mov_b32_dpp v52, v51 row_mirror row_mask:0xf bank_mask:0xf bound_ctrl:1
	s_and_saveexec_b64 s[10:11], s[4:5]
	s_cbranch_execz .LBB0_217
	v_add_f32_e32 v51, v51, v52
	v_mov_b32_e32 v52, 0x830
	v_lshl_add_u32 v54, v160, 4, v52
	v_ashrrev_i32_e32 v55, 31, v54
	v_lshl_add_u64 v[54:55], v[54:55], 2, v[142:143]
	global_store_dword v[54:55], v51, off

; __device__ __forceinline__ unsigned pack2(float a, float b) { return (unsigned)f2bf(a) | ((unsigned)f2bf(b) << 16); }
; template <int EPI, bool HS = false>
; __device__ __forceinline__ void gemm_phase(const Params& p, const GemmCfg& g, char* shm, const int wave_s) {
;     ...
;             for (int bj = 0; bj < 2; ++bj) xv[j][bj] = *(const float2*)(xl + (m * 16 + j) * XROW + bj * 512);
; #pragma unroll
;           for (int j = 0; j < 4; ++j) {
;             float ss = 0.f;
; #pragma unroll
;             for (int bj = 0; bj < 2; ++bj) {
;               float2 xn;
;               xn.x = xv[j][bj].x + gt[bj][0] * acc[ai][bj][m][0][j];
;               xn.y = xv[j][bj].y + gt[bj][1] * acc[ai][bj][m][1][j];
;               const unsigned o = tb + (unsigned)((ai * 128 + m * 16 + j) * 1024 + bj * 128);
;               *(float2*)(xout_t + o) = xn;
;               if (g.has_next) *(unsigned*)(xg_t + o) = pack2(xn.x * gn[bj][0], xn.y * gn[bj][1]);
;               ss += xn.x * xn.x + xn.y * xn.y;
;             }
;             if (g.has_next) {
;               ss = dpp_row_sum16(ss);
;               if (fr == 0) rss_t[(wr * 64 + fq * 4 + ai * 128 + m * 16 + j) * 16] = ss;
;             }
.LBB0_220:
	ds_read2st64_b64 v[62:65], v134 offset0:32 offset1:33
	ds_read2st64_b64 v[58:61], v135 offset0:34 offset1:35
	ds_read2st64_b64 v[54:57], v136 offset0:36 offset1:37
	ds_read2st64_b64 v[50:53], v137 offset0:38 offset1:39
	v_add_u32_e32 v68, 0x24000, v0
	v_mov_b32_e32 v66, v42
	v_mov_b32_e32 v67, v46
	v_mov_b32_e32 v69, v1
	s_waitcnt lgkmcnt(3)
	v_pk_fma_f32 v[66:67], v[150:151], v[66:67], v[62:63]
	v_lshl_add_u64 v[62:63], v[68:69], 2, s[2:3]
	global_store_dwordx2 v[62:63], v[66:67], off
	s_mov_b64 s[10:11], -1
	s_and_b64 vcc, exec, s[6:7]
	v_add_u32_e32 v62, 0x24080, v0
	s_cbranch_vccnz .LBB0_224
	v_pk_mul_f32 v[70:71], v[148:149], v[66:67]
	v_lshl_add_u64 v[68:69], v[68:69], 1, s[8:9]
	s_nop 0
	s_nop 0
	v_cvt_pk_bf16_f32 v46, v70, v70
	v_cvt_pk_bf16_f32 v42, v71, v71
	v_lshrrev_b32_e32 v46, 16, v46
	v_and_or_b32 v42, v42, s28, v46
	global_store_dword v[68:69], v42, off
	v_mov_b32_e32 v68, v34
	v_mov_b32_e32 v69, v38
	v_mov_b32_e32 v63, v1
	v_pk_fma_f32 v[68:69], v[146:147], v[68:69], v[64:65]
	v_lshl_add_u64 v[70:71], v[62:63], 2, s[2:3]
	global_store_dwordx2 v[70:71], v[68:69], off
	v_pk_mul_f32 v[70:71], v[152:153], v[68:69]
	v_pk_mul_f32 v[66:67], v[66:67], v[66:67]
	s_nop 0
	s_nop 0
	v_cvt_pk_bf16_f32 v46, v70, v70
	v_cvt_pk_bf16_f32 v42, v71, v71
	v_lshrrev_b32_e32 v46, 16, v46
	v_and_or_b32 v42, v42, s28, v46
	v_lshl_add_u64 v[70:71], v[62:63], 1, s[8:9]
	v_pk_mul_f32 v[68:69], v[68:69], v[68:69]
	global_store_dword v[70:71], v42, off
	v_add_f32_e32 v42, v68, v69
	v_add_f32_e32 v46, v66, v67
	v_add_f32_e32 v42, v46, v42
	s_nop 1
	v_add_f32_dpp v42, v42, v42 quad_perm:[1,0,3,2] row_mask:0xf bank_mask:0xf bound_ctrl:1
	s_nop 1
	v_add_f32_dpp v42, v42, v42 quad_perm:[2,3,0,1] row_mask:0xf bank_mask:0xf bound_ctrl:1
	s_nop 1
	v_add_f32_dpp v42, v42, v42 row_half_mirror row_mask:0xf bank_mask:0xf bound_ctrl:1
	s_nop 1
	v_mov_b32_dpp v46, v42 row_mirror row_mask:0xf bank_mask:0xf bound_ctrl:1
	s_and_saveexec_b64 s[10:11], s[4:5]
	s_cbranch_execz .LBB0_223
	v_add_f32_e32 v42, v42, v46
	v_mov_b32_e32 v46, 0x900
	v_lshl_add_u32 v66, v160, 4, v46
	v_ashrrev_i32_e32 v67, 31, v66
	v_lshl_add_u64 v[66:67], v[66:67], 2, v[142:143]
	global_store_dword v[66:67], v42, off

; __device__ __forceinline__ unsigned pack2(float a, float b) { return (unsigned)f2bf(a) | ((unsigned)f2bf(b) << 16); }
; template <int EPI, bool HS = false>
; __device__ __forceinline__ void gemm_phase(const Params& p, const GemmCfg& g, char* shm, const int wave_s) {
;     ...
;           for (int j = 0; j < 4; ++j) {
;             float ss = 0.f;
; #pragma unroll
;             for (int bj = 0; bj < 2; ++bj) {
;               float2 xn;
;               xn.x = xv[j][bj].x + gt[bj][0] * acc[ai][bj][m][0][j];
;               xn.y = xv[j][bj].y + gt[bj][1] * acc[ai][bj][m][1][j];
;               const unsigned o = tb + (unsigned)((ai * 128 + m * 16 + j) * 1024 + bj * 128);
;               *(float2*)(xout_t + o) = xn;
;               if (g.has_next) *(unsigned*)(xg_t + o) = pack2(xn.x * gn[bj][0], xn.y * gn[bj][1]);
;               ss += xn.x * xn.x + xn.y * xn.y;
;             }
;             if (g.has_next) {
;               ss = dpp_row_sum16(ss);
;               if (fr == 0) rss_t[(wr * 64 + fq * 4 + ai * 128 + m * 16 + j) * 16] = ss;
;             }
.LBB0_226:
	v_add_u32_e32 v62, 0x24400, v0
	v_mov_b32_e32 v46, v43
	v_mov_b32_e32 v63, v1
	s_waitcnt lgkmcnt(2)
	v_pk_fma_f32 v[46:47], v[150:151], v[46:47], v[58:59]
	v_lshl_add_u64 v[42:43], v[62:63], 2, s[2:3]
	global_store_dwordx2 v[42:43], v[46:47], off
	s_mov_b64 s[10:11], -1
	s_and_b64 vcc, exec, s[6:7]
	v_add_u32_e32 v42, 0x24480, v0
	s_cbranch_vccnz .LBB0_230
	v_pk_mul_f32 v[58:59], v[148:149], v[46:47]
	v_mov_b32_e32 v43, v1
	s_nop 0
	s_nop 0
	v_cvt_pk_bf16_f32 v38, v58, v58
	v_cvt_pk_bf16_f32 v34, v59, v59
	v_lshrrev_b32_e32 v38, 16, v38
	v_and_or_b32 v34, v34, s28, v38
	v_lshl_add_u64 v[58:59], v[62:63], 1, s[8:9]
	v_mov_b32_e32 v38, v35
	global_store_dword v[58:59], v34, off
	v_pk_fma_f32 v[58:59], v[146:147], v[38:39], v[60:61]
	v_lshl_add_u64 v[62:63], v[42:43], 2, s[2:3]
	global_store_dwordx2 v[62:63], v[58:59], off
	v_pk_mul_f32 v[62:63], v[152:153], v[58:59]
	v_pk_mul_f32 v[46:47], v[46:47], v[46:47]
	s_nop 0
	s_nop 0
	v_cvt_pk_bf16_f32 v38, v62, v62
	v_cvt_pk_bf16_f32 v34, v63, v63
	v_lshrrev_b32_e32 v38, 16, v38
	v_and_or_b32 v34, v34, s28, v38
	v_lshl_add_u64 v[62:63], v[42:43], 1, s[8:9]
	v_pk_mul_f32 v[58:59], v[58:59], v[58:59]
	global_store_dword v[62:63], v34, off
	v_add_f32_e32 v34, v58, v59
	v_add_f32_e32 v38, v46, v47
	v_add_f32_e32 v34, v38, v34
	s_nop 1
	v_add_f32_dpp v34, v34, v34 quad_perm:[1,0,3,2] row_mask:0xf bank_mask:0xf bound_ctrl:1
	s_nop 1
	v_add_f32_dpp v34, v34, v34 quad_perm:[2,3,0,1] row_mask:0xf bank_mask:0xf bound_ctrl:1
	s_nop 1
	v_add_f32_dpp v34, v34, v34 row_half_mirror row_mask:0xf bank_mask:0xf bound_ctrl:1
	s_nop 1
	v_mov_b32_dpp v38, v34 row_mirror row_mask:0xf bank_mask:0xf bound_ctrl:1
	s_and_saveexec_b64 s[10:11], s[4:5]
	s_cbranch_execz .LBB0_229
	v_add_f32_e32 v34, v34, v38
	v_mov_b32_e32 v38, 0x910
	v_lshl_add_u32 v46, v160, 4, v38
	v_ashrrev_i32_e32 v47, 31, v46
	v_lshl_add_u64 v[46:47], v[46:47], 2, v[142:143]
	global_store_dword v[46:47], v34, off

; __device__ __forceinline__ unsigned pack2(float a, float b) { return (unsigned)f2bf(a) | ((unsigned)f2bf(b) << 16); }
; template <int EPI, bool HS = false>
; __device__ __forceinline__ void gemm_phase(const Params& p, const GemmCfg& g, char* shm, const int wave_s) {
;     ...
;           for (int j = 0; j < 4; ++j) {
;             float ss = 0.f;
; #pragma unroll
;             for (int bj = 0; bj < 2; ++bj) {
;               float2 xn;
;               xn.x = xv[j][bj].x + gt[bj][0] * acc[ai][bj][m][0][j];
;               xn.y = xv[j][bj].y + gt[bj][1] * acc[ai][bj][m][1][j];
;               const unsigned o = tb + (unsigned)((ai * 128 + m * 16 + j) * 1024 + bj * 128);
;               *(float2*)(xout_t + o) = xn;
;               if (g.has_next) *(unsigned*)(xg_t + o) = pack2(xn.x * gn[bj][0], xn.y * gn[bj][1]);
;               ss += xn.x * xn.x + xn.y * xn.y;
;             }
;             if (g.has_next) {
;               ss = dpp_row_sum16(ss);
;               if (fr == 0) rss_t[(wr * 64 + fq * 4 + ai * 128 + m * 16 + j) * 16] = ss;
;             }
.LBB0_232:
	v_add_u32_e32 v42, 0x24800, v0
	v_mov_b32_e32 v34, v44
	v_mov_b32_e32 v35, v48
	v_mov_b32_e32 v43, v1
	s_waitcnt lgkmcnt(1)
	v_pk_fma_f32 v[38:39], v[150:151], v[34:35], v[54:55]
	v_lshl_add_u64 v[34:35], v[42:43], 2, s[2:3]
	global_store_dwordx2 v[34:35], v[38:39], off
	s_mov_b64 s[10:11], -1
	s_and_b64 vcc, exec, s[6:7]
	v_add_u32_e32 v34, 0x24880, v0
	s_cbranch_vccnz .LBB0_236
	v_pk_mul_f32 v[46:47], v[148:149], v[38:39]
	v_lshl_add_u64 v[42:43], v[42:43], 1, s[8:9]
	s_nop 0
	s_nop 0
	v_cvt_pk_bf16_f32 v44, v46, v46
	v_cvt_pk_bf16_f32 v35, v47, v47
	v_lshrrev_b32_e32 v44, 16, v44
	v_and_or_b32 v35, v35, s28, v44
	global_store_dword v[42:43], v35, off
	v_mov_b32_e32 v42, v36
	v_mov_b32_e32 v43, v40
	v_mov_b32_e32 v35, v1
	v_pk_fma_f32 v[42:43], v[146:147], v[42:43], v[56:57]
	v_lshl_add_u64 v[46:47], v[34:35], 2, s[2:3]
	global_store_dwordx2 v[46:47], v[42:43], off
	v_pk_mul_f32 v[46:47], v[152:153], v[42:43]
	v_pk_mul_f32 v[38:39], v[38:39], v[38:39]
	v_and_b32_sdwa v48, v46, v178 dst_sel:DWORD dst_unused:UNUSED_PAD src0_sel:WORD_1 src1_sel:DWORD
	s_nop 0
	v_add3_u32 v46, v46, v48, s81
	v_cvt_pk_bf16_f32 v44, v47, v47
	v_lshrrev_b32_e32 v46, 16, v46
	v_pk_mul_f32 v[42:43], v[42:43], v[42:43]
	v_and_or_b32 v44, v44, s28, v46
	v_lshl_add_u64 v[46:47], v[34:35], 1, s[8:9]
	v_add_f32_e32 v35, v42, v43
	v_add_f32_e32 v38, v38, v39
	v_add_f32_e32 v35, v38, v35
	global_store_dword v[46:47], v44, off
	s_nop 0
	v_add_f32_dpp v35, v35, v35 quad_perm:[1,0,3,2] row_mask:0xf bank_mask:0xf bound_ctrl:1
	s_nop 1
	v_add_f32_dpp v35, v35, v35 quad_perm:[2,3,0,1] row_mask:0xf bank_mask:0xf bound_ctrl:1
	s_nop 1
	v_add_f32_dpp v35, v35, v35 row_half_mirror row_mask:0xf bank_mask:0xf bound_ctrl:1
	s_nop 1
	v_mov_b32_dpp v38, v35 row_mirror row_mask:0xf bank_mask:0xf bound_ctrl:1
	s_and_saveexec_b64 s[10:11], s[4:5]
	s_cbranch_execz .LBB0_235
	v_add_f32_e32 v35, v35, v38
	v_mov_b32_e32 v38, 0x920
	v_lshl_add_u32 v38, v160, 4, v38
	v_ashrrev_i32_e32 v39, 31, v38
	v_lshl_add_u64 v[38:39], v[38:39], 2, v[142:143]
	global_store_dword v[38:39], v35, off

; __device__ __forceinline__ unsigned pack2(float a, float b) { return (unsigned)f2bf(a) | ((unsigned)f2bf(b) << 16); }
; template <int EPI, bool HS = false>
; __device__ __forceinline__ void gemm_phase(const Params& p, const GemmCfg& g, char* shm, const int wave_s) {
;     ...
;           for (int j = 0; j < 4; ++j) {
;             float ss = 0.f;
; #pragma unroll
;             for (int bj = 0; bj < 2; ++bj) {
;               float2 xn;
;               xn.x = xv[j][bj].x + gt[bj][0] * acc[ai][bj][m][0][j];
;               xn.y = xv[j][bj].y + gt[bj][1] * acc[ai][bj][m][1][j];
;               const unsigned o = tb + (unsigned)((ai * 128 + m * 16 + j) * 1024 + bj * 128);
;               *(float2*)(xout_t + o) = xn;
;               if (g.has_next) *(unsigned*)(xg_t + o) = pack2(xn.x * gn[bj][0], xn.y * gn[bj][1]);
;               ss += xn.x * xn.x + xn.y * xn.y;
;             }
;             if (g.has_next) {
;               ss = dpp_row_sum16(ss);
;               if (fr == 0) rss_t[(wr * 64 + fq * 4 + ai * 128 + m * 16 + j) * 16] = ss;
;             }
.LBB0_238:
	v_add_u32_e32 v42, 0x24c00, v0
	v_mov_b32_e32 v48, v45
	v_mov_b32_e32 v43, v1
	s_waitcnt lgkmcnt(0)
	v_pk_fma_f32 v[38:39], v[150:151], v[48:49], v[50:51]
	v_lshl_add_u64 v[34:35], v[42:43], 2, s[2:3]
	global_store_dwordx2 v[34:35], v[38:39], off
	s_mov_b64 s[10:11], -1
	s_and_b64 vcc, exec, s[6:7]
	v_add_u32_e32 v34, 0x24c80, v0
	s_cbranch_vccnz .LBB0_242
	v_pk_mul_f32 v[44:45], v[148:149], v[38:39]
	v_lshl_add_u64 v[42:43], v[42:43], 1, s[8:9]
	s_nop 0
	s_nop 0
	v_cvt_pk_bf16_f32 v36, v44, v44
	v_cvt_pk_bf16_f32 v35, v45, v45
	v_lshrrev_b32_e32 v36, 16, v36
	v_and_or_b32 v35, v35, s28, v36
	global_store_dword v[42:43], v35, off
	v_mov_b32_e32 v40, v37
	v_mov_b32_e32 v35, v1
	v_pk_fma_f32 v[42:43], v[146:147], v[40:41], v[52:53]
	v_lshl_add_u64 v[44:45], v[34:35], 2, s[2:3]
	global_store_dwordx2 v[44:45], v[42:43], off
	v_pk_mul_f32 v[44:45], v[152:153], v[42:43]
	v_pk_mul_f32 v[38:39], v[38:39], v[38:39]
	s_nop 0
	s_nop 0
	v_cvt_pk_bf16_f32 v40, v44, v44
	v_cvt_pk_bf16_f32 v36, v45, v45
	v_lshrrev_b32_e32 v40, 16, v40
	v_and_or_b32 v36, v36, s28, v40
	v_lshl_add_u64 v[44:45], v[34:35], 1, s[8:9]
	v_pk_mul_f32 v[42:43], v[42:43], v[42:43]
	global_store_dword v[44:45], v36, off
	v_add_f32_e32 v35, v42, v43
	v_add_f32_e32 v36, v38, v39
	v_add_f32_e32 v35, v36, v35
	s_nop 1
	v_add_f32_dpp v35, v35, v35 quad_perm:[1,0,3,2] row_mask:0xf bank_mask:0xf bound_ctrl:1
	s_nop 1
	v_add_f32_dpp v35, v35, v35 quad_perm:[2,3,0,1] row_mask:0xf bank_mask:0xf bound_ctrl:1
	s_nop 1
	v_add_f32_dpp v35, v35, v35 row_half_mirror row_mask:0xf bank_mask:0xf bound_ctrl:1
	s_nop 1
	v_mov_b32_dpp v36, v35 row_mirror row_mask:0xf bank_mask:0xf bound_ctrl:1
	s_and_saveexec_b64 s[10:11], s[4:5]
	s_cbranch_execz .LBB0_241
	v_add_f32_e32 v35, v35, v36
	v_mov_b32_e32 v36, 0x930
	v_lshl_add_u32 v38, v160, 4, v36
	v_ashrrev_i32_e32 v39, 31, v38
	v_lshl_add_u64 v[38:39], v[38:39], 2, v[142:143]
	global_store_dword v[38:39], v35, off

; __device__ __forceinline__ unsigned pack2(float a, float b) { return (unsigned)f2bf(a) | ((unsigned)f2bf(b) << 16); }
; template <int EPI, bool HS = false>
; __device__ __forceinline__ void gemm_phase(const Params& p, const GemmCfg& g, char* shm, const int wave_s) {
;     ...
;             for (int bj = 0; bj < 2; ++bj) xv[j][bj] = *(const float2*)(xl + (m * 16 + j) * XROW + bj * 512);
; #pragma unroll
;           for (int j = 0; j < 4; ++j) {
;             float ss = 0.f;
; #pragma unroll
;             for (int bj = 0; bj < 2; ++bj) {
;               float2 xn;
;               xn.x = xv[j][bj].x + gt[bj][0] * acc[ai][bj][m][0][j];
;               xn.y = xv[j][bj].y + gt[bj][1] * acc[ai][bj][m][1][j];
;               const unsigned o = tb + (unsigned)((ai * 128 + m * 16 + j) * 1024 + bj * 128);
;               *(float2*)(xout_t + o) = xn;
;               if (g.has_next) *(unsigned*)(xg_t + o) = pack2(xn.x * gn[bj][0], xn.y * gn[bj][1]);
;               ss += xn.x * xn.x + xn.y * xn.y;
;             }
;             if (g.has_next) {
;               ss = dpp_row_sum16(ss);
;               if (fr == 0) rss_t[(wr * 64 + fq * 4 + ai * 128 + m * 16 + j) * 16] = ss;
;             }
.LBB0_244:
	ds_read2st64_b64 v[46:49], v161 offset0:65 offset1:66
	ds_read2st64_b64 v[42:45], v118 offset0:67 offset1:68
	ds_read2st64_b64 v[38:41], v162 offset0:69 offset1:70
	ds_read2st64_b64 v[34:37], v163 offset0:71 offset1:72
	v_add_u32_e32 v52, 0x28000, v0
	v_mov_b32_e32 v50, v26
	v_mov_b32_e32 v51, v30
	v_mov_b32_e32 v53, v1
	s_waitcnt lgkmcnt(3)
	v_pk_fma_f32 v[50:51], v[150:151], v[50:51], v[46:47]
	v_lshl_add_u64 v[46:47], v[52:53], 2, s[2:3]
	global_store_dwordx2 v[46:47], v[50:51], off
	s_mov_b64 s[10:11], -1
	s_and_b64 vcc, exec, s[6:7]
	v_add_u32_e32 v46, 0x28080, v0
	s_cbranch_vccnz .LBB0_248
	v_pk_mul_f32 v[54:55], v[148:149], v[50:51]
	v_lshl_add_u64 v[52:53], v[52:53], 1, s[8:9]
	s_nop 0
	s_nop 0
	v_cvt_pk_bf16_f32 v30, v54, v54
	v_cvt_pk_bf16_f32 v26, v55, v55
	v_lshrrev_b32_e32 v30, 16, v30
	v_and_or_b32 v26, v26, s28, v30
	global_store_dword v[52:53], v26, off
	v_mov_b32_e32 v52, v18
	v_mov_b32_e32 v53, v22
	v_mov_b32_e32 v47, v1
	v_pk_fma_f32 v[52:53], v[146:147], v[52:53], v[48:49]
	v_lshl_add_u64 v[54:55], v[46:47], 2, s[2:3]
	global_store_dwordx2 v[54:55], v[52:53], off
	v_pk_mul_f32 v[54:55], v[152:153], v[52:53]
	v_pk_mul_f32 v[50:51], v[50:51], v[50:51]
	s_nop 0
	s_nop 0
	v_cvt_pk_bf16_f32 v30, v54, v54
	v_cvt_pk_bf16_f32 v26, v55, v55
	v_lshrrev_b32_e32 v30, 16, v30
	v_and_or_b32 v26, v26, s28, v30
	v_lshl_add_u64 v[54:55], v[46:47], 1, s[8:9]
	v_pk_mul_f32 v[52:53], v[52:53], v[52:53]
	global_store_dword v[54:55], v26, off
	v_add_f32_e32 v26, v52, v53
	v_add_f32_e32 v30, v50, v51
	v_add_f32_e32 v26, v30, v26
	s_nop 1
	v_add_f32_dpp v26, v26, v26 quad_perm:[1,0,3,2] row_mask:0xf bank_mask:0xf bound_ctrl:1
	s_nop 1
	v_add_f32_dpp v26, v26, v26 quad_perm:[2,3,0,1] row_mask:0xf bank_mask:0xf bound_ctrl:1
	s_nop 1
	v_add_f32_dpp v26, v26, v26 row_half_mirror row_mask:0xf bank_mask:0xf bound_ctrl:1
	s_nop 1
	v_mov_b32_dpp v30, v26 row_mirror row_mask:0xf bank_mask:0xf bound_ctrl:1
	s_and_saveexec_b64 s[10:11], s[4:5]
	s_cbranch_execz .LBB0_247
	v_add_f32_e32 v26, v26, v30
	v_mov_b32_e32 v30, 0xa00
	v_lshl_add_u32 v50, v160, 4, v30
	v_ashrrev_i32_e32 v51, 31, v50
	v_lshl_add_u64 v[50:51], v[50:51], 2, v[142:143]
	global_store_dword v[50:51], v26, off

; __device__ __forceinline__ unsigned pack2(float a, float b) { return (unsigned)f2bf(a) | ((unsigned)f2bf(b) << 16); }
; template <int EPI, bool HS = false>
; __device__ __forceinline__ void gemm_phase(const Params& p, const GemmCfg& g, char* shm, const int wave_s) {
;     ...
;           for (int j = 0; j < 4; ++j) {
;             float ss = 0.f;
; #pragma unroll
;             for (int bj = 0; bj < 2; ++bj) {
;               float2 xn;
;               xn.x = xv[j][bj].x + gt[bj][0] * acc[ai][bj][m][0][j];
;               xn.y = xv[j][bj].y + gt[bj][1] * acc[ai][bj][m][1][j];
;               const unsigned o = tb + (unsigned)((ai * 128 + m * 16 + j) * 1024 + bj * 128);
;               *(float2*)(xout_t + o) = xn;
;               if (g.has_next) *(unsigned*)(xg_t + o) = pack2(xn.x * gn[bj][0], xn.y * gn[bj][1]);
;               ss += xn.x * xn.x + xn.y * xn.y;
;             }
;             if (g.has_next) {
;               ss = dpp_row_sum16(ss);
;               if (fr == 0) rss_t[(wr * 64 + fq * 4 + ai * 128 + m * 16 + j) * 16] = ss;
;             }
.LBB0_250:
	v_add_u32_e32 v46, 0x28400, v0
	v_mov_b32_e32 v30, v27
	v_mov_b32_e32 v47, v1
	s_waitcnt lgkmcnt(2)
	v_pk_fma_f32 v[30:31], v[150:151], v[30:31], v[42:43]
	v_lshl_add_u64 v[26:27], v[46:47], 2, s[2:3]
	global_store_dwordx2 v[26:27], v[30:31], off
	s_mov_b64 s[10:11], -1
	s_and_b64 vcc, exec, s[6:7]
	v_add_u32_e32 v26, 0x28480, v0
	s_cbranch_vccnz .LBB0_254
	v_pk_mul_f32 v[42:43], v[148:149], v[30:31]
	v_mov_b32_e32 v27, v1
	s_nop 0
	s_nop 0
	v_cvt_pk_bf16_f32 v22, v42, v42
	v_cvt_pk_bf16_f32 v18, v43, v43
	v_lshrrev_b32_e32 v22, 16, v22
	v_and_or_b32 v18, v18, s28, v22
	v_lshl_add_u64 v[42:43], v[46:47], 1, s[8:9]
	v_mov_b32_e32 v22, v19
	global_store_dword v[42:43], v18, off
	v_pk_fma_f32 v[42:43], v[146:147], v[22:23], v[44:45]
	v_lshl_add_u64 v[46:47], v[26:27], 2, s[2:3]
	global_store_dwordx2 v[46:47], v[42:43], off
	v_pk_mul_f32 v[46:47], v[152:153], v[42:43]
	v_pk_mul_f32 v[30:31], v[30:31], v[30:31]
	s_nop 0
	s_nop 0
	v_cvt_pk_bf16_f32 v22, v46, v46
	v_cvt_pk_bf16_f32 v18, v47, v47
	v_lshrrev_b32_e32 v22, 16, v22
	v_and_or_b32 v18, v18, s28, v22
	v_lshl_add_u64 v[46:47], v[26:27], 1, s[8:9]
	v_pk_mul_f32 v[42:43], v[42:43], v[42:43]
	global_store_dword v[46:47], v18, off
	v_add_f32_e32 v18, v42, v43
	v_add_f32_e32 v22, v30, v31
	v_add_f32_e32 v18, v22, v18
	s_nop 1
	v_add_f32_dpp v18, v18, v18 quad_perm:[1,0,3,2] row_mask:0xf bank_mask:0xf bound_ctrl:1
	s_nop 1
	v_add_f32_dpp v18, v18, v18 quad_perm:[2,3,0,1] row_mask:0xf bank_mask:0xf bound_ctrl:1
	s_nop 1
	v_add_f32_dpp v18, v18, v18 row_half_mirror row_mask:0xf bank_mask:0xf bound_ctrl:1
	s_nop 1
	v_mov_b32_dpp v22, v18 row_mirror row_mask:0xf bank_mask:0xf bound_ctrl:1
	s_and_saveexec_b64 s[10:11], s[4:5]
	s_cbranch_execz .LBB0_253
	v_add_f32_e32 v18, v18, v22
	v_mov_b32_e32 v22, 0xa10
	v_lshl_add_u32 v30, v160, 4, v22
	v_ashrrev_i32_e32 v31, 31, v30
	v_lshl_add_u64 v[30:31], v[30:31], 2, v[142:143]
	global_store_dword v[30:31], v18, off

; __device__ __forceinline__ unsigned pack2(float a, float b) { return (unsigned)f2bf(a) | ((unsigned)f2bf(b) << 16); }
; template <int EPI, bool HS = false>
; __device__ __forceinline__ void gemm_phase(const Params& p, const GemmCfg& g, char* shm, const int wave_s) {
;     ...
;           for (int j = 0; j < 4; ++j) {
;             float ss = 0.f;
; #pragma unroll
;             for (int bj = 0; bj < 2; ++bj) {
;               float2 xn;
;               xn.x = xv[j][bj].x + gt[bj][0] * acc[ai][bj][m][0][j];
;               xn.y = xv[j][bj].y + gt[bj][1] * acc[ai][bj][m][1][j];
;               const unsigned o = tb + (unsigned)((ai * 128 + m * 16 + j) * 1024 + bj * 128);
;               *(float2*)(xout_t + o) = xn;
;               if (g.has_next) *(unsigned*)(xg_t + o) = pack2(xn.x * gn[bj][0], xn.y * gn[bj][1]);
;               ss += xn.x * xn.x + xn.y * xn.y;
;             }
;             if (g.has_next) {
;               ss = dpp_row_sum16(ss);
;               if (fr == 0) rss_t[(wr * 64 + fq * 4 + ai * 128 + m * 16 + j) * 16] = ss;
;             }
.LBB0_256:
	v_add_u32_e32 v26, 0x28800, v0
	v_mov_b32_e32 v18, v28
	v_mov_b32_e32 v19, v32
	v_mov_b32_e32 v27, v1
	s_waitcnt lgkmcnt(1)
	v_pk_fma_f32 v[22:23], v[150:151], v[18:19], v[38:39]
	v_lshl_add_u64 v[18:19], v[26:27], 2, s[2:3]
	global_store_dwordx2 v[18:19], v[22:23], off
	s_mov_b64 s[10:11], -1
	s_and_b64 vcc, exec, s[6:7]
	v_add_u32_e32 v18, 0x28880, v0
	s_cbranch_vccnz .LBB0_260
	v_pk_mul_f32 v[30:31], v[148:149], v[22:23]
	v_lshl_add_u64 v[26:27], v[26:27], 1, s[8:9]
	s_nop 0
	s_nop 0
	v_cvt_pk_bf16_f32 v28, v30, v30
	v_cvt_pk_bf16_f32 v19, v31, v31
	v_lshrrev_b32_e32 v28, 16, v28
	v_and_or_b32 v19, v19, s28, v28
	global_store_dword v[26:27], v19, off
	v_mov_b32_e32 v26, v20
	v_mov_b32_e32 v27, v24
	v_mov_b32_e32 v19, v1
	v_pk_fma_f32 v[26:27], v[146:147], v[26:27], v[40:41]
	v_lshl_add_u64 v[30:31], v[18:19], 2, s[2:3]
	global_store_dwordx2 v[30:31], v[26:27], off
	v_pk_mul_f32 v[30:31], v[152:153], v[26:27]
	v_pk_mul_f32 v[22:23], v[22:23], v[22:23]
	v_and_b32_sdwa v32, v30, v178 dst_sel:DWORD dst_unused:UNUSED_PAD src0_sel:WORD_1 src1_sel:DWORD
	s_nop 0
	v_add3_u32 v30, v30, v32, s81
	v_cvt_pk_bf16_f32 v28, v31, v31
	v_lshrrev_b32_e32 v30, 16, v30
	v_pk_mul_f32 v[26:27], v[26:27], v[26:27]
	v_and_or_b32 v28, v28, s28, v30
	v_lshl_add_u64 v[30:31], v[18:19], 1, s[8:9]
	v_add_f32_e32 v19, v26, v27
	v_add_f32_e32 v22, v22, v23
	v_add_f32_e32 v19, v22, v19
	global_store_dword v[30:31], v28, off
	s_nop 0
	v_add_f32_dpp v19, v19, v19 quad_perm:[1,0,3,2] row_mask:0xf bank_mask:0xf bound_ctrl:1
	s_nop 1
	v_add_f32_dpp v19, v19, v19 quad_perm:[2,3,0,1] row_mask:0xf bank_mask:0xf bound_ctrl:1
	s_nop 1
	v_add_f32_dpp v19, v19, v19 row_half_mirror row_mask:0xf bank_mask:0xf bound_ctrl:1
	s_nop 1
	v_mov_b32_dpp v22, v19 row_mirror row_mask:0xf bank_mask:0xf bound_ctrl:1
	s_and_saveexec_b64 s[10:11], s[4:5]
	s_cbranch_execz .LBB0_259
	v_add_f32_e32 v19, v19, v22
	v_mov_b32_e32 v22, 0xa20
	v_lshl_add_u32 v22, v160, 4, v22
	v_ashrrev_i32_e32 v23, 31, v22
	v_lshl_add_u64 v[22:23], v[22:23], 2, v[142:143]
	global_store_dword v[22:23], v19, off

; __device__ __forceinline__ unsigned pack2(float a, float b) { return (unsigned)f2bf(a) | ((unsigned)f2bf(b) << 16); }
; template <int EPI, bool HS = false>
; __device__ __forceinline__ void gemm_phase(const Params& p, const GemmCfg& g, char* shm, const int wave_s) {
;     ...
;           for (int j = 0; j < 4; ++j) {
;             float ss = 0.f;
; #pragma unroll
;             for (int bj = 0; bj < 2; ++bj) {
;               float2 xn;
;               xn.x = xv[j][bj].x + gt[bj][0] * acc[ai][bj][m][0][j];
;               xn.y = xv[j][bj].y + gt[bj][1] * acc[ai][bj][m][1][j];
;               const unsigned o = tb + (unsigned)((ai * 128 + m * 16 + j) * 1024 + bj * 128);
;               *(float2*)(xout_t + o) = xn;
;               if (g.has_next) *(unsigned*)(xg_t + o) = pack2(xn.x * gn[bj][0], xn.y * gn[bj][1]);
;               ss += xn.x * xn.x + xn.y * xn.y;
;             }
;             if (g.has_next) {
;               ss = dpp_row_sum16(ss);
;               if (fr == 0) rss_t[(wr * 64 + fq * 4 + ai * 128 + m * 16 + j) * 16] = ss;
;             }
.LBB0_262:
	v_add_u32_e32 v26, 0x28c00, v0
	v_mov_b32_e32 v32, v29
	v_mov_b32_e32 v27, v1
	s_waitcnt lgkmcnt(0)
	v_pk_fma_f32 v[22:23], v[150:151], v[32:33], v[34:35]
	v_lshl_add_u64 v[18:19], v[26:27], 2, s[2:3]
	global_store_dwordx2 v[18:19], v[22:23], off
	s_mov_b64 s[10:11], -1
	s_and_b64 vcc, exec, s[6:7]
	v_add_u32_e32 v18, 0x28c80, v0
	s_cbranch_vccnz .LBB0_266
	v_pk_mul_f32 v[28:29], v[148:149], v[22:23]
	v_lshl_add_u64 v[26:27], v[26:27], 1, s[8:9]
	s_nop 0
	s_nop 0
	v_cvt_pk_bf16_f32 v20, v28, v28
	v_cvt_pk_bf16_f32 v19, v29, v29
	v_lshrrev_b32_e32 v20, 16, v20
	v_and_or_b32 v19, v19, s28, v20
	global_store_dword v[26:27], v19, off
	v_mov_b32_e32 v24, v21
	v_mov_b32_e32 v19, v1
	v_pk_fma_f32 v[26:27], v[146:147], v[24:25], v[36:37]
	v_lshl_add_u64 v[28:29], v[18:19], 2, s[2:3]
	global_store_dwordx2 v[28:29], v[26:27], off
	v_pk_mul_f32 v[28:29], v[152:153], v[26:27]
	v_pk_mul_f32 v[22:23], v[22:23], v[22:23]
	s_nop 0
	s_nop 0
	v_cvt_pk_bf16_f32 v24, v28, v28
	v_cvt_pk_bf16_f32 v20, v29, v29
	v_lshrrev_b32_e32 v24, 16, v24
	v_and_or_b32 v20, v20, s28, v24
	v_lshl_add_u64 v[28:29], v[18:19], 1, s[8:9]
	v_pk_mul_f32 v[26:27], v[26:27], v[26:27]
	global_store_dword v[28:29], v20, off
	v_add_f32_e32 v19, v26, v27
	v_add_f32_e32 v20, v22, v23
	v_add_f32_e32 v19, v20, v19
	s_nop 1
	v_add_f32_dpp v19, v19, v19 quad_perm:[1,0,3,2] row_mask:0xf bank_mask:0xf bound_ctrl:1
	s_nop 1
	v_add_f32_dpp v19, v19, v19 quad_perm:[2,3,0,1] row_mask:0xf bank_mask:0xf bound_ctrl:1
	s_nop 1
	v_add_f32_dpp v19, v19, v19 row_half_mirror row_mask:0xf bank_mask:0xf bound_ctrl:1
	s_nop 1
	v_mov_b32_dpp v20, v19 row_mirror row_mask:0xf bank_mask:0xf bound_ctrl:1
	s_and_saveexec_b64 s[10:11], s[4:5]
	s_cbranch_execz .LBB0_265
	v_add_f32_e32 v19, v19, v20
	v_mov_b32_e32 v20, 0xa30
	v_lshl_add_u32 v22, v160, 4, v20
	v_ashrrev_i32_e32 v23, 31, v22
	v_lshl_add_u64 v[22:23], v[22:23], 2, v[142:143]
	global_store_dword v[22:23], v19, off

; __device__ __forceinline__ unsigned pack2(float a, float b) { return (unsigned)f2bf(a) | ((unsigned)f2bf(b) << 16); }
; template <int EPI, bool HS = false>
; __device__ __forceinline__ void gemm_phase(const Params& p, const GemmCfg& g, char* shm, const int wave_s) {
;     ...
;             for (int bj = 0; bj < 2; ++bj) xv[j][bj] = *(const float2*)(xl + (m * 16 + j) * XROW + bj * 512);
; #pragma unroll
;           for (int j = 0; j < 4; ++j) {
;             float ss = 0.f;
; #pragma unroll
;             for (int bj = 0; bj < 2; ++bj) {
;               float2 xn;
;               xn.x = xv[j][bj].x + gt[bj][0] * acc[ai][bj][m][0][j];
;               xn.y = xv[j][bj].y + gt[bj][1] * acc[ai][bj][m][1][j];
;               const unsigned o = tb + (unsigned)((ai * 128 + m * 16 + j) * 1024 + bj * 128);
;               *(float2*)(xout_t + o) = xn;
;               if (g.has_next) *(unsigned*)(xg_t + o) = pack2(xn.x * gn[bj][0], xn.y * gn[bj][1]);
;               ss += xn.x * xn.x + xn.y * xn.y;
;             }
;             if (g.has_next) {
;               ss = dpp_row_sum16(ss);
;               if (fr == 0) rss_t[(wr * 64 + fq * 4 + ai * 128 + m * 16 + j) * 16] = ss;
;             }
.LBB0_268:
	ds_read2st64_b64 v[30:33], v134 offset0:97 offset1:98
	ds_read2st64_b64 v[26:29], v135 offset0:99 offset1:100
	ds_read2st64_b64 v[22:25], v136 offset0:101 offset1:102
	ds_read2st64_b64 v[18:21], v137 offset0:103 offset1:104
	v_add_u32_e32 v36, 0x2c000, v0
	v_mov_b32_e32 v34, v10
	v_mov_b32_e32 v35, v14
	v_mov_b32_e32 v37, v1
	s_waitcnt lgkmcnt(3)
	v_pk_fma_f32 v[34:35], v[150:151], v[34:35], v[30:31]
	v_lshl_add_u64 v[30:31], v[36:37], 2, s[2:3]
	global_store_dwordx2 v[30:31], v[34:35], off
	s_mov_b64 s[10:11], -1
	s_and_b64 vcc, exec, s[6:7]
	v_add_u32_e32 v30, 0x2c080, v0
	s_cbranch_vccnz .LBB0_272
	v_pk_mul_f32 v[38:39], v[148:149], v[34:35]
	v_lshl_add_u64 v[36:37], v[36:37], 1, s[8:9]
	s_nop 0
	s_nop 0
	v_cvt_pk_bf16_f32 v14, v38, v38
	v_cvt_pk_bf16_f32 v10, v39, v39
	v_lshrrev_b32_e32 v14, 16, v14
	v_and_or_b32 v10, v10, s28, v14
	global_store_dword v[36:37], v10, off
	v_mov_b32_e32 v36, v2
	v_mov_b32_e32 v37, v6
	v_mov_b32_e32 v31, v1
	v_pk_fma_f32 v[36:37], v[146:147], v[36:37], v[32:33]
	v_lshl_add_u64 v[38:39], v[30:31], 2, s[2:3]
	global_store_dwordx2 v[38:39], v[36:37], off
	v_pk_mul_f32 v[38:39], v[152:153], v[36:37]
	v_pk_mul_f32 v[34:35], v[34:35], v[34:35]
	s_nop 0
	s_nop 0
	v_cvt_pk_bf16_f32 v14, v38, v38
	v_cvt_pk_bf16_f32 v10, v39, v39
	v_lshrrev_b32_e32 v14, 16, v14
	v_and_or_b32 v10, v10, s28, v14
	v_lshl_add_u64 v[38:39], v[30:31], 1, s[8:9]
	v_pk_mul_f32 v[36:37], v[36:37], v[36:37]
	global_store_dword v[38:39], v10, off
	v_add_f32_e32 v10, v36, v37
	v_add_f32_e32 v14, v34, v35
	v_add_f32_e32 v10, v14, v10
	s_nop 1
	v_add_f32_dpp v10, v10, v10 quad_perm:[1,0,3,2] row_mask:0xf bank_mask:0xf bound_ctrl:1
	s_nop 1
	v_add_f32_dpp v10, v10, v10 quad_perm:[2,3,0,1] row_mask:0xf bank_mask:0xf bound_ctrl:1
	s_nop 1
	v_add_f32_dpp v10, v10, v10 row_half_mirror row_mask:0xf bank_mask:0xf bound_ctrl:1
	s_nop 1
	v_mov_b32_dpp v14, v10 row_mirror row_mask:0xf bank_mask:0xf bound_ctrl:1
	s_and_saveexec_b64 s[10:11], s[4:5]
	s_cbranch_execz .LBB0_271
	v_add_f32_e32 v10, v10, v14
	v_mov_b32_e32 v14, 0xb00
	v_lshl_add_u32 v34, v160, 4, v14
	v_ashrrev_i32_e32 v35, 31, v34
	v_lshl_add_u64 v[34:35], v[34:35], 2, v[142:143]
	global_store_dword v[34:35], v10, off

; __device__ __forceinline__ unsigned pack2(float a, float b) { return (unsigned)f2bf(a) | ((unsigned)f2bf(b) << 16); }
; template <int EPI, bool HS = false>
; __device__ __forceinline__ void gemm_phase(const Params& p, const GemmCfg& g, char* shm, const int wave_s) {
;     ...
;           for (int j = 0; j < 4; ++j) {
;             float ss = 0.f;
; #pragma unroll
;             for (int bj = 0; bj < 2; ++bj) {
;               float2 xn;
;               xn.x = xv[j][bj].x + gt[bj][0] * acc[ai][bj][m][0][j];
;               xn.y = xv[j][bj].y + gt[bj][1] * acc[ai][bj][m][1][j];
;               const unsigned o = tb + (unsigned)((ai * 128 + m * 16 + j) * 1024 + bj * 128);
;               *(float2*)(xout_t + o) = xn;
;               if (g.has_next) *(unsigned*)(xg_t + o) = pack2(xn.x * gn[bj][0], xn.y * gn[bj][1]);
;               ss += xn.x * xn.x + xn.y * xn.y;
;             }
;             if (g.has_next) {
;               ss = dpp_row_sum16(ss);
;               if (fr == 0) rss_t[(wr * 64 + fq * 4 + ai * 128 + m * 16 + j) * 16] = ss;
;             }
.LBB0_274:
	v_add_u32_e32 v30, 0x2c400, v0
	v_mov_b32_e32 v14, v11
	v_mov_b32_e32 v31, v1
	s_waitcnt lgkmcnt(2)
	v_pk_fma_f32 v[14:15], v[150:151], v[14:15], v[26:27]
	v_lshl_add_u64 v[10:11], v[30:31], 2, s[2:3]
	global_store_dwordx2 v[10:11], v[14:15], off
	s_mov_b64 s[10:11], -1
	s_and_b64 vcc, exec, s[6:7]
	v_add_u32_e32 v10, 0x2c480, v0
	s_cbranch_vccnz .LBB0_278
	v_pk_mul_f32 v[26:27], v[148:149], v[14:15]
	v_mov_b32_e32 v11, v1
	s_nop 0
	s_nop 0
	v_cvt_pk_bf16_f32 v6, v26, v26
	v_cvt_pk_bf16_f32 v2, v27, v27
	v_lshrrev_b32_e32 v6, 16, v6
	v_and_or_b32 v2, v2, s28, v6
	v_lshl_add_u64 v[26:27], v[30:31], 1, s[8:9]
	v_mov_b32_e32 v6, v3
	global_store_dword v[26:27], v2, off
	v_pk_fma_f32 v[26:27], v[146:147], v[6:7], v[28:29]
	v_lshl_add_u64 v[30:31], v[10:11], 2, s[2:3]
	global_store_dwordx2 v[30:31], v[26:27], off
	v_pk_mul_f32 v[30:31], v[152:153], v[26:27]
	v_pk_mul_f32 v[14:15], v[14:15], v[14:15]
	s_nop 0
	s_nop 0
	v_cvt_pk_bf16_f32 v6, v30, v30
	v_cvt_pk_bf16_f32 v2, v31, v31
	v_lshrrev_b32_e32 v6, 16, v6
	v_and_or_b32 v2, v2, s28, v6
	v_lshl_add_u64 v[30:31], v[10:11], 1, s[8:9]
	v_pk_mul_f32 v[26:27], v[26:27], v[26:27]
	global_store_dword v[30:31], v2, off
	v_add_f32_e32 v2, v26, v27
	v_add_f32_e32 v6, v14, v15
	v_add_f32_e32 v2, v6, v2
	s_nop 1
	v_add_f32_dpp v2, v2, v2 quad_perm:[1,0,3,2] row_mask:0xf bank_mask:0xf bound_ctrl:1
	s_nop 1
	v_add_f32_dpp v2, v2, v2 quad_perm:[2,3,0,1] row_mask:0xf bank_mask:0xf bound_ctrl:1
	s_nop 1
	v_add_f32_dpp v2, v2, v2 row_half_mirror row_mask:0xf bank_mask:0xf bound_ctrl:1
	s_nop 1
	v_mov_b32_dpp v6, v2 row_mirror row_mask:0xf bank_mask:0xf bound_ctrl:1
	s_and_saveexec_b64 s[10:11], s[4:5]
	s_cbranch_execz .LBB0_277
	v_add_f32_e32 v2, v2, v6
	v_mov_b32_e32 v6, 0xb10
	v_lshl_add_u32 v14, v160, 4, v6
	v_ashrrev_i32_e32 v15, 31, v14
	v_lshl_add_u64 v[14:15], v[14:15], 2, v[142:143]
	global_store_dword v[14:15], v2, off

; __device__ __forceinline__ unsigned pack2(float a, float b) { return (unsigned)f2bf(a) | ((unsigned)f2bf(b) << 16); }
; template <int EPI, bool HS = false>
; __device__ __forceinline__ void gemm_phase(const Params& p, const GemmCfg& g, char* shm, const int wave_s) {
;     ...
;           for (int j = 0; j < 4; ++j) {
;             float ss = 0.f;
; #pragma unroll
;             for (int bj = 0; bj < 2; ++bj) {
;               float2 xn;
;               xn.x = xv[j][bj].x + gt[bj][0] * acc[ai][bj][m][0][j];
;               xn.y = xv[j][bj].y + gt[bj][1] * acc[ai][bj][m][1][j];
;               const unsigned o = tb + (unsigned)((ai * 128 + m * 16 + j) * 1024 + bj * 128);
;               *(float2*)(xout_t + o) = xn;
;               if (g.has_next) *(unsigned*)(xg_t + o) = pack2(xn.x * gn[bj][0], xn.y * gn[bj][1]);
;               ss += xn.x * xn.x + xn.y * xn.y;
;             }
;             if (g.has_next) {
;               ss = dpp_row_sum16(ss);
;               if (fr == 0) rss_t[(wr * 64 + fq * 4 + ai * 128 + m * 16 + j) * 16] = ss;
;             }
.LBB0_280:
	v_add_u32_e32 v10, 0x2c800, v0
	v_mov_b32_e32 v2, v12
	v_mov_b32_e32 v3, v16
	v_mov_b32_e32 v11, v1
	s_waitcnt lgkmcnt(1)
	v_pk_fma_f32 v[6:7], v[150:151], v[2:3], v[22:23]
	v_lshl_add_u64 v[2:3], v[10:11], 2, s[2:3]
	global_store_dwordx2 v[2:3], v[6:7], off
	s_mov_b64 s[10:11], -1
	s_and_b64 vcc, exec, s[6:7]
	v_add_u32_e32 v2, 0x2c880, v0
	s_cbranch_vccnz .LBB0_284
	v_pk_mul_f32 v[14:15], v[148:149], v[6:7]
	v_lshl_add_u64 v[10:11], v[10:11], 1, s[8:9]
	s_nop 0
	s_nop 0
	v_cvt_pk_bf16_f32 v12, v14, v14
	v_cvt_pk_bf16_f32 v3, v15, v15
	v_lshrrev_b32_e32 v12, 16, v12
	v_and_or_b32 v3, v3, s28, v12
	global_store_dword v[10:11], v3, off
	v_mov_b32_e32 v10, v4
	v_mov_b32_e32 v11, v8
	v_mov_b32_e32 v3, v1
	v_pk_fma_f32 v[10:11], v[146:147], v[10:11], v[24:25]
	v_lshl_add_u64 v[14:15], v[2:3], 2, s[2:3]
	global_store_dwordx2 v[14:15], v[10:11], off
	v_pk_mul_f32 v[14:15], v[152:153], v[10:11]
	v_pk_mul_f32 v[6:7], v[6:7], v[6:7]
	v_and_b32_sdwa v16, v14, v178 dst_sel:DWORD dst_unused:UNUSED_PAD src0_sel:WORD_1 src1_sel:DWORD
	s_nop 0
	v_add3_u32 v14, v14, v16, s81
	v_cvt_pk_bf16_f32 v12, v15, v15
	v_lshrrev_b32_e32 v14, 16, v14
	v_pk_mul_f32 v[10:11], v[10:11], v[10:11]
	v_and_or_b32 v12, v12, s28, v14
	v_lshl_add_u64 v[14:15], v[2:3], 1, s[8:9]
	v_add_f32_e32 v3, v10, v11
	v_add_f32_e32 v6, v6, v7
	v_add_f32_e32 v3, v6, v3
	global_store_dword v[14:15], v12, off
	s_nop 0
	v_add_f32_dpp v3, v3, v3 quad_perm:[1,0,3,2] row_mask:0xf bank_mask:0xf bound_ctrl:1
	s_nop 1
	v_add_f32_dpp v3, v3, v3 quad_perm:[2,3,0,1] row_mask:0xf bank_mask:0xf bound_ctrl:1
	s_nop 1
	v_add_f32_dpp v3, v3, v3 row_half_mirror row_mask:0xf bank_mask:0xf bound_ctrl:1
	s_nop 1
	v_mov_b32_dpp v6, v3 row_mirror row_mask:0xf bank_mask:0xf bound_ctrl:1
	s_and_saveexec_b64 s[10:11], s[4:5]
	s_cbranch_execz .LBB0_283
	v_add_f32_e32 v3, v3, v6
	v_mov_b32_e32 v6, 0xb20
	v_lshl_add_u32 v6, v160, 4, v6
	v_ashrrev_i32_e32 v7, 31, v6
	v_lshl_add_u64 v[6:7], v[6:7], 2, v[142:143]
	global_store_dword v[6:7], v3, off

; __device__ __forceinline__ u16 f2bf(float f) {
;   unsigned u = __float_as_uint(f);
;   u += 0x7fffu + ((u >> 16) & 1u);
;   return (u16)(u >> 16);
; }
; __device__ __forceinline__ float bf2f(u16 h) { return __uint_as_float(((unsigned)h) << 16); }
; __device__ __forceinline__ float bfs2f(short h) { return __uint_as_float(((unsigned)(u16)h) << 16); }
; __device__ __forceinline__ unsigned pack2(float a, float b) { return (unsigned)f2bf(a) | ((unsigned)f2bf(b) << 16); }
; template <int EPI, bool HS = false>
; __device__ __forceinline__ void gemm_phase(const Params& p, const GemmCfg& g, char* shm, const int wave_s) {
;     ...
;             for (int bj = 0; bj < 2; ++bj) {
;               float2 xn;
;               xn.x = xv[j][bj].x + gt[bj][0] * acc[ai][bj][m][0][j];
;               xn.y = xv[j][bj].y + gt[bj][1] * acc[ai][bj][m][1][j];
;               const unsigned o = tb + (unsigned)((ai * 128 + m * 16 + j) * 1024 + bj * 128);
;               *(float2*)(xout_t + o) = xn;
;               if (g.has_next) *(unsigned*)(xg_t + o) = pack2(xn.x * gn[bj][0], xn.y * gn[bj][1]);
;               ss += xn.x * xn.x + xn.y * xn.y;
;             }
;             if (g.has_next) {
;               ss = dpp_row_sum16(ss);
;               if (fr == 0) rss_t[(wr * 64 + fq * 4 + ai * 128 + m * 16 + j) * 16] = ss;
;             }
.LBB0_286:
	v_add_u32_e32 v6, 0x2cc00, v0
	v_mov_b32_e32 v16, v13
	v_mov_b32_e32 v7, v1
	s_waitcnt lgkmcnt(0)
	v_pk_fma_f32 v[2:3], v[150:151], v[16:17], v[18:19]
	v_lshl_add_u64 v[10:11], v[6:7], 2, s[2:3]
	s_mov_b64 s[10:11], -1
	s_and_b64 vcc, exec, s[6:7]
	v_add_u32_e32 v0, 0x2cc80, v0
	global_store_dwordx2 v[10:11], v[2:3], off
	s_cbranch_vccnz .LBB0_290
	v_pk_mul_f32 v[10:11], v[148:149], v[2:3]
	v_lshl_add_u64 v[6:7], v[6:7], 1, s[8:9]
	s_nop 0
	s_nop 0
	v_cvt_pk_bf16_f32 v8, v10, v10
	v_cvt_pk_bf16_f32 v4, v11, v11
	v_lshrrev_b32_e32 v8, 16, v8
	v_and_or_b32 v4, v4, s28, v8
	v_mov_b32_e32 v8, v5
	global_store_dword v[6:7], v4, off
	v_pk_fma_f32 v[6:7], v[146:147], v[8:9], v[20:21]
	v_lshl_add_u64 v[10:11], v[0:1], 2, s[2:3]
	global_store_dwordx2 v[10:11], v[6:7], off
	v_pk_mul_f32 v[10:11], v[152:153], v[6:7]
	v_pk_mul_f32 v[2:3], v[2:3], v[2:3]
	s_nop 0
	s_nop 0
	v_cvt_pk_bf16_f32 v8, v10, v10
	v_cvt_pk_bf16_f32 v4, v11, v11
	v_lshrrev_b32_e32 v8, 16, v8
	v_and_or_b32 v4, v4, s28, v8
	v_lshl_add_u64 v[10:11], v[0:1], 1, s[8:9]
	v_pk_mul_f32 v[6:7], v[6:7], v[6:7]
	global_store_dword v[10:11], v4, off
	v_add_f32_e32 v4, v6, v7
	v_add_f32_e32 v2, v2, v3
	v_add_f32_e32 v2, v2, v4
	s_nop 1
	v_add_f32_dpp v2, v2, v2 quad_perm:[1,0,3,2] row_mask:0xf bank_mask:0xf bound_ctrl:1
	s_nop 1
	v_add_f32_dpp v2, v2, v2 quad_perm:[2,3,0,1] row_mask:0xf bank_mask:0xf bound_ctrl:1
	s_nop 1
	v_add_f32_dpp v2, v2, v2 row_half_mirror row_mask:0xf bank_mask:0xf bound_ctrl:1
	s_nop 1
	v_mov_b32_dpp v3, v2 row_mirror row_mask:0xf bank_mask:0xf bound_ctrl:1
	s_and_saveexec_b64 s[6:7], s[4:5]
	s_cbranch_execz .LBB0_289
	v_add_f32_e32 v4, v2, v3
	v_mov_b32_e32 v2, 0xb30
	v_lshl_add_u32 v2, v160, 4, v2
	v_ashrrev_i32_e32 v3, 31, v2
	v_lshl_add_u64 v[2:3], v[2:3], 2, v[142:143]
	global_store_dword v[2:3], v4, off

; __device__ __forceinline__ u16 f2bf(float f) {
;   unsigned u = __float_as_uint(f);
;   u += 0x7fffu + ((u >> 16) & 1u);
;   return (u16)(u >> 16);
; }
; __device__ __forceinline__ float bf2f(u16 h) { return __uint_as_float(((unsigned)h) << 16); }
; __device__ __forceinline__ float bfs2f(short h) { return __uint_as_float(((unsigned)(u16)h) << 16); }
; __device__ __forceinline__ unsigned pack2(float a, float b) { return (unsigned)f2bf(a) | ((unsigned)f2bf(b) << 16); }
; template <int EPI, bool HS = false>
; __device__ __forceinline__ void gemm_phase(const Params& p, const GemmCfg& g, char* shm, const int wave_s) {
;     ...
;       float* rss_t = p.rowss + (size_t)orow0 * 16 + pn * 4 + wc;
;     ...
;             for (int bj = 0; bj < 2; ++bj) {
;               float2 xn;
;               xn.x = xv[j][bj].x + gt[bj][0] * acc[ai][bj][m][0][j];
;               xn.y = xv[j][bj].y + gt[bj][1] * acc[ai][bj][m][1][j];
;               const unsigned o = tb + (unsigned)((ai * 128 + m * 16 + j) * 1024 + bj * 128);
;               *(float2*)(xout_t + o) = xn;
;               if (g.has_next) *(unsigned*)(xg_t + o) = pack2(xn.x * gn[bj][0], xn.y * gn[bj][1]);
;               ss += xn.x * xn.x + xn.y * xn.y;
;             }
;             if (g.has_next) {
;               ss = dpp_row_sum16(ss);
;               if (fr == 0) rss_t[(wr * 64 + fq * 4 + ai * 128 + m * 16 + j) * 16] = ss;
;             }
.LBB0_357:
	v_readlane_b32 s16, v252, 0
	s_lshl_b64 s[4:5], s[4:5], 6
	v_readlane_b32 s22, v252, 6
	v_readlane_b32 s23, v252, 7
	s_add_u32 s14, s22, s4
	s_addc_u32 s15, s23, s5
	s_lshl_b32 s4, s13, 2
	s_ashr_i32 s5, s4, 31
	s_lshl_b64 s[4:5], s[4:5], 2
	s_add_u32 s4, s14, s4
	v_pk_mul_f32 v[146:147], v[146:147], v[158:159]
	v_pk_mul_f32 v[142:143], v[142:143], v[158:159]
	s_addc_u32 s5, s15, s5
	v_lshlrev_b32_e32 v150, 2, v200
	v_mov_b32_e32 v151, v1
	v_mov_b32_e32 v158, v146
	v_mov_b32_e32 v159, v142
	v_pk_mul_f32 v[156:157], v[156:157], v[160:161]
	v_pk_mul_f32 v[152:153], v[152:153], v[160:161]
	v_lshl_add_u64 v[150:151], s[4:5], 0, v[150:151]
	v_cmp_eq_u32_e64 s[4:5], 0, v199
	v_pk_mul_f32 v[148:149], v[148:149], v[160:161]
	v_pk_mul_f32 v[144:145], v[144:145], v[160:161]
	s_waitcnt vmcnt(1)
	v_pk_fma_f32 v[158:159], v[158:159], v[180:181], v[176:177]
	s_and_b64 vcc, exec, s[6:7]
	s_mov_b64 s[68:69], -1
	v_readlane_b32 s17, v252, 1
	v_readlane_b32 s18, v252, 2
	v_readlane_b32 s19, v252, 3
	v_readlane_b32 s20, v252, 4
	v_readlane_b32 s21, v252, 5
	global_store_dwordx2 v[192:193], v[158:159], off offset:512
	s_cbranch_vccnz .LBB0_363
	v_pk_mul_f32 v[176:177], v[186:187], v[158:159]
	v_pk_mul_f32 v[160:161], v[190:191], v[190:191]
	s_nop 0
	s_nop 0
	v_cvt_pk_bf16_f32 v146, v176, v176
	v_cvt_pk_bf16_f32 v142, v177, v177
	v_lshrrev_b32_e32 v146, 16, v146
	v_and_or_b32 v142, v142, s28, v146
	v_pk_mul_f32 v[158:159], v[158:159], v[158:159]
	global_store_dword v[174:175], v142, off offset:256
	v_add_f32_e32 v142, v158, v159
	v_add_f32_e32 v146, v160, v161
	v_add_f32_e32 v142, v146, v142
	s_nop 1
	v_add_f32_dpp v142, v142, v142 quad_perm:[1,0,3,2] row_mask:0xf bank_mask:0xf bound_ctrl:1
	s_nop 1
	v_add_f32_dpp v142, v142, v142 quad_perm:[2,3,0,1] row_mask:0xf bank_mask:0xf bound_ctrl:1
	s_nop 1
	v_add_f32_dpp v142, v142, v142 row_half_mirror row_mask:0xf bank_mask:0xf bound_ctrl:1
	s_nop 1
	v_mov_b32_dpp v146, v142 row_mirror row_mask:0xf bank_mask:0xf bound_ctrl:1
	s_and_saveexec_b64 s[68:69], s[4:5]
	s_cbranch_execz .LBB0_360
	v_lshlrev_b32_e32 v158, 4, v194
	v_ashrrev_i32_e32 v159, 31, v158
	v_add_f32_e32 v142, v142, v146
	v_lshl_add_u64 v[158:159], v[158:159], 2, v[150:151]
	global_store_dword v[158:159], v142, off
.LBB0_360:
	s_or_b64 exec, exec, s[68:69]
	v_or_b32_e32 v158, 0x400, v0
	v_mov_b32_e32 v154, v189
	v_mov_b32_e32 v159, v1
	s_waitcnt lgkmcnt(2)
	v_pk_fma_f32 v[160:161], v[154:155], v[184:185], v[170:171]
	v_lshl_add_u64 v[158:159], v[158:159], 2, s[2:3]
	global_store_dwordx2 v[158:159], v[160:161], off
	v_pk_mul_f32 v[158:159], v[182:183], v[160:161]
	v_or_b32_e32 v176, 0x480, v0
	s_nop 0
	s_nop 0
	v_cvt_pk_bf16_f32 v146, v158, v158
	v_cvt_pk_bf16_f32 v142, v159, v159
	v_lshrrev_b32_e32 v146, 16, v146
	v_and_or_b32 v142, v142, s28, v146
	global_store_dword v[174:175], v142, off offset:2048
	v_mov_b32_e32 v142, v147
	v_mov_b32_e32 v177, v1
	v_pk_fma_f32 v[158:159], v[142:143], v[180:181], v[172:173]
	v_lshl_add_u64 v[176:177], v[176:177], 2, s[2:3]
	global_store_dwordx2 v[176:177], v[158:159], off
	v_pk_mul_f32 v[176:177], v[186:187], v[158:159]
	v_pk_mul_f32 v[160:161], v[160:161], v[160:161]
	s_nop 0
	s_nop 0
	v_cvt_pk_bf16_f32 v146, v176, v176
	v_cvt_pk_bf16_f32 v142, v177, v177
	v_lshrrev_b32_e32 v146, 16, v146
	v_and_or_b32 v142, v142, s28, v146
	v_pk_mul_f32 v[158:159], v[158:159], v[158:159]
	global_store_dword v[174:175], v142, off offset:2304
	v_add_f32_e32 v142, v158, v159
	v_add_f32_e32 v146, v160, v161
	v_add_f32_e32 v142, v146, v142
	s_nop 1
	v_add_f32_dpp v142, v142, v142 quad_perm:[1,0,3,2] row_mask:0xf bank_mask:0xf bound_ctrl:1
	s_nop 1
	v_add_f32_dpp v142, v142, v142 quad_perm:[2,3,0,1] row_mask:0xf bank_mask:0xf bound_ctrl:1
	s_nop 1
	v_add_f32_dpp v142, v142, v142 row_half_mirror row_mask:0xf bank_mask:0xf bound_ctrl:1
	s_nop 1
	v_mov_b32_dpp v146, v142 row_mirror row_mask:0xf bank_mask:0xf bound_ctrl:1
	s_and_saveexec_b64 s[68:69], s[4:5]
	s_cbranch_execz .LBB0_362
	v_lshlrev_b32_e32 v158, 4, v194
	v_ashrrev_i32_e32 v159, 31, v158
	v_add_f32_e32 v142, v142, v146
	v_lshl_add_u64 v[158:159], v[158:159], 2, v[150:151]
	global_store_dword v[158:159], v142, off offset:64

; __device__ __forceinline__ u16 f2bf(float f) {
;   unsigned u = __float_as_uint(f);
;   u += 0x7fffu + ((u >> 16) & 1u);
;   return (u16)(u >> 16);
; }
; __device__ __forceinline__ float bf2f(u16 h) { return __uint_as_float(((unsigned)h) << 16); }
; __device__ __forceinline__ float bfs2f(short h) { return __uint_as_float(((unsigned)(u16)h) << 16); }
; __device__ __forceinline__ unsigned pack2(float a, float b) { return (unsigned)f2bf(a) | ((unsigned)f2bf(b) << 16); }
; template <int EPI, bool HS = false>
; __device__ __forceinline__ void gemm_phase(const Params& p, const GemmCfg& g, char* shm, const int wave_s) {
;     ...
;             for (int bj = 0; bj < 2; ++bj) {
;               float2 xn;
;               xn.x = xv[j][bj].x + gt[bj][0] * acc[ai][bj][m][0][j];
;               xn.y = xv[j][bj].y + gt[bj][1] * acc[ai][bj][m][1][j];
;               const unsigned o = tb + (unsigned)((ai * 128 + m * 16 + j) * 1024 + bj * 128);
;               *(float2*)(xout_t + o) = xn;
;               if (g.has_next) *(unsigned*)(xg_t + o) = pack2(xn.x * gn[bj][0], xn.y * gn[bj][1]);
;               ss += xn.x * xn.x + xn.y * xn.y;
;             }
;             if (g.has_next) {
;               ss = dpp_row_sum16(ss);
;               if (fr == 0) rss_t[(wr * 64 + fq * 4 + ai * 128 + m * 16 + j) * 16] = ss;
;             }
.LBB0_365:
	v_or_b32_e32 v154, 0x800, v0
	v_mov_b32_e32 v142, v156
	v_mov_b32_e32 v143, v152
	v_mov_b32_e32 v155, v1
	s_waitcnt lgkmcnt(1)
	v_pk_fma_f32 v[146:147], v[142:143], v[184:185], v[166:167]
	v_lshl_add_u64 v[142:143], v[154:155], 2, s[2:3]
	global_store_dwordx2 v[142:143], v[146:147], off
	s_mov_b64 s[68:69], -1
	s_and_b64 vcc, exec, s[6:7]
	v_or_b32_e32 v142, 0x880, v0
	s_cbranch_vccnz .LBB0_369
	v_pk_mul_f32 v[158:159], v[182:183], v[146:147]
	v_lshl_add_u64 v[154:155], v[154:155], 1, s[8:9]
	s_nop 0
	s_nop 0
	v_cvt_pk_bf16_f32 v152, v158, v158
	v_cvt_pk_bf16_f32 v143, v159, v159
	v_lshrrev_b32_e32 v152, 16, v152
	v_and_or_b32 v143, v143, s28, v152
	global_store_dword v[154:155], v143, off
	v_mov_b32_e32 v154, v148
	v_mov_b32_e32 v155, v144
	v_mov_b32_e32 v143, v1
	v_pk_fma_f32 v[154:155], v[154:155], v[180:181], v[168:169]
	v_lshl_add_u64 v[158:159], v[142:143], 2, s[2:3]
	global_store_dwordx2 v[158:159], v[154:155], off
	v_pk_mul_f32 v[158:159], v[186:187], v[154:155]
	v_pk_mul_f32 v[146:147], v[146:147], v[146:147]
	s_nop 0
	s_nop 0
	v_pk_mul_f32 v[154:155], v[154:155], v[154:155]
	v_cvt_pk_bf16_f32 v152, v159, v159
	v_cvt_pk_bf16_f32 v156, v158, v158
	v_lshl_add_u64 v[158:159], v[142:143], 1, s[8:9]
	v_add_f32_e32 v143, v154, v155
	v_add_f32_e32 v146, v146, v147
	v_add_f32_e32 v143, v146, v143
	v_lshrrev_b32_e32 v156, 16, v156
	v_and_or_b32 v152, v152, s28, v156
	v_add_f32_dpp v143, v143, v143 quad_perm:[1,0,3,2] row_mask:0xf bank_mask:0xf bound_ctrl:1
	global_store_dword v[158:159], v152, off
	s_nop 0
	v_add_f32_dpp v143, v143, v143 quad_perm:[2,3,0,1] row_mask:0xf bank_mask:0xf bound_ctrl:1
	s_nop 1
	v_add_f32_dpp v143, v143, v143 row_half_mirror row_mask:0xf bank_mask:0xf bound_ctrl:1
	s_nop 1
	v_mov_b32_dpp v146, v143 row_mirror row_mask:0xf bank_mask:0xf bound_ctrl:1
	s_and_saveexec_b64 s[68:69], s[4:5]
	s_cbranch_execz .LBB0_368
	v_add_f32_e32 v143, v143, v146
	v_lshlrev_b32_e32 v146, 4, v194
	v_ashrrev_i32_e32 v147, 31, v146
	v_lshl_add_u64 v[146:147], v[146:147], 2, v[150:151]
	global_store_dword v[146:147], v143, off offset:128

; __device__ __forceinline__ u16 f2bf(float f) {
;   unsigned u = __float_as_uint(f);
;   u += 0x7fffu + ((u >> 16) & 1u);
;   return (u16)(u >> 16);
; }
; __device__ __forceinline__ float bf2f(u16 h) { return __uint_as_float(((unsigned)h) << 16); }
; __device__ __forceinline__ float bfs2f(short h) { return __uint_as_float(((unsigned)(u16)h) << 16); }
; __device__ __forceinline__ unsigned pack2(float a, float b) { return (unsigned)f2bf(a) | ((unsigned)f2bf(b) << 16); }
; template <int EPI, bool HS = false>
; __device__ __forceinline__ void gemm_phase(const Params& p, const GemmCfg& g, char* shm, const int wave_s) {
;     ...
;             for (int bj = 0; bj < 2; ++bj) {
;               float2 xn;
;               xn.x = xv[j][bj].x + gt[bj][0] * acc[ai][bj][m][0][j];
;               xn.y = xv[j][bj].y + gt[bj][1] * acc[ai][bj][m][1][j];
;               const unsigned o = tb + (unsigned)((ai * 128 + m * 16 + j) * 1024 + bj * 128);
;               *(float2*)(xout_t + o) = xn;
;               if (g.has_next) *(unsigned*)(xg_t + o) = pack2(xn.x * gn[bj][0], xn.y * gn[bj][1]);
;               ss += xn.x * xn.x + xn.y * xn.y;
;             }
;             if (g.has_next) {
;               ss = dpp_row_sum16(ss);
;               if (fr == 0) rss_t[(wr * 64 + fq * 4 + ai * 128 + m * 16 + j) * 16] = ss;
;             }
.LBB0_371:
	v_or_b32_e32 v154, 0xc00, v0
	v_mov_b32_e32 v152, v157
	v_mov_b32_e32 v155, v1
	s_waitcnt lgkmcnt(0)
	v_pk_fma_f32 v[146:147], v[152:153], v[184:185], v[162:163]
	v_lshl_add_u64 v[142:143], v[154:155], 2, s[2:3]
	global_store_dwordx2 v[142:143], v[146:147], off
	s_mov_b64 s[68:69], -1
	s_and_b64 vcc, exec, s[6:7]
	v_or_b32_e32 v142, 0xc80, v0
	s_cbranch_vccnz .LBB0_375
	v_pk_mul_f32 v[152:153], v[182:183], v[146:147]
	v_pk_mul_f32 v[146:147], v[146:147], v[146:147]
	s_nop 0
	s_nop 0
	v_cvt_pk_bf16_f32 v144, v152, v152
	v_cvt_pk_bf16_f32 v143, v153, v153
	v_lshrrev_b32_e32 v144, 16, v144
	v_and_or_b32 v143, v143, s28, v144
	v_lshl_add_u64 v[152:153], v[154:155], 1, s[8:9]
	global_store_dword v[152:153], v143, off
	v_mov_b32_e32 v144, v149
	v_mov_b32_e32 v143, v1
	v_pk_fma_f32 v[152:153], v[144:145], v[180:181], v[164:165]
	v_lshl_add_u64 v[154:155], v[142:143], 2, s[2:3]
	global_store_dwordx2 v[154:155], v[152:153], off
	v_pk_mul_f32 v[154:155], v[186:187], v[152:153]
	v_pk_mul_f32 v[152:153], v[152:153], v[152:153]
	s_nop 0
	s_nop 0
	v_cvt_pk_bf16_f32 v148, v154, v154
	v_cvt_pk_bf16_f32 v144, v155, v155
	v_lshrrev_b32_e32 v148, 16, v148
	v_and_or_b32 v144, v144, s28, v148
	v_lshl_add_u64 v[154:155], v[142:143], 1, s[8:9]
	global_store_dword v[154:155], v144, off
	v_add_f32_e32 v143, v152, v153
	v_add_f32_e32 v144, v146, v147
	v_add_f32_e32 v143, v144, v143
	s_nop 1
	v_add_f32_dpp v143, v143, v143 quad_perm:[1,0,3,2] row_mask:0xf bank_mask:0xf bound_ctrl:1
	s_nop 1
	v_add_f32_dpp v143, v143, v143 quad_perm:[2,3,0,1] row_mask:0xf bank_mask:0xf bound_ctrl:1
	s_nop 1
	v_add_f32_dpp v143, v143, v143 row_half_mirror row_mask:0xf bank_mask:0xf bound_ctrl:1
	s_nop 1
	v_mov_b32_dpp v144, v143 row_mirror row_mask:0xf bank_mask:0xf bound_ctrl:1
	s_and_saveexec_b64 s[68:69], s[4:5]
	s_cbranch_execz .LBB0_374
	v_lshlrev_b32_e32 v146, 4, v194
	v_ashrrev_i32_e32 v147, 31, v146
	v_add_f32_e32 v143, v143, v144
	v_lshl_add_u64 v[146:147], v[146:147], 2, v[150:151]
	global_store_dword v[146:147], v143, off offset:192

; __device__ __forceinline__ u16 f2bf(float f) {
;   unsigned u = __float_as_uint(f);
;   u += 0x7fffu + ((u >> 16) & 1u);
;   return (u16)(u >> 16);
; }
; __device__ __forceinline__ float bf2f(u16 h) { return __uint_as_float(((unsigned)h) << 16); }
; __device__ __forceinline__ float bfs2f(short h) { return __uint_as_float(((unsigned)(u16)h) << 16); }
; __device__ __forceinline__ unsigned pack2(float a, float b) { return (unsigned)f2bf(a) | ((unsigned)f2bf(b) << 16); }
; template <int EPI, bool HS = false>
; __device__ __forceinline__ void gemm_phase(const Params& p, const GemmCfg& g, char* shm, const int wave_s) {
;     ...
;         for (int m = 0; m < 4; ++m) {
;           float2 xv[4][2];
; #pragma unroll
;           for (int j = 0; j < 4; ++j)
; #pragma unroll
;             for (int bj = 0; bj < 2; ++bj) xv[j][bj] = *(const float2*)(xl + (m * 16 + j) * XROW + bj * 512);
; #pragma unroll
;           for (int j = 0; j < 4; ++j) {
;             float ss = 0.f;
; #pragma unroll
;             for (int bj = 0; bj < 2; ++bj) {
;               float2 xn;
;               xn.x = xv[j][bj].x + gt[bj][0] * acc[ai][bj][m][0][j];
;               xn.y = xv[j][bj].y + gt[bj][1] * acc[ai][bj][m][1][j];
;               const unsigned o = tb + (unsigned)((ai * 128 + m * 16 + j) * 1024 + bj * 128);
;               *(float2*)(xout_t + o) = xn;
;               if (g.has_next) *(unsigned*)(xg_t + o) = pack2(xn.x * gn[bj][0], xn.y * gn[bj][1]);
;               ss += xn.x * xn.x + xn.y * xn.y;
;             }
;             if (g.has_next) {
;               ss = dpp_row_sum16(ss);
;               if (fr == 0) rss_t[(wr * 64 + fq * 4 + ai * 128 + m * 16 + j) * 16] = ss;
;             }
.LBB0_377:
	v_pk_mul_f32 v[156:157], v[126:127], v[130:131]
	v_pk_mul_f32 v[154:155], v[122:123], v[130:131]
	v_pk_mul_f32 v[122:123], v[140:141], v[132:133]
	v_pk_mul_f32 v[152:153], v[138:139], v[130:131]
	v_pk_mul_f32 v[126:127], v[136:137], v[132:133]
	v_pk_mul_f32 v[130:131], v[134:135], v[130:131]
	v_add_u32_e32 v162, 0x100, v195
	ds_read2st64_b64 v[146:149], v162 offset0:32 offset1:33
	v_add_u32_e32 v163, 0x110, v195
	v_add_u32_e32 v164, 0x120, v195
	v_add_u32_e32 v165, 0x130, v195
	ds_read2st64_b64 v[142:145], v163 offset0:34 offset1:35
	ds_read2st64_b64 v[138:141], v164 offset0:36 offset1:37
	ds_read2st64_b64 v[134:137], v165 offset0:38 offset1:39
	v_or_b32_e32 v160, 0x4000, v0
	v_mov_b32_e32 v158, v156
	v_mov_b32_e32 v159, v154
	v_mov_b32_e32 v161, v1
	s_waitcnt lgkmcnt(3)
	v_pk_fma_f32 v[158:159], v[158:159], v[184:185], v[146:147]
	v_lshl_add_u64 v[146:147], v[160:161], 2, s[2:3]
	global_store_dwordx2 v[146:147], v[158:159], off
	s_mov_b64 s[68:69], -1
	s_and_b64 vcc, exec, s[6:7]
	v_or_b32_e32 v146, 0x4080, v0
	s_cbranch_vccnz .LBB0_381
	v_pk_mul_f32 v[166:167], v[182:183], v[158:159]
	v_lshl_add_u64 v[160:161], v[160:161], 1, s[8:9]
	s_nop 0
	s_nop 0
	v_cvt_pk_bf16_f32 v154, v166, v166
	v_cvt_pk_bf16_f32 v147, v167, v167
	v_lshrrev_b32_e32 v154, 16, v154
	v_and_or_b32 v147, v147, s28, v154
	global_store_dword v[160:161], v147, off
	v_mov_b32_e32 v160, v152
	v_mov_b32_e32 v161, v130
	v_mov_b32_e32 v147, v1
	v_pk_fma_f32 v[160:161], v[160:161], v[180:181], v[148:149]
	v_lshl_add_u64 v[166:167], v[146:147], 2, s[2:3]
	global_store_dwordx2 v[166:167], v[160:161], off
	v_pk_mul_f32 v[166:167], v[186:187], v[160:161]
	v_pk_mul_f32 v[158:159], v[158:159], v[158:159]
	s_nop 0
	s_nop 0
	v_cvt_pk_bf16_f32 v156, v166, v166
	v_cvt_pk_bf16_f32 v154, v167, v167
	v_lshrrev_b32_e32 v156, 16, v156
	v_and_or_b32 v154, v154, s28, v156
	v_lshl_add_u64 v[166:167], v[146:147], 1, s[8:9]
	v_pk_mul_f32 v[160:161], v[160:161], v[160:161]
	global_store_dword v[166:167], v154, off
	v_add_f32_e32 v147, v160, v161
	v_add_f32_e32 v154, v158, v159
	v_add_f32_e32 v147, v154, v147
	s_nop 1
	v_add_f32_dpp v147, v147, v147 quad_perm:[1,0,3,2] row_mask:0xf bank_mask:0xf bound_ctrl:1
	s_nop 1
	v_add_f32_dpp v147, v147, v147 quad_perm:[2,3,0,1] row_mask:0xf bank_mask:0xf bound_ctrl:1
	s_nop 1
	v_add_f32_dpp v147, v147, v147 row_half_mirror row_mask:0xf bank_mask:0xf bound_ctrl:1
	s_nop 1
	v_mov_b32_dpp v154, v147 row_mirror row_mask:0xf bank_mask:0xf bound_ctrl:1
	s_and_saveexec_b64 s[68:69], s[4:5]
	s_cbranch_execz .LBB0_380
	v_lshlrev_b32_e32 v158, 4, v194
	v_ashrrev_i32_e32 v159, 31, v158
	v_add_f32_e32 v147, v147, v154
	v_lshl_add_u64 v[158:159], v[158:159], 2, v[150:151]
	global_store_dword v[158:159], v147, off offset:1024

; __device__ __forceinline__ u16 f2bf(float f) {
;   unsigned u = __float_as_uint(f);
;   u += 0x7fffu + ((u >> 16) & 1u);
;   return (u16)(u >> 16);
; }
; __device__ __forceinline__ float bf2f(u16 h) { return __uint_as_float(((unsigned)h) << 16); }
; __device__ __forceinline__ float bfs2f(short h) { return __uint_as_float(((unsigned)(u16)h) << 16); }
; __device__ __forceinline__ unsigned pack2(float a, float b) { return (unsigned)f2bf(a) | ((unsigned)f2bf(b) << 16); }
; template <int EPI, bool HS = false>
; __device__ __forceinline__ void gemm_phase(const Params& p, const GemmCfg& g, char* shm, const int wave_s) {
;     ...
;             for (int bj = 0; bj < 2; ++bj) {
;               float2 xn;
;               xn.x = xv[j][bj].x + gt[bj][0] * acc[ai][bj][m][0][j];
;               xn.y = xv[j][bj].y + gt[bj][1] * acc[ai][bj][m][1][j];
;               const unsigned o = tb + (unsigned)((ai * 128 + m * 16 + j) * 1024 + bj * 128);
;               *(float2*)(xout_t + o) = xn;
;               if (g.has_next) *(unsigned*)(xg_t + o) = pack2(xn.x * gn[bj][0], xn.y * gn[bj][1]);
;               ss += xn.x * xn.x + xn.y * xn.y;
;             }
;             if (g.has_next) {
;               ss = dpp_row_sum16(ss);
;               if (fr == 0) rss_t[(wr * 64 + fq * 4 + ai * 128 + m * 16 + j) * 16] = ss;
;             }
.LBB0_383:
	v_or_b32_e32 v146, 0x4400, v0
	v_mov_b32_e32 v154, v157
	v_mov_b32_e32 v147, v1
	v_pk_mul_f32 v[128:129], v[128:129], v[132:133]
	v_pk_mul_f32 v[124:125], v[124:125], v[132:133]
	s_waitcnt lgkmcnt(2)
	v_pk_fma_f32 v[142:143], v[154:155], v[184:185], v[142:143]
	v_lshl_add_u64 v[132:133], v[146:147], 2, s[2:3]
	global_store_dwordx2 v[132:133], v[142:143], off
	s_mov_b64 s[68:69], -1
	s_and_b64 vcc, exec, s[6:7]
	v_or_b32_e32 v132, 0x4480, v0
	s_cbranch_vccnz .LBB0_387
	v_pk_mul_f32 v[148:149], v[182:183], v[142:143]
	v_lshl_add_u64 v[146:147], v[146:147], 1, s[8:9]
	s_nop 0
	s_nop 0
	v_cvt_pk_bf16_f32 v133, v148, v148
	v_cvt_pk_bf16_f32 v130, v149, v149
	v_lshrrev_b32_e32 v133, 16, v133
	v_and_or_b32 v130, v130, s28, v133
	global_store_dword v[146:147], v130, off
	v_mov_b32_e32 v130, v153
	v_mov_b32_e32 v133, v1
	v_pk_fma_f32 v[146:147], v[130:131], v[180:181], v[144:145]
	v_lshl_add_u64 v[148:149], v[132:133], 2, s[2:3]
	global_store_dwordx2 v[148:149], v[146:147], off
	v_pk_mul_f32 v[148:149], v[186:187], v[146:147]
	v_pk_mul_f32 v[142:143], v[142:143], v[142:143]
	v_and_b32_sdwa v152, v148, v178 dst_sel:DWORD dst_unused:UNUSED_PAD src0_sel:WORD_1 src1_sel:DWORD
	s_nop 0
	v_add3_u32 v148, v148, v152, s81
	v_cvt_pk_bf16_f32 v130, v149, v149
	v_lshrrev_b32_e32 v148, 16, v148
	v_and_or_b32 v130, v130, s28, v148
	v_lshl_add_u64 v[148:149], v[132:133], 1, s[8:9]
	v_pk_mul_f32 v[146:147], v[146:147], v[146:147]
	global_store_dword v[148:149], v130, off
	v_add_f32_e32 v130, v146, v147
	v_add_f32_e32 v133, v142, v143
	v_add_f32_e32 v130, v133, v130
	s_nop 1
	v_add_f32_dpp v130, v130, v130 quad_perm:[1,0,3,2] row_mask:0xf bank_mask:0xf bound_ctrl:1
	s_nop 1
	v_add_f32_dpp v130, v130, v130 quad_perm:[2,3,0,1] row_mask:0xf bank_mask:0xf bound_ctrl:1
	s_nop 1
	v_add_f32_dpp v130, v130, v130 row_half_mirror row_mask:0xf bank_mask:0xf bound_ctrl:1
	s_nop 1
	v_mov_b32_dpp v133, v130 row_mirror row_mask:0xf bank_mask:0xf bound_ctrl:1
	s_and_saveexec_b64 s[68:69], s[4:5]
	s_cbranch_execz .LBB0_386
	v_lshlrev_b32_e32 v142, 4, v194
	v_ashrrev_i32_e32 v143, 31, v142
	v_add_f32_e32 v130, v130, v133
	v_lshl_add_u64 v[142:143], v[142:143], 2, v[150:151]
	global_store_dword v[142:143], v130, off offset:1088

; __device__ __forceinline__ u16 f2bf(float f) {
;   unsigned u = __float_as_uint(f);
;   u += 0x7fffu + ((u >> 16) & 1u);
;   return (u16)(u >> 16);
; }
; __device__ __forceinline__ float bf2f(u16 h) { return __uint_as_float(((unsigned)h) << 16); }
; __device__ __forceinline__ float bfs2f(short h) { return __uint_as_float(((unsigned)(u16)h) << 16); }
; __device__ __forceinline__ unsigned pack2(float a, float b) { return (unsigned)f2bf(a) | ((unsigned)f2bf(b) << 16); }
; template <int EPI, bool HS = false>
; __device__ __forceinline__ void gemm_phase(const Params& p, const GemmCfg& g, char* shm, const int wave_s) {
;     ...
;             for (int bj = 0; bj < 2; ++bj) {
;               float2 xn;
;               xn.x = xv[j][bj].x + gt[bj][0] * acc[ai][bj][m][0][j];
;               xn.y = xv[j][bj].y + gt[bj][1] * acc[ai][bj][m][1][j];
;               const unsigned o = tb + (unsigned)((ai * 128 + m * 16 + j) * 1024 + bj * 128);
;               *(float2*)(xout_t + o) = xn;
;               if (g.has_next) *(unsigned*)(xg_t + o) = pack2(xn.x * gn[bj][0], xn.y * gn[bj][1]);
;               ss += xn.x * xn.x + xn.y * xn.y;
;             }
;             if (g.has_next) {
;               ss = dpp_row_sum16(ss);
;               if (fr == 0) rss_t[(wr * 64 + fq * 4 + ai * 128 + m * 16 + j) * 16] = ss;
;             }
.LBB0_389:
	v_or_b32_e32 v142, 0x4800, v0
	v_mov_b32_e32 v130, v128
	v_mov_b32_e32 v131, v124
	v_mov_b32_e32 v143, v1
	s_waitcnt lgkmcnt(1)
	v_pk_fma_f32 v[132:133], v[130:131], v[184:185], v[138:139]
	v_lshl_add_u64 v[130:131], v[142:143], 2, s[2:3]
	global_store_dwordx2 v[130:131], v[132:133], off
	s_mov_b64 s[68:69], -1
	s_and_b64 vcc, exec, s[6:7]
	v_or_b32_e32 v130, 0x4880, v0
	s_cbranch_vccnz .LBB0_393
	v_pk_mul_f32 v[138:139], v[182:183], v[132:133]
	v_mov_b32_e32 v131, v1
	s_nop 0
	s_nop 0
	v_cvt_pk_bf16_f32 v128, v138, v138
	v_cvt_pk_bf16_f32 v124, v139, v139
	v_lshrrev_b32_e32 v128, 16, v128
	v_and_or_b32 v124, v124, s28, v128
	v_lshl_add_u64 v[138:139], v[142:143], 1, s[8:9]
	global_store_dword v[138:139], v124, off
	v_mov_b32_e32 v138, v122
	v_mov_b32_e32 v139, v126
	v_pk_fma_f32 v[138:139], v[138:139], v[180:181], v[140:141]
	v_lshl_add_u64 v[142:143], v[130:131], 2, s[2:3]
	global_store_dwordx2 v[142:143], v[138:139], off
	v_pk_mul_f32 v[142:143], v[186:187], v[138:139]
	v_pk_mul_f32 v[132:133], v[132:133], v[132:133]
	s_nop 0
	s_nop 0
	v_cvt_pk_bf16_f32 v128, v142, v142
	v_cvt_pk_bf16_f32 v124, v143, v143
	v_lshrrev_b32_e32 v128, 16, v128
	v_and_or_b32 v124, v124, s28, v128
	v_lshl_add_u64 v[142:143], v[130:131], 1, s[8:9]
	v_pk_mul_f32 v[138:139], v[138:139], v[138:139]
	global_store_dword v[142:143], v124, off
	v_add_f32_e32 v124, v138, v139
	v_add_f32_e32 v128, v132, v133
	v_add_f32_e32 v124, v128, v124
	s_nop 1
	v_add_f32_dpp v124, v124, v124 quad_perm:[1,0,3,2] row_mask:0xf bank_mask:0xf bound_ctrl:1
	s_nop 1
	v_add_f32_dpp v124, v124, v124 quad_perm:[2,3,0,1] row_mask:0xf bank_mask:0xf bound_ctrl:1
	s_nop 1
	v_add_f32_dpp v124, v124, v124 row_half_mirror row_mask:0xf bank_mask:0xf bound_ctrl:1
	s_nop 1
	v_mov_b32_dpp v128, v124 row_mirror row_mask:0xf bank_mask:0xf bound_ctrl:1
	s_and_saveexec_b64 s[68:69], s[4:5]
	s_cbranch_execz .LBB0_392
	v_lshlrev_b32_e32 v132, 4, v194
	v_ashrrev_i32_e32 v133, 31, v132
	v_add_f32_e32 v124, v124, v128
	v_lshl_add_u64 v[132:133], v[132:133], 2, v[150:151]
	global_store_dword v[132:133], v124, off offset:1152

; __device__ __forceinline__ u16 f2bf(float f) {
;   unsigned u = __float_as_uint(f);
;   u += 0x7fffu + ((u >> 16) & 1u);
;   return (u16)(u >> 16);
; }
; __device__ __forceinline__ float bf2f(u16 h) { return __uint_as_float(((unsigned)h) << 16); }
; __device__ __forceinline__ float bfs2f(short h) { return __uint_as_float(((unsigned)(u16)h) << 16); }
; __device__ __forceinline__ unsigned pack2(float a, float b) { return (unsigned)f2bf(a) | ((unsigned)f2bf(b) << 16); }
; template <int EPI, bool HS = false>
; __device__ __forceinline__ void gemm_phase(const Params& p, const GemmCfg& g, char* shm, const int wave_s) {
;     ...
;             for (int bj = 0; bj < 2; ++bj) {
;               float2 xn;
;               xn.x = xv[j][bj].x + gt[bj][0] * acc[ai][bj][m][0][j];
;               xn.y = xv[j][bj].y + gt[bj][1] * acc[ai][bj][m][1][j];
;               const unsigned o = tb + (unsigned)((ai * 128 + m * 16 + j) * 1024 + bj * 128);
;               *(float2*)(xout_t + o) = xn;
;               if (g.has_next) *(unsigned*)(xg_t + o) = pack2(xn.x * gn[bj][0], xn.y * gn[bj][1]);
;               ss += xn.x * xn.x + xn.y * xn.y;
;             }
;             if (g.has_next) {
;               ss = dpp_row_sum16(ss);
;               if (fr == 0) rss_t[(wr * 64 + fq * 4 + ai * 128 + m * 16 + j) * 16] = ss;
;             }
.LBB0_395:
	v_or_b32_e32 v130, 0x4c00, v0
	v_mov_b32_e32 v124, v129
	v_mov_b32_e32 v131, v1
	s_waitcnt lgkmcnt(0)
	v_pk_fma_f32 v[128:129], v[124:125], v[184:185], v[134:135]
	v_lshl_add_u64 v[124:125], v[130:131], 2, s[2:3]
	global_store_dwordx2 v[124:125], v[128:129], off
	s_mov_b64 s[68:69], -1
	s_and_b64 vcc, exec, s[6:7]
	v_or_b32_e32 v124, 0x4c80, v0
	s_cbranch_vccnz .LBB0_399
	v_pk_mul_f32 v[132:133], v[182:183], v[128:129]
	v_lshl_add_u64 v[130:131], v[130:131], 1, s[8:9]
	s_nop 0
	s_nop 0
	v_cvt_pk_bf16_f32 v125, v132, v132
	v_cvt_pk_bf16_f32 v122, v133, v133
	v_lshrrev_b32_e32 v125, 16, v125
	v_and_or_b32 v122, v122, s28, v125
	v_mov_b32_e32 v126, v123
	v_mov_b32_e32 v125, v1
	global_store_dword v[130:131], v122, off
	v_pk_fma_f32 v[130:131], v[126:127], v[180:181], v[136:137]
	v_lshl_add_u64 v[132:133], v[124:125], 2, s[2:3]
	global_store_dwordx2 v[132:133], v[130:131], off
	v_pk_mul_f32 v[132:133], v[186:187], v[130:131]
	v_pk_mul_f32 v[128:129], v[128:129], v[128:129]
	s_nop 0
	s_nop 0
	v_cvt_pk_bf16_f32 v126, v132, v132
	v_cvt_pk_bf16_f32 v122, v133, v133
	v_lshrrev_b32_e32 v126, 16, v126
	v_and_or_b32 v122, v122, s28, v126
	v_lshl_add_u64 v[132:133], v[124:125], 1, s[8:9]
	v_pk_mul_f32 v[130:131], v[130:131], v[130:131]
	global_store_dword v[132:133], v122, off
	v_add_f32_e32 v122, v130, v131
	v_add_f32_e32 v125, v128, v129
	v_add_f32_e32 v122, v125, v122
	s_nop 1
	v_add_f32_dpp v122, v122, v122 quad_perm:[1,0,3,2] row_mask:0xf bank_mask:0xf bound_ctrl:1
	s_nop 1
	v_add_f32_dpp v122, v122, v122 quad_perm:[2,3,0,1] row_mask:0xf bank_mask:0xf bound_ctrl:1
	s_nop 1
	v_add_f32_dpp v122, v122, v122 row_half_mirror row_mask:0xf bank_mask:0xf bound_ctrl:1
	s_nop 1
	v_mov_b32_dpp v125, v122 row_mirror row_mask:0xf bank_mask:0xf bound_ctrl:1
	s_and_saveexec_b64 s[68:69], s[4:5]
	s_cbranch_execz .LBB0_398
	v_lshlrev_b32_e32 v128, 4, v194
	v_ashrrev_i32_e32 v129, 31, v128
	v_add_f32_e32 v122, v122, v125
	v_lshl_add_u64 v[128:129], v[128:129], 2, v[150:151]
	global_store_dword v[128:129], v122, off offset:1216

; __device__ __forceinline__ u16 f2bf(float f) {
;   unsigned u = __float_as_uint(f);
;   u += 0x7fffu + ((u >> 16) & 1u);
;   return (u16)(u >> 16);
; }
; __device__ __forceinline__ float bf2f(u16 h) { return __uint_as_float(((unsigned)h) << 16); }
; __device__ __forceinline__ float bfs2f(short h) { return __uint_as_float(((unsigned)(u16)h) << 16); }
; __device__ __forceinline__ unsigned pack2(float a, float b) { return (unsigned)f2bf(a) | ((unsigned)f2bf(b) << 16); }
; template <int EPI, bool HS = false>
; __device__ __forceinline__ void gemm_phase(const Params& p, const GemmCfg& g, char* shm, const int wave_s) {
;     ...
;         for (int m = 0; m < 4; ++m) {
;           float2 xv[4][2];
; #pragma unroll
;           for (int j = 0; j < 4; ++j)
; #pragma unroll
;             for (int bj = 0; bj < 2; ++bj) xv[j][bj] = *(const float2*)(xl + (m * 16 + j) * XROW + bj * 512);
; #pragma unroll
;           for (int j = 0; j < 4; ++j) {
;             float ss = 0.f;
; #pragma unroll
;             for (int bj = 0; bj < 2; ++bj) {
;               float2 xn;
;               xn.x = xv[j][bj].x + gt[bj][0] * acc[ai][bj][m][0][j];
;               xn.y = xv[j][bj].y + gt[bj][1] * acc[ai][bj][m][1][j];
;               const unsigned o = tb + (unsigned)((ai * 128 + m * 16 + j) * 1024 + bj * 128);
;               *(float2*)(xout_t + o) = xn;
;               if (g.has_next) *(unsigned*)(xg_t + o) = pack2(xn.x * gn[bj][0], xn.y * gn[bj][1]);
;               ss += xn.x * xn.x + xn.y * xn.y;
;             }
;             if (g.has_next) {
;               ss = dpp_row_sum16(ss);
;               if (fr == 0) rss_t[(wr * 64 + fq * 4 + ai * 128 + m * 16 + j) * 16] = ss;
;             }
.LBB0_401:
	v_pk_mul_f32 v[134:135], v[106:107], v[110:111]
	v_pk_mul_f32 v[132:133], v[102:103], v[110:111]
	v_pk_mul_f32 v[102:103], v[120:121], v[112:113]
	v_pk_mul_f32 v[130:131], v[118:119], v[110:111]
	v_pk_mul_f32 v[106:107], v[116:117], v[112:113]
	v_pk_mul_f32 v[110:111], v[114:115], v[110:111]
	ds_read2st64_b64 v[126:129], v195 offset0:65 offset1:66
	v_add_u32_e32 v140, 16, v195
	ds_read2st64_b64 v[122:125], v140 offset0:67 offset1:68
	ds_read2st64_b64 v[118:121], v196 offset0:69 offset1:70
	ds_read2st64_b64 v[114:117], v197 offset0:71 offset1:72
	v_or_b32_e32 v138, 0x8000, v0
	v_mov_b32_e32 v136, v134
	v_mov_b32_e32 v137, v132
	v_mov_b32_e32 v139, v1
	s_waitcnt lgkmcnt(3)
	v_pk_fma_f32 v[136:137], v[136:137], v[184:185], v[126:127]
	v_lshl_add_u64 v[126:127], v[138:139], 2, s[2:3]
	global_store_dwordx2 v[126:127], v[136:137], off
	s_mov_b64 s[68:69], -1
	s_and_b64 vcc, exec, s[6:7]
	v_or_b32_e32 v126, 0x8080, v0
	s_cbranch_vccnz .LBB0_405
	v_pk_mul_f32 v[142:143], v[182:183], v[136:137]
	v_lshl_add_u64 v[138:139], v[138:139], 1, s[8:9]
	s_nop 0
	s_nop 0
	v_cvt_pk_bf16_f32 v132, v142, v142
	v_cvt_pk_bf16_f32 v127, v143, v143
	v_lshrrev_b32_e32 v132, 16, v132
	v_and_or_b32 v127, v127, s28, v132
	global_store_dword v[138:139], v127, off
	v_mov_b32_e32 v138, v130
	v_mov_b32_e32 v139, v110
	v_mov_b32_e32 v127, v1
	v_pk_fma_f32 v[138:139], v[138:139], v[180:181], v[128:129]
	v_lshl_add_u64 v[142:143], v[126:127], 2, s[2:3]
	global_store_dwordx2 v[142:143], v[138:139], off
	v_pk_mul_f32 v[142:143], v[186:187], v[138:139]
	v_pk_mul_f32 v[136:137], v[136:137], v[136:137]
	s_nop 0
	s_nop 0
	v_cvt_pk_bf16_f32 v134, v142, v142
	v_cvt_pk_bf16_f32 v132, v143, v143
	v_lshrrev_b32_e32 v134, 16, v134
	v_and_or_b32 v132, v132, s28, v134
	v_lshl_add_u64 v[142:143], v[126:127], 1, s[8:9]
	v_pk_mul_f32 v[138:139], v[138:139], v[138:139]
	global_store_dword v[142:143], v132, off
	v_add_f32_e32 v127, v138, v139
	v_add_f32_e32 v132, v136, v137
	v_add_f32_e32 v127, v132, v127
	s_nop 1
	v_add_f32_dpp v127, v127, v127 quad_perm:[1,0,3,2] row_mask:0xf bank_mask:0xf bound_ctrl:1
	s_nop 1
	v_add_f32_dpp v127, v127, v127 quad_perm:[2,3,0,1] row_mask:0xf bank_mask:0xf bound_ctrl:1
	s_nop 1
	v_add_f32_dpp v127, v127, v127 row_half_mirror row_mask:0xf bank_mask:0xf bound_ctrl:1
	s_nop 1
	v_mov_b32_dpp v132, v127 row_mirror row_mask:0xf bank_mask:0xf bound_ctrl:1
	s_and_saveexec_b64 s[68:69], s[4:5]
	s_cbranch_execz .LBB0_404
	v_lshlrev_b32_e32 v136, 4, v194
	v_ashrrev_i32_e32 v137, 31, v136
	v_add_f32_e32 v127, v127, v132
	v_lshl_add_u64 v[136:137], v[136:137], 2, v[150:151]
	global_store_dword v[136:137], v127, off offset:2048

; __device__ __forceinline__ u16 f2bf(float f) {
;   unsigned u = __float_as_uint(f);
;   u += 0x7fffu + ((u >> 16) & 1u);
;   return (u16)(u >> 16);
; }
; __device__ __forceinline__ float bf2f(u16 h) { return __uint_as_float(((unsigned)h) << 16); }
; __device__ __forceinline__ float bfs2f(short h) { return __uint_as_float(((unsigned)(u16)h) << 16); }
; __device__ __forceinline__ unsigned pack2(float a, float b) { return (unsigned)f2bf(a) | ((unsigned)f2bf(b) << 16); }
; template <int EPI, bool HS = false>
; __device__ __forceinline__ void gemm_phase(const Params& p, const GemmCfg& g, char* shm, const int wave_s) {
;     ...
;             for (int bj = 0; bj < 2; ++bj) {
;               float2 xn;
;               xn.x = xv[j][bj].x + gt[bj][0] * acc[ai][bj][m][0][j];
;               xn.y = xv[j][bj].y + gt[bj][1] * acc[ai][bj][m][1][j];
;               const unsigned o = tb + (unsigned)((ai * 128 + m * 16 + j) * 1024 + bj * 128);
;               *(float2*)(xout_t + o) = xn;
;               if (g.has_next) *(unsigned*)(xg_t + o) = pack2(xn.x * gn[bj][0], xn.y * gn[bj][1]);
;               ss += xn.x * xn.x + xn.y * xn.y;
;             }
;             if (g.has_next) {
;               ss = dpp_row_sum16(ss);
;               if (fr == 0) rss_t[(wr * 64 + fq * 4 + ai * 128 + m * 16 + j) * 16] = ss;
;             }
.LBB0_407:
	v_or_b32_e32 v126, 0x8400, v0
	v_mov_b32_e32 v132, v135
	v_mov_b32_e32 v127, v1
	v_pk_mul_f32 v[108:109], v[108:109], v[112:113]
	v_pk_mul_f32 v[104:105], v[104:105], v[112:113]
	s_waitcnt lgkmcnt(2)
	v_pk_fma_f32 v[122:123], v[132:133], v[184:185], v[122:123]
	v_lshl_add_u64 v[112:113], v[126:127], 2, s[2:3]
	global_store_dwordx2 v[112:113], v[122:123], off
	s_mov_b64 s[68:69], -1
	s_and_b64 vcc, exec, s[6:7]
	v_or_b32_e32 v112, 0x8480, v0
	s_cbranch_vccnz .LBB0_411
	v_pk_mul_f32 v[128:129], v[182:183], v[122:123]
	v_lshl_add_u64 v[126:127], v[126:127], 1, s[8:9]
	s_nop 0
	s_nop 0
	v_cvt_pk_bf16_f32 v113, v128, v128
	v_cvt_pk_bf16_f32 v110, v129, v129
	v_lshrrev_b32_e32 v113, 16, v113
	v_and_or_b32 v110, v110, s28, v113
	global_store_dword v[126:127], v110, off
	v_mov_b32_e32 v110, v131
	v_mov_b32_e32 v113, v1
	v_pk_fma_f32 v[126:127], v[110:111], v[180:181], v[124:125]
	v_lshl_add_u64 v[128:129], v[112:113], 2, s[2:3]
	global_store_dwordx2 v[128:129], v[126:127], off
	v_pk_mul_f32 v[128:129], v[186:187], v[126:127]
	v_pk_mul_f32 v[122:123], v[122:123], v[122:123]
	v_and_b32_sdwa v130, v128, v178 dst_sel:DWORD dst_unused:UNUSED_PAD src0_sel:WORD_1 src1_sel:DWORD
	s_nop 0
	v_add3_u32 v128, v128, v130, s81
	v_cvt_pk_bf16_f32 v110, v129, v129
	v_lshrrev_b32_e32 v128, 16, v128
	v_and_or_b32 v110, v110, s28, v128
	v_lshl_add_u64 v[128:129], v[112:113], 1, s[8:9]
	v_pk_mul_f32 v[126:127], v[126:127], v[126:127]
	global_store_dword v[128:129], v110, off
	v_add_f32_e32 v110, v126, v127
	v_add_f32_e32 v113, v122, v123
	v_add_f32_e32 v110, v113, v110
	s_nop 1
	v_add_f32_dpp v110, v110, v110 quad_perm:[1,0,3,2] row_mask:0xf bank_mask:0xf bound_ctrl:1
	s_nop 1
	v_add_f32_dpp v110, v110, v110 quad_perm:[2,3,0,1] row_mask:0xf bank_mask:0xf bound_ctrl:1
	s_nop 1
	v_add_f32_dpp v110, v110, v110 row_half_mirror row_mask:0xf bank_mask:0xf bound_ctrl:1
	s_nop 1
	v_mov_b32_dpp v113, v110 row_mirror row_mask:0xf bank_mask:0xf bound_ctrl:1
	s_and_saveexec_b64 s[68:69], s[4:5]
	s_cbranch_execz .LBB0_410
	v_lshlrev_b32_e32 v122, 4, v194
	v_ashrrev_i32_e32 v123, 31, v122
	v_add_f32_e32 v110, v110, v113
	v_lshl_add_u64 v[122:123], v[122:123], 2, v[150:151]
	global_store_dword v[122:123], v110, off offset:2112

; __device__ __forceinline__ u16 f2bf(float f) {
;   unsigned u = __float_as_uint(f);
;   u += 0x7fffu + ((u >> 16) & 1u);
;   return (u16)(u >> 16);
; }
; __device__ __forceinline__ float bf2f(u16 h) { return __uint_as_float(((unsigned)h) << 16); }
; __device__ __forceinline__ float bfs2f(short h) { return __uint_as_float(((unsigned)(u16)h) << 16); }
; __device__ __forceinline__ unsigned pack2(float a, float b) { return (unsigned)f2bf(a) | ((unsigned)f2bf(b) << 16); }
; template <int EPI, bool HS = false>
; __device__ __forceinline__ void gemm_phase(const Params& p, const GemmCfg& g, char* shm, const int wave_s) {
;     ...
;             for (int bj = 0; bj < 2; ++bj) {
;               float2 xn;
;               xn.x = xv[j][bj].x + gt[bj][0] * acc[ai][bj][m][0][j];
;               xn.y = xv[j][bj].y + gt[bj][1] * acc[ai][bj][m][1][j];
;               const unsigned o = tb + (unsigned)((ai * 128 + m * 16 + j) * 1024 + bj * 128);
;               *(float2*)(xout_t + o) = xn;
;               if (g.has_next) *(unsigned*)(xg_t + o) = pack2(xn.x * gn[bj][0], xn.y * gn[bj][1]);
;               ss += xn.x * xn.x + xn.y * xn.y;
;             }
;             if (g.has_next) {
;               ss = dpp_row_sum16(ss);
;               if (fr == 0) rss_t[(wr * 64 + fq * 4 + ai * 128 + m * 16 + j) * 16] = ss;
;             }
.LBB0_413:
	v_or_b32_e32 v122, 0x8800, v0
	v_mov_b32_e32 v110, v108
	v_mov_b32_e32 v111, v104
	v_mov_b32_e32 v123, v1
	s_waitcnt lgkmcnt(1)
	v_pk_fma_f32 v[112:113], v[110:111], v[184:185], v[118:119]
	v_lshl_add_u64 v[110:111], v[122:123], 2, s[2:3]
	global_store_dwordx2 v[110:111], v[112:113], off
	s_mov_b64 s[68:69], -1
	s_and_b64 vcc, exec, s[6:7]
	v_or_b32_e32 v110, 0x8880, v0
	s_cbranch_vccnz .LBB0_417
	v_pk_mul_f32 v[118:119], v[182:183], v[112:113]
	v_mov_b32_e32 v111, v1
	s_nop 0
	s_nop 0
	v_cvt_pk_bf16_f32 v108, v118, v118
	v_cvt_pk_bf16_f32 v104, v119, v119
	v_lshrrev_b32_e32 v108, 16, v108
	v_and_or_b32 v104, v104, s28, v108
	v_lshl_add_u64 v[118:119], v[122:123], 1, s[8:9]
	global_store_dword v[118:119], v104, off
	v_mov_b32_e32 v118, v102
	v_mov_b32_e32 v119, v106
	v_pk_fma_f32 v[118:119], v[118:119], v[180:181], v[120:121]
	v_lshl_add_u64 v[122:123], v[110:111], 2, s[2:3]
	global_store_dwordx2 v[122:123], v[118:119], off
	v_pk_mul_f32 v[122:123], v[186:187], v[118:119]
	v_pk_mul_f32 v[112:113], v[112:113], v[112:113]
	s_nop 0
	s_nop 0
	v_cvt_pk_bf16_f32 v108, v122, v122
	v_cvt_pk_bf16_f32 v104, v123, v123
	v_lshrrev_b32_e32 v108, 16, v108
	v_and_or_b32 v104, v104, s28, v108
	v_lshl_add_u64 v[122:123], v[110:111], 1, s[8:9]
	v_pk_mul_f32 v[118:119], v[118:119], v[118:119]
	global_store_dword v[122:123], v104, off
	v_add_f32_e32 v104, v118, v119
	v_add_f32_e32 v108, v112, v113
	v_add_f32_e32 v104, v108, v104
	s_nop 1
	v_add_f32_dpp v104, v104, v104 quad_perm:[1,0,3,2] row_mask:0xf bank_mask:0xf bound_ctrl:1
	s_nop 1
	v_add_f32_dpp v104, v104, v104 quad_perm:[2,3,0,1] row_mask:0xf bank_mask:0xf bound_ctrl:1
	s_nop 1
	v_add_f32_dpp v104, v104, v104 row_half_mirror row_mask:0xf bank_mask:0xf bound_ctrl:1
	s_nop 1
	v_mov_b32_dpp v108, v104 row_mirror row_mask:0xf bank_mask:0xf bound_ctrl:1
	s_and_saveexec_b64 s[68:69], s[4:5]
	s_cbranch_execz .LBB0_416
	v_lshlrev_b32_e32 v112, 4, v194
	v_ashrrev_i32_e32 v113, 31, v112
	v_add_f32_e32 v104, v104, v108
	v_lshl_add_u64 v[112:113], v[112:113], 2, v[150:151]
	global_store_dword v[112:113], v104, off offset:2176

; __device__ __forceinline__ u16 f2bf(float f) {
;   unsigned u = __float_as_uint(f);
;   u += 0x7fffu + ((u >> 16) & 1u);
;   return (u16)(u >> 16);
; }
; __device__ __forceinline__ float bf2f(u16 h) { return __uint_as_float(((unsigned)h) << 16); }
; __device__ __forceinline__ float bfs2f(short h) { return __uint_as_float(((unsigned)(u16)h) << 16); }
; __device__ __forceinline__ unsigned pack2(float a, float b) { return (unsigned)f2bf(a) | ((unsigned)f2bf(b) << 16); }
; template <int EPI, bool HS = false>
; __device__ __forceinline__ void gemm_phase(const Params& p, const GemmCfg& g, char* shm, const int wave_s) {
;     ...
;             for (int bj = 0; bj < 2; ++bj) {
;               float2 xn;
;               xn.x = xv[j][bj].x + gt[bj][0] * acc[ai][bj][m][0][j];
;               xn.y = xv[j][bj].y + gt[bj][1] * acc[ai][bj][m][1][j];
;               const unsigned o = tb + (unsigned)((ai * 128 + m * 16 + j) * 1024 + bj * 128);
;               *(float2*)(xout_t + o) = xn;
;               if (g.has_next) *(unsigned*)(xg_t + o) = pack2(xn.x * gn[bj][0], xn.y * gn[bj][1]);
;               ss += xn.x * xn.x + xn.y * xn.y;
;             }
;             if (g.has_next) {
;               ss = dpp_row_sum16(ss);
;               if (fr == 0) rss_t[(wr * 64 + fq * 4 + ai * 128 + m * 16 + j) * 16] = ss;
;             }
.LBB0_419:
	v_or_b32_e32 v110, 0x8c00, v0
	v_mov_b32_e32 v104, v109
	v_mov_b32_e32 v111, v1
	s_waitcnt lgkmcnt(0)
	v_pk_fma_f32 v[108:109], v[104:105], v[184:185], v[114:115]
	v_lshl_add_u64 v[104:105], v[110:111], 2, s[2:3]
	global_store_dwordx2 v[104:105], v[108:109], off
	s_mov_b64 s[68:69], -1
	s_and_b64 vcc, exec, s[6:7]
	v_or_b32_e32 v104, 0x8c80, v0
	s_cbranch_vccnz .LBB0_423
	v_pk_mul_f32 v[112:113], v[182:183], v[108:109]
	v_lshl_add_u64 v[110:111], v[110:111], 1, s[8:9]
	s_nop 0
	s_nop 0
	v_cvt_pk_bf16_f32 v105, v112, v112
	v_cvt_pk_bf16_f32 v102, v113, v113
	v_lshrrev_b32_e32 v105, 16, v105
	v_and_or_b32 v102, v102, s28, v105
	v_mov_b32_e32 v106, v103
	v_mov_b32_e32 v105, v1
	global_store_dword v[110:111], v102, off
	v_pk_fma_f32 v[110:111], v[106:107], v[180:181], v[116:117]
	v_lshl_add_u64 v[112:113], v[104:105], 2, s[2:3]
	global_store_dwordx2 v[112:113], v[110:111], off
	v_pk_mul_f32 v[112:113], v[186:187], v[110:111]
	v_pk_mul_f32 v[108:109], v[108:109], v[108:109]
	s_nop 0
	s_nop 0
	v_cvt_pk_bf16_f32 v106, v112, v112
	v_cvt_pk_bf16_f32 v102, v113, v113
	v_lshrrev_b32_e32 v106, 16, v106
	v_and_or_b32 v102, v102, s28, v106
	v_lshl_add_u64 v[112:113], v[104:105], 1, s[8:9]
	v_pk_mul_f32 v[110:111], v[110:111], v[110:111]
	global_store_dword v[112:113], v102, off
	v_add_f32_e32 v102, v110, v111
	v_add_f32_e32 v105, v108, v109
	v_add_f32_e32 v102, v105, v102
	s_nop 1
	v_add_f32_dpp v102, v102, v102 quad_perm:[1,0,3,2] row_mask:0xf bank_mask:0xf bound_ctrl:1
	s_nop 1
	v_add_f32_dpp v102, v102, v102 quad_perm:[2,3,0,1] row_mask:0xf bank_mask:0xf bound_ctrl:1
	s_nop 1
	v_add_f32_dpp v102, v102, v102 row_half_mirror row_mask:0xf bank_mask:0xf bound_ctrl:1
	s_nop 1
	v_mov_b32_dpp v105, v102 row_mirror row_mask:0xf bank_mask:0xf bound_ctrl:1
	s_and_saveexec_b64 s[68:69], s[4:5]
	s_cbranch_execz .LBB0_422
	v_lshlrev_b32_e32 v108, 4, v194
	v_ashrrev_i32_e32 v109, 31, v108
	v_add_f32_e32 v102, v102, v105
	v_lshl_add_u64 v[108:109], v[108:109], 2, v[150:151]
	global_store_dword v[108:109], v102, off offset:2240

; __device__ __forceinline__ u16 f2bf(float f) {
;   unsigned u = __float_as_uint(f);
;   u += 0x7fffu + ((u >> 16) & 1u);
;   return (u16)(u >> 16);
; }
; __device__ __forceinline__ float bf2f(u16 h) { return __uint_as_float(((unsigned)h) << 16); }
; __device__ __forceinline__ float bfs2f(short h) { return __uint_as_float(((unsigned)(u16)h) << 16); }
; __device__ __forceinline__ unsigned pack2(float a, float b) { return (unsigned)f2bf(a) | ((unsigned)f2bf(b) << 16); }
; template <int EPI, bool HS = false>
; __device__ __forceinline__ void gemm_phase(const Params& p, const GemmCfg& g, char* shm, const int wave_s) {
;     ...
;         for (int m = 0; m < 4; ++m) {
;           float2 xv[4][2];
; #pragma unroll
;           for (int j = 0; j < 4; ++j)
; #pragma unroll
;             for (int bj = 0; bj < 2; ++bj) xv[j][bj] = *(const float2*)(xl + (m * 16 + j) * XROW + bj * 512);
; #pragma unroll
;           for (int j = 0; j < 4; ++j) {
;             float ss = 0.f;
; #pragma unroll
;             for (int bj = 0; bj < 2; ++bj) {
;               float2 xn;
;               xn.x = xv[j][bj].x + gt[bj][0] * acc[ai][bj][m][0][j];
;               xn.y = xv[j][bj].y + gt[bj][1] * acc[ai][bj][m][1][j];
;               const unsigned o = tb + (unsigned)((ai * 128 + m * 16 + j) * 1024 + bj * 128);
;               *(float2*)(xout_t + o) = xn;
;               if (g.has_next) *(unsigned*)(xg_t + o) = pack2(xn.x * gn[bj][0], xn.y * gn[bj][1]);
;               ss += xn.x * xn.x + xn.y * xn.y;
;             }
;             if (g.has_next) {
;               ss = dpp_row_sum16(ss);
;               if (fr == 0) rss_t[(wr * 64 + fq * 4 + ai * 128 + m * 16 + j) * 16] = ss;
;             }
.LBB0_425:
	v_pk_mul_f32 v[114:115], v[86:87], v[90:91]
	v_pk_mul_f32 v[112:113], v[82:83], v[90:91]
	v_pk_mul_f32 v[82:83], v[100:101], v[92:93]
	v_pk_mul_f32 v[110:111], v[98:99], v[90:91]
	v_pk_mul_f32 v[86:87], v[96:97], v[92:93]
	v_pk_mul_f32 v[90:91], v[94:95], v[90:91]
	ds_read2st64_b64 v[106:109], v162 offset0:97 offset1:98
	ds_read2st64_b64 v[102:105], v163 offset0:99 offset1:100
	ds_read2st64_b64 v[98:101], v164 offset0:101 offset1:102
	ds_read2st64_b64 v[94:97], v165 offset0:103 offset1:104
	v_or_b32_e32 v118, 0xc000, v0
	v_mov_b32_e32 v116, v114
	v_mov_b32_e32 v117, v112
	v_mov_b32_e32 v119, v1
	s_waitcnt lgkmcnt(3)
	v_pk_fma_f32 v[116:117], v[116:117], v[184:185], v[106:107]
	v_lshl_add_u64 v[106:107], v[118:119], 2, s[2:3]
	global_store_dwordx2 v[106:107], v[116:117], off
	s_mov_b64 s[68:69], -1
	s_and_b64 vcc, exec, s[6:7]
	v_or_b32_e32 v106, 0xc080, v0
	s_cbranch_vccnz .LBB0_429
	v_pk_mul_f32 v[120:121], v[182:183], v[116:117]
	v_lshl_add_u64 v[118:119], v[118:119], 1, s[8:9]
	s_nop 0
	s_nop 0
	v_cvt_pk_bf16_f32 v112, v120, v120
	v_cvt_pk_bf16_f32 v107, v121, v121
	v_lshrrev_b32_e32 v112, 16, v112
	v_and_or_b32 v107, v107, s28, v112
	global_store_dword v[118:119], v107, off
	v_mov_b32_e32 v118, v110
	v_mov_b32_e32 v119, v90
	v_mov_b32_e32 v107, v1
	v_pk_fma_f32 v[118:119], v[118:119], v[180:181], v[108:109]
	v_lshl_add_u64 v[120:121], v[106:107], 2, s[2:3]
	global_store_dwordx2 v[120:121], v[118:119], off
	v_pk_mul_f32 v[120:121], v[186:187], v[118:119]
	v_pk_mul_f32 v[116:117], v[116:117], v[116:117]
	s_nop 0
	s_nop 0
	v_cvt_pk_bf16_f32 v114, v120, v120
	v_cvt_pk_bf16_f32 v112, v121, v121
	v_lshrrev_b32_e32 v114, 16, v114
	v_and_or_b32 v112, v112, s28, v114
	v_lshl_add_u64 v[120:121], v[106:107], 1, s[8:9]
	v_pk_mul_f32 v[118:119], v[118:119], v[118:119]
	global_store_dword v[120:121], v112, off
	v_add_f32_e32 v107, v118, v119
	v_add_f32_e32 v112, v116, v117
	v_add_f32_e32 v107, v112, v107
	s_nop 1
	v_add_f32_dpp v107, v107, v107 quad_perm:[1,0,3,2] row_mask:0xf bank_mask:0xf bound_ctrl:1
	s_nop 1
	v_add_f32_dpp v107, v107, v107 quad_perm:[2,3,0,1] row_mask:0xf bank_mask:0xf bound_ctrl:1
	s_nop 1
	v_add_f32_dpp v107, v107, v107 row_half_mirror row_mask:0xf bank_mask:0xf bound_ctrl:1
	s_nop 1
	v_mov_b32_dpp v112, v107 row_mirror row_mask:0xf bank_mask:0xf bound_ctrl:1
	s_and_saveexec_b64 s[68:69], s[4:5]
	s_cbranch_execz .LBB0_428
	v_lshlrev_b32_e32 v116, 4, v194
	v_ashrrev_i32_e32 v117, 31, v116
	v_add_f32_e32 v107, v107, v112
	v_lshl_add_u64 v[116:117], v[116:117], 2, v[150:151]
	global_store_dword v[116:117], v107, off offset:3072

; __device__ __forceinline__ u16 f2bf(float f) {
;   unsigned u = __float_as_uint(f);
;   u += 0x7fffu + ((u >> 16) & 1u);
;   return (u16)(u >> 16);
; }
; __device__ __forceinline__ float bf2f(u16 h) { return __uint_as_float(((unsigned)h) << 16); }
; __device__ __forceinline__ float bfs2f(short h) { return __uint_as_float(((unsigned)(u16)h) << 16); }
; __device__ __forceinline__ unsigned pack2(float a, float b) { return (unsigned)f2bf(a) | ((unsigned)f2bf(b) << 16); }
; template <int EPI, bool HS = false>
; __device__ __forceinline__ void gemm_phase(const Params& p, const GemmCfg& g, char* shm, const int wave_s) {
;     ...
;             for (int bj = 0; bj < 2; ++bj) {
;               float2 xn;
;               xn.x = xv[j][bj].x + gt[bj][0] * acc[ai][bj][m][0][j];
;               xn.y = xv[j][bj].y + gt[bj][1] * acc[ai][bj][m][1][j];
;               const unsigned o = tb + (unsigned)((ai * 128 + m * 16 + j) * 1024 + bj * 128);
;               *(float2*)(xout_t + o) = xn;
;               if (g.has_next) *(unsigned*)(xg_t + o) = pack2(xn.x * gn[bj][0], xn.y * gn[bj][1]);
;               ss += xn.x * xn.x + xn.y * xn.y;
;             }
;             if (g.has_next) {
;               ss = dpp_row_sum16(ss);
;               if (fr == 0) rss_t[(wr * 64 + fq * 4 + ai * 128 + m * 16 + j) * 16] = ss;
;             }
.LBB0_431:
	v_or_b32_e32 v106, 0xc400, v0
	v_mov_b32_e32 v112, v115
	v_mov_b32_e32 v107, v1
	v_pk_mul_f32 v[88:89], v[88:89], v[92:93]
	v_pk_mul_f32 v[84:85], v[84:85], v[92:93]
	s_waitcnt lgkmcnt(2)
	v_pk_fma_f32 v[102:103], v[112:113], v[184:185], v[102:103]
	v_lshl_add_u64 v[92:93], v[106:107], 2, s[2:3]
	global_store_dwordx2 v[92:93], v[102:103], off
	s_mov_b64 s[68:69], -1
	s_and_b64 vcc, exec, s[6:7]
	v_or_b32_e32 v92, 0xc480, v0
	s_cbranch_vccnz .LBB0_435
	v_pk_mul_f32 v[108:109], v[182:183], v[102:103]
	v_lshl_add_u64 v[106:107], v[106:107], 1, s[8:9]
	s_nop 0
	s_nop 0
	v_cvt_pk_bf16_f32 v93, v108, v108
	v_cvt_pk_bf16_f32 v90, v109, v109
	v_lshrrev_b32_e32 v93, 16, v93
	v_and_or_b32 v90, v90, s28, v93
	global_store_dword v[106:107], v90, off
	v_mov_b32_e32 v90, v111
	v_mov_b32_e32 v93, v1
	v_pk_fma_f32 v[106:107], v[90:91], v[180:181], v[104:105]
	v_lshl_add_u64 v[108:109], v[92:93], 2, s[2:3]
	global_store_dwordx2 v[108:109], v[106:107], off
	v_pk_mul_f32 v[108:109], v[186:187], v[106:107]
	v_pk_mul_f32 v[102:103], v[102:103], v[102:103]
	v_and_b32_sdwa v110, v108, v178 dst_sel:DWORD dst_unused:UNUSED_PAD src0_sel:WORD_1 src1_sel:DWORD
	s_nop 0
	v_add3_u32 v108, v108, v110, s81
	v_cvt_pk_bf16_f32 v90, v109, v109
	v_lshrrev_b32_e32 v108, 16, v108
	v_and_or_b32 v90, v90, s28, v108
	v_lshl_add_u64 v[108:109], v[92:93], 1, s[8:9]
	v_pk_mul_f32 v[106:107], v[106:107], v[106:107]
	global_store_dword v[108:109], v90, off
	v_add_f32_e32 v90, v106, v107
	v_add_f32_e32 v93, v102, v103
	v_add_f32_e32 v90, v93, v90
	s_nop 1
	v_add_f32_dpp v90, v90, v90 quad_perm:[1,0,3,2] row_mask:0xf bank_mask:0xf bound_ctrl:1
	s_nop 1
	v_add_f32_dpp v90, v90, v90 quad_perm:[2,3,0,1] row_mask:0xf bank_mask:0xf bound_ctrl:1
	s_nop 1
	v_add_f32_dpp v90, v90, v90 row_half_mirror row_mask:0xf bank_mask:0xf bound_ctrl:1
	s_nop 1
	v_mov_b32_dpp v93, v90 row_mirror row_mask:0xf bank_mask:0xf bound_ctrl:1
	s_and_saveexec_b64 s[68:69], s[4:5]
	s_cbranch_execz .LBB0_434
	v_lshlrev_b32_e32 v102, 4, v194
	v_ashrrev_i32_e32 v103, 31, v102
	v_add_f32_e32 v90, v90, v93
	v_lshl_add_u64 v[102:103], v[102:103], 2, v[150:151]
	global_store_dword v[102:103], v90, off offset:3136

; __device__ __forceinline__ u16 f2bf(float f) {
;   unsigned u = __float_as_uint(f);
;   u += 0x7fffu + ((u >> 16) & 1u);
;   return (u16)(u >> 16);
; }
; __device__ __forceinline__ float bf2f(u16 h) { return __uint_as_float(((unsigned)h) << 16); }
; __device__ __forceinline__ float bfs2f(short h) { return __uint_as_float(((unsigned)(u16)h) << 16); }
; __device__ __forceinline__ unsigned pack2(float a, float b) { return (unsigned)f2bf(a) | ((unsigned)f2bf(b) << 16); }
; template <int EPI, bool HS = false>
; __device__ __forceinline__ void gemm_phase(const Params& p, const GemmCfg& g, char* shm, const int wave_s) {
;     ...
;             for (int bj = 0; bj < 2; ++bj) {
;               float2 xn;
;               xn.x = xv[j][bj].x + gt[bj][0] * acc[ai][bj][m][0][j];
;               xn.y = xv[j][bj].y + gt[bj][1] * acc[ai][bj][m][1][j];
;               const unsigned o = tb + (unsigned)((ai * 128 + m * 16 + j) * 1024 + bj * 128);
;               *(float2*)(xout_t + o) = xn;
;               if (g.has_next) *(unsigned*)(xg_t + o) = pack2(xn.x * gn[bj][0], xn.y * gn[bj][1]);
;               ss += xn.x * xn.x + xn.y * xn.y;
;             }
;             if (g.has_next) {
;               ss = dpp_row_sum16(ss);
;               if (fr == 0) rss_t[(wr * 64 + fq * 4 + ai * 128 + m * 16 + j) * 16] = ss;
;             }
.LBB0_437:
	v_or_b32_e32 v102, 0xc800, v0
	v_mov_b32_e32 v90, v88
	v_mov_b32_e32 v91, v84
	v_mov_b32_e32 v103, v1
	s_waitcnt lgkmcnt(1)
	v_pk_fma_f32 v[92:93], v[90:91], v[184:185], v[98:99]
	v_lshl_add_u64 v[90:91], v[102:103], 2, s[2:3]
	global_store_dwordx2 v[90:91], v[92:93], off
	s_mov_b64 s[68:69], -1
	s_and_b64 vcc, exec, s[6:7]
	v_or_b32_e32 v90, 0xc880, v0
	s_cbranch_vccnz .LBB0_441
	v_pk_mul_f32 v[98:99], v[182:183], v[92:93]
	v_mov_b32_e32 v91, v1
	s_nop 0
	s_nop 0
	v_cvt_pk_bf16_f32 v88, v98, v98
	v_cvt_pk_bf16_f32 v84, v99, v99
	v_lshrrev_b32_e32 v88, 16, v88
	v_and_or_b32 v84, v84, s28, v88
	v_lshl_add_u64 v[98:99], v[102:103], 1, s[8:9]
	global_store_dword v[98:99], v84, off
	v_mov_b32_e32 v98, v82
	v_mov_b32_e32 v99, v86
	v_pk_fma_f32 v[98:99], v[98:99], v[180:181], v[100:101]
	v_lshl_add_u64 v[102:103], v[90:91], 2, s[2:3]
	global_store_dwordx2 v[102:103], v[98:99], off
	v_pk_mul_f32 v[102:103], v[186:187], v[98:99]
	v_pk_mul_f32 v[92:93], v[92:93], v[92:93]
	s_nop 0
	s_nop 0
	v_cvt_pk_bf16_f32 v88, v102, v102
	v_cvt_pk_bf16_f32 v84, v103, v103
	v_lshrrev_b32_e32 v88, 16, v88
	v_and_or_b32 v84, v84, s28, v88
	v_lshl_add_u64 v[102:103], v[90:91], 1, s[8:9]
	v_pk_mul_f32 v[98:99], v[98:99], v[98:99]
	global_store_dword v[102:103], v84, off
	v_add_f32_e32 v84, v98, v99
	v_add_f32_e32 v88, v92, v93
	v_add_f32_e32 v84, v88, v84
	s_nop 1
	v_add_f32_dpp v84, v84, v84 quad_perm:[1,0,3,2] row_mask:0xf bank_mask:0xf bound_ctrl:1
	s_nop 1
	v_add_f32_dpp v84, v84, v84 quad_perm:[2,3,0,1] row_mask:0xf bank_mask:0xf bound_ctrl:1
	s_nop 1
	v_add_f32_dpp v84, v84, v84 row_half_mirror row_mask:0xf bank_mask:0xf bound_ctrl:1
	s_nop 1
	v_mov_b32_dpp v88, v84 row_mirror row_mask:0xf bank_mask:0xf bound_ctrl:1
	s_and_saveexec_b64 s[68:69], s[4:5]
	s_cbranch_execz .LBB0_440
	v_lshlrev_b32_e32 v92, 4, v194
	v_ashrrev_i32_e32 v93, 31, v92
	v_add_f32_e32 v84, v84, v88
	v_lshl_add_u64 v[92:93], v[92:93], 2, v[150:151]
	global_store_dword v[92:93], v84, off offset:3200

; __device__ __forceinline__ u16 f2bf(float f) {
;   unsigned u = __float_as_uint(f);
;   u += 0x7fffu + ((u >> 16) & 1u);
;   return (u16)(u >> 16);
; }
; __device__ __forceinline__ float bf2f(u16 h) { return __uint_as_float(((unsigned)h) << 16); }
; __device__ __forceinline__ float bfs2f(short h) { return __uint_as_float(((unsigned)(u16)h) << 16); }
; __device__ __forceinline__ unsigned pack2(float a, float b) { return (unsigned)f2bf(a) | ((unsigned)f2bf(b) << 16); }
; template <int EPI, bool HS = false>
; __device__ __forceinline__ void gemm_phase(const Params& p, const GemmCfg& g, char* shm, const int wave_s) {
;     ...
;             for (int bj = 0; bj < 2; ++bj) {
;               float2 xn;
;               xn.x = xv[j][bj].x + gt[bj][0] * acc[ai][bj][m][0][j];
;               xn.y = xv[j][bj].y + gt[bj][1] * acc[ai][bj][m][1][j];
;               const unsigned o = tb + (unsigned)((ai * 128 + m * 16 + j) * 1024 + bj * 128);
;               *(float2*)(xout_t + o) = xn;
;               if (g.has_next) *(unsigned*)(xg_t + o) = pack2(xn.x * gn[bj][0], xn.y * gn[bj][1]);
;               ss += xn.x * xn.x + xn.y * xn.y;
;             }
;             if (g.has_next) {
;               ss = dpp_row_sum16(ss);
;               if (fr == 0) rss_t[(wr * 64 + fq * 4 + ai * 128 + m * 16 + j) * 16] = ss;
;             }
.LBB0_443:
	v_or_b32_e32 v90, 0xcc00, v0
	v_mov_b32_e32 v84, v89
	v_mov_b32_e32 v91, v1
	s_waitcnt lgkmcnt(0)
	v_pk_fma_f32 v[88:89], v[84:85], v[184:185], v[94:95]
	v_lshl_add_u64 v[84:85], v[90:91], 2, s[2:3]
	global_store_dwordx2 v[84:85], v[88:89], off
	s_mov_b64 s[68:69], -1
	s_and_b64 vcc, exec, s[6:7]
	v_or_b32_e32 v84, 0xcc80, v0
	s_cbranch_vccnz .LBB0_447
	v_pk_mul_f32 v[92:93], v[182:183], v[88:89]
	v_lshl_add_u64 v[90:91], v[90:91], 1, s[8:9]
	s_nop 0
	s_nop 0
	v_cvt_pk_bf16_f32 v85, v92, v92
	v_cvt_pk_bf16_f32 v82, v93, v93
	v_lshrrev_b32_e32 v85, 16, v85
	v_and_or_b32 v82, v82, s28, v85
	v_mov_b32_e32 v86, v83
	v_mov_b32_e32 v85, v1
	global_store_dword v[90:91], v82, off
	v_pk_fma_f32 v[90:91], v[86:87], v[180:181], v[96:97]
	v_lshl_add_u64 v[92:93], v[84:85], 2, s[2:3]
	global_store_dwordx2 v[92:93], v[90:91], off
	v_pk_mul_f32 v[92:93], v[186:187], v[90:91]
	v_pk_mul_f32 v[88:89], v[88:89], v[88:89]
	s_nop 0
	s_nop 0
	v_cvt_pk_bf16_f32 v86, v92, v92
	v_cvt_pk_bf16_f32 v82, v93, v93
	v_lshrrev_b32_e32 v86, 16, v86
	v_and_or_b32 v82, v82, s28, v86
	v_lshl_add_u64 v[92:93], v[84:85], 1, s[8:9]
	v_pk_mul_f32 v[90:91], v[90:91], v[90:91]
	global_store_dword v[92:93], v82, off
	v_add_f32_e32 v82, v90, v91
	v_add_f32_e32 v85, v88, v89
	v_add_f32_e32 v82, v85, v82
	s_nop 1
	v_add_f32_dpp v82, v82, v82 quad_perm:[1,0,3,2] row_mask:0xf bank_mask:0xf bound_ctrl:1
	s_nop 1
	v_add_f32_dpp v82, v82, v82 quad_perm:[2,3,0,1] row_mask:0xf bank_mask:0xf bound_ctrl:1
	s_nop 1
	v_add_f32_dpp v82, v82, v82 row_half_mirror row_mask:0xf bank_mask:0xf bound_ctrl:1
	s_nop 1
	v_mov_b32_dpp v85, v82 row_mirror row_mask:0xf bank_mask:0xf bound_ctrl:1
	s_and_saveexec_b64 s[68:69], s[4:5]
	s_cbranch_execz .LBB0_446
	v_lshlrev_b32_e32 v88, 4, v194
	v_ashrrev_i32_e32 v89, 31, v88
	v_add_f32_e32 v82, v82, v85
	v_lshl_add_u64 v[88:89], v[88:89], 2, v[150:151]
	global_store_dword v[88:89], v82, off offset:3264

; __device__ __forceinline__ unsigned pack2(float a, float b) { return (unsigned)f2bf(a) | ((unsigned)f2bf(b) << 16); }
; #define WAIT_V(n) asm volatile("s_waitcnt vmcnt(" #n ")" ::: "memory")
; __device__ __forceinline__ void glds16_s(const void* sbase, unsigned voff, unsigned lds_dst) {
;   unsigned keep;
;   asm volatile("s_mov_b32 %0, m0\n\ts_mov_b32 m0, %3\n\ts_nop 2\n\tglobal_load_lds_dwordx4 %1, %2\n\ts_mov_b32 m0, %0"
;                : "=&s"(keep) : "v"(voff), "s"(sbase), "s"(lds_dst) : "memory");
; template <int EPI, bool HS = false>
; __device__ __forceinline__ void gemm_phase(const Params& p, const GemmCfg& g, char* shm, const int wave_s) {
;     ...
; #pragma unroll
;       for (int ai = 0; ai < 2; ++ai) {
; #pragma unroll
;         for (int i = 0; i < 16; ++i) {
;           const int r = wv_s * 16 + i;
;           glds_row(xin_t + (size_t)(ai * 128 + r) * 1024, (unsigned)lane * 16u, ldsb + (unsigned)(r * XROW));
;         }
;         WAIT_V(0);
;         __syncthreads();
; #pragma unroll
;         for (int m = 0; m < 4; ++m) {
;           float2 xv[4][2];
; #pragma unroll
;           for (int j = 0; j < 4; ++j)
; #pragma unroll
;             for (int bj = 0; bj < 2; ++bj) xv[j][bj] = *(const float2*)(xl + (m * 16 + j) * XROW + bj * 512);
; #pragma unroll
;           for (int j = 0; j < 4; ++j) {
;             float ss = 0.f;
; #pragma unroll
;             for (int bj = 0; bj < 2; ++bj) {
;               float2 xn;
;               xn.x = xv[j][bj].x + gt[bj][0] * acc[ai][bj][m][0][j];
;               xn.y = xv[j][bj].y + gt[bj][1] * acc[ai][bj][m][1][j];
;               const unsigned o = tb + (unsigned)((ai * 128 + m * 16 + j) * 1024 + bj * 128);
;               *(float2*)(xout_t + o) = xn;
;               if (g.has_next) *(unsigned*)(xg_t + o) = pack2(xn.x * gn[bj][0], xn.y * gn[bj][1]);
;               ss += xn.x * xn.x + xn.y * xn.y;
;             }
;             if (g.has_next) {
;               ss = dpp_row_sum16(ss);
;               if (fr == 0) rss_t[(wr * 64 + fq * 4 + ai * 128 + m * 16 + j) * 16] = ss;
;             }
.LBB0_449:
	v_pk_mul_f32 v[94:95], v[66:67], v[70:71]
	v_pk_mul_f32 v[92:93], v[62:63], v[70:71]
	v_pk_mul_f32 v[62:63], v[80:81], v[72:73]
	v_pk_mul_f32 v[90:91], v[78:79], v[70:71]
	v_pk_mul_f32 v[66:67], v[76:77], v[72:73]
	v_pk_mul_f32 v[70:71], v[74:75], v[70:71]
	s_lshl_b64 s[10:11], s[10:11], 12
	s_add_u32 s13, s76, s10
	s_addc_u32 s14, s77, s11
	s_add_u32 s10, s13, 0x80000
	s_addc_u32 s11, s14, 0
	s_waitcnt vmcnt(63) expcnt(7) lgkmcnt(15)
	s_barrier
	s_mov_b32 m0, s84
	s_nop 0
	global_load_lds_dwordx4 v198, s[10:11]
	s_add_u32 s10, s13, 0x81000
	s_addc_u32 s11, s14, 0
	s_mov_b32 m0, s85
	s_nop 0
	global_load_lds_dwordx4 v198, s[10:11]
	s_add_u32 s10, s13, 0x82000
	s_addc_u32 s11, s14, 0
	s_mov_b32 m0, s88
	s_nop 0
	global_load_lds_dwordx4 v198, s[10:11]
	s_add_u32 s10, s13, 0x83000
	s_addc_u32 s11, s14, 0
	s_mov_b32 m0, s89
	s_nop 0
	global_load_lds_dwordx4 v198, s[10:11]
	s_add_u32 s10, s13, 0x84000
	s_addc_u32 s11, s14, 0
	s_mov_b32 m0, s90
	s_nop 0
	global_load_lds_dwordx4 v198, s[10:11]
	s_add_u32 s10, s13, 0x85000
	s_addc_u32 s11, s14, 0
	s_mov_b32 m0, s91
	s_nop 0
	global_load_lds_dwordx4 v198, s[10:11]
	s_add_u32 s10, s13, 0x86000
	s_addc_u32 s11, s14, 0
	s_mov_b32 m0, s92
	s_nop 0
	global_load_lds_dwordx4 v198, s[10:11]
	s_add_u32 s10, s13, 0x87000
	s_addc_u32 s11, s14, 0
	s_mov_b32 m0, s93
	s_nop 0
	global_load_lds_dwordx4 v198, s[10:11]
	s_add_u32 s10, s13, 0x88000
	s_addc_u32 s11, s14, 0
	s_mov_b32 m0, s71
	s_nop 0
	global_load_lds_dwordx4 v198, s[10:11]
	s_add_u32 s10, s13, 0x89000
	s_addc_u32 s11, s14, 0
	s_mov_b32 m0, s70
	s_nop 0
	global_load_lds_dwordx4 v198, s[10:11]
	s_add_u32 s10, s13, 0x8a000
	s_addc_u32 s11, s14, 0
	s_mov_b32 m0, s72
	s_nop 0
	global_load_lds_dwordx4 v198, s[10:11]
	s_add_u32 s10, s13, 0x8b000
	s_addc_u32 s11, s14, 0
	s_mov_b32 m0, s73
	s_nop 0
	global_load_lds_dwordx4 v198, s[10:11]
	s_add_u32 s10, s13, 0x8c000
	s_addc_u32 s11, s14, 0
	s_mov_b32 m0, s74
	s_nop 0
	global_load_lds_dwordx4 v198, s[10:11]
	s_add_u32 s10, s13, 0x8d000
	s_addc_u32 s11, s14, 0
	s_mov_b32 m0, s0
	s_nop 0
	global_load_lds_dwordx4 v198, s[10:11]
	s_add_u32 s10, s13, 0x8e000
	s_addc_u32 s11, s14, 0
	s_mov_b32 m0, s1
	s_nop 0
	global_load_lds_dwordx4 v198, s[10:11]
	s_add_u32 s0, s13, 0x8f000
	s_addc_u32 s1, s14, 0
	s_mov_b32 m0, s12
	s_nop 0
	global_load_lds_dwordx4 v198, s[0:1]
	s_waitcnt vmcnt(0)
	s_barrier
	ds_read2st64_b64 v[86:89], v195 offset1:1
	ds_read2_b64 v[82:85], v195 offset0:130 offset1:194
	ds_read2st64_b64 v[78:81], v196 offset0:4 offset1:5
	ds_read2st64_b64 v[74:77], v197 offset0:6 offset1:7
	v_add_u32_e32 v98, 0x20000, v0
	v_mov_b32_e32 v96, v94
	v_mov_b32_e32 v97, v92
	v_mov_b32_e32 v99, v1
	s_waitcnt lgkmcnt(3)
	v_pk_fma_f32 v[96:97], v[96:97], v[184:185], v[86:87]
	v_lshl_add_u64 v[86:87], v[98:99], 2, s[2:3]
	v_readlane_b32 s88, v254, 47
	global_store_dwordx2 v[86:87], v[96:97], off
	s_mov_b64 s[10:11], -1
	s_and_b64 vcc, exec, s[6:7]
	v_add_u32_e32 v86, 0x20080, v0
	s_mov_b32 s84, 0x8000
	v_readlane_b32 s89, v254, 48
	v_readlane_b32 s90, v254, 49
	v_readlane_b32 s91, v254, 50
	s_cbranch_vccnz .LBB0_453
	v_pk_mul_f32 v[100:101], v[182:183], v[96:97]
	v_lshl_add_u64 v[98:99], v[98:99], 1, s[8:9]
	s_nop 0
	s_nop 0
	v_cvt_pk_bf16_f32 v92, v100, v100
	v_cvt_pk_bf16_f32 v87, v101, v101
	v_lshrrev_b32_e32 v92, 16, v92
	v_and_or_b32 v87, v87, s28, v92
	global_store_dword v[98:99], v87, off
	v_mov_b32_e32 v98, v90
	v_mov_b32_e32 v99, v70
	v_mov_b32_e32 v87, v1
	v_pk_fma_f32 v[98:99], v[98:99], v[180:181], v[88:89]
	v_lshl_add_u64 v[100:101], v[86:87], 2, s[2:3]
	global_store_dwordx2 v[100:101], v[98:99], off
	v_pk_mul_f32 v[100:101], v[186:187], v[98:99]
	v_pk_mul_f32 v[96:97], v[96:97], v[96:97]
	s_nop 0
	s_nop 0
	v_cvt_pk_bf16_f32 v94, v100, v100
	v_cvt_pk_bf16_f32 v92, v101, v101
	v_lshrrev_b32_e32 v94, 16, v94
	v_and_or_b32 v92, v92, s28, v94
	v_lshl_add_u64 v[100:101], v[86:87], 1, s[8:9]
	v_pk_mul_f32 v[98:99], v[98:99], v[98:99]
	global_store_dword v[100:101], v92, off
	v_add_f32_e32 v87, v98, v99
	v_add_f32_e32 v92, v96, v97
	v_add_f32_e32 v87, v92, v87
	s_nop 1
	v_add_f32_dpp v87, v87, v87 quad_perm:[1,0,3,2] row_mask:0xf bank_mask:0xf bound_ctrl:1
	s_nop 1
	v_add_f32_dpp v87, v87, v87 quad_perm:[2,3,0,1] row_mask:0xf bank_mask:0xf bound_ctrl:1
	s_nop 1
	v_add_f32_dpp v87, v87, v87 row_half_mirror row_mask:0xf bank_mask:0xf bound_ctrl:1
	s_nop 1
	v_mov_b32_dpp v92, v87 row_mirror row_mask:0xf bank_mask:0xf bound_ctrl:1
	s_and_saveexec_b64 s[10:11], s[4:5]
	s_cbranch_execz .LBB0_452
	v_add_f32_e32 v87, v87, v92
	v_mov_b32_e32 v92, 0x800
	v_lshl_add_u32 v96, v194, 4, v92
	v_ashrrev_i32_e32 v97, 31, v96
	v_lshl_add_u64 v[96:97], v[96:97], 2, v[150:151]
	global_store_dword v[96:97], v87, off

; __device__ __forceinline__ u16 f2bf(float f) {
;   unsigned u = __float_as_uint(f);
;   u += 0x7fffu + ((u >> 16) & 1u);
;   return (u16)(u >> 16);
; }
; __device__ __forceinline__ float bf2f(u16 h) { return __uint_as_float(((unsigned)h) << 16); }
; __device__ __forceinline__ float bfs2f(short h) { return __uint_as_float(((unsigned)(u16)h) << 16); }
; __device__ __forceinline__ unsigned pack2(float a, float b) { return (unsigned)f2bf(a) | ((unsigned)f2bf(b) << 16); }
; template <int EPI, bool HS = false>
; __device__ __forceinline__ void gemm_phase(const Params& p, const GemmCfg& g, char* shm, const int wave_s) {
;     ...
;             for (int bj = 0; bj < 2; ++bj) {
;               float2 xn;
;               xn.x = xv[j][bj].x + gt[bj][0] * acc[ai][bj][m][0][j];
;               xn.y = xv[j][bj].y + gt[bj][1] * acc[ai][bj][m][1][j];
;               const unsigned o = tb + (unsigned)((ai * 128 + m * 16 + j) * 1024 + bj * 128);
;               *(float2*)(xout_t + o) = xn;
;               if (g.has_next) *(unsigned*)(xg_t + o) = pack2(xn.x * gn[bj][0], xn.y * gn[bj][1]);
;               ss += xn.x * xn.x + xn.y * xn.y;
;             }
;             if (g.has_next) {
;               ss = dpp_row_sum16(ss);
;               if (fr == 0) rss_t[(wr * 64 + fq * 4 + ai * 128 + m * 16 + j) * 16] = ss;
;             }
.LBB0_455:
	v_add_u32_e32 v86, 0x20400, v0
	v_mov_b32_e32 v92, v95
	v_mov_b32_e32 v87, v1
	v_pk_mul_f32 v[68:69], v[68:69], v[72:73]
	v_pk_mul_f32 v[64:65], v[64:65], v[72:73]
	s_waitcnt lgkmcnt(2)
	v_pk_fma_f32 v[82:83], v[92:93], v[184:185], v[82:83]
	v_lshl_add_u64 v[72:73], v[86:87], 2, s[2:3]
	global_store_dwordx2 v[72:73], v[82:83], off
	s_mov_b64 s[10:11], -1
	s_and_b64 vcc, exec, s[6:7]
	v_add_u32_e32 v72, 0x20480, v0
	s_cbranch_vccnz .LBB0_459
	v_pk_mul_f32 v[88:89], v[182:183], v[82:83]
	v_lshl_add_u64 v[86:87], v[86:87], 1, s[8:9]
	s_nop 0
	s_nop 0
	v_cvt_pk_bf16_f32 v73, v88, v88
	v_cvt_pk_bf16_f32 v70, v89, v89
	v_lshrrev_b32_e32 v73, 16, v73
	v_and_or_b32 v70, v70, s28, v73
	global_store_dword v[86:87], v70, off
	v_mov_b32_e32 v70, v91
	v_mov_b32_e32 v73, v1
	v_pk_fma_f32 v[86:87], v[70:71], v[180:181], v[84:85]
	v_lshl_add_u64 v[88:89], v[72:73], 2, s[2:3]
	global_store_dwordx2 v[88:89], v[86:87], off
	v_pk_mul_f32 v[88:89], v[186:187], v[86:87]
	v_pk_mul_f32 v[82:83], v[82:83], v[82:83]
	v_and_b32_sdwa v90, v88, v178 dst_sel:DWORD dst_unused:UNUSED_PAD src0_sel:WORD_1 src1_sel:DWORD
	s_nop 0
	v_add3_u32 v88, v88, v90, s81
	v_cvt_pk_bf16_f32 v70, v89, v89
	v_lshrrev_b32_e32 v88, 16, v88
	v_and_or_b32 v70, v70, s28, v88
	v_lshl_add_u64 v[88:89], v[72:73], 1, s[8:9]
	v_pk_mul_f32 v[86:87], v[86:87], v[86:87]
	global_store_dword v[88:89], v70, off
	v_add_f32_e32 v70, v86, v87
	v_add_f32_e32 v73, v82, v83
	v_add_f32_e32 v70, v73, v70
	s_nop 1
	v_add_f32_dpp v70, v70, v70 quad_perm:[1,0,3,2] row_mask:0xf bank_mask:0xf bound_ctrl:1
	s_nop 1
	v_add_f32_dpp v70, v70, v70 quad_perm:[2,3,0,1] row_mask:0xf bank_mask:0xf bound_ctrl:1
	s_nop 1
	v_add_f32_dpp v70, v70, v70 row_half_mirror row_mask:0xf bank_mask:0xf bound_ctrl:1
	s_nop 1
	v_mov_b32_dpp v73, v70 row_mirror row_mask:0xf bank_mask:0xf bound_ctrl:1
	s_and_saveexec_b64 s[10:11], s[4:5]
	s_cbranch_execz .LBB0_458
	v_add_f32_e32 v70, v70, v73
	v_mov_b32_e32 v73, 0x810
	v_lshl_add_u32 v82, v194, 4, v73
	v_ashrrev_i32_e32 v83, 31, v82
	v_lshl_add_u64 v[82:83], v[82:83], 2, v[150:151]
	global_store_dword v[82:83], v70, off

; __device__ __forceinline__ u16 f2bf(float f) {
;   unsigned u = __float_as_uint(f);
;   u += 0x7fffu + ((u >> 16) & 1u);
;   return (u16)(u >> 16);
; }
; __device__ __forceinline__ float bf2f(u16 h) { return __uint_as_float(((unsigned)h) << 16); }
; __device__ __forceinline__ float bfs2f(short h) { return __uint_as_float(((unsigned)(u16)h) << 16); }
; __device__ __forceinline__ unsigned pack2(float a, float b) { return (unsigned)f2bf(a) | ((unsigned)f2bf(b) << 16); }
; template <int EPI, bool HS = false>
; __device__ __forceinline__ void gemm_phase(const Params& p, const GemmCfg& g, char* shm, const int wave_s) {
;     ...
;             for (int bj = 0; bj < 2; ++bj) {
;               float2 xn;
;               xn.x = xv[j][bj].x + gt[bj][0] * acc[ai][bj][m][0][j];
;               xn.y = xv[j][bj].y + gt[bj][1] * acc[ai][bj][m][1][j];
;               const unsigned o = tb + (unsigned)((ai * 128 + m * 16 + j) * 1024 + bj * 128);
;               *(float2*)(xout_t + o) = xn;
;               if (g.has_next) *(unsigned*)(xg_t + o) = pack2(xn.x * gn[bj][0], xn.y * gn[bj][1]);
;               ss += xn.x * xn.x + xn.y * xn.y;
;             }
;             if (g.has_next) {
;               ss = dpp_row_sum16(ss);
;               if (fr == 0) rss_t[(wr * 64 + fq * 4 + ai * 128 + m * 16 + j) * 16] = ss;
;             }
.LBB0_461:
	v_add_u32_e32 v82, 0x20800, v0
	v_mov_b32_e32 v70, v68
	v_mov_b32_e32 v71, v64
	v_mov_b32_e32 v83, v1
	s_waitcnt lgkmcnt(1)
	v_pk_fma_f32 v[72:73], v[70:71], v[184:185], v[78:79]
	v_lshl_add_u64 v[70:71], v[82:83], 2, s[2:3]
	global_store_dwordx2 v[70:71], v[72:73], off
	s_mov_b64 s[10:11], -1
	s_and_b64 vcc, exec, s[6:7]
	v_add_u32_e32 v70, 0x20880, v0
	s_cbranch_vccnz .LBB0_465
	v_pk_mul_f32 v[78:79], v[182:183], v[72:73]
	v_mov_b32_e32 v71, v1
	s_nop 0
	s_nop 0
	v_cvt_pk_bf16_f32 v68, v78, v78
	v_cvt_pk_bf16_f32 v64, v79, v79
	v_lshrrev_b32_e32 v68, 16, v68
	v_and_or_b32 v64, v64, s28, v68
	v_lshl_add_u64 v[78:79], v[82:83], 1, s[8:9]
	global_store_dword v[78:79], v64, off
	v_mov_b32_e32 v78, v62
	v_mov_b32_e32 v79, v66
	v_pk_fma_f32 v[78:79], v[78:79], v[180:181], v[80:81]
	v_lshl_add_u64 v[82:83], v[70:71], 2, s[2:3]
	global_store_dwordx2 v[82:83], v[78:79], off
	v_pk_mul_f32 v[82:83], v[186:187], v[78:79]
	v_pk_mul_f32 v[72:73], v[72:73], v[72:73]
	s_nop 0
	s_nop 0
	v_cvt_pk_bf16_f32 v68, v82, v82
	v_cvt_pk_bf16_f32 v64, v83, v83
	v_lshrrev_b32_e32 v68, 16, v68
	v_and_or_b32 v64, v64, s28, v68
	v_lshl_add_u64 v[82:83], v[70:71], 1, s[8:9]
	v_pk_mul_f32 v[78:79], v[78:79], v[78:79]
	global_store_dword v[82:83], v64, off
	v_add_f32_e32 v64, v78, v79
	v_add_f32_e32 v68, v72, v73
	v_add_f32_e32 v64, v68, v64
	s_nop 1
	v_add_f32_dpp v64, v64, v64 quad_perm:[1,0,3,2] row_mask:0xf bank_mask:0xf bound_ctrl:1
	s_nop 1
	v_add_f32_dpp v64, v64, v64 quad_perm:[2,3,0,1] row_mask:0xf bank_mask:0xf bound_ctrl:1
	s_nop 1
	v_add_f32_dpp v64, v64, v64 row_half_mirror row_mask:0xf bank_mask:0xf bound_ctrl:1
	s_nop 1
	v_mov_b32_dpp v68, v64 row_mirror row_mask:0xf bank_mask:0xf bound_ctrl:1
	s_and_saveexec_b64 s[10:11], s[4:5]
	s_cbranch_execz .LBB0_464
	v_add_f32_e32 v64, v64, v68
	v_mov_b32_e32 v68, 0x820
	v_lshl_add_u32 v72, v194, 4, v68
	v_ashrrev_i32_e32 v73, 31, v72
	v_lshl_add_u64 v[72:73], v[72:73], 2, v[150:151]
	global_store_dword v[72:73], v64, off

; __device__ __forceinline__ u16 f2bf(float f) {
;   unsigned u = __float_as_uint(f);
;   u += 0x7fffu + ((u >> 16) & 1u);
;   return (u16)(u >> 16);
; }
; __device__ __forceinline__ float bf2f(u16 h) { return __uint_as_float(((unsigned)h) << 16); }
; __device__ __forceinline__ float bfs2f(short h) { return __uint_as_float(((unsigned)(u16)h) << 16); }
; __device__ __forceinline__ unsigned pack2(float a, float b) { return (unsigned)f2bf(a) | ((unsigned)f2bf(b) << 16); }
; template <int EPI, bool HS = false>
; __device__ __forceinline__ void gemm_phase(const Params& p, const GemmCfg& g, char* shm, const int wave_s) {
;     ...
;             for (int bj = 0; bj < 2; ++bj) {
;               float2 xn;
;               xn.x = xv[j][bj].x + gt[bj][0] * acc[ai][bj][m][0][j];
;               xn.y = xv[j][bj].y + gt[bj][1] * acc[ai][bj][m][1][j];
;               const unsigned o = tb + (unsigned)((ai * 128 + m * 16 + j) * 1024 + bj * 128);
;               *(float2*)(xout_t + o) = xn;
;               if (g.has_next) *(unsigned*)(xg_t + o) = pack2(xn.x * gn[bj][0], xn.y * gn[bj][1]);
;               ss += xn.x * xn.x + xn.y * xn.y;
;             }
;             if (g.has_next) {
;               ss = dpp_row_sum16(ss);
;               if (fr == 0) rss_t[(wr * 64 + fq * 4 + ai * 128 + m * 16 + j) * 16] = ss;
;             }
.LBB0_467:
	v_add_u32_e32 v70, 0x20c00, v0
	v_mov_b32_e32 v64, v69
	v_mov_b32_e32 v71, v1
	s_waitcnt lgkmcnt(0)
	v_pk_fma_f32 v[68:69], v[64:65], v[184:185], v[74:75]
	v_lshl_add_u64 v[64:65], v[70:71], 2, s[2:3]
	global_store_dwordx2 v[64:65], v[68:69], off
	s_mov_b64 s[10:11], -1
	s_and_b64 vcc, exec, s[6:7]
	v_add_u32_e32 v64, 0x20c80, v0
	s_cbranch_vccnz .LBB0_471
	v_pk_mul_f32 v[72:73], v[182:183], v[68:69]
	v_lshl_add_u64 v[70:71], v[70:71], 1, s[8:9]
	s_nop 0
	s_nop 0
	v_cvt_pk_bf16_f32 v65, v72, v72
	v_cvt_pk_bf16_f32 v62, v73, v73
	v_lshrrev_b32_e32 v65, 16, v65
	v_and_or_b32 v62, v62, s28, v65
	v_mov_b32_e32 v66, v63
	v_mov_b32_e32 v65, v1
	global_store_dword v[70:71], v62, off
	v_pk_fma_f32 v[70:71], v[66:67], v[180:181], v[76:77]
	v_lshl_add_u64 v[72:73], v[64:65], 2, s[2:3]
	global_store_dwordx2 v[72:73], v[70:71], off
	v_pk_mul_f32 v[72:73], v[186:187], v[70:71]
	v_pk_mul_f32 v[68:69], v[68:69], v[68:69]
	s_nop 0
	s_nop 0
	v_cvt_pk_bf16_f32 v66, v72, v72
	v_cvt_pk_bf16_f32 v62, v73, v73
	v_lshrrev_b32_e32 v66, 16, v66
	v_and_or_b32 v62, v62, s28, v66
	v_lshl_add_u64 v[72:73], v[64:65], 1, s[8:9]
	v_pk_mul_f32 v[70:71], v[70:71], v[70:71]
	global_store_dword v[72:73], v62, off
	v_add_f32_e32 v62, v70, v71
	v_add_f32_e32 v65, v68, v69
	v_add_f32_e32 v62, v65, v62
	s_nop 1
	v_add_f32_dpp v62, v62, v62 quad_perm:[1,0,3,2] row_mask:0xf bank_mask:0xf bound_ctrl:1
	s_nop 1
	v_add_f32_dpp v62, v62, v62 quad_perm:[2,3,0,1] row_mask:0xf bank_mask:0xf bound_ctrl:1
	s_nop 1
	v_add_f32_dpp v62, v62, v62 row_half_mirror row_mask:0xf bank_mask:0xf bound_ctrl:1
	s_nop 1
	v_mov_b32_dpp v65, v62 row_mirror row_mask:0xf bank_mask:0xf bound_ctrl:1
	s_and_saveexec_b64 s[10:11], s[4:5]
	s_cbranch_execz .LBB0_470
	v_add_f32_e32 v62, v62, v65
	v_mov_b32_e32 v65, 0x830
	v_lshl_add_u32 v68, v194, 4, v65
	v_ashrrev_i32_e32 v69, 31, v68
	v_lshl_add_u64 v[68:69], v[68:69], 2, v[150:151]
	global_store_dword v[68:69], v62, off

; __device__ __forceinline__ u16 f2bf(float f) {
;   unsigned u = __float_as_uint(f);
;   u += 0x7fffu + ((u >> 16) & 1u);
;   return (u16)(u >> 16);
; }
; __device__ __forceinline__ float bf2f(u16 h) { return __uint_as_float(((unsigned)h) << 16); }
; __device__ __forceinline__ float bfs2f(short h) { return __uint_as_float(((unsigned)(u16)h) << 16); }
; __device__ __forceinline__ unsigned pack2(float a, float b) { return (unsigned)f2bf(a) | ((unsigned)f2bf(b) << 16); }
; template <int EPI, bool HS = false>
; __device__ __forceinline__ void gemm_phase(const Params& p, const GemmCfg& g, char* shm, const int wave_s) {
;     ...
;         for (int m = 0; m < 4; ++m) {
;           float2 xv[4][2];
; #pragma unroll
;           for (int j = 0; j < 4; ++j)
; #pragma unroll
;             for (int bj = 0; bj < 2; ++bj) xv[j][bj] = *(const float2*)(xl + (m * 16 + j) * XROW + bj * 512);
; #pragma unroll
;           for (int j = 0; j < 4; ++j) {
;             float ss = 0.f;
; #pragma unroll
;             for (int bj = 0; bj < 2; ++bj) {
;               float2 xn;
;               xn.x = xv[j][bj].x + gt[bj][0] * acc[ai][bj][m][0][j];
;               xn.y = xv[j][bj].y + gt[bj][1] * acc[ai][bj][m][1][j];
;               const unsigned o = tb + (unsigned)((ai * 128 + m * 16 + j) * 1024 + bj * 128);
;               *(float2*)(xout_t + o) = xn;
;               if (g.has_next) *(unsigned*)(xg_t + o) = pack2(xn.x * gn[bj][0], xn.y * gn[bj][1]);
;               ss += xn.x * xn.x + xn.y * xn.y;
;             }
;             if (g.has_next) {
;               ss = dpp_row_sum16(ss);
;               if (fr == 0) rss_t[(wr * 64 + fq * 4 + ai * 128 + m * 16 + j) * 16] = ss;
;             }
.LBB0_473:
	v_pk_mul_f32 v[74:75], v[46:47], v[50:51]
	v_pk_mul_f32 v[72:73], v[42:43], v[50:51]
	v_pk_mul_f32 v[42:43], v[60:61], v[52:53]
	v_pk_mul_f32 v[70:71], v[58:59], v[50:51]
	v_pk_mul_f32 v[46:47], v[56:57], v[52:53]
	v_pk_mul_f32 v[50:51], v[54:55], v[50:51]
	ds_read2st64_b64 v[66:69], v162 offset0:32 offset1:33
	ds_read2st64_b64 v[62:65], v163 offset0:34 offset1:35
	ds_read2st64_b64 v[58:61], v164 offset0:36 offset1:37
	ds_read2st64_b64 v[54:57], v165 offset0:38 offset1:39
	v_add_u32_e32 v78, 0x24000, v0
	v_mov_b32_e32 v76, v74
	v_mov_b32_e32 v77, v72
	v_mov_b32_e32 v79, v1
	s_waitcnt lgkmcnt(3)
	v_pk_fma_f32 v[76:77], v[76:77], v[184:185], v[66:67]
	v_lshl_add_u64 v[66:67], v[78:79], 2, s[2:3]
	global_store_dwordx2 v[66:67], v[76:77], off
	s_mov_b64 s[10:11], -1
	s_and_b64 vcc, exec, s[6:7]
	v_add_u32_e32 v66, 0x24080, v0
	s_cbranch_vccnz .LBB0_477
	v_pk_mul_f32 v[80:81], v[182:183], v[76:77]
	v_lshl_add_u64 v[78:79], v[78:79], 1, s[8:9]
	s_nop 0
	s_nop 0
	v_cvt_pk_bf16_f32 v72, v80, v80
	v_cvt_pk_bf16_f32 v67, v81, v81
	v_lshrrev_b32_e32 v72, 16, v72
	v_and_or_b32 v67, v67, s28, v72
	global_store_dword v[78:79], v67, off
	v_mov_b32_e32 v78, v70
	v_mov_b32_e32 v79, v50
	v_mov_b32_e32 v67, v1
	v_pk_fma_f32 v[78:79], v[78:79], v[180:181], v[68:69]
	v_lshl_add_u64 v[80:81], v[66:67], 2, s[2:3]
	global_store_dwordx2 v[80:81], v[78:79], off
	v_pk_mul_f32 v[80:81], v[186:187], v[78:79]
	v_pk_mul_f32 v[76:77], v[76:77], v[76:77]
	s_nop 0
	s_nop 0
	v_cvt_pk_bf16_f32 v74, v80, v80
	v_cvt_pk_bf16_f32 v72, v81, v81
	v_lshrrev_b32_e32 v74, 16, v74
	v_and_or_b32 v72, v72, s28, v74
	v_lshl_add_u64 v[80:81], v[66:67], 1, s[8:9]
	v_pk_mul_f32 v[78:79], v[78:79], v[78:79]
	global_store_dword v[80:81], v72, off
	v_add_f32_e32 v67, v78, v79
	v_add_f32_e32 v72, v76, v77
	v_add_f32_e32 v67, v72, v67
	s_nop 1
	v_add_f32_dpp v67, v67, v67 quad_perm:[1,0,3,2] row_mask:0xf bank_mask:0xf bound_ctrl:1
	s_nop 1
	v_add_f32_dpp v67, v67, v67 quad_perm:[2,3,0,1] row_mask:0xf bank_mask:0xf bound_ctrl:1
	s_nop 1
	v_add_f32_dpp v67, v67, v67 row_half_mirror row_mask:0xf bank_mask:0xf bound_ctrl:1
	s_nop 1
	v_mov_b32_dpp v72, v67 row_mirror row_mask:0xf bank_mask:0xf bound_ctrl:1
	s_and_saveexec_b64 s[10:11], s[4:5]
	s_cbranch_execz .LBB0_476
	v_add_f32_e32 v67, v67, v72
	v_mov_b32_e32 v72, 0x900
	v_lshl_add_u32 v76, v194, 4, v72
	v_ashrrev_i32_e32 v77, 31, v76
	v_lshl_add_u64 v[76:77], v[76:77], 2, v[150:151]
	global_store_dword v[76:77], v67, off

; __device__ __forceinline__ u16 f2bf(float f) {
;   unsigned u = __float_as_uint(f);
;   u += 0x7fffu + ((u >> 16) & 1u);
;   return (u16)(u >> 16);
; }
; __device__ __forceinline__ float bf2f(u16 h) { return __uint_as_float(((unsigned)h) << 16); }
; __device__ __forceinline__ float bfs2f(short h) { return __uint_as_float(((unsigned)(u16)h) << 16); }
; __device__ __forceinline__ unsigned pack2(float a, float b) { return (unsigned)f2bf(a) | ((unsigned)f2bf(b) << 16); }
; template <int EPI, bool HS = false>
; __device__ __forceinline__ void gemm_phase(const Params& p, const GemmCfg& g, char* shm, const int wave_s) {
;     ...
;             for (int bj = 0; bj < 2; ++bj) {
;               float2 xn;
;               xn.x = xv[j][bj].x + gt[bj][0] * acc[ai][bj][m][0][j];
;               xn.y = xv[j][bj].y + gt[bj][1] * acc[ai][bj][m][1][j];
;               const unsigned o = tb + (unsigned)((ai * 128 + m * 16 + j) * 1024 + bj * 128);
;               *(float2*)(xout_t + o) = xn;
;               if (g.has_next) *(unsigned*)(xg_t + o) = pack2(xn.x * gn[bj][0], xn.y * gn[bj][1]);
;               ss += xn.x * xn.x + xn.y * xn.y;
;             }
;             if (g.has_next) {
;               ss = dpp_row_sum16(ss);
;               if (fr == 0) rss_t[(wr * 64 + fq * 4 + ai * 128 + m * 16 + j) * 16] = ss;
;             }
.LBB0_479:
	v_add_u32_e32 v66, 0x24400, v0
	v_mov_b32_e32 v72, v75
	v_mov_b32_e32 v67, v1
	v_pk_mul_f32 v[48:49], v[48:49], v[52:53]
	v_pk_mul_f32 v[44:45], v[44:45], v[52:53]
	s_waitcnt lgkmcnt(2)
	v_pk_fma_f32 v[62:63], v[72:73], v[184:185], v[62:63]
	v_lshl_add_u64 v[52:53], v[66:67], 2, s[2:3]
	global_store_dwordx2 v[52:53], v[62:63], off
	s_mov_b64 s[10:11], -1
	s_and_b64 vcc, exec, s[6:7]
	v_add_u32_e32 v52, 0x24480, v0
	s_cbranch_vccnz .LBB0_483
	v_pk_mul_f32 v[68:69], v[182:183], v[62:63]
	v_lshl_add_u64 v[66:67], v[66:67], 1, s[8:9]
	s_nop 0
	s_nop 0
	v_cvt_pk_bf16_f32 v53, v68, v68
	v_cvt_pk_bf16_f32 v50, v69, v69
	v_lshrrev_b32_e32 v53, 16, v53
	v_and_or_b32 v50, v50, s28, v53
	global_store_dword v[66:67], v50, off
	v_mov_b32_e32 v50, v71
	v_mov_b32_e32 v53, v1
	v_pk_fma_f32 v[66:67], v[50:51], v[180:181], v[64:65]
	v_lshl_add_u64 v[68:69], v[52:53], 2, s[2:3]
	global_store_dwordx2 v[68:69], v[66:67], off
	v_pk_mul_f32 v[68:69], v[186:187], v[66:67]
	v_pk_mul_f32 v[62:63], v[62:63], v[62:63]
	v_and_b32_sdwa v70, v68, v178 dst_sel:DWORD dst_unused:UNUSED_PAD src0_sel:WORD_1 src1_sel:DWORD
	s_nop 0
	v_add3_u32 v68, v68, v70, s81
	v_cvt_pk_bf16_f32 v50, v69, v69
	v_lshrrev_b32_e32 v68, 16, v68
	v_and_or_b32 v50, v50, s28, v68
	v_lshl_add_u64 v[68:69], v[52:53], 1, s[8:9]
	v_pk_mul_f32 v[66:67], v[66:67], v[66:67]
	global_store_dword v[68:69], v50, off
	v_add_f32_e32 v50, v66, v67
	v_add_f32_e32 v53, v62, v63
	v_add_f32_e32 v50, v53, v50
	s_nop 1
	v_add_f32_dpp v50, v50, v50 quad_perm:[1,0,3,2] row_mask:0xf bank_mask:0xf bound_ctrl:1
	s_nop 1
	v_add_f32_dpp v50, v50, v50 quad_perm:[2,3,0,1] row_mask:0xf bank_mask:0xf bound_ctrl:1
	s_nop 1
	v_add_f32_dpp v50, v50, v50 row_half_mirror row_mask:0xf bank_mask:0xf bound_ctrl:1
	s_nop 1
	v_mov_b32_dpp v53, v50 row_mirror row_mask:0xf bank_mask:0xf bound_ctrl:1
	s_and_saveexec_b64 s[10:11], s[4:5]
	s_cbranch_execz .LBB0_482
	v_add_f32_e32 v50, v50, v53
	v_mov_b32_e32 v53, 0x910
	v_lshl_add_u32 v62, v194, 4, v53
	v_ashrrev_i32_e32 v63, 31, v62
	v_lshl_add_u64 v[62:63], v[62:63], 2, v[150:151]
	global_store_dword v[62:63], v50, off

; __device__ __forceinline__ u16 f2bf(float f) {
;   unsigned u = __float_as_uint(f);
;   u += 0x7fffu + ((u >> 16) & 1u);
;   return (u16)(u >> 16);
; }
; __device__ __forceinline__ float bf2f(u16 h) { return __uint_as_float(((unsigned)h) << 16); }
; __device__ __forceinline__ float bfs2f(short h) { return __uint_as_float(((unsigned)(u16)h) << 16); }
; __device__ __forceinline__ unsigned pack2(float a, float b) { return (unsigned)f2bf(a) | ((unsigned)f2bf(b) << 16); }
; template <int EPI, bool HS = false>
; __device__ __forceinline__ void gemm_phase(const Params& p, const GemmCfg& g, char* shm, const int wave_s) {
;     ...
;             for (int bj = 0; bj < 2; ++bj) {
;               float2 xn;
;               xn.x = xv[j][bj].x + gt[bj][0] * acc[ai][bj][m][0][j];
;               xn.y = xv[j][bj].y + gt[bj][1] * acc[ai][bj][m][1][j];
;               const unsigned o = tb + (unsigned)((ai * 128 + m * 16 + j) * 1024 + bj * 128);
;               *(float2*)(xout_t + o) = xn;
;               if (g.has_next) *(unsigned*)(xg_t + o) = pack2(xn.x * gn[bj][0], xn.y * gn[bj][1]);
;               ss += xn.x * xn.x + xn.y * xn.y;
;             }
;             if (g.has_next) {
;               ss = dpp_row_sum16(ss);
;               if (fr == 0) rss_t[(wr * 64 + fq * 4 + ai * 128 + m * 16 + j) * 16] = ss;
;             }
.LBB0_485:
	v_add_u32_e32 v62, 0x24800, v0
	v_mov_b32_e32 v50, v48
	v_mov_b32_e32 v51, v44
	v_mov_b32_e32 v63, v1
	s_waitcnt lgkmcnt(1)
	v_pk_fma_f32 v[52:53], v[50:51], v[184:185], v[58:59]
	v_lshl_add_u64 v[50:51], v[62:63], 2, s[2:3]
	global_store_dwordx2 v[50:51], v[52:53], off
	s_mov_b64 s[10:11], -1
	s_and_b64 vcc, exec, s[6:7]
	v_add_u32_e32 v50, 0x24880, v0
	s_cbranch_vccnz .LBB0_489
	v_pk_mul_f32 v[58:59], v[182:183], v[52:53]
	v_mov_b32_e32 v51, v1
	s_nop 0
	s_nop 0
	v_cvt_pk_bf16_f32 v48, v58, v58
	v_cvt_pk_bf16_f32 v44, v59, v59
	v_lshrrev_b32_e32 v48, 16, v48
	v_and_or_b32 v44, v44, s28, v48
	v_lshl_add_u64 v[58:59], v[62:63], 1, s[8:9]
	global_store_dword v[58:59], v44, off
	v_mov_b32_e32 v58, v42
	v_mov_b32_e32 v59, v46
	v_pk_fma_f32 v[58:59], v[58:59], v[180:181], v[60:61]
	v_lshl_add_u64 v[62:63], v[50:51], 2, s[2:3]
	global_store_dwordx2 v[62:63], v[58:59], off
	v_pk_mul_f32 v[62:63], v[186:187], v[58:59]
	v_pk_mul_f32 v[52:53], v[52:53], v[52:53]
	s_nop 0
	s_nop 0
	v_cvt_pk_bf16_f32 v48, v62, v62
	v_cvt_pk_bf16_f32 v44, v63, v63
	v_lshrrev_b32_e32 v48, 16, v48
	v_and_or_b32 v44, v44, s28, v48
	v_lshl_add_u64 v[62:63], v[50:51], 1, s[8:9]
	v_pk_mul_f32 v[58:59], v[58:59], v[58:59]
	global_store_dword v[62:63], v44, off
	v_add_f32_e32 v44, v58, v59
	v_add_f32_e32 v48, v52, v53
	v_add_f32_e32 v44, v48, v44
	s_nop 1
	v_add_f32_dpp v44, v44, v44 quad_perm:[1,0,3,2] row_mask:0xf bank_mask:0xf bound_ctrl:1
	s_nop 1
	v_add_f32_dpp v44, v44, v44 quad_perm:[2,3,0,1] row_mask:0xf bank_mask:0xf bound_ctrl:1
	s_nop 1
	v_add_f32_dpp v44, v44, v44 row_half_mirror row_mask:0xf bank_mask:0xf bound_ctrl:1
	s_nop 1
	v_mov_b32_dpp v48, v44 row_mirror row_mask:0xf bank_mask:0xf bound_ctrl:1
	s_and_saveexec_b64 s[10:11], s[4:5]
	s_cbranch_execz .LBB0_488
	v_add_f32_e32 v44, v44, v48
	v_mov_b32_e32 v48, 0x920
	v_lshl_add_u32 v52, v194, 4, v48
	v_ashrrev_i32_e32 v53, 31, v52
	v_lshl_add_u64 v[52:53], v[52:53], 2, v[150:151]
	global_store_dword v[52:53], v44, off

; __device__ __forceinline__ u16 f2bf(float f) {
;   unsigned u = __float_as_uint(f);
;   u += 0x7fffu + ((u >> 16) & 1u);
;   return (u16)(u >> 16);
; }
; __device__ __forceinline__ float bf2f(u16 h) { return __uint_as_float(((unsigned)h) << 16); }
; __device__ __forceinline__ float bfs2f(short h) { return __uint_as_float(((unsigned)(u16)h) << 16); }
; __device__ __forceinline__ unsigned pack2(float a, float b) { return (unsigned)f2bf(a) | ((unsigned)f2bf(b) << 16); }
; template <int EPI, bool HS = false>
; __device__ __forceinline__ void gemm_phase(const Params& p, const GemmCfg& g, char* shm, const int wave_s) {
;     ...
;             for (int bj = 0; bj < 2; ++bj) {
;               float2 xn;
;               xn.x = xv[j][bj].x + gt[bj][0] * acc[ai][bj][m][0][j];
;               xn.y = xv[j][bj].y + gt[bj][1] * acc[ai][bj][m][1][j];
;               const unsigned o = tb + (unsigned)((ai * 128 + m * 16 + j) * 1024 + bj * 128);
;               *(float2*)(xout_t + o) = xn;
;               if (g.has_next) *(unsigned*)(xg_t + o) = pack2(xn.x * gn[bj][0], xn.y * gn[bj][1]);
;               ss += xn.x * xn.x + xn.y * xn.y;
;             }
;             if (g.has_next) {
;               ss = dpp_row_sum16(ss);
;               if (fr == 0) rss_t[(wr * 64 + fq * 4 + ai * 128 + m * 16 + j) * 16] = ss;
;             }
.LBB0_491:
	v_add_u32_e32 v50, 0x24c00, v0
	v_mov_b32_e32 v44, v49
	v_mov_b32_e32 v51, v1
	s_waitcnt lgkmcnt(0)
	v_pk_fma_f32 v[48:49], v[44:45], v[184:185], v[54:55]
	v_lshl_add_u64 v[44:45], v[50:51], 2, s[2:3]
	global_store_dwordx2 v[44:45], v[48:49], off
	s_mov_b64 s[10:11], -1
	s_and_b64 vcc, exec, s[6:7]
	v_add_u32_e32 v44, 0x24c80, v0
	s_cbranch_vccnz .LBB0_495
	v_pk_mul_f32 v[52:53], v[182:183], v[48:49]
	v_lshl_add_u64 v[50:51], v[50:51], 1, s[8:9]
	s_nop 0
	s_nop 0
	v_cvt_pk_bf16_f32 v45, v52, v52
	v_cvt_pk_bf16_f32 v42, v53, v53
	v_lshrrev_b32_e32 v45, 16, v45
	v_and_or_b32 v42, v42, s28, v45
	v_mov_b32_e32 v46, v43
	v_mov_b32_e32 v45, v1
	global_store_dword v[50:51], v42, off
	v_pk_fma_f32 v[50:51], v[46:47], v[180:181], v[56:57]
	v_lshl_add_u64 v[52:53], v[44:45], 2, s[2:3]
	global_store_dwordx2 v[52:53], v[50:51], off
	v_pk_mul_f32 v[52:53], v[186:187], v[50:51]
	v_pk_mul_f32 v[48:49], v[48:49], v[48:49]
	s_nop 0
	s_nop 0
	v_cvt_pk_bf16_f32 v46, v52, v52
	v_cvt_pk_bf16_f32 v42, v53, v53
	v_lshrrev_b32_e32 v46, 16, v46
	v_and_or_b32 v42, v42, s28, v46
	v_lshl_add_u64 v[52:53], v[44:45], 1, s[8:9]
	v_pk_mul_f32 v[50:51], v[50:51], v[50:51]
	global_store_dword v[52:53], v42, off
	v_add_f32_e32 v42, v50, v51
	v_add_f32_e32 v45, v48, v49
	v_add_f32_e32 v42, v45, v42
	s_nop 1
	v_add_f32_dpp v42, v42, v42 quad_perm:[1,0,3,2] row_mask:0xf bank_mask:0xf bound_ctrl:1
	s_nop 1
	v_add_f32_dpp v42, v42, v42 quad_perm:[2,3,0,1] row_mask:0xf bank_mask:0xf bound_ctrl:1
	s_nop 1
	v_add_f32_dpp v42, v42, v42 row_half_mirror row_mask:0xf bank_mask:0xf bound_ctrl:1
	s_nop 1
	v_mov_b32_dpp v45, v42 row_mirror row_mask:0xf bank_mask:0xf bound_ctrl:1
	s_and_saveexec_b64 s[10:11], s[4:5]
	s_cbranch_execz .LBB0_494
	v_add_f32_e32 v42, v42, v45
	v_mov_b32_e32 v45, 0x930
	v_lshl_add_u32 v48, v194, 4, v45
	v_ashrrev_i32_e32 v49, 31, v48
	v_lshl_add_u64 v[48:49], v[48:49], 2, v[150:151]
	global_store_dword v[48:49], v42, off

; __device__ __forceinline__ u16 f2bf(float f) {
;   unsigned u = __float_as_uint(f);
;   u += 0x7fffu + ((u >> 16) & 1u);
;   return (u16)(u >> 16);
; }
; __device__ __forceinline__ float bf2f(u16 h) { return __uint_as_float(((unsigned)h) << 16); }
; __device__ __forceinline__ float bfs2f(short h) { return __uint_as_float(((unsigned)(u16)h) << 16); }
; __device__ __forceinline__ unsigned pack2(float a, float b) { return (unsigned)f2bf(a) | ((unsigned)f2bf(b) << 16); }
; template <int EPI, bool HS = false>
; __device__ __forceinline__ void gemm_phase(const Params& p, const GemmCfg& g, char* shm, const int wave_s) {
;     ...
;         for (int m = 0; m < 4; ++m) {
;           float2 xv[4][2];
; #pragma unroll
;           for (int j = 0; j < 4; ++j)
; #pragma unroll
;             for (int bj = 0; bj < 2; ++bj) xv[j][bj] = *(const float2*)(xl + (m * 16 + j) * XROW + bj * 512);
; #pragma unroll
;           for (int j = 0; j < 4; ++j) {
;             float ss = 0.f;
; #pragma unroll
;             for (int bj = 0; bj < 2; ++bj) {
;               float2 xn;
;               xn.x = xv[j][bj].x + gt[bj][0] * acc[ai][bj][m][0][j];
;               xn.y = xv[j][bj].y + gt[bj][1] * acc[ai][bj][m][1][j];
;               const unsigned o = tb + (unsigned)((ai * 128 + m * 16 + j) * 1024 + bj * 128);
;               *(float2*)(xout_t + o) = xn;
;               if (g.has_next) *(unsigned*)(xg_t + o) = pack2(xn.x * gn[bj][0], xn.y * gn[bj][1]);
;               ss += xn.x * xn.x + xn.y * xn.y;
;             }
;             if (g.has_next) {
;               ss = dpp_row_sum16(ss);
;               if (fr == 0) rss_t[(wr * 64 + fq * 4 + ai * 128 + m * 16 + j) * 16] = ss;
;             }
.LBB0_497:
	v_pk_mul_f32 v[54:55], v[26:27], v[30:31]
	v_pk_mul_f32 v[52:53], v[22:23], v[30:31]
	v_pk_mul_f32 v[22:23], v[40:41], v[32:33]
	v_pk_mul_f32 v[50:51], v[38:39], v[30:31]
	v_pk_mul_f32 v[26:27], v[36:37], v[32:33]
	v_pk_mul_f32 v[30:31], v[34:35], v[30:31]
	ds_read2st64_b64 v[46:49], v195 offset0:65 offset1:66
	ds_read2st64_b64 v[42:45], v140 offset0:67 offset1:68
	ds_read2st64_b64 v[38:41], v196 offset0:69 offset1:70
	ds_read2st64_b64 v[34:37], v197 offset0:71 offset1:72
	v_add_u32_e32 v58, 0x28000, v0
	v_mov_b32_e32 v56, v54
	v_mov_b32_e32 v57, v52
	v_mov_b32_e32 v59, v1
	s_waitcnt lgkmcnt(3)
	v_pk_fma_f32 v[56:57], v[56:57], v[184:185], v[46:47]
	v_lshl_add_u64 v[46:47], v[58:59], 2, s[2:3]
	global_store_dwordx2 v[46:47], v[56:57], off
	s_mov_b64 s[10:11], -1
	s_and_b64 vcc, exec, s[6:7]
	v_add_u32_e32 v46, 0x28080, v0
	s_cbranch_vccnz .LBB0_501
	v_pk_mul_f32 v[60:61], v[182:183], v[56:57]
	v_lshl_add_u64 v[58:59], v[58:59], 1, s[8:9]
	s_nop 0
	s_nop 0
	v_cvt_pk_bf16_f32 v52, v60, v60
	v_cvt_pk_bf16_f32 v47, v61, v61
	v_lshrrev_b32_e32 v52, 16, v52
	v_and_or_b32 v47, v47, s28, v52
	global_store_dword v[58:59], v47, off
	v_mov_b32_e32 v58, v50
	v_mov_b32_e32 v59, v30
	v_mov_b32_e32 v47, v1
	v_pk_fma_f32 v[58:59], v[58:59], v[180:181], v[48:49]
	v_lshl_add_u64 v[60:61], v[46:47], 2, s[2:3]
	global_store_dwordx2 v[60:61], v[58:59], off
	v_pk_mul_f32 v[60:61], v[186:187], v[58:59]
	v_pk_mul_f32 v[56:57], v[56:57], v[56:57]
	s_nop 0
	s_nop 0
	v_cvt_pk_bf16_f32 v54, v60, v60
	v_cvt_pk_bf16_f32 v52, v61, v61
	v_lshrrev_b32_e32 v54, 16, v54
	v_and_or_b32 v52, v52, s28, v54
	v_lshl_add_u64 v[60:61], v[46:47], 1, s[8:9]
	v_pk_mul_f32 v[58:59], v[58:59], v[58:59]
	global_store_dword v[60:61], v52, off
	v_add_f32_e32 v47, v58, v59
	v_add_f32_e32 v52, v56, v57
	v_add_f32_e32 v47, v52, v47
	s_nop 1
	v_add_f32_dpp v47, v47, v47 quad_perm:[1,0,3,2] row_mask:0xf bank_mask:0xf bound_ctrl:1
	s_nop 1
	v_add_f32_dpp v47, v47, v47 quad_perm:[2,3,0,1] row_mask:0xf bank_mask:0xf bound_ctrl:1
	s_nop 1
	v_add_f32_dpp v47, v47, v47 row_half_mirror row_mask:0xf bank_mask:0xf bound_ctrl:1
	s_nop 1
	v_mov_b32_dpp v52, v47 row_mirror row_mask:0xf bank_mask:0xf bound_ctrl:1
	s_and_saveexec_b64 s[10:11], s[4:5]
	s_cbranch_execz .LBB0_500
	v_add_f32_e32 v47, v47, v52
	v_mov_b32_e32 v52, 0xa00
	v_lshl_add_u32 v56, v194, 4, v52
	v_ashrrev_i32_e32 v57, 31, v56
	v_lshl_add_u64 v[56:57], v[56:57], 2, v[150:151]
	global_store_dword v[56:57], v47, off

; __device__ __forceinline__ u16 f2bf(float f) {
;   unsigned u = __float_as_uint(f);
;   u += 0x7fffu + ((u >> 16) & 1u);
;   return (u16)(u >> 16);
; }
; __device__ __forceinline__ float bf2f(u16 h) { return __uint_as_float(((unsigned)h) << 16); }
; __device__ __forceinline__ float bfs2f(short h) { return __uint_as_float(((unsigned)(u16)h) << 16); }
; __device__ __forceinline__ unsigned pack2(float a, float b) { return (unsigned)f2bf(a) | ((unsigned)f2bf(b) << 16); }
; template <int EPI, bool HS = false>
; __device__ __forceinline__ void gemm_phase(const Params& p, const GemmCfg& g, char* shm, const int wave_s) {
;     ...
;             for (int bj = 0; bj < 2; ++bj) {
;               float2 xn;
;               xn.x = xv[j][bj].x + gt[bj][0] * acc[ai][bj][m][0][j];
;               xn.y = xv[j][bj].y + gt[bj][1] * acc[ai][bj][m][1][j];
;               const unsigned o = tb + (unsigned)((ai * 128 + m * 16 + j) * 1024 + bj * 128);
;               *(float2*)(xout_t + o) = xn;
;               if (g.has_next) *(unsigned*)(xg_t + o) = pack2(xn.x * gn[bj][0], xn.y * gn[bj][1]);
;               ss += xn.x * xn.x + xn.y * xn.y;
;             }
;             if (g.has_next) {
;               ss = dpp_row_sum16(ss);
;               if (fr == 0) rss_t[(wr * 64 + fq * 4 + ai * 128 + m * 16 + j) * 16] = ss;
;             }
.LBB0_503:
	v_add_u32_e32 v46, 0x28400, v0
	v_mov_b32_e32 v52, v55
	v_mov_b32_e32 v47, v1
	v_pk_mul_f32 v[28:29], v[28:29], v[32:33]
	v_pk_mul_f32 v[24:25], v[24:25], v[32:33]
	s_waitcnt lgkmcnt(2)
	v_pk_fma_f32 v[42:43], v[52:53], v[184:185], v[42:43]
	v_lshl_add_u64 v[32:33], v[46:47], 2, s[2:3]
	global_store_dwordx2 v[32:33], v[42:43], off
	s_mov_b64 s[10:11], -1
	s_and_b64 vcc, exec, s[6:7]
	v_add_u32_e32 v32, 0x28480, v0
	s_cbranch_vccnz .LBB0_507
	v_pk_mul_f32 v[48:49], v[182:183], v[42:43]
	v_lshl_add_u64 v[46:47], v[46:47], 1, s[8:9]
	s_nop 0
	s_nop 0
	v_cvt_pk_bf16_f32 v33, v48, v48
	v_cvt_pk_bf16_f32 v30, v49, v49
	v_lshrrev_b32_e32 v33, 16, v33
	v_and_or_b32 v30, v30, s28, v33
	global_store_dword v[46:47], v30, off
	v_mov_b32_e32 v30, v51
	v_mov_b32_e32 v33, v1
	v_pk_fma_f32 v[46:47], v[30:31], v[180:181], v[44:45]
	v_lshl_add_u64 v[48:49], v[32:33], 2, s[2:3]
	global_store_dwordx2 v[48:49], v[46:47], off
	v_pk_mul_f32 v[48:49], v[186:187], v[46:47]
	v_pk_mul_f32 v[42:43], v[42:43], v[42:43]
	v_and_b32_sdwa v50, v48, v178 dst_sel:DWORD dst_unused:UNUSED_PAD src0_sel:WORD_1 src1_sel:DWORD
	s_nop 0
	v_add3_u32 v48, v48, v50, s81
	v_cvt_pk_bf16_f32 v30, v49, v49
	v_lshrrev_b32_e32 v48, 16, v48
	v_and_or_b32 v30, v30, s28, v48
	v_lshl_add_u64 v[48:49], v[32:33], 1, s[8:9]
	v_pk_mul_f32 v[46:47], v[46:47], v[46:47]
	global_store_dword v[48:49], v30, off
	v_add_f32_e32 v30, v46, v47
	v_add_f32_e32 v33, v42, v43
	v_add_f32_e32 v30, v33, v30
	s_nop 1
	v_add_f32_dpp v30, v30, v30 quad_perm:[1,0,3,2] row_mask:0xf bank_mask:0xf bound_ctrl:1
	s_nop 1
	v_add_f32_dpp v30, v30, v30 quad_perm:[2,3,0,1] row_mask:0xf bank_mask:0xf bound_ctrl:1
	s_nop 1
	v_add_f32_dpp v30, v30, v30 row_half_mirror row_mask:0xf bank_mask:0xf bound_ctrl:1
	s_nop 1
	v_mov_b32_dpp v33, v30 row_mirror row_mask:0xf bank_mask:0xf bound_ctrl:1
	s_and_saveexec_b64 s[10:11], s[4:5]
	s_cbranch_execz .LBB0_506
	v_add_f32_e32 v30, v30, v33
	v_mov_b32_e32 v33, 0xa10
	v_lshl_add_u32 v42, v194, 4, v33
	v_ashrrev_i32_e32 v43, 31, v42
	v_lshl_add_u64 v[42:43], v[42:43], 2, v[150:151]
	global_store_dword v[42:43], v30, off

; __device__ __forceinline__ u16 f2bf(float f) {
;   unsigned u = __float_as_uint(f);
;   u += 0x7fffu + ((u >> 16) & 1u);
;   return (u16)(u >> 16);
; }
; __device__ __forceinline__ float bf2f(u16 h) { return __uint_as_float(((unsigned)h) << 16); }
; __device__ __forceinline__ float bfs2f(short h) { return __uint_as_float(((unsigned)(u16)h) << 16); }
; __device__ __forceinline__ unsigned pack2(float a, float b) { return (unsigned)f2bf(a) | ((unsigned)f2bf(b) << 16); }
; template <int EPI, bool HS = false>
; __device__ __forceinline__ void gemm_phase(const Params& p, const GemmCfg& g, char* shm, const int wave_s) {
;     ...
;             for (int bj = 0; bj < 2; ++bj) {
;               float2 xn;
;               xn.x = xv[j][bj].x + gt[bj][0] * acc[ai][bj][m][0][j];
;               xn.y = xv[j][bj].y + gt[bj][1] * acc[ai][bj][m][1][j];
;               const unsigned o = tb + (unsigned)((ai * 128 + m * 16 + j) * 1024 + bj * 128);
;               *(float2*)(xout_t + o) = xn;
;               if (g.has_next) *(unsigned*)(xg_t + o) = pack2(xn.x * gn[bj][0], xn.y * gn[bj][1]);
;               ss += xn.x * xn.x + xn.y * xn.y;
;             }
;             if (g.has_next) {
;               ss = dpp_row_sum16(ss);
;               if (fr == 0) rss_t[(wr * 64 + fq * 4 + ai * 128 + m * 16 + j) * 16] = ss;
;             }
.LBB0_509:
	v_add_u32_e32 v42, 0x28800, v0
	v_mov_b32_e32 v30, v28
	v_mov_b32_e32 v31, v24
	v_mov_b32_e32 v43, v1
	s_waitcnt lgkmcnt(1)
	v_pk_fma_f32 v[32:33], v[30:31], v[184:185], v[38:39]
	v_lshl_add_u64 v[30:31], v[42:43], 2, s[2:3]
	global_store_dwordx2 v[30:31], v[32:33], off
	s_mov_b64 s[10:11], -1
	s_and_b64 vcc, exec, s[6:7]
	v_add_u32_e32 v30, 0x28880, v0
	s_cbranch_vccnz .LBB0_513
	v_pk_mul_f32 v[38:39], v[182:183], v[32:33]
	v_mov_b32_e32 v31, v1
	s_nop 0
	s_nop 0
	v_cvt_pk_bf16_f32 v28, v38, v38
	v_cvt_pk_bf16_f32 v24, v39, v39
	v_lshrrev_b32_e32 v28, 16, v28
	v_and_or_b32 v24, v24, s28, v28
	v_lshl_add_u64 v[38:39], v[42:43], 1, s[8:9]
	global_store_dword v[38:39], v24, off
	v_mov_b32_e32 v38, v22
	v_mov_b32_e32 v39, v26
	v_pk_fma_f32 v[38:39], v[38:39], v[180:181], v[40:41]
	v_lshl_add_u64 v[42:43], v[30:31], 2, s[2:3]
	global_store_dwordx2 v[42:43], v[38:39], off
	v_pk_mul_f32 v[42:43], v[186:187], v[38:39]
	v_pk_mul_f32 v[32:33], v[32:33], v[32:33]
	s_nop 0
	s_nop 0
	v_cvt_pk_bf16_f32 v28, v42, v42
	v_cvt_pk_bf16_f32 v24, v43, v43
	v_lshrrev_b32_e32 v28, 16, v28
	v_and_or_b32 v24, v24, s28, v28
	v_lshl_add_u64 v[42:43], v[30:31], 1, s[8:9]
	v_pk_mul_f32 v[38:39], v[38:39], v[38:39]
	global_store_dword v[42:43], v24, off
	v_add_f32_e32 v24, v38, v39
	v_add_f32_e32 v28, v32, v33
	v_add_f32_e32 v24, v28, v24
	s_nop 1
	v_add_f32_dpp v24, v24, v24 quad_perm:[1,0,3,2] row_mask:0xf bank_mask:0xf bound_ctrl:1
	s_nop 1
	v_add_f32_dpp v24, v24, v24 quad_perm:[2,3,0,1] row_mask:0xf bank_mask:0xf bound_ctrl:1
	s_nop 1
	v_add_f32_dpp v24, v24, v24 row_half_mirror row_mask:0xf bank_mask:0xf bound_ctrl:1
	s_nop 1
	v_mov_b32_dpp v28, v24 row_mirror row_mask:0xf bank_mask:0xf bound_ctrl:1
	s_and_saveexec_b64 s[10:11], s[4:5]
	s_cbranch_execz .LBB0_512
	v_add_f32_e32 v24, v24, v28
	v_mov_b32_e32 v28, 0xa20
	v_lshl_add_u32 v32, v194, 4, v28
	v_ashrrev_i32_e32 v33, 31, v32
	v_lshl_add_u64 v[32:33], v[32:33], 2, v[150:151]
	global_store_dword v[32:33], v24, off

; __device__ __forceinline__ u16 f2bf(float f) {
;   unsigned u = __float_as_uint(f);
;   u += 0x7fffu + ((u >> 16) & 1u);
;   return (u16)(u >> 16);
; }
; __device__ __forceinline__ float bf2f(u16 h) { return __uint_as_float(((unsigned)h) << 16); }
; __device__ __forceinline__ float bfs2f(short h) { return __uint_as_float(((unsigned)(u16)h) << 16); }
; __device__ __forceinline__ unsigned pack2(float a, float b) { return (unsigned)f2bf(a) | ((unsigned)f2bf(b) << 16); }
; template <int EPI, bool HS = false>
; __device__ __forceinline__ void gemm_phase(const Params& p, const GemmCfg& g, char* shm, const int wave_s) {
;     ...
;             for (int bj = 0; bj < 2; ++bj) {
;               float2 xn;
;               xn.x = xv[j][bj].x + gt[bj][0] * acc[ai][bj][m][0][j];
;               xn.y = xv[j][bj].y + gt[bj][1] * acc[ai][bj][m][1][j];
;               const unsigned o = tb + (unsigned)((ai * 128 + m * 16 + j) * 1024 + bj * 128);
;               *(float2*)(xout_t + o) = xn;
;               if (g.has_next) *(unsigned*)(xg_t + o) = pack2(xn.x * gn[bj][0], xn.y * gn[bj][1]);
;               ss += xn.x * xn.x + xn.y * xn.y;
;             }
;             if (g.has_next) {
;               ss = dpp_row_sum16(ss);
;               if (fr == 0) rss_t[(wr * 64 + fq * 4 + ai * 128 + m * 16 + j) * 16] = ss;
;             }
.LBB0_515:
	v_add_u32_e32 v30, 0x28c00, v0
	v_mov_b32_e32 v24, v29
	v_mov_b32_e32 v31, v1
	s_waitcnt lgkmcnt(0)
	v_pk_fma_f32 v[28:29], v[24:25], v[184:185], v[34:35]
	v_lshl_add_u64 v[24:25], v[30:31], 2, s[2:3]
	global_store_dwordx2 v[24:25], v[28:29], off
	s_mov_b64 s[10:11], -1
	s_and_b64 vcc, exec, s[6:7]
	v_add_u32_e32 v24, 0x28c80, v0
	s_cbranch_vccnz .LBB0_519
	v_pk_mul_f32 v[32:33], v[182:183], v[28:29]
	v_lshl_add_u64 v[30:31], v[30:31], 1, s[8:9]
	s_nop 0
	s_nop 0
	v_cvt_pk_bf16_f32 v25, v32, v32
	v_cvt_pk_bf16_f32 v22, v33, v33
	v_lshrrev_b32_e32 v25, 16, v25
	v_and_or_b32 v22, v22, s28, v25
	v_mov_b32_e32 v26, v23
	v_mov_b32_e32 v25, v1
	global_store_dword v[30:31], v22, off
	v_pk_fma_f32 v[30:31], v[26:27], v[180:181], v[36:37]
	v_lshl_add_u64 v[32:33], v[24:25], 2, s[2:3]
	global_store_dwordx2 v[32:33], v[30:31], off
	v_pk_mul_f32 v[32:33], v[186:187], v[30:31]
	v_pk_mul_f32 v[28:29], v[28:29], v[28:29]
	s_nop 0
	s_nop 0
	v_cvt_pk_bf16_f32 v26, v32, v32
	v_cvt_pk_bf16_f32 v22, v33, v33
	v_lshrrev_b32_e32 v26, 16, v26
	v_and_or_b32 v22, v22, s28, v26
	v_lshl_add_u64 v[32:33], v[24:25], 1, s[8:9]
	v_pk_mul_f32 v[30:31], v[30:31], v[30:31]
	global_store_dword v[32:33], v22, off
	v_add_f32_e32 v22, v30, v31
	v_add_f32_e32 v25, v28, v29
	v_add_f32_e32 v22, v25, v22
	s_nop 1
	v_add_f32_dpp v22, v22, v22 quad_perm:[1,0,3,2] row_mask:0xf bank_mask:0xf bound_ctrl:1
	s_nop 1
	v_add_f32_dpp v22, v22, v22 quad_perm:[2,3,0,1] row_mask:0xf bank_mask:0xf bound_ctrl:1
	s_nop 1
	v_add_f32_dpp v22, v22, v22 row_half_mirror row_mask:0xf bank_mask:0xf bound_ctrl:1
	s_nop 1
	v_mov_b32_dpp v25, v22 row_mirror row_mask:0xf bank_mask:0xf bound_ctrl:1
	s_and_saveexec_b64 s[10:11], s[4:5]
	s_cbranch_execz .LBB0_518
	v_add_f32_e32 v22, v22, v25
	v_mov_b32_e32 v25, 0xa30
	v_lshl_add_u32 v28, v194, 4, v25
	v_ashrrev_i32_e32 v29, 31, v28
	v_lshl_add_u64 v[28:29], v[28:29], 2, v[150:151]
	global_store_dword v[28:29], v22, off

; __device__ __forceinline__ u16 f2bf(float f) {
;   unsigned u = __float_as_uint(f);
;   u += 0x7fffu + ((u >> 16) & 1u);
;   return (u16)(u >> 16);
; }
; __device__ __forceinline__ float bf2f(u16 h) { return __uint_as_float(((unsigned)h) << 16); }
; __device__ __forceinline__ float bfs2f(short h) { return __uint_as_float(((unsigned)(u16)h) << 16); }
; __device__ __forceinline__ unsigned pack2(float a, float b) { return (unsigned)f2bf(a) | ((unsigned)f2bf(b) << 16); }
; template <int EPI, bool HS = false>
; __device__ __forceinline__ void gemm_phase(const Params& p, const GemmCfg& g, char* shm, const int wave_s) {
;     ...
;         for (int m = 0; m < 4; ++m) {
;           float2 xv[4][2];
; #pragma unroll
;           for (int j = 0; j < 4; ++j)
; #pragma unroll
;             for (int bj = 0; bj < 2; ++bj) xv[j][bj] = *(const float2*)(xl + (m * 16 + j) * XROW + bj * 512);
; #pragma unroll
;           for (int j = 0; j < 4; ++j) {
;             float ss = 0.f;
; #pragma unroll
;             for (int bj = 0; bj < 2; ++bj) {
;               float2 xn;
;               xn.x = xv[j][bj].x + gt[bj][0] * acc[ai][bj][m][0][j];
;               xn.y = xv[j][bj].y + gt[bj][1] * acc[ai][bj][m][1][j];
;               const unsigned o = tb + (unsigned)((ai * 128 + m * 16 + j) * 1024 + bj * 128);
;               *(float2*)(xout_t + o) = xn;
;               if (g.has_next) *(unsigned*)(xg_t + o) = pack2(xn.x * gn[bj][0], xn.y * gn[bj][1]);
;               ss += xn.x * xn.x + xn.y * xn.y;
;             }
;             if (g.has_next) {
;               ss = dpp_row_sum16(ss);
;               if (fr == 0) rss_t[(wr * 64 + fq * 4 + ai * 128 + m * 16 + j) * 16] = ss;
;             }
.LBB0_521:
	v_pk_mul_f32 v[34:35], v[6:7], v[10:11]
	v_pk_mul_f32 v[32:33], v[2:3], v[10:11]
	v_pk_mul_f32 v[2:3], v[20:21], v[12:13]
	v_pk_mul_f32 v[30:31], v[18:19], v[10:11]
	v_pk_mul_f32 v[6:7], v[16:17], v[12:13]
	v_pk_mul_f32 v[10:11], v[14:15], v[10:11]
	ds_read2st64_b64 v[26:29], v162 offset0:97 offset1:98
	ds_read2st64_b64 v[22:25], v163 offset0:99 offset1:100
	ds_read2st64_b64 v[18:21], v164 offset0:101 offset1:102
	ds_read2st64_b64 v[14:17], v165 offset0:103 offset1:104
	v_add_u32_e32 v38, 0x2c000, v0
	v_mov_b32_e32 v36, v34
	v_mov_b32_e32 v37, v32
	v_mov_b32_e32 v39, v1
	s_waitcnt lgkmcnt(3)
	v_pk_fma_f32 v[36:37], v[36:37], v[184:185], v[26:27]
	v_lshl_add_u64 v[26:27], v[38:39], 2, s[2:3]
	global_store_dwordx2 v[26:27], v[36:37], off
	s_mov_b64 s[10:11], -1
	s_and_b64 vcc, exec, s[6:7]
	v_add_u32_e32 v26, 0x2c080, v0
	s_cbranch_vccnz .LBB0_525
	v_pk_mul_f32 v[40:41], v[182:183], v[36:37]
	v_lshl_add_u64 v[38:39], v[38:39], 1, s[8:9]
	s_nop 0
	s_nop 0
	v_cvt_pk_bf16_f32 v32, v40, v40
	v_cvt_pk_bf16_f32 v27, v41, v41
	v_lshrrev_b32_e32 v32, 16, v32
	v_and_or_b32 v27, v27, s28, v32
	global_store_dword v[38:39], v27, off
	v_mov_b32_e32 v38, v30
	v_mov_b32_e32 v39, v10
	v_mov_b32_e32 v27, v1
	v_pk_fma_f32 v[38:39], v[38:39], v[180:181], v[28:29]
	v_lshl_add_u64 v[40:41], v[26:27], 2, s[2:3]
	global_store_dwordx2 v[40:41], v[38:39], off
	v_pk_mul_f32 v[40:41], v[186:187], v[38:39]
	v_pk_mul_f32 v[36:37], v[36:37], v[36:37]
	s_nop 0
	s_nop 0
	v_cvt_pk_bf16_f32 v34, v40, v40
	v_cvt_pk_bf16_f32 v32, v41, v41
	v_lshrrev_b32_e32 v34, 16, v34
	v_and_or_b32 v32, v32, s28, v34
	v_lshl_add_u64 v[40:41], v[26:27], 1, s[8:9]
	v_pk_mul_f32 v[38:39], v[38:39], v[38:39]
	global_store_dword v[40:41], v32, off
	v_add_f32_e32 v27, v38, v39
	v_add_f32_e32 v32, v36, v37
	v_add_f32_e32 v27, v32, v27
	s_nop 1
	v_add_f32_dpp v27, v27, v27 quad_perm:[1,0,3,2] row_mask:0xf bank_mask:0xf bound_ctrl:1
	s_nop 1
	v_add_f32_dpp v27, v27, v27 quad_perm:[2,3,0,1] row_mask:0xf bank_mask:0xf bound_ctrl:1
	s_nop 1
	v_add_f32_dpp v27, v27, v27 row_half_mirror row_mask:0xf bank_mask:0xf bound_ctrl:1
	s_nop 1
	v_mov_b32_dpp v32, v27 row_mirror row_mask:0xf bank_mask:0xf bound_ctrl:1
	s_and_saveexec_b64 s[10:11], s[4:5]
	s_cbranch_execz .LBB0_524
	v_add_f32_e32 v27, v27, v32
	v_mov_b32_e32 v32, 0xb00
	v_lshl_add_u32 v36, v194, 4, v32
	v_ashrrev_i32_e32 v37, 31, v36
	v_lshl_add_u64 v[36:37], v[36:37], 2, v[150:151]
	global_store_dword v[36:37], v27, off

; __device__ __forceinline__ u16 f2bf(float f) {
;   unsigned u = __float_as_uint(f);
;   u += 0x7fffu + ((u >> 16) & 1u);
;   return (u16)(u >> 16);
; }
; __device__ __forceinline__ float bf2f(u16 h) { return __uint_as_float(((unsigned)h) << 16); }
; __device__ __forceinline__ float bfs2f(short h) { return __uint_as_float(((unsigned)(u16)h) << 16); }
; __device__ __forceinline__ unsigned pack2(float a, float b) { return (unsigned)f2bf(a) | ((unsigned)f2bf(b) << 16); }
; template <int EPI, bool HS = false>
; __device__ __forceinline__ void gemm_phase(const Params& p, const GemmCfg& g, char* shm, const int wave_s) {
;     ...
;             for (int bj = 0; bj < 2; ++bj) {
;               float2 xn;
;               xn.x = xv[j][bj].x + gt[bj][0] * acc[ai][bj][m][0][j];
;               xn.y = xv[j][bj].y + gt[bj][1] * acc[ai][bj][m][1][j];
;               const unsigned o = tb + (unsigned)((ai * 128 + m * 16 + j) * 1024 + bj * 128);
;               *(float2*)(xout_t + o) = xn;
;               if (g.has_next) *(unsigned*)(xg_t + o) = pack2(xn.x * gn[bj][0], xn.y * gn[bj][1]);
;               ss += xn.x * xn.x + xn.y * xn.y;
;             }
;             if (g.has_next) {
;               ss = dpp_row_sum16(ss);
;               if (fr == 0) rss_t[(wr * 64 + fq * 4 + ai * 128 + m * 16 + j) * 16] = ss;
;             }
.LBB0_527:
	v_add_u32_e32 v26, 0x2c400, v0
	v_mov_b32_e32 v32, v35
	v_mov_b32_e32 v27, v1
	v_pk_mul_f32 v[8:9], v[8:9], v[12:13]
	v_pk_mul_f32 v[4:5], v[4:5], v[12:13]
	s_waitcnt lgkmcnt(2)
	v_pk_fma_f32 v[22:23], v[32:33], v[184:185], v[22:23]
	v_lshl_add_u64 v[12:13], v[26:27], 2, s[2:3]
	global_store_dwordx2 v[12:13], v[22:23], off
	s_mov_b64 s[10:11], -1
	s_and_b64 vcc, exec, s[6:7]
	v_add_u32_e32 v12, 0x2c480, v0
	s_cbranch_vccnz .LBB0_531
	v_pk_mul_f32 v[28:29], v[182:183], v[22:23]
	v_lshl_add_u64 v[26:27], v[26:27], 1, s[8:9]
	s_nop 0
	s_nop 0
	v_cvt_pk_bf16_f32 v13, v28, v28
	v_cvt_pk_bf16_f32 v10, v29, v29
	v_lshrrev_b32_e32 v13, 16, v13
	v_and_or_b32 v10, v10, s28, v13
	global_store_dword v[26:27], v10, off
	v_mov_b32_e32 v10, v31
	v_mov_b32_e32 v13, v1
	v_pk_fma_f32 v[26:27], v[10:11], v[180:181], v[24:25]
	v_lshl_add_u64 v[28:29], v[12:13], 2, s[2:3]
	global_store_dwordx2 v[28:29], v[26:27], off
	v_pk_mul_f32 v[28:29], v[186:187], v[26:27]
	v_pk_mul_f32 v[22:23], v[22:23], v[22:23]
	v_and_b32_sdwa v30, v28, v178 dst_sel:DWORD dst_unused:UNUSED_PAD src0_sel:WORD_1 src1_sel:DWORD
	s_nop 0
	v_add3_u32 v28, v28, v30, s81
	v_cvt_pk_bf16_f32 v10, v29, v29
	v_lshrrev_b32_e32 v28, 16, v28
	v_and_or_b32 v10, v10, s28, v28
	v_lshl_add_u64 v[28:29], v[12:13], 1, s[8:9]
	v_pk_mul_f32 v[26:27], v[26:27], v[26:27]
	global_store_dword v[28:29], v10, off
	v_add_f32_e32 v10, v26, v27
	v_add_f32_e32 v13, v22, v23
	v_add_f32_e32 v10, v13, v10
	s_nop 1
	v_add_f32_dpp v10, v10, v10 quad_perm:[1,0,3,2] row_mask:0xf bank_mask:0xf bound_ctrl:1
	s_nop 1
	v_add_f32_dpp v10, v10, v10 quad_perm:[2,3,0,1] row_mask:0xf bank_mask:0xf bound_ctrl:1
	s_nop 1
	v_add_f32_dpp v10, v10, v10 row_half_mirror row_mask:0xf bank_mask:0xf bound_ctrl:1
	s_nop 1
	v_mov_b32_dpp v13, v10 row_mirror row_mask:0xf bank_mask:0xf bound_ctrl:1
	s_and_saveexec_b64 s[10:11], s[4:5]
	s_cbranch_execz .LBB0_530
	v_add_f32_e32 v10, v10, v13
	v_mov_b32_e32 v13, 0xb10
	v_lshl_add_u32 v22, v194, 4, v13
	v_ashrrev_i32_e32 v23, 31, v22
	v_lshl_add_u64 v[22:23], v[22:23], 2, v[150:151]
	global_store_dword v[22:23], v10, off

; __device__ __forceinline__ u16 f2bf(float f) {
;   unsigned u = __float_as_uint(f);
;   u += 0x7fffu + ((u >> 16) & 1u);
;   return (u16)(u >> 16);
; }
; __device__ __forceinline__ float bf2f(u16 h) { return __uint_as_float(((unsigned)h) << 16); }
; __device__ __forceinline__ float bfs2f(short h) { return __uint_as_float(((unsigned)(u16)h) << 16); }
; __device__ __forceinline__ unsigned pack2(float a, float b) { return (unsigned)f2bf(a) | ((unsigned)f2bf(b) << 16); }
; template <int EPI, bool HS = false>
; __device__ __forceinline__ void gemm_phase(const Params& p, const GemmCfg& g, char* shm, const int wave_s) {
;     ...
;             for (int bj = 0; bj < 2; ++bj) {
;               float2 xn;
;               xn.x = xv[j][bj].x + gt[bj][0] * acc[ai][bj][m][0][j];
;               xn.y = xv[j][bj].y + gt[bj][1] * acc[ai][bj][m][1][j];
;               const unsigned o = tb + (unsigned)((ai * 128 + m * 16 + j) * 1024 + bj * 128);
;               *(float2*)(xout_t + o) = xn;
;               if (g.has_next) *(unsigned*)(xg_t + o) = pack2(xn.x * gn[bj][0], xn.y * gn[bj][1]);
;               ss += xn.x * xn.x + xn.y * xn.y;
;             }
;             if (g.has_next) {
;               ss = dpp_row_sum16(ss);
;               if (fr == 0) rss_t[(wr * 64 + fq * 4 + ai * 128 + m * 16 + j) * 16] = ss;
;             }
.LBB0_533:
	v_add_u32_e32 v22, 0x2c800, v0
	v_mov_b32_e32 v10, v8
	v_mov_b32_e32 v11, v4
	v_mov_b32_e32 v23, v1
	s_waitcnt lgkmcnt(1)
	v_pk_fma_f32 v[12:13], v[10:11], v[184:185], v[18:19]
	v_lshl_add_u64 v[10:11], v[22:23], 2, s[2:3]
	global_store_dwordx2 v[10:11], v[12:13], off
	s_mov_b64 s[10:11], -1
	s_and_b64 vcc, exec, s[6:7]
	v_add_u32_e32 v10, 0x2c880, v0
	s_cbranch_vccnz .LBB0_537
	v_pk_mul_f32 v[18:19], v[182:183], v[12:13]
	v_mov_b32_e32 v11, v1
	s_nop 0
	s_nop 0
	v_cvt_pk_bf16_f32 v8, v18, v18
	v_cvt_pk_bf16_f32 v4, v19, v19
	v_lshrrev_b32_e32 v8, 16, v8
	v_and_or_b32 v4, v4, s28, v8
	v_lshl_add_u64 v[18:19], v[22:23], 1, s[8:9]
	global_store_dword v[18:19], v4, off
	v_mov_b32_e32 v18, v2
	v_mov_b32_e32 v19, v6
	v_pk_fma_f32 v[18:19], v[18:19], v[180:181], v[20:21]
	v_lshl_add_u64 v[22:23], v[10:11], 2, s[2:3]
	global_store_dwordx2 v[22:23], v[18:19], off
	v_pk_mul_f32 v[22:23], v[186:187], v[18:19]
	v_pk_mul_f32 v[12:13], v[12:13], v[12:13]
	s_nop 0
	s_nop 0
	v_cvt_pk_bf16_f32 v8, v22, v22
	v_cvt_pk_bf16_f32 v4, v23, v23
	v_lshrrev_b32_e32 v8, 16, v8
	v_and_or_b32 v4, v4, s28, v8
	v_lshl_add_u64 v[22:23], v[10:11], 1, s[8:9]
	v_pk_mul_f32 v[18:19], v[18:19], v[18:19]
	global_store_dword v[22:23], v4, off
	v_add_f32_e32 v4, v18, v19
	v_add_f32_e32 v8, v12, v13
	v_add_f32_e32 v4, v8, v4
	s_nop 1
	v_add_f32_dpp v4, v4, v4 quad_perm:[1,0,3,2] row_mask:0xf bank_mask:0xf bound_ctrl:1
	s_nop 1
	v_add_f32_dpp v4, v4, v4 quad_perm:[2,3,0,1] row_mask:0xf bank_mask:0xf bound_ctrl:1
	s_nop 1
	v_add_f32_dpp v4, v4, v4 row_half_mirror row_mask:0xf bank_mask:0xf bound_ctrl:1
	s_nop 1
	v_mov_b32_dpp v8, v4 row_mirror row_mask:0xf bank_mask:0xf bound_ctrl:1
	s_and_saveexec_b64 s[10:11], s[4:5]
	s_cbranch_execz .LBB0_536
	v_add_f32_e32 v4, v4, v8
	v_mov_b32_e32 v8, 0xb20
	v_lshl_add_u32 v12, v194, 4, v8
	v_ashrrev_i32_e32 v13, 31, v12
	v_lshl_add_u64 v[12:13], v[12:13], 2, v[150:151]
	global_store_dword v[12:13], v4, off

; __device__ __forceinline__ u16 f2bf(float f) {
;   unsigned u = __float_as_uint(f);
;   u += 0x7fffu + ((u >> 16) & 1u);
;   return (u16)(u >> 16);
; }
; __device__ __forceinline__ float bf2f(u16 h) { return __uint_as_float(((unsigned)h) << 16); }
; __device__ __forceinline__ float bfs2f(short h) { return __uint_as_float(((unsigned)(u16)h) << 16); }
; __device__ __forceinline__ unsigned pack2(float a, float b) { return (unsigned)f2bf(a) | ((unsigned)f2bf(b) << 16); }
; template <int EPI, bool HS = false>
; __device__ __forceinline__ void gemm_phase(const Params& p, const GemmCfg& g, char* shm, const int wave_s) {
;     ...
;             for (int bj = 0; bj < 2; ++bj) {
;               float2 xn;
;               xn.x = xv[j][bj].x + gt[bj][0] * acc[ai][bj][m][0][j];
;               xn.y = xv[j][bj].y + gt[bj][1] * acc[ai][bj][m][1][j];
;               const unsigned o = tb + (unsigned)((ai * 128 + m * 16 + j) * 1024 + bj * 128);
;               *(float2*)(xout_t + o) = xn;
;               if (g.has_next) *(unsigned*)(xg_t + o) = pack2(xn.x * gn[bj][0], xn.y * gn[bj][1]);
;               ss += xn.x * xn.x + xn.y * xn.y;
;             }
;             if (g.has_next) {
;               ss = dpp_row_sum16(ss);
;               if (fr == 0) rss_t[(wr * 64 + fq * 4 + ai * 128 + m * 16 + j) * 16] = ss;
;             }
.LBB0_539:
	v_add_u32_e32 v8, 0x2cc00, v0
	v_mov_b32_e32 v4, v9
	v_mov_b32_e32 v9, v1
	s_waitcnt lgkmcnt(0)
	v_pk_fma_f32 v[4:5], v[4:5], v[184:185], v[14:15]
	v_lshl_add_u64 v[10:11], v[8:9], 2, s[2:3]
	s_mov_b64 s[10:11], -1
	s_and_b64 vcc, exec, s[6:7]
	v_add_u32_e32 v0, 0x2cc80, v0
	global_store_dwordx2 v[10:11], v[4:5], off
	s_cbranch_vccnz .LBB0_543
	v_pk_mul_f32 v[10:11], v[182:183], v[4:5]
	v_lshl_add_u64 v[8:9], v[8:9], 1, s[8:9]
	s_nop 0
	s_nop 0
	v_cvt_pk_bf16_f32 v6, v10, v10
	v_cvt_pk_bf16_f32 v2, v11, v11
	v_lshrrev_b32_e32 v6, 16, v6
	v_and_or_b32 v2, v2, s28, v6
	v_mov_b32_e32 v6, v3
	global_store_dword v[8:9], v2, off
	v_pk_fma_f32 v[8:9], v[6:7], v[180:181], v[16:17]
	v_lshl_add_u64 v[10:11], v[0:1], 2, s[2:3]
	global_store_dwordx2 v[10:11], v[8:9], off
	v_pk_mul_f32 v[10:11], v[186:187], v[8:9]
	v_pk_mul_f32 v[4:5], v[4:5], v[4:5]
	s_nop 0
	s_nop 0
	v_cvt_pk_bf16_f32 v6, v10, v10
	v_cvt_pk_bf16_f32 v2, v11, v11
	v_lshrrev_b32_e32 v6, 16, v6
	v_and_or_b32 v2, v2, s28, v6
	v_lshl_add_u64 v[10:11], v[0:1], 1, s[8:9]
	v_pk_mul_f32 v[8:9], v[8:9], v[8:9]
	global_store_dword v[10:11], v2, off
	v_add_f32_e32 v2, v8, v9
	v_add_f32_e32 v4, v4, v5
	v_add_f32_e32 v2, v4, v2
	s_nop 1
	v_add_f32_dpp v2, v2, v2 quad_perm:[1,0,3,2] row_mask:0xf bank_mask:0xf bound_ctrl:1
	s_nop 1
	v_add_f32_dpp v2, v2, v2 quad_perm:[2,3,0,1] row_mask:0xf bank_mask:0xf bound_ctrl:1
	s_nop 1
	v_add_f32_dpp v2, v2, v2 row_half_mirror row_mask:0xf bank_mask:0xf bound_ctrl:1
	s_nop 1
	v_mov_b32_dpp v4, v2 row_mirror row_mask:0xf bank_mask:0xf bound_ctrl:1
	s_and_saveexec_b64 s[6:7], s[4:5]
	s_cbranch_execz .LBB0_542
	v_add_f32_e32 v2, v2, v4
	v_mov_b32_e32 v4, 0xb30
	v_lshl_add_u32 v4, v194, 4, v4
	v_ashrrev_i32_e32 v5, 31, v4
	v_lshl_add_u64 v[4:5], v[4:5], 2, v[150:151]
	global_store_dword v[4:5], v2, off

; #define WAIT_V(n) asm volatile("s_waitcnt vmcnt(" #n ")" ::: "memory")
; __device__ __forceinline__ void glds16_s(const void* sbase, unsigned voff, unsigned lds_dst) {
;   unsigned keep;
;   asm volatile("s_mov_b32 %0, m0\n\ts_mov_b32 m0, %3\n\ts_nop 2\n\tglobal_load_lds_dwordx4 %1, %2\n\ts_mov_b32 m0, %0"
;                : "=&s"(keep) : "v"(voff), "s"(sbase), "s"(lds_dst) : "memory");
; template <int EPI, bool HS = false>
; __device__ __forceinline__ void gemm_phase(const Params& p, const GemmCfg& g, char* shm, const int wave_s) {
;     ...
;       const float* xin_t = g.xin + (size_t)orow0 * 1024 + pn * 256;
;       float* xout_t = g.xout + (size_t)orow0 * 1024 + pn * 256;
;       u16* xg_t = p.h + (size_t)orow0 * 1024 + pn * 256;
;       float* rss_t = p.rowss + (size_t)orow0 * 16 + pn * 4 + wc;
;       const unsigned tb = (unsigned)((wr * 64 + fq * 4) * 1024 + wc * 32 + 2 * fr);
;       const unsigned ldsb = (unsigned)(size_t)(__attribute__((address_space(3))) char*)shm;
;       const int wv_s = __builtin_amdgcn_readfirstlane(wid);
;       constexpr int XROW = 1040;
;       const char* xl = shm + (wr * 64 + fq * 4) * XROW + (wc * 32 + 2 * fr) * 4;
; #pragma unroll
;       for (int ai = 0; ai < 2; ++ai) {
; #pragma unroll
;         for (int i = 0; i < 16; ++i) {
;           const int r = wv_s * 16 + i;
;           glds_row(xin_t + (size_t)(ai * 128 + r) * 1024, (unsigned)lane * 16u, ldsb + (unsigned)(r * XROW));
;         }
;         WAIT_V(0);
;         __syncthreads();
; #pragma unroll
;         for (int m = 0; m < 4; ++m) {
;           float2 xv[4][2];
; #pragma unroll
;           for (int j = 0; j < 4; ++j)
; #pragma unroll
;             for (int bj = 0; bj < 2; ++bj) xv[j][bj] = *(const float2*)(xl + (m * 16 + j) * XROW + bj * 512);
.LBB0_654:
	s_or_b64 exec, exec, s[0:1]
	s_mov_b32 s0, s82
	s_mov_b32 s1, -1
	v_readlane_b32 s3, v254, 56
	v_mbcnt_lo_u32_b32 v0, s1, 0
	v_mbcnt_hi_u32_b32 v0, s1, v0
	v_lshl_add_u32 v0, s0, 6, v0
	s_lshl_b64 s[0:1], s[4:5], 12
	s_add_u32 s11, s3, s0
	v_readlane_b32 s3, v254, 55
	s_addc_u32 s12, s3, s1
	s_ashr_i32 s3, s2, 31
	s_lshl_b64 s[8:9], s[2:3], 2
	s_add_u32 s71, s11, s8
	s_addc_u32 s72, s12, s9
	v_readlane_b32 s12, v253, 25
	v_readlane_b32 s24, v253, 37
	v_readlane_b32 s25, v253, 38
	s_add_u32 s0, s24, s0
	s_addc_u32 s1, s25, s1
	s_add_u32 s0, s0, s8
	s_addc_u32 s1, s1, s9
	s_lshl_b64 s[8:9], s[4:5], 11
	s_add_u32 s8, s88, s8
	s_addc_u32 s9, s89, s9
	v_lshrrev_b32_e32 v132, 2, v0
	s_lshl_b64 s[2:3], s[2:3], 1
	v_ashrrev_i32_e32 v130, 6, v0
	v_ashrrev_i32_e32 v131, 2, v0
	v_and_b32_e32 v132, 12, v132
	s_add_u32 s2, s8, s2
	s_movk_i32 s8, 0xffc0
	v_and_or_b32 v163, v131, s8, v132
	v_readfirstlane_b32 s8, v130
	s_addc_u32 s3, s9, s3
	s_movk_i32 s9, 0x410
	s_lshl_b32 s8, s8, 4
	v_and_b32_e32 v169, 3, v130
	v_readlane_b32 s13, v253, 26
	v_mul_lo_u32 v130, v163, s9
	s_ashr_i32 s9, s8, 31
	s_lshl_b64 s[12:13], s[8:9], 12
	v_and_b32_e32 v168, 15, v0
	v_lshlrev_b32_e32 v0, 4, v0
	s_add_u32 s12, s71, s12
	s_mul_i32 s73, s8, 0x410
	v_and_b32_e32 v167, 0x3f0, v0
	s_addc_u32 s13, s72, s13
	s_add_i32 s73, s73, 0
	s_mov_b32 m0, s73
	s_nop 0
	global_load_lds_dwordx4 v167, s[12:13]
	s_or_b32 s12, s8, 1
	v_readlane_b32 s14, v253, 27
	v_readlane_b32 s15, v253, 28
	s_ashr_i32 s13, s12, 31
	s_lshl_b64 s[14:15], s[12:13], 12
	s_add_u32 s14, s71, s14
	s_addc_u32 s15, s72, s15
	s_mul_i32 s74, s12, 0x410
	s_or_b32 s12, s8, 2
	s_ashr_i32 s13, s12, 31
	s_add_i32 s74, s74, 0
	s_mov_b32 m0, s74
	s_nop 0
	global_load_lds_dwordx4 v167, s[14:15]
	s_lshl_b64 s[14:15], s[12:13], 12
	s_add_u32 s14, s71, s14
	s_mulk_i32 s12, 0x410
	s_addc_u32 s15, s72, s15
	s_add_i32 s12, s12, 0
	s_mov_b32 m0, s12
	s_nop 0
	global_load_lds_dwordx4 v167, s[14:15]
	s_or_b32 s14, s8, 3
	v_readlane_b32 s16, v253, 29
	v_readlane_b32 s17, v253, 30
	s_ashr_i32 s15, s14, 31
	s_lshl_b64 s[16:17], s[14:15], 12
	s_add_u32 s16, s71, s16
	s_addc_u32 s17, s72, s17
	s_mul_i32 s13, s14, 0x410
	s_or_b32 s14, s8, 4
	s_ashr_i32 s15, s14, 31
	s_add_i32 s13, s13, 0
	s_mov_b32 m0, s13
	s_nop 0
	global_load_lds_dwordx4 v167, s[16:17]
	s_lshl_b64 s[16:17], s[14:15], 12
	s_add_u32 s16, s71, s16
	s_mulk_i32 s14, 0x410
	s_addc_u32 s17, s72, s17
	s_add_i32 s14, s14, 0
	s_mov_b32 m0, s14
	s_nop 0
	global_load_lds_dwordx4 v167, s[16:17]
	s_or_b32 s16, s8, 5
	v_readlane_b32 s18, v253, 31
	v_readlane_b32 s19, v253, 32
	s_ashr_i32 s17, s16, 31
	s_lshl_b64 s[18:19], s[16:17], 12
	s_add_u32 s18, s71, s18
	s_addc_u32 s19, s72, s19
	s_mul_i32 s15, s16, 0x410
	s_or_b32 s16, s8, 6
	s_ashr_i32 s17, s16, 31
	s_add_i32 s15, s15, 0
	s_mov_b32 m0, s15
	s_nop 0
	global_load_lds_dwordx4 v167, s[18:19]
	s_lshl_b64 s[18:19], s[16:17], 12
	s_add_u32 s18, s71, s18
	s_mulk_i32 s16, 0x410
	s_addc_u32 s19, s72, s19
	s_add_i32 s16, s16, 0
	s_mov_b32 m0, s16
	s_nop 0
	global_load_lds_dwordx4 v167, s[18:19]
	s_or_b32 s18, s8, 7
	v_readlane_b32 s20, v253, 33
	v_readlane_b32 s21, v253, 34
	s_ashr_i32 s19, s18, 31
	s_lshl_b64 s[20:21], s[18:19], 12
	s_add_u32 s20, s71, s20
	s_addc_u32 s21, s72, s21
	s_mul_i32 s17, s18, 0x410
	s_or_b32 s18, s8, 8
	s_ashr_i32 s19, s18, 31
	s_add_i32 s17, s17, 0
	s_mov_b32 m0, s17
	s_nop 0
	global_load_lds_dwordx4 v167, s[20:21]
	s_lshl_b64 s[20:21], s[18:19], 12
	s_add_u32 s20, s71, s20
	s_mulk_i32 s18, 0x410
	s_addc_u32 s21, s72, s21
	s_add_i32 s18, s18, 0
	s_mov_b32 m0, s18
	s_nop 0
	global_load_lds_dwordx4 v167, s[20:21]
	s_or_b32 s20, s8, 9
	v_readlane_b32 s22, v253, 35
	v_readlane_b32 s23, v253, 36
	s_ashr_i32 s21, s20, 31
	s_lshl_b64 s[22:23], s[20:21], 12
	s_add_u32 s22, s71, s22
	s_addc_u32 s23, s72, s23
	s_mul_i32 s19, s20, 0x410
	s_or_b32 s20, s8, 10
	s_ashr_i32 s21, s20, 31
	s_add_i32 s19, s19, 0
	s_mov_b32 m0, s19
	s_nop 0
	global_load_lds_dwordx4 v167, s[22:23]
	s_lshl_b64 s[22:23], s[20:21], 12
	s_add_u32 s22, s71, s22
	s_mulk_i32 s20, 0x410
	s_addc_u32 s23, s72, s23
	s_add_i32 s20, s20, 0
	s_mov_b32 m0, s20
	s_nop 0
	global_load_lds_dwordx4 v167, s[22:23]
	s_or_b32 s22, s8, 11
	s_ashr_i32 s23, s22, 31
	s_lshl_b64 s[24:25], s[22:23], 12
	s_add_u32 s24, s71, s24
	s_addc_u32 s25, s72, s25
	s_mul_i32 s21, s22, 0x410
	s_or_b32 s22, s8, 12
	s_ashr_i32 s23, s22, 31
	s_add_i32 s21, s21, 0
	s_mov_b32 m0, s21
	s_nop 0
	global_load_lds_dwordx4 v167, s[24:25]
	s_lshl_b64 s[24:25], s[22:23], 12
	s_add_u32 s24, s71, s24
	s_mulk_i32 s22, 0x410
	s_addc_u32 s25, s72, s25
	s_add_i32 s22, s22, 0
	s_mov_b32 m0, s22
	s_nop 0
	global_load_lds_dwordx4 v167, s[24:25]
	s_or_b32 s24, s8, 13
	v_readlane_b32 s26, v253, 39
	v_readlane_b32 s27, v253, 40
	s_ashr_i32 s25, s24, 31
	s_lshl_b64 s[26:27], s[24:25], 12
	s_add_u32 s26, s71, s26
	s_addc_u32 s27, s72, s27
	s_mul_i32 s23, s24, 0x410
	s_or_b32 s24, s8, 14
	s_ashr_i32 s25, s24, 31
	s_add_i32 s23, s23, 0
	s_mov_b32 m0, s23
	s_nop 0
	global_load_lds_dwordx4 v167, s[26:27]
	s_lshl_b64 s[26:27], s[24:25], 12
	s_add_u32 s26, s71, s26
	s_mulk_i32 s24, 0x410
	v_lshlrev_b32_e32 v132, 5, v169
	v_lshlrev_b32_e32 v133, 1, v168
	s_addc_u32 s27, s72, s27
	s_add_i32 s24, s24, 0
	s_mov_b32 m0, s24
	s_nop 0
	global_load_lds_dwordx4 v167, s[26:27]
	s_or_b32 s26, s8, 15
	v_or_b32_e32 v134, v132, v133
	s_ashr_i32 s27, s26, 31
	v_add_u32_e32 v130, 0, v130
	v_lshlrev_b32_e32 v134, 2, v134
	s_lshl_b64 s[76:77], s[26:27], 12
	v_add_u32_e32 v164, v130, v134
	s_add_u32 s76, s71, s76
	s_mul_i32 s25, s26, 0x410
	v_lshlrev_b32_e32 v131, 10, v163
	s_addc_u32 s77, s72, s77
	s_add_i32 s25, s25, 0
	s_mov_b32 m0, s25
	s_nop 0
	global_load_lds_dwordx4 v167, s[76:77]
	v_add_u32_e32 v165, 32, v164
	v_add_u32_e32 v166, 48, v164
	v_or3_b32 v0, v131, v133, v132
	s_waitcnt vmcnt(0)
	s_barrier
	ds_read2st64_b64 v[142:145], v164 offset1:1
	ds_read2_b64 v[138:141], v164 offset0:130 offset1:194
	ds_read2st64_b64 v[134:137], v165 offset0:4 offset1:5
	ds_read2st64_b64 v[130:133], v166 offset0:6 offset1:7
	v_readlane_b32 s26, v254, 60
	v_mov_b32_e32 v156, v122
	v_mov_b32_e32 v157, v126
	v_readlane_b32 s27, v254, 61
	s_waitcnt lgkmcnt(3)
	v_pk_fma_f32 v[158:159], v[154:155], v[156:157], v[142:143]
	v_lshl_add_u64 v[160:161], v[0:1], 2, s[0:1]
	s_and_b64 vcc, exec, s[26:27]
	v_lshl_add_u64 v[156:157], v[0:1], 1, s[2:3]
	global_store_dwordx2 v[160:161], v[158:159], off
	s_cbranch_vccz .LBB0_656
	v_pk_mul_f32 v[142:143], v[148:149], v[158:159]
	s_nop 0
	s_nop 0
	s_nop 0
	v_cvt_pk_bf16_f32 v126, v142, v142
	v_cvt_pk_bf16_f32 v122, v143, v143
	v_lshrrev_b32_e32 v126, 16, v126
	v_and_or_b32 v122, v122, s28, v126
	global_store_dword v[156:157], v122, off
; __device__ __forceinline__ u16 f2bf(float f) {
;   unsigned u = __float_as_uint(f);
;   u += 0x7fffu + ((u >> 16) & 1u);
;   return (u16)(u >> 16);
; }
; __device__ __forceinline__ float bf2f(u16 h) { return __uint_as_float(((unsigned)h) << 16); }
; __device__ __forceinline__ float bfs2f(short h) { return __uint_as_float(((unsigned)(u16)h) << 16); }
; __device__ __forceinline__ unsigned pack2(float a, float b) { return (unsigned)f2bf(a) | ((unsigned)f2bf(b) << 16); }
; template <int EPI, bool HS = false>
; __device__ __forceinline__ void gemm_phase(const Params& p, const GemmCfg& g, char* shm, const int wave_s) {
;     ...
;       float* rss_t = p.rowss + (size_t)orow0 * 16 + pn * 4 + wc;
;     ...
;             for (int bj = 0; bj < 2; ++bj) {
;               float2 xn;
;               xn.x = xv[j][bj].x + gt[bj][0] * acc[ai][bj][m][0][j];
;               xn.y = xv[j][bj].y + gt[bj][1] * acc[ai][bj][m][1][j];
;               const unsigned o = tb + (unsigned)((ai * 128 + m * 16 + j) * 1024 + bj * 128);
;               *(float2*)(xout_t + o) = xn;
;               if (g.has_next) *(unsigned*)(xg_t + o) = pack2(xn.x * gn[bj][0], xn.y * gn[bj][1]);
;               ss += xn.x * xn.x + xn.y * xn.y;
;             }
;             if (g.has_next) {
;               ss = dpp_row_sum16(ss);
;               if (fr == 0) rss_t[(wr * 64 + fq * 4 + ai * 128 + m * 16 + j) * 16] = ss;
;             }
.LBB0_656:
	v_readlane_b32 s36, v252, 0
	s_lshl_b64 s[4:5], s[4:5], 6
	v_readlane_b32 s42, v252, 6
	v_readlane_b32 s43, v252, 7
	s_add_u32 s11, s42, s4
	s_addc_u32 s26, s43, s5
	s_lshl_b32 s4, s10, 2
	s_ashr_i32 s5, s4, 31
	s_lshl_b64 s[4:5], s[4:5], 2
	s_add_u32 s4, s11, s4
	s_addc_u32 s5, s26, s5
	v_lshlrev_b32_e32 v142, 2, v169
	v_mov_b32_e32 v143, v1
	v_lshl_add_u64 v[142:143], s[4:5], 0, v[142:143]
	v_cmp_eq_u32_e64 s[4:5], 0, v168
	v_mov_b32_e32 v168, v114
	v_mov_b32_e32 v169, v118
	v_pk_fma_f32 v[144:145], v[150:151], v[168:169], v[144:145]
	s_and_b64 vcc, exec, s[6:7]
	s_mov_b64 s[10:11], -1
	v_readlane_b32 s37, v252, 1
	v_readlane_b32 s38, v252, 2
	v_readlane_b32 s39, v252, 3
	v_readlane_b32 s40, v252, 4
	v_readlane_b32 s41, v252, 5
	global_store_dwordx2 v[160:161], v[144:145], off offset:512
	s_cbranch_vccnz .LBB0_662
	v_pk_mul_f32 v[160:161], v[152:153], v[144:145]
	v_pk_mul_f32 v[158:159], v[158:159], v[158:159]
	s_nop 0
	s_nop 0
	v_cvt_pk_bf16_f32 v118, v160, v160
	v_cvt_pk_bf16_f32 v114, v161, v161
	v_lshrrev_b32_e32 v118, 16, v118
	v_and_or_b32 v114, v114, s28, v118
	v_pk_mul_f32 v[144:145], v[144:145], v[144:145]
	global_store_dword v[156:157], v114, off offset:256
	v_add_f32_e32 v114, v144, v145
	v_add_f32_e32 v118, v158, v159
	v_add_f32_e32 v114, v118, v114
	s_nop 1
	v_add_f32_dpp v114, v114, v114 quad_perm:[1,0,3,2] row_mask:0xf bank_mask:0xf bound_ctrl:1
	s_nop 1
	v_add_f32_dpp v114, v114, v114 quad_perm:[2,3,0,1] row_mask:0xf bank_mask:0xf bound_ctrl:1
	s_nop 1
	v_add_f32_dpp v114, v114, v114 row_half_mirror row_mask:0xf bank_mask:0xf bound_ctrl:1
	s_nop 1
	v_mov_b32_dpp v118, v114 row_mirror row_mask:0xf bank_mask:0xf bound_ctrl:1
	s_and_saveexec_b64 s[10:11], s[4:5]
	s_cbranch_execz .LBB0_659
	v_lshlrev_b32_e32 v144, 4, v163
	v_ashrrev_i32_e32 v145, 31, v144
	v_add_f32_e32 v114, v114, v118
	v_lshl_add_u64 v[144:145], v[144:145], 2, v[142:143]
	global_store_dword v[144:145], v114, off
.LBB0_659:
	s_or_b64 exec, exec, s[10:11]
	v_or_b32_e32 v144, 0x400, v0
	v_mov_b32_e32 v126, v123
	v_mov_b32_e32 v145, v1
	s_waitcnt lgkmcnt(2)
	v_pk_fma_f32 v[158:159], v[154:155], v[126:127], v[138:139]
	v_lshl_add_u64 v[144:145], v[144:145], 2, s[0:1]
	global_store_dwordx2 v[144:145], v[158:159], off
	v_pk_mul_f32 v[144:145], v[148:149], v[158:159]
	v_or_b32_e32 v160, 0x480, v0
	s_nop 0
	s_nop 0
	v_cvt_pk_bf16_f32 v118, v144, v144
	v_cvt_pk_bf16_f32 v114, v145, v145
	v_lshrrev_b32_e32 v118, 16, v118
	v_and_or_b32 v114, v114, s28, v118
	v_mov_b32_e32 v118, v115
	v_mov_b32_e32 v161, v1
	v_pk_fma_f32 v[144:145], v[150:151], v[118:119], v[140:141]
	v_lshl_add_u64 v[160:161], v[160:161], 2, s[0:1]
	global_store_dword v[156:157], v114, off offset:2048
	global_store_dwordx2 v[160:161], v[144:145], off
	v_pk_mul_f32 v[160:161], v[152:153], v[144:145]
	v_pk_mul_f32 v[158:159], v[158:159], v[158:159]
	s_nop 0
	s_nop 0
	v_cvt_pk_bf16_f32 v118, v160, v160
	v_cvt_pk_bf16_f32 v114, v161, v161
	v_lshrrev_b32_e32 v118, 16, v118
	v_and_or_b32 v114, v114, s28, v118
	v_pk_mul_f32 v[144:145], v[144:145], v[144:145]
	global_store_dword v[156:157], v114, off offset:2304
	v_add_f32_e32 v114, v144, v145
	v_add_f32_e32 v118, v158, v159
	v_add_f32_e32 v114, v118, v114
	s_nop 1
	v_add_f32_dpp v114, v114, v114 quad_perm:[1,0,3,2] row_mask:0xf bank_mask:0xf bound_ctrl:1
	s_nop 1
	v_add_f32_dpp v114, v114, v114 quad_perm:[2,3,0,1] row_mask:0xf bank_mask:0xf bound_ctrl:1
	s_nop 1
	v_add_f32_dpp v114, v114, v114 row_half_mirror row_mask:0xf bank_mask:0xf bound_ctrl:1
	s_nop 1
	v_mov_b32_dpp v118, v114 row_mirror row_mask:0xf bank_mask:0xf bound_ctrl:1
	s_and_saveexec_b64 s[10:11], s[4:5]
	s_cbranch_execz .LBB0_661
	v_lshlrev_b32_e32 v144, 4, v163
	v_ashrrev_i32_e32 v145, 31, v144
	v_add_f32_e32 v114, v114, v118
	v_lshl_add_u64 v[144:145], v[144:145], 2, v[142:143]
	global_store_dword v[144:145], v114, off offset:64

; __device__ __forceinline__ u16 f2bf(float f) {
;   unsigned u = __float_as_uint(f);
;   u += 0x7fffu + ((u >> 16) & 1u);
;   return (u16)(u >> 16);
; }
; __device__ __forceinline__ float bf2f(u16 h) { return __uint_as_float(((unsigned)h) << 16); }
; __device__ __forceinline__ float bfs2f(short h) { return __uint_as_float(((unsigned)(u16)h) << 16); }
; __device__ __forceinline__ unsigned pack2(float a, float b) { return (unsigned)f2bf(a) | ((unsigned)f2bf(b) << 16); }
; template <int EPI, bool HS = false>
; __device__ __forceinline__ void gemm_phase(const Params& p, const GemmCfg& g, char* shm, const int wave_s) {
;     ...
;             for (int bj = 0; bj < 2; ++bj) {
;               float2 xn;
;               xn.x = xv[j][bj].x + gt[bj][0] * acc[ai][bj][m][0][j];
;               xn.y = xv[j][bj].y + gt[bj][1] * acc[ai][bj][m][1][j];
;               const unsigned o = tb + (unsigned)((ai * 128 + m * 16 + j) * 1024 + bj * 128);
;               *(float2*)(xout_t + o) = xn;
;               if (g.has_next) *(unsigned*)(xg_t + o) = pack2(xn.x * gn[bj][0], xn.y * gn[bj][1]);
;               ss += xn.x * xn.x + xn.y * xn.y;
;             }
;             if (g.has_next) {
;               ss = dpp_row_sum16(ss);
;               if (fr == 0) rss_t[(wr * 64 + fq * 4 + ai * 128 + m * 16 + j) * 16] = ss;
;             }
.LBB0_664:
	v_or_b32_e32 v122, 0x800, v0
	v_mov_b32_e32 v114, v124
	v_mov_b32_e32 v115, v128
	v_mov_b32_e32 v123, v1
	s_waitcnt lgkmcnt(1)
	v_pk_fma_f32 v[118:119], v[154:155], v[114:115], v[134:135]
	v_lshl_add_u64 v[114:115], v[122:123], 2, s[0:1]
	global_store_dwordx2 v[114:115], v[118:119], off
	s_mov_b64 s[10:11], -1
	s_and_b64 vcc, exec, s[6:7]
	v_or_b32_e32 v114, 0x880, v0
	s_mov_b32 s42, 0x800000
	s_cbranch_vccnz .LBB0_668
	v_pk_mul_f32 v[126:127], v[148:149], v[118:119]
	v_lshl_add_u64 v[122:123], v[122:123], 1, s[2:3]
	s_nop 0
	s_nop 0
	v_cvt_pk_bf16_f32 v124, v126, v126
	v_cvt_pk_bf16_f32 v115, v127, v127
	v_lshrrev_b32_e32 v124, 16, v124
	v_and_or_b32 v115, v115, s28, v124
	global_store_dword v[122:123], v115, off
	v_mov_b32_e32 v122, v116
	v_mov_b32_e32 v123, v120
	v_mov_b32_e32 v115, v1
	v_pk_fma_f32 v[122:123], v[150:151], v[122:123], v[136:137]
	v_lshl_add_u64 v[126:127], v[114:115], 2, s[0:1]
	global_store_dwordx2 v[126:127], v[122:123], off
	v_pk_mul_f32 v[126:127], v[152:153], v[122:123]
	v_pk_mul_f32 v[118:119], v[118:119], v[118:119]
	v_and_b32_sdwa v128, v126, v178 dst_sel:DWORD dst_unused:UNUSED_PAD src0_sel:WORD_1 src1_sel:DWORD
	s_nop 0
	v_add3_u32 v126, v126, v128, s81
	v_cvt_pk_bf16_f32 v124, v127, v127
	v_lshrrev_b32_e32 v126, 16, v126
	v_pk_mul_f32 v[122:123], v[122:123], v[122:123]
	v_and_or_b32 v124, v124, s28, v126
	v_lshl_add_u64 v[126:127], v[114:115], 1, s[2:3]
	v_add_f32_e32 v115, v122, v123
	v_add_f32_e32 v118, v118, v119
	v_add_f32_e32 v115, v118, v115
	global_store_dword v[126:127], v124, off
	s_nop 0
	v_add_f32_dpp v115, v115, v115 quad_perm:[1,0,3,2] row_mask:0xf bank_mask:0xf bound_ctrl:1
	s_nop 1
	v_add_f32_dpp v115, v115, v115 quad_perm:[2,3,0,1] row_mask:0xf bank_mask:0xf bound_ctrl:1
	s_nop 1
	v_add_f32_dpp v115, v115, v115 row_half_mirror row_mask:0xf bank_mask:0xf bound_ctrl:1
	s_nop 1
	v_mov_b32_dpp v118, v115 row_mirror row_mask:0xf bank_mask:0xf bound_ctrl:1
	s_and_saveexec_b64 s[10:11], s[4:5]
	s_cbranch_execz .LBB0_667
	v_add_f32_e32 v115, v115, v118
	v_lshlrev_b32_e32 v118, 4, v163
	v_ashrrev_i32_e32 v119, 31, v118
	v_lshl_add_u64 v[118:119], v[118:119], 2, v[142:143]
	global_store_dword v[118:119], v115, off offset:128

; __device__ __forceinline__ u16 f2bf(float f) {
;   unsigned u = __float_as_uint(f);
;   u += 0x7fffu + ((u >> 16) & 1u);
;   return (u16)(u >> 16);
; }
; __device__ __forceinline__ float bf2f(u16 h) { return __uint_as_float(((unsigned)h) << 16); }
; __device__ __forceinline__ float bfs2f(short h) { return __uint_as_float(((unsigned)(u16)h) << 16); }
; __device__ __forceinline__ unsigned pack2(float a, float b) { return (unsigned)f2bf(a) | ((unsigned)f2bf(b) << 16); }
; template <int EPI, bool HS = false>
; __device__ __forceinline__ void gemm_phase(const Params& p, const GemmCfg& g, char* shm, const int wave_s) {
;     ...
;             for (int bj = 0; bj < 2; ++bj) {
;               float2 xn;
;               xn.x = xv[j][bj].x + gt[bj][0] * acc[ai][bj][m][0][j];
;               xn.y = xv[j][bj].y + gt[bj][1] * acc[ai][bj][m][1][j];
;               const unsigned o = tb + (unsigned)((ai * 128 + m * 16 + j) * 1024 + bj * 128);
;               *(float2*)(xout_t + o) = xn;
;               if (g.has_next) *(unsigned*)(xg_t + o) = pack2(xn.x * gn[bj][0], xn.y * gn[bj][1]);
;               ss += xn.x * xn.x + xn.y * xn.y;
;             }
;             if (g.has_next) {
;               ss = dpp_row_sum16(ss);
;               if (fr == 0) rss_t[(wr * 64 + fq * 4 + ai * 128 + m * 16 + j) * 16] = ss;
;             }
.LBB0_670:
	v_or_b32_e32 v122, 0xc00, v0
	v_mov_b32_e32 v128, v125
	v_mov_b32_e32 v123, v1
	s_waitcnt lgkmcnt(0)
	v_pk_fma_f32 v[118:119], v[154:155], v[128:129], v[130:131]
	v_lshl_add_u64 v[114:115], v[122:123], 2, s[0:1]
	global_store_dwordx2 v[114:115], v[118:119], off
	s_mov_b64 s[10:11], -1
	s_and_b64 vcc, exec, s[6:7]
	v_or_b32_e32 v114, 0xc80, v0
	s_cbranch_vccnz .LBB0_674
	v_pk_mul_f32 v[124:125], v[148:149], v[118:119]
	v_lshl_add_u64 v[122:123], v[122:123], 1, s[2:3]
	s_nop 0
	s_nop 0
	v_cvt_pk_bf16_f32 v116, v124, v124
	v_cvt_pk_bf16_f32 v115, v125, v125
	v_lshrrev_b32_e32 v116, 16, v116
	v_and_or_b32 v115, v115, s28, v116
	global_store_dword v[122:123], v115, off
	v_mov_b32_e32 v120, v117
	v_mov_b32_e32 v115, v1
	v_pk_fma_f32 v[122:123], v[150:151], v[120:121], v[132:133]
	v_lshl_add_u64 v[124:125], v[114:115], 2, s[0:1]
	global_store_dwordx2 v[124:125], v[122:123], off
	v_pk_mul_f32 v[124:125], v[152:153], v[122:123]
	v_pk_mul_f32 v[118:119], v[118:119], v[118:119]
	s_nop 0
	s_nop 0
	v_cvt_pk_bf16_f32 v120, v124, v124
	v_cvt_pk_bf16_f32 v116, v125, v125
	v_lshrrev_b32_e32 v120, 16, v120
	v_and_or_b32 v116, v116, s28, v120
	v_lshl_add_u64 v[124:125], v[114:115], 1, s[2:3]
	v_pk_mul_f32 v[122:123], v[122:123], v[122:123]
	global_store_dword v[124:125], v116, off
	v_add_f32_e32 v115, v122, v123
	v_add_f32_e32 v116, v118, v119
	v_add_f32_e32 v115, v116, v115
	s_nop 1
	v_add_f32_dpp v115, v115, v115 quad_perm:[1,0,3,2] row_mask:0xf bank_mask:0xf bound_ctrl:1
	s_nop 1
	v_add_f32_dpp v115, v115, v115 quad_perm:[2,3,0,1] row_mask:0xf bank_mask:0xf bound_ctrl:1
	s_nop 1
	v_add_f32_dpp v115, v115, v115 row_half_mirror row_mask:0xf bank_mask:0xf bound_ctrl:1
	s_nop 1
	v_mov_b32_dpp v116, v115 row_mirror row_mask:0xf bank_mask:0xf bound_ctrl:1
	s_and_saveexec_b64 s[10:11], s[4:5]
	s_cbranch_execz .LBB0_673
	v_lshlrev_b32_e32 v118, 4, v163
	v_ashrrev_i32_e32 v119, 31, v118
	v_add_f32_e32 v115, v115, v116
	v_lshl_add_u64 v[118:119], v[118:119], 2, v[142:143]
	global_store_dword v[118:119], v115, off offset:192

; __device__ __forceinline__ u16 f2bf(float f) {
;   unsigned u = __float_as_uint(f);
;   u += 0x7fffu + ((u >> 16) & 1u);
;   return (u16)(u >> 16);
; }
; __device__ __forceinline__ float bf2f(u16 h) { return __uint_as_float(((unsigned)h) << 16); }
; __device__ __forceinline__ float bfs2f(short h) { return __uint_as_float(((unsigned)(u16)h) << 16); }
; __device__ __forceinline__ unsigned pack2(float a, float b) { return (unsigned)f2bf(a) | ((unsigned)f2bf(b) << 16); }
; template <int EPI, bool HS = false>
; __device__ __forceinline__ void gemm_phase(const Params& p, const GemmCfg& g, char* shm, const int wave_s) {
;     ...
;         for (int m = 0; m < 4; ++m) {
;           float2 xv[4][2];
; #pragma unroll
;           for (int j = 0; j < 4; ++j)
; #pragma unroll
;             for (int bj = 0; bj < 2; ++bj) xv[j][bj] = *(const float2*)(xl + (m * 16 + j) * XROW + bj * 512);
; #pragma unroll
;           for (int j = 0; j < 4; ++j) {
;             float ss = 0.f;
; #pragma unroll
;             for (int bj = 0; bj < 2; ++bj) {
;               float2 xn;
;               xn.x = xv[j][bj].x + gt[bj][0] * acc[ai][bj][m][0][j];
;               xn.y = xv[j][bj].y + gt[bj][1] * acc[ai][bj][m][1][j];
;               const unsigned o = tb + (unsigned)((ai * 128 + m * 16 + j) * 1024 + bj * 128);
;               *(float2*)(xout_t + o) = xn;
;               if (g.has_next) *(unsigned*)(xg_t + o) = pack2(xn.x * gn[bj][0], xn.y * gn[bj][1]);
;               ss += xn.x * xn.x + xn.y * xn.y;
;             }
;             if (g.has_next) {
;               ss = dpp_row_sum16(ss);
;               if (fr == 0) rss_t[(wr * 64 + fq * 4 + ai * 128 + m * 16 + j) * 16] = ss;
;             }
.LBB0_676:
	v_add_u32_e32 v134, 0x100, v164
	ds_read2st64_b64 v[126:129], v134 offset0:32 offset1:33
	v_add_u32_e32 v135, 0x110, v164
	v_add_u32_e32 v136, 0x120, v164
	v_add_u32_e32 v137, 0x130, v164
	ds_read2st64_b64 v[122:125], v135 offset0:34 offset1:35
	ds_read2st64_b64 v[118:121], v136 offset0:36 offset1:37
	ds_read2st64_b64 v[114:117], v137 offset0:38 offset1:39
	v_or_b32_e32 v132, 0x4000, v0
	v_mov_b32_e32 v130, v106
	v_mov_b32_e32 v131, v110
	v_mov_b32_e32 v133, v1
	s_waitcnt lgkmcnt(3)
	v_pk_fma_f32 v[130:131], v[154:155], v[130:131], v[126:127]
	v_lshl_add_u64 v[126:127], v[132:133], 2, s[0:1]
	global_store_dwordx2 v[126:127], v[130:131], off
	s_mov_b64 s[10:11], -1
	s_and_b64 vcc, exec, s[6:7]
	v_or_b32_e32 v126, 0x4080, v0
	s_cbranch_vccnz .LBB0_680
	v_pk_mul_f32 v[138:139], v[148:149], v[130:131]
	v_lshl_add_u64 v[132:133], v[132:133], 1, s[2:3]
	s_nop 0
	s_nop 0
	v_cvt_pk_bf16_f32 v110, v138, v138
	v_cvt_pk_bf16_f32 v106, v139, v139
	v_lshrrev_b32_e32 v110, 16, v110
	v_and_or_b32 v106, v106, s28, v110
	global_store_dword v[132:133], v106, off
	v_mov_b32_e32 v132, v98
	v_mov_b32_e32 v133, v102
	v_mov_b32_e32 v127, v1
	v_pk_fma_f32 v[132:133], v[150:151], v[132:133], v[128:129]
	v_lshl_add_u64 v[138:139], v[126:127], 2, s[0:1]
	global_store_dwordx2 v[138:139], v[132:133], off
	v_pk_mul_f32 v[138:139], v[152:153], v[132:133]
	v_pk_mul_f32 v[130:131], v[130:131], v[130:131]
	s_nop 0
	s_nop 0
	v_cvt_pk_bf16_f32 v110, v138, v138
	v_cvt_pk_bf16_f32 v106, v139, v139
	v_lshrrev_b32_e32 v110, 16, v110
	v_and_or_b32 v106, v106, s28, v110
	v_lshl_add_u64 v[138:139], v[126:127], 1, s[2:3]
	v_pk_mul_f32 v[132:133], v[132:133], v[132:133]
	global_store_dword v[138:139], v106, off
	v_add_f32_e32 v106, v132, v133
	v_add_f32_e32 v110, v130, v131
	v_add_f32_e32 v106, v110, v106
	s_nop 1
	v_add_f32_dpp v106, v106, v106 quad_perm:[1,0,3,2] row_mask:0xf bank_mask:0xf bound_ctrl:1
	s_nop 1
	v_add_f32_dpp v106, v106, v106 quad_perm:[2,3,0,1] row_mask:0xf bank_mask:0xf bound_ctrl:1
	s_nop 1
	v_add_f32_dpp v106, v106, v106 row_half_mirror row_mask:0xf bank_mask:0xf bound_ctrl:1
	s_nop 1
	v_mov_b32_dpp v110, v106 row_mirror row_mask:0xf bank_mask:0xf bound_ctrl:1
	s_and_saveexec_b64 s[10:11], s[4:5]
	s_cbranch_execz .LBB0_679
	v_lshlrev_b32_e32 v130, 4, v163
	v_ashrrev_i32_e32 v131, 31, v130
	v_add_f32_e32 v106, v106, v110
	v_lshl_add_u64 v[130:131], v[130:131], 2, v[142:143]
	global_store_dword v[130:131], v106, off offset:1024

; __device__ __forceinline__ u16 f2bf(float f) {
;   unsigned u = __float_as_uint(f);
;   u += 0x7fffu + ((u >> 16) & 1u);
;   return (u16)(u >> 16);
; }
; __device__ __forceinline__ float bf2f(u16 h) { return __uint_as_float(((unsigned)h) << 16); }
; __device__ __forceinline__ float bfs2f(short h) { return __uint_as_float(((unsigned)(u16)h) << 16); }
; __device__ __forceinline__ unsigned pack2(float a, float b) { return (unsigned)f2bf(a) | ((unsigned)f2bf(b) << 16); }
; template <int EPI, bool HS = false>
; __device__ __forceinline__ void gemm_phase(const Params& p, const GemmCfg& g, char* shm, const int wave_s) {
;     ...
;             for (int bj = 0; bj < 2; ++bj) {
;               float2 xn;
;               xn.x = xv[j][bj].x + gt[bj][0] * acc[ai][bj][m][0][j];
;               xn.y = xv[j][bj].y + gt[bj][1] * acc[ai][bj][m][1][j];
;               const unsigned o = tb + (unsigned)((ai * 128 + m * 16 + j) * 1024 + bj * 128);
;               *(float2*)(xout_t + o) = xn;
;               if (g.has_next) *(unsigned*)(xg_t + o) = pack2(xn.x * gn[bj][0], xn.y * gn[bj][1]);
;               ss += xn.x * xn.x + xn.y * xn.y;
;             }
;             if (g.has_next) {
;               ss = dpp_row_sum16(ss);
;               if (fr == 0) rss_t[(wr * 64 + fq * 4 + ai * 128 + m * 16 + j) * 16] = ss;
;             }
.LBB0_682:
	v_or_b32_e32 v126, 0x4400, v0
	v_mov_b32_e32 v110, v107
	v_mov_b32_e32 v127, v1
	s_waitcnt lgkmcnt(2)
	v_pk_fma_f32 v[110:111], v[154:155], v[110:111], v[122:123]
	v_lshl_add_u64 v[106:107], v[126:127], 2, s[0:1]
	global_store_dwordx2 v[106:107], v[110:111], off
	s_mov_b64 s[10:11], -1
	s_and_b64 vcc, exec, s[6:7]
	v_or_b32_e32 v106, 0x4480, v0
	s_cbranch_vccnz .LBB0_686
	v_pk_mul_f32 v[122:123], v[148:149], v[110:111]
	v_mov_b32_e32 v107, v1
	s_nop 0
	s_nop 0
	v_cvt_pk_bf16_f32 v102, v122, v122
	v_cvt_pk_bf16_f32 v98, v123, v123
	v_lshrrev_b32_e32 v102, 16, v102
	v_and_or_b32 v98, v98, s28, v102
	v_lshl_add_u64 v[122:123], v[126:127], 1, s[2:3]
	v_mov_b32_e32 v102, v99
	global_store_dword v[122:123], v98, off
	v_pk_fma_f32 v[122:123], v[150:151], v[102:103], v[124:125]
	v_lshl_add_u64 v[126:127], v[106:107], 2, s[0:1]
	global_store_dwordx2 v[126:127], v[122:123], off
	v_pk_mul_f32 v[126:127], v[152:153], v[122:123]
	v_pk_mul_f32 v[110:111], v[110:111], v[110:111]
	s_nop 0
	s_nop 0
	v_cvt_pk_bf16_f32 v102, v126, v126
	v_cvt_pk_bf16_f32 v98, v127, v127
	v_lshrrev_b32_e32 v102, 16, v102
	v_and_or_b32 v98, v98, s28, v102
	v_lshl_add_u64 v[126:127], v[106:107], 1, s[2:3]
	v_pk_mul_f32 v[122:123], v[122:123], v[122:123]
	global_store_dword v[126:127], v98, off
	v_add_f32_e32 v98, v122, v123
	v_add_f32_e32 v102, v110, v111
	v_add_f32_e32 v98, v102, v98
	s_nop 1
	v_add_f32_dpp v98, v98, v98 quad_perm:[1,0,3,2] row_mask:0xf bank_mask:0xf bound_ctrl:1
	s_nop 1
	v_add_f32_dpp v98, v98, v98 quad_perm:[2,3,0,1] row_mask:0xf bank_mask:0xf bound_ctrl:1
	s_nop 1
	v_add_f32_dpp v98, v98, v98 row_half_mirror row_mask:0xf bank_mask:0xf bound_ctrl:1
	s_nop 1
	v_mov_b32_dpp v102, v98 row_mirror row_mask:0xf bank_mask:0xf bound_ctrl:1
	s_and_saveexec_b64 s[10:11], s[4:5]
	s_cbranch_execz .LBB0_685
	v_lshlrev_b32_e32 v110, 4, v163
	v_ashrrev_i32_e32 v111, 31, v110
	v_add_f32_e32 v98, v98, v102
	v_lshl_add_u64 v[110:111], v[110:111], 2, v[142:143]
	global_store_dword v[110:111], v98, off offset:1088

; __device__ __forceinline__ u16 f2bf(float f) {
;   unsigned u = __float_as_uint(f);
;   u += 0x7fffu + ((u >> 16) & 1u);
;   return (u16)(u >> 16);
; }
; __device__ __forceinline__ float bf2f(u16 h) { return __uint_as_float(((unsigned)h) << 16); }
; __device__ __forceinline__ float bfs2f(short h) { return __uint_as_float(((unsigned)(u16)h) << 16); }
; __device__ __forceinline__ unsigned pack2(float a, float b) { return (unsigned)f2bf(a) | ((unsigned)f2bf(b) << 16); }
; template <int EPI, bool HS = false>
; __device__ __forceinline__ void gemm_phase(const Params& p, const GemmCfg& g, char* shm, const int wave_s) {
;     ...
;             for (int bj = 0; bj < 2; ++bj) {
;               float2 xn;
;               xn.x = xv[j][bj].x + gt[bj][0] * acc[ai][bj][m][0][j];
;               xn.y = xv[j][bj].y + gt[bj][1] * acc[ai][bj][m][1][j];
;               const unsigned o = tb + (unsigned)((ai * 128 + m * 16 + j) * 1024 + bj * 128);
;               *(float2*)(xout_t + o) = xn;
;               if (g.has_next) *(unsigned*)(xg_t + o) = pack2(xn.x * gn[bj][0], xn.y * gn[bj][1]);
;               ss += xn.x * xn.x + xn.y * xn.y;
;             }
;             if (g.has_next) {
;               ss = dpp_row_sum16(ss);
;               if (fr == 0) rss_t[(wr * 64 + fq * 4 + ai * 128 + m * 16 + j) * 16] = ss;
;             }
.LBB0_688:
	v_or_b32_e32 v106, 0x4800, v0
	v_mov_b32_e32 v98, v108
	v_mov_b32_e32 v99, v112
	v_mov_b32_e32 v107, v1
	s_waitcnt lgkmcnt(1)
	v_pk_fma_f32 v[102:103], v[154:155], v[98:99], v[118:119]
	v_lshl_add_u64 v[98:99], v[106:107], 2, s[0:1]
	global_store_dwordx2 v[98:99], v[102:103], off
	s_mov_b64 s[10:11], -1
	s_and_b64 vcc, exec, s[6:7]
	v_or_b32_e32 v98, 0x4880, v0
	s_cbranch_vccnz .LBB0_692
	v_pk_mul_f32 v[110:111], v[148:149], v[102:103]
	v_lshl_add_u64 v[106:107], v[106:107], 1, s[2:3]
	s_nop 0
	s_nop 0
	v_cvt_pk_bf16_f32 v108, v110, v110
	v_cvt_pk_bf16_f32 v99, v111, v111
	v_lshrrev_b32_e32 v108, 16, v108
	v_and_or_b32 v99, v99, s28, v108
	global_store_dword v[106:107], v99, off
	v_mov_b32_e32 v106, v100
	v_mov_b32_e32 v107, v104
	v_mov_b32_e32 v99, v1
	v_pk_fma_f32 v[106:107], v[150:151], v[106:107], v[120:121]
	v_lshl_add_u64 v[110:111], v[98:99], 2, s[0:1]
	global_store_dwordx2 v[110:111], v[106:107], off
	v_pk_mul_f32 v[110:111], v[152:153], v[106:107]
	v_pk_mul_f32 v[102:103], v[102:103], v[102:103]
	v_and_b32_sdwa v112, v110, v178 dst_sel:DWORD dst_unused:UNUSED_PAD src0_sel:WORD_1 src1_sel:DWORD
	s_nop 0
	v_add3_u32 v110, v110, v112, s81
	v_cvt_pk_bf16_f32 v108, v111, v111
	v_lshrrev_b32_e32 v110, 16, v110
	v_pk_mul_f32 v[106:107], v[106:107], v[106:107]
	v_and_or_b32 v108, v108, s28, v110
	v_lshl_add_u64 v[110:111], v[98:99], 1, s[2:3]
	v_add_f32_e32 v99, v106, v107
	v_add_f32_e32 v102, v102, v103
	v_add_f32_e32 v99, v102, v99
	global_store_dword v[110:111], v108, off
	s_nop 0
	v_add_f32_dpp v99, v99, v99 quad_perm:[1,0,3,2] row_mask:0xf bank_mask:0xf bound_ctrl:1
	s_nop 1
	v_add_f32_dpp v99, v99, v99 quad_perm:[2,3,0,1] row_mask:0xf bank_mask:0xf bound_ctrl:1
	s_nop 1
	v_add_f32_dpp v99, v99, v99 row_half_mirror row_mask:0xf bank_mask:0xf bound_ctrl:1
	s_nop 1
	v_mov_b32_dpp v102, v99 row_mirror row_mask:0xf bank_mask:0xf bound_ctrl:1
	s_and_saveexec_b64 s[10:11], s[4:5]
	s_cbranch_execz .LBB0_691
	v_add_f32_e32 v99, v99, v102
	v_lshlrev_b32_e32 v102, 4, v163
	v_ashrrev_i32_e32 v103, 31, v102
	v_lshl_add_u64 v[102:103], v[102:103], 2, v[142:143]
	global_store_dword v[102:103], v99, off offset:1152

; __device__ __forceinline__ u16 f2bf(float f) {
;   unsigned u = __float_as_uint(f);
;   u += 0x7fffu + ((u >> 16) & 1u);
;   return (u16)(u >> 16);
; }
; __device__ __forceinline__ float bf2f(u16 h) { return __uint_as_float(((unsigned)h) << 16); }
; __device__ __forceinline__ float bfs2f(short h) { return __uint_as_float(((unsigned)(u16)h) << 16); }
; __device__ __forceinline__ unsigned pack2(float a, float b) { return (unsigned)f2bf(a) | ((unsigned)f2bf(b) << 16); }
; template <int EPI, bool HS = false>
; __device__ __forceinline__ void gemm_phase(const Params& p, const GemmCfg& g, char* shm, const int wave_s) {
;     ...
;             for (int bj = 0; bj < 2; ++bj) {
;               float2 xn;
;               xn.x = xv[j][bj].x + gt[bj][0] * acc[ai][bj][m][0][j];
;               xn.y = xv[j][bj].y + gt[bj][1] * acc[ai][bj][m][1][j];
;               const unsigned o = tb + (unsigned)((ai * 128 + m * 16 + j) * 1024 + bj * 128);
;               *(float2*)(xout_t + o) = xn;
;               if (g.has_next) *(unsigned*)(xg_t + o) = pack2(xn.x * gn[bj][0], xn.y * gn[bj][1]);
;               ss += xn.x * xn.x + xn.y * xn.y;
;             }
;             if (g.has_next) {
;               ss = dpp_row_sum16(ss);
;               if (fr == 0) rss_t[(wr * 64 + fq * 4 + ai * 128 + m * 16 + j) * 16] = ss;
;             }
.LBB0_694:
	v_or_b32_e32 v106, 0x4c00, v0
	v_mov_b32_e32 v112, v109
	v_mov_b32_e32 v107, v1
	s_waitcnt lgkmcnt(0)
	v_pk_fma_f32 v[102:103], v[154:155], v[112:113], v[114:115]
	v_lshl_add_u64 v[98:99], v[106:107], 2, s[0:1]
	global_store_dwordx2 v[98:99], v[102:103], off
	s_mov_b64 s[10:11], -1
	s_and_b64 vcc, exec, s[6:7]
	v_or_b32_e32 v98, 0x4c80, v0
	s_cbranch_vccnz .LBB0_698
	v_pk_mul_f32 v[108:109], v[148:149], v[102:103]
	v_lshl_add_u64 v[106:107], v[106:107], 1, s[2:3]
	s_nop 0
	s_nop 0
	v_cvt_pk_bf16_f32 v100, v108, v108
	v_cvt_pk_bf16_f32 v99, v109, v109
	v_lshrrev_b32_e32 v100, 16, v100
	v_and_or_b32 v99, v99, s28, v100
	global_store_dword v[106:107], v99, off
	v_mov_b32_e32 v104, v101
	v_mov_b32_e32 v99, v1
	v_pk_fma_f32 v[106:107], v[150:151], v[104:105], v[116:117]
	v_lshl_add_u64 v[108:109], v[98:99], 2, s[0:1]
	global_store_dwordx2 v[108:109], v[106:107], off
	v_pk_mul_f32 v[108:109], v[152:153], v[106:107]
	v_pk_mul_f32 v[102:103], v[102:103], v[102:103]
	s_nop 0
	s_nop 0
	v_cvt_pk_bf16_f32 v104, v108, v108
	v_cvt_pk_bf16_f32 v100, v109, v109
	v_lshrrev_b32_e32 v104, 16, v104
	v_and_or_b32 v100, v100, s28, v104
	v_lshl_add_u64 v[108:109], v[98:99], 1, s[2:3]
	v_pk_mul_f32 v[106:107], v[106:107], v[106:107]
	global_store_dword v[108:109], v100, off
	v_add_f32_e32 v99, v106, v107
	v_add_f32_e32 v100, v102, v103
	v_add_f32_e32 v99, v100, v99
	s_nop 1
	v_add_f32_dpp v99, v99, v99 quad_perm:[1,0,3,2] row_mask:0xf bank_mask:0xf bound_ctrl:1
	s_nop 1
	v_add_f32_dpp v99, v99, v99 quad_perm:[2,3,0,1] row_mask:0xf bank_mask:0xf bound_ctrl:1
	s_nop 1
	v_add_f32_dpp v99, v99, v99 row_half_mirror row_mask:0xf bank_mask:0xf bound_ctrl:1
	s_nop 1
	v_mov_b32_dpp v100, v99 row_mirror row_mask:0xf bank_mask:0xf bound_ctrl:1
	s_and_saveexec_b64 s[10:11], s[4:5]
	s_cbranch_execz .LBB0_697
	v_lshlrev_b32_e32 v102, 4, v163
	v_ashrrev_i32_e32 v103, 31, v102
	v_add_f32_e32 v99, v99, v100
	v_lshl_add_u64 v[102:103], v[102:103], 2, v[142:143]
	global_store_dword v[102:103], v99, off offset:1216

; __device__ __forceinline__ u16 f2bf(float f) {
;   unsigned u = __float_as_uint(f);
;   u += 0x7fffu + ((u >> 16) & 1u);
;   return (u16)(u >> 16);
; }
; __device__ __forceinline__ float bf2f(u16 h) { return __uint_as_float(((unsigned)h) << 16); }
; __device__ __forceinline__ float bfs2f(short h) { return __uint_as_float(((unsigned)(u16)h) << 16); }
; __device__ __forceinline__ unsigned pack2(float a, float b) { return (unsigned)f2bf(a) | ((unsigned)f2bf(b) << 16); }
; template <int EPI, bool HS = false>
; __device__ __forceinline__ void gemm_phase(const Params& p, const GemmCfg& g, char* shm, const int wave_s) {
;     ...
;         for (int m = 0; m < 4; ++m) {
;           float2 xv[4][2];
; #pragma unroll
;           for (int j = 0; j < 4; ++j)
; #pragma unroll
;             for (int bj = 0; bj < 2; ++bj) xv[j][bj] = *(const float2*)(xl + (m * 16 + j) * XROW + bj * 512);
; #pragma unroll
;           for (int j = 0; j < 4; ++j) {
;             float ss = 0.f;
; #pragma unroll
;             for (int bj = 0; bj < 2; ++bj) {
;               float2 xn;
;               xn.x = xv[j][bj].x + gt[bj][0] * acc[ai][bj][m][0][j];
;               xn.y = xv[j][bj].y + gt[bj][1] * acc[ai][bj][m][1][j];
;               const unsigned o = tb + (unsigned)((ai * 128 + m * 16 + j) * 1024 + bj * 128);
;               *(float2*)(xout_t + o) = xn;
;               if (g.has_next) *(unsigned*)(xg_t + o) = pack2(xn.x * gn[bj][0], xn.y * gn[bj][1]);
;               ss += xn.x * xn.x + xn.y * xn.y;
;             }
;             if (g.has_next) {
;               ss = dpp_row_sum16(ss);
;               if (fr == 0) rss_t[(wr * 64 + fq * 4 + ai * 128 + m * 16 + j) * 16] = ss;
;             }
.LBB0_700:
	ds_read2st64_b64 v[110:113], v164 offset0:65 offset1:66
	v_add_u32_e32 v118, 16, v164
	ds_read2st64_b64 v[106:109], v118 offset0:67 offset1:68
	ds_read2st64_b64 v[102:105], v165 offset0:69 offset1:70
	ds_read2st64_b64 v[98:101], v166 offset0:71 offset1:72
	v_or_b32_e32 v116, 0x8000, v0
	v_mov_b32_e32 v114, v90
	v_mov_b32_e32 v115, v94
	v_mov_b32_e32 v117, v1
	s_waitcnt lgkmcnt(3)
	v_pk_fma_f32 v[114:115], v[154:155], v[114:115], v[110:111]
	v_lshl_add_u64 v[110:111], v[116:117], 2, s[0:1]
	global_store_dwordx2 v[110:111], v[114:115], off
	s_mov_b64 s[10:11], -1
	s_and_b64 vcc, exec, s[6:7]
	v_or_b32_e32 v110, 0x8080, v0
	s_cbranch_vccnz .LBB0_704
	v_pk_mul_f32 v[120:121], v[148:149], v[114:115]
	v_lshl_add_u64 v[116:117], v[116:117], 1, s[2:3]
	s_nop 0
	s_nop 0
	v_cvt_pk_bf16_f32 v94, v120, v120
	v_cvt_pk_bf16_f32 v90, v121, v121
	v_lshrrev_b32_e32 v94, 16, v94
	v_and_or_b32 v90, v90, s28, v94
	global_store_dword v[116:117], v90, off
	v_mov_b32_e32 v116, v82
	v_mov_b32_e32 v117, v86
	v_mov_b32_e32 v111, v1
	v_pk_fma_f32 v[116:117], v[150:151], v[116:117], v[112:113]
	v_lshl_add_u64 v[120:121], v[110:111], 2, s[0:1]
	global_store_dwordx2 v[120:121], v[116:117], off
	v_pk_mul_f32 v[120:121], v[152:153], v[116:117]
	v_pk_mul_f32 v[114:115], v[114:115], v[114:115]
	s_nop 0
	s_nop 0
	v_cvt_pk_bf16_f32 v94, v120, v120
	v_cvt_pk_bf16_f32 v90, v121, v121
	v_lshrrev_b32_e32 v94, 16, v94
	v_and_or_b32 v90, v90, s28, v94
	v_lshl_add_u64 v[120:121], v[110:111], 1, s[2:3]
	v_pk_mul_f32 v[116:117], v[116:117], v[116:117]
	global_store_dword v[120:121], v90, off
	v_add_f32_e32 v90, v116, v117
	v_add_f32_e32 v94, v114, v115
	v_add_f32_e32 v90, v94, v90
	s_nop 1
	v_add_f32_dpp v90, v90, v90 quad_perm:[1,0,3,2] row_mask:0xf bank_mask:0xf bound_ctrl:1
	s_nop 1
	v_add_f32_dpp v90, v90, v90 quad_perm:[2,3,0,1] row_mask:0xf bank_mask:0xf bound_ctrl:1
	s_nop 1
	v_add_f32_dpp v90, v90, v90 row_half_mirror row_mask:0xf bank_mask:0xf bound_ctrl:1
	s_nop 1
	v_mov_b32_dpp v94, v90 row_mirror row_mask:0xf bank_mask:0xf bound_ctrl:1
	s_and_saveexec_b64 s[10:11], s[4:5]
	s_cbranch_execz .LBB0_703
	v_lshlrev_b32_e32 v114, 4, v163
	v_ashrrev_i32_e32 v115, 31, v114
	v_add_f32_e32 v90, v90, v94
	v_lshl_add_u64 v[114:115], v[114:115], 2, v[142:143]
	global_store_dword v[114:115], v90, off offset:2048

; __device__ __forceinline__ u16 f2bf(float f) {
;   unsigned u = __float_as_uint(f);
;   u += 0x7fffu + ((u >> 16) & 1u);
;   return (u16)(u >> 16);
; }
; __device__ __forceinline__ float bf2f(u16 h) { return __uint_as_float(((unsigned)h) << 16); }
; __device__ __forceinline__ float bfs2f(short h) { return __uint_as_float(((unsigned)(u16)h) << 16); }
; __device__ __forceinline__ unsigned pack2(float a, float b) { return (unsigned)f2bf(a) | ((unsigned)f2bf(b) << 16); }
; template <int EPI, bool HS = false>
; __device__ __forceinline__ void gemm_phase(const Params& p, const GemmCfg& g, char* shm, const int wave_s) {
;     ...
;             for (int bj = 0; bj < 2; ++bj) {
;               float2 xn;
;               xn.x = xv[j][bj].x + gt[bj][0] * acc[ai][bj][m][0][j];
;               xn.y = xv[j][bj].y + gt[bj][1] * acc[ai][bj][m][1][j];
;               const unsigned o = tb + (unsigned)((ai * 128 + m * 16 + j) * 1024 + bj * 128);
;               *(float2*)(xout_t + o) = xn;
;               if (g.has_next) *(unsigned*)(xg_t + o) = pack2(xn.x * gn[bj][0], xn.y * gn[bj][1]);
;               ss += xn.x * xn.x + xn.y * xn.y;
;             }
;             if (g.has_next) {
;               ss = dpp_row_sum16(ss);
;               if (fr == 0) rss_t[(wr * 64 + fq * 4 + ai * 128 + m * 16 + j) * 16] = ss;
;             }
.LBB0_706:
	v_or_b32_e32 v110, 0x8400, v0
	v_mov_b32_e32 v94, v91
	v_mov_b32_e32 v111, v1
	s_waitcnt lgkmcnt(2)
	v_pk_fma_f32 v[94:95], v[154:155], v[94:95], v[106:107]
	v_lshl_add_u64 v[90:91], v[110:111], 2, s[0:1]
	global_store_dwordx2 v[90:91], v[94:95], off
	s_mov_b64 s[10:11], -1
	s_and_b64 vcc, exec, s[6:7]
	v_or_b32_e32 v90, 0x8480, v0
	s_cbranch_vccnz .LBB0_710
	v_pk_mul_f32 v[106:107], v[148:149], v[94:95]
	v_mov_b32_e32 v91, v1
	s_nop 0
	s_nop 0
	v_cvt_pk_bf16_f32 v86, v106, v106
	v_cvt_pk_bf16_f32 v82, v107, v107
	v_lshrrev_b32_e32 v86, 16, v86
	v_and_or_b32 v82, v82, s28, v86
	v_lshl_add_u64 v[106:107], v[110:111], 1, s[2:3]
	v_mov_b32_e32 v86, v83
	global_store_dword v[106:107], v82, off
	v_pk_fma_f32 v[106:107], v[150:151], v[86:87], v[108:109]
	v_lshl_add_u64 v[110:111], v[90:91], 2, s[0:1]
	global_store_dwordx2 v[110:111], v[106:107], off
	v_pk_mul_f32 v[110:111], v[152:153], v[106:107]
	v_pk_mul_f32 v[94:95], v[94:95], v[94:95]
	s_nop 0
	s_nop 0
	v_cvt_pk_bf16_f32 v86, v110, v110
	v_cvt_pk_bf16_f32 v82, v111, v111
	v_lshrrev_b32_e32 v86, 16, v86
	v_and_or_b32 v82, v82, s28, v86
	v_lshl_add_u64 v[110:111], v[90:91], 1, s[2:3]
	v_pk_mul_f32 v[106:107], v[106:107], v[106:107]
	global_store_dword v[110:111], v82, off
	v_add_f32_e32 v82, v106, v107
	v_add_f32_e32 v86, v94, v95
	v_add_f32_e32 v82, v86, v82
	s_nop 1
	v_add_f32_dpp v82, v82, v82 quad_perm:[1,0,3,2] row_mask:0xf bank_mask:0xf bound_ctrl:1
	s_nop 1
	v_add_f32_dpp v82, v82, v82 quad_perm:[2,3,0,1] row_mask:0xf bank_mask:0xf bound_ctrl:1
	s_nop 1
	v_add_f32_dpp v82, v82, v82 row_half_mirror row_mask:0xf bank_mask:0xf bound_ctrl:1
	s_nop 1
	v_mov_b32_dpp v86, v82 row_mirror row_mask:0xf bank_mask:0xf bound_ctrl:1
	s_and_saveexec_b64 s[10:11], s[4:5]
	s_cbranch_execz .LBB0_709
	v_lshlrev_b32_e32 v94, 4, v163
	v_ashrrev_i32_e32 v95, 31, v94
	v_add_f32_e32 v82, v82, v86
	v_lshl_add_u64 v[94:95], v[94:95], 2, v[142:143]
	global_store_dword v[94:95], v82, off offset:2112

; __device__ __forceinline__ u16 f2bf(float f) {
;   unsigned u = __float_as_uint(f);
;   u += 0x7fffu + ((u >> 16) & 1u);
;   return (u16)(u >> 16);
; }
; __device__ __forceinline__ float bf2f(u16 h) { return __uint_as_float(((unsigned)h) << 16); }
; __device__ __forceinline__ float bfs2f(short h) { return __uint_as_float(((unsigned)(u16)h) << 16); }
; __device__ __forceinline__ unsigned pack2(float a, float b) { return (unsigned)f2bf(a) | ((unsigned)f2bf(b) << 16); }
; template <int EPI, bool HS = false>
; __device__ __forceinline__ void gemm_phase(const Params& p, const GemmCfg& g, char* shm, const int wave_s) {
;     ...
;             for (int bj = 0; bj < 2; ++bj) {
;               float2 xn;
;               xn.x = xv[j][bj].x + gt[bj][0] * acc[ai][bj][m][0][j];
;               xn.y = xv[j][bj].y + gt[bj][1] * acc[ai][bj][m][1][j];
;               const unsigned o = tb + (unsigned)((ai * 128 + m * 16 + j) * 1024 + bj * 128);
;               *(float2*)(xout_t + o) = xn;
;               if (g.has_next) *(unsigned*)(xg_t + o) = pack2(xn.x * gn[bj][0], xn.y * gn[bj][1]);
;               ss += xn.x * xn.x + xn.y * xn.y;
;             }
;             if (g.has_next) {
;               ss = dpp_row_sum16(ss);
;               if (fr == 0) rss_t[(wr * 64 + fq * 4 + ai * 128 + m * 16 + j) * 16] = ss;
;             }
.LBB0_712:
	v_or_b32_e32 v90, 0x8800, v0
	v_mov_b32_e32 v82, v92
	v_mov_b32_e32 v83, v96
	v_mov_b32_e32 v91, v1
	s_waitcnt lgkmcnt(1)
	v_pk_fma_f32 v[86:87], v[154:155], v[82:83], v[102:103]
	v_lshl_add_u64 v[82:83], v[90:91], 2, s[0:1]
	global_store_dwordx2 v[82:83], v[86:87], off
	s_mov_b64 s[10:11], -1
	s_and_b64 vcc, exec, s[6:7]
	v_or_b32_e32 v82, 0x8880, v0
	s_cbranch_vccnz .LBB0_716
	v_pk_mul_f32 v[94:95], v[148:149], v[86:87]
	v_lshl_add_u64 v[90:91], v[90:91], 1, s[2:3]
	s_nop 0
	s_nop 0
	v_cvt_pk_bf16_f32 v92, v94, v94
	v_cvt_pk_bf16_f32 v83, v95, v95
	v_lshrrev_b32_e32 v92, 16, v92
	v_and_or_b32 v83, v83, s28, v92
	global_store_dword v[90:91], v83, off
	v_mov_b32_e32 v90, v84
	v_mov_b32_e32 v91, v88
	v_mov_b32_e32 v83, v1
	v_pk_fma_f32 v[90:91], v[150:151], v[90:91], v[104:105]
	v_lshl_add_u64 v[94:95], v[82:83], 2, s[0:1]
	global_store_dwordx2 v[94:95], v[90:91], off
	v_pk_mul_f32 v[94:95], v[152:153], v[90:91]
	v_pk_mul_f32 v[86:87], v[86:87], v[86:87]
	v_and_b32_sdwa v96, v94, v178 dst_sel:DWORD dst_unused:UNUSED_PAD src0_sel:WORD_1 src1_sel:DWORD
	s_nop 0
	v_add3_u32 v94, v94, v96, s81
	v_cvt_pk_bf16_f32 v92, v95, v95
	v_lshrrev_b32_e32 v94, 16, v94
	v_pk_mul_f32 v[90:91], v[90:91], v[90:91]
	v_and_or_b32 v92, v92, s28, v94
	v_lshl_add_u64 v[94:95], v[82:83], 1, s[2:3]
	v_add_f32_e32 v83, v90, v91
	v_add_f32_e32 v86, v86, v87
	v_add_f32_e32 v83, v86, v83
	global_store_dword v[94:95], v92, off
	s_nop 0
	v_add_f32_dpp v83, v83, v83 quad_perm:[1,0,3,2] row_mask:0xf bank_mask:0xf bound_ctrl:1
	s_nop 1
	v_add_f32_dpp v83, v83, v83 quad_perm:[2,3,0,1] row_mask:0xf bank_mask:0xf bound_ctrl:1
	s_nop 1
	v_add_f32_dpp v83, v83, v83 row_half_mirror row_mask:0xf bank_mask:0xf bound_ctrl:1
	s_nop 1
	v_mov_b32_dpp v86, v83 row_mirror row_mask:0xf bank_mask:0xf bound_ctrl:1
	s_and_saveexec_b64 s[10:11], s[4:5]
	s_cbranch_execz .LBB0_715
	v_add_f32_e32 v83, v83, v86
	v_lshlrev_b32_e32 v86, 4, v163
	v_ashrrev_i32_e32 v87, 31, v86
	v_lshl_add_u64 v[86:87], v[86:87], 2, v[142:143]
	global_store_dword v[86:87], v83, off offset:2176

; __device__ __forceinline__ u16 f2bf(float f) {
;   unsigned u = __float_as_uint(f);
;   u += 0x7fffu + ((u >> 16) & 1u);
;   return (u16)(u >> 16);
; }
; __device__ __forceinline__ float bf2f(u16 h) { return __uint_as_float(((unsigned)h) << 16); }
; __device__ __forceinline__ float bfs2f(short h) { return __uint_as_float(((unsigned)(u16)h) << 16); }
; __device__ __forceinline__ unsigned pack2(float a, float b) { return (unsigned)f2bf(a) | ((unsigned)f2bf(b) << 16); }
; template <int EPI, bool HS = false>
; __device__ __forceinline__ void gemm_phase(const Params& p, const GemmCfg& g, char* shm, const int wave_s) {
;     ...
;             for (int bj = 0; bj < 2; ++bj) {
;               float2 xn;
;               xn.x = xv[j][bj].x + gt[bj][0] * acc[ai][bj][m][0][j];
;               xn.y = xv[j][bj].y + gt[bj][1] * acc[ai][bj][m][1][j];
;               const unsigned o = tb + (unsigned)((ai * 128 + m * 16 + j) * 1024 + bj * 128);
;               *(float2*)(xout_t + o) = xn;
;               if (g.has_next) *(unsigned*)(xg_t + o) = pack2(xn.x * gn[bj][0], xn.y * gn[bj][1]);
;               ss += xn.x * xn.x + xn.y * xn.y;
;             }
;             if (g.has_next) {
;               ss = dpp_row_sum16(ss);
;               if (fr == 0) rss_t[(wr * 64 + fq * 4 + ai * 128 + m * 16 + j) * 16] = ss;
;             }
.LBB0_718:
	v_or_b32_e32 v90, 0x8c00, v0
	v_mov_b32_e32 v96, v93
	v_mov_b32_e32 v91, v1
	s_waitcnt lgkmcnt(0)
	v_pk_fma_f32 v[86:87], v[154:155], v[96:97], v[98:99]
	v_lshl_add_u64 v[82:83], v[90:91], 2, s[0:1]
	global_store_dwordx2 v[82:83], v[86:87], off
	s_mov_b64 s[10:11], -1
	s_and_b64 vcc, exec, s[6:7]
	v_or_b32_e32 v82, 0x8c80, v0
	s_cbranch_vccnz .LBB0_722
	v_pk_mul_f32 v[92:93], v[148:149], v[86:87]
	v_lshl_add_u64 v[90:91], v[90:91], 1, s[2:3]
	s_nop 0
	s_nop 0
	v_cvt_pk_bf16_f32 v84, v92, v92
	v_cvt_pk_bf16_f32 v83, v93, v93
	v_lshrrev_b32_e32 v84, 16, v84
	v_and_or_b32 v83, v83, s28, v84
	global_store_dword v[90:91], v83, off
	v_mov_b32_e32 v88, v85
	v_mov_b32_e32 v83, v1
	v_pk_fma_f32 v[90:91], v[150:151], v[88:89], v[100:101]
	v_lshl_add_u64 v[92:93], v[82:83], 2, s[0:1]
	global_store_dwordx2 v[92:93], v[90:91], off
	v_pk_mul_f32 v[92:93], v[152:153], v[90:91]
	v_pk_mul_f32 v[86:87], v[86:87], v[86:87]
	s_nop 0
	s_nop 0
	v_cvt_pk_bf16_f32 v88, v92, v92
	v_cvt_pk_bf16_f32 v84, v93, v93
	v_lshrrev_b32_e32 v88, 16, v88
	v_and_or_b32 v84, v84, s28, v88
	v_lshl_add_u64 v[92:93], v[82:83], 1, s[2:3]
	v_pk_mul_f32 v[90:91], v[90:91], v[90:91]
	global_store_dword v[92:93], v84, off
	v_add_f32_e32 v83, v90, v91
	v_add_f32_e32 v84, v86, v87
	v_add_f32_e32 v83, v84, v83
	s_nop 1
	v_add_f32_dpp v83, v83, v83 quad_perm:[1,0,3,2] row_mask:0xf bank_mask:0xf bound_ctrl:1
	s_nop 1
	v_add_f32_dpp v83, v83, v83 quad_perm:[2,3,0,1] row_mask:0xf bank_mask:0xf bound_ctrl:1
	s_nop 1
	v_add_f32_dpp v83, v83, v83 row_half_mirror row_mask:0xf bank_mask:0xf bound_ctrl:1
	s_nop 1
	v_mov_b32_dpp v84, v83 row_mirror row_mask:0xf bank_mask:0xf bound_ctrl:1
	s_and_saveexec_b64 s[10:11], s[4:5]
	s_cbranch_execz .LBB0_721
	v_lshlrev_b32_e32 v86, 4, v163
	v_ashrrev_i32_e32 v87, 31, v86
	v_add_f32_e32 v83, v83, v84
	v_lshl_add_u64 v[86:87], v[86:87], 2, v[142:143]
	global_store_dword v[86:87], v83, off offset:2240

; __device__ __forceinline__ u16 f2bf(float f) {
;   unsigned u = __float_as_uint(f);
;   u += 0x7fffu + ((u >> 16) & 1u);
;   return (u16)(u >> 16);
; }
; __device__ __forceinline__ float bf2f(u16 h) { return __uint_as_float(((unsigned)h) << 16); }
; __device__ __forceinline__ float bfs2f(short h) { return __uint_as_float(((unsigned)(u16)h) << 16); }
; __device__ __forceinline__ unsigned pack2(float a, float b) { return (unsigned)f2bf(a) | ((unsigned)f2bf(b) << 16); }
; template <int EPI, bool HS = false>
; __device__ __forceinline__ void gemm_phase(const Params& p, const GemmCfg& g, char* shm, const int wave_s) {
;     ...
;         for (int m = 0; m < 4; ++m) {
;           float2 xv[4][2];
; #pragma unroll
;           for (int j = 0; j < 4; ++j)
; #pragma unroll
;             for (int bj = 0; bj < 2; ++bj) xv[j][bj] = *(const float2*)(xl + (m * 16 + j) * XROW + bj * 512);
; #pragma unroll
;           for (int j = 0; j < 4; ++j) {
;             float ss = 0.f;
; #pragma unroll
;             for (int bj = 0; bj < 2; ++bj) {
;               float2 xn;
;               xn.x = xv[j][bj].x + gt[bj][0] * acc[ai][bj][m][0][j];
;               xn.y = xv[j][bj].y + gt[bj][1] * acc[ai][bj][m][1][j];
;               const unsigned o = tb + (unsigned)((ai * 128 + m * 16 + j) * 1024 + bj * 128);
;               *(float2*)(xout_t + o) = xn;
;               if (g.has_next) *(unsigned*)(xg_t + o) = pack2(xn.x * gn[bj][0], xn.y * gn[bj][1]);
;               ss += xn.x * xn.x + xn.y * xn.y;
;             }
;             if (g.has_next) {
;               ss = dpp_row_sum16(ss);
;               if (fr == 0) rss_t[(wr * 64 + fq * 4 + ai * 128 + m * 16 + j) * 16] = ss;
;             }
.LBB0_724:
	ds_read2st64_b64 v[94:97], v134 offset0:97 offset1:98
	ds_read2st64_b64 v[90:93], v135 offset0:99 offset1:100
	ds_read2st64_b64 v[86:89], v136 offset0:101 offset1:102
	ds_read2st64_b64 v[82:85], v137 offset0:103 offset1:104
	v_or_b32_e32 v100, 0xc000, v0
	v_mov_b32_e32 v98, v74
	v_mov_b32_e32 v99, v78
	v_mov_b32_e32 v101, v1
	s_waitcnt lgkmcnt(3)
	v_pk_fma_f32 v[98:99], v[154:155], v[98:99], v[94:95]
	v_lshl_add_u64 v[94:95], v[100:101], 2, s[0:1]
	global_store_dwordx2 v[94:95], v[98:99], off
	s_mov_b64 s[10:11], -1
	s_and_b64 vcc, exec, s[6:7]
	v_or_b32_e32 v94, 0xc080, v0
	s_cbranch_vccnz .LBB0_728
	v_pk_mul_f32 v[102:103], v[148:149], v[98:99]
	v_lshl_add_u64 v[100:101], v[100:101], 1, s[2:3]
	s_nop 0
	s_nop 0
	v_cvt_pk_bf16_f32 v78, v102, v102
	v_cvt_pk_bf16_f32 v74, v103, v103
	v_lshrrev_b32_e32 v78, 16, v78
	v_and_or_b32 v74, v74, s28, v78
	global_store_dword v[100:101], v74, off
	v_mov_b32_e32 v100, v66
	v_mov_b32_e32 v101, v70
	v_mov_b32_e32 v95, v1
	v_pk_fma_f32 v[100:101], v[150:151], v[100:101], v[96:97]
	v_lshl_add_u64 v[102:103], v[94:95], 2, s[0:1]
	global_store_dwordx2 v[102:103], v[100:101], off
	v_pk_mul_f32 v[102:103], v[152:153], v[100:101]
	v_pk_mul_f32 v[98:99], v[98:99], v[98:99]
	s_nop 0
	s_nop 0
	v_cvt_pk_bf16_f32 v78, v102, v102
	v_cvt_pk_bf16_f32 v74, v103, v103
	v_lshrrev_b32_e32 v78, 16, v78
	v_and_or_b32 v74, v74, s28, v78
	v_lshl_add_u64 v[102:103], v[94:95], 1, s[2:3]
	v_pk_mul_f32 v[100:101], v[100:101], v[100:101]
	global_store_dword v[102:103], v74, off
	v_add_f32_e32 v74, v100, v101
	v_add_f32_e32 v78, v98, v99
	v_add_f32_e32 v74, v78, v74
	s_nop 1
	v_add_f32_dpp v74, v74, v74 quad_perm:[1,0,3,2] row_mask:0xf bank_mask:0xf bound_ctrl:1
	s_nop 1
	v_add_f32_dpp v74, v74, v74 quad_perm:[2,3,0,1] row_mask:0xf bank_mask:0xf bound_ctrl:1
	s_nop 1
	v_add_f32_dpp v74, v74, v74 row_half_mirror row_mask:0xf bank_mask:0xf bound_ctrl:1
	s_nop 1
	v_mov_b32_dpp v78, v74 row_mirror row_mask:0xf bank_mask:0xf bound_ctrl:1
	s_and_saveexec_b64 s[10:11], s[4:5]
	s_cbranch_execz .LBB0_727
	v_lshlrev_b32_e32 v98, 4, v163
	v_ashrrev_i32_e32 v99, 31, v98
	v_add_f32_e32 v74, v74, v78
	v_lshl_add_u64 v[98:99], v[98:99], 2, v[142:143]
	global_store_dword v[98:99], v74, off offset:3072

; __device__ __forceinline__ u16 f2bf(float f) {
;   unsigned u = __float_as_uint(f);
;   u += 0x7fffu + ((u >> 16) & 1u);
;   return (u16)(u >> 16);
; }
; __device__ __forceinline__ float bf2f(u16 h) { return __uint_as_float(((unsigned)h) << 16); }
; __device__ __forceinline__ float bfs2f(short h) { return __uint_as_float(((unsigned)(u16)h) << 16); }
; __device__ __forceinline__ unsigned pack2(float a, float b) { return (unsigned)f2bf(a) | ((unsigned)f2bf(b) << 16); }
; template <int EPI, bool HS = false>
; __device__ __forceinline__ void gemm_phase(const Params& p, const GemmCfg& g, char* shm, const int wave_s) {
;     ...
;             for (int bj = 0; bj < 2; ++bj) {
;               float2 xn;
;               xn.x = xv[j][bj].x + gt[bj][0] * acc[ai][bj][m][0][j];
;               xn.y = xv[j][bj].y + gt[bj][1] * acc[ai][bj][m][1][j];
;               const unsigned o = tb + (unsigned)((ai * 128 + m * 16 + j) * 1024 + bj * 128);
;               *(float2*)(xout_t + o) = xn;
;               if (g.has_next) *(unsigned*)(xg_t + o) = pack2(xn.x * gn[bj][0], xn.y * gn[bj][1]);
;               ss += xn.x * xn.x + xn.y * xn.y;
;             }
;             if (g.has_next) {
;               ss = dpp_row_sum16(ss);
;               if (fr == 0) rss_t[(wr * 64 + fq * 4 + ai * 128 + m * 16 + j) * 16] = ss;
;             }
.LBB0_730:
	v_or_b32_e32 v94, 0xc400, v0
	v_mov_b32_e32 v78, v75
	v_mov_b32_e32 v95, v1
	s_waitcnt lgkmcnt(2)
	v_pk_fma_f32 v[78:79], v[154:155], v[78:79], v[90:91]
	v_lshl_add_u64 v[74:75], v[94:95], 2, s[0:1]
	global_store_dwordx2 v[74:75], v[78:79], off
	s_mov_b64 s[10:11], -1
	s_and_b64 vcc, exec, s[6:7]
	v_or_b32_e32 v74, 0xc480, v0
	s_cbranch_vccnz .LBB0_734
	v_pk_mul_f32 v[90:91], v[148:149], v[78:79]
	v_mov_b32_e32 v75, v1
	s_nop 0
	s_nop 0
	v_cvt_pk_bf16_f32 v70, v90, v90
	v_cvt_pk_bf16_f32 v66, v91, v91
	v_lshrrev_b32_e32 v70, 16, v70
	v_and_or_b32 v66, v66, s28, v70
	v_lshl_add_u64 v[90:91], v[94:95], 1, s[2:3]
	v_mov_b32_e32 v70, v67
	global_store_dword v[90:91], v66, off
	v_pk_fma_f32 v[90:91], v[150:151], v[70:71], v[92:93]
	v_lshl_add_u64 v[94:95], v[74:75], 2, s[0:1]
	global_store_dwordx2 v[94:95], v[90:91], off
	v_pk_mul_f32 v[94:95], v[152:153], v[90:91]
	v_pk_mul_f32 v[78:79], v[78:79], v[78:79]
	s_nop 0
	s_nop 0
	v_cvt_pk_bf16_f32 v70, v94, v94
	v_cvt_pk_bf16_f32 v66, v95, v95
	v_lshrrev_b32_e32 v70, 16, v70
	v_and_or_b32 v66, v66, s28, v70
	v_lshl_add_u64 v[94:95], v[74:75], 1, s[2:3]
	v_pk_mul_f32 v[90:91], v[90:91], v[90:91]
	global_store_dword v[94:95], v66, off
	v_add_f32_e32 v66, v90, v91
	v_add_f32_e32 v70, v78, v79
	v_add_f32_e32 v66, v70, v66
	s_nop 1
	v_add_f32_dpp v66, v66, v66 quad_perm:[1,0,3,2] row_mask:0xf bank_mask:0xf bound_ctrl:1
	s_nop 1
	v_add_f32_dpp v66, v66, v66 quad_perm:[2,3,0,1] row_mask:0xf bank_mask:0xf bound_ctrl:1
	s_nop 1
	v_add_f32_dpp v66, v66, v66 row_half_mirror row_mask:0xf bank_mask:0xf bound_ctrl:1
	s_nop 1
	v_mov_b32_dpp v70, v66 row_mirror row_mask:0xf bank_mask:0xf bound_ctrl:1
	s_and_saveexec_b64 s[10:11], s[4:5]
	s_cbranch_execz .LBB0_733
	v_lshlrev_b32_e32 v78, 4, v163
	v_ashrrev_i32_e32 v79, 31, v78
	v_add_f32_e32 v66, v66, v70
	v_lshl_add_u64 v[78:79], v[78:79], 2, v[142:143]
	global_store_dword v[78:79], v66, off offset:3136

; __device__ __forceinline__ unsigned pack2(float a, float b) { return (unsigned)f2bf(a) | ((unsigned)f2bf(b) << 16); }
; __device__ __forceinline__ float dpp_row_sum16(float v) {
;   v += __int_as_float(__builtin_amdgcn_update_dpp(0, __float_as_int(v), 0xB1, 0xF, 0xF, true));
;   v += __int_as_float(__builtin_amdgcn_update_dpp(0, __float_as_int(v), 0x4E, 0xF, 0xF, true));
;   v += __int_as_float(__builtin_amdgcn_update_dpp(0, __float_as_int(v), 0x141, 0xF, 0xF, true));
;   v += __int_as_float(__builtin_amdgcn_update_dpp(0, __float_as_int(v), 0x140, 0xF, 0xF, true));
;   return v;
; }
; template <int EPI, bool HS = false>
; __device__ __forceinline__ void gemm_phase(const Params& p, const GemmCfg& g, char* shm, const int wave_s) {
;     ...
;             for (int bj = 0; bj < 2; ++bj) {
;               float2 xn;
;               xn.x = xv[j][bj].x + gt[bj][0] * acc[ai][bj][m][0][j];
;               xn.y = xv[j][bj].y + gt[bj][1] * acc[ai][bj][m][1][j];
;               const unsigned o = tb + (unsigned)((ai * 128 + m * 16 + j) * 1024 + bj * 128);
;               *(float2*)(xout_t + o) = xn;
;               if (g.has_next) *(unsigned*)(xg_t + o) = pack2(xn.x * gn[bj][0], xn.y * gn[bj][1]);
;               ss += xn.x * xn.x + xn.y * xn.y;
;             }
;             if (g.has_next) {
;               ss = dpp_row_sum16(ss);
;               if (fr == 0) rss_t[(wr * 64 + fq * 4 + ai * 128 + m * 16 + j) * 16] = ss;
;             }
.LBB0_736:
	v_or_b32_e32 v74, 0xc800, v0
	v_mov_b32_e32 v66, v76
	v_mov_b32_e32 v67, v80
	v_mov_b32_e32 v75, v1
	s_waitcnt lgkmcnt(1)
	v_pk_fma_f32 v[70:71], v[154:155], v[66:67], v[86:87]
	v_lshl_add_u64 v[66:67], v[74:75], 2, s[0:1]
	global_store_dwordx2 v[66:67], v[70:71], off
	s_mov_b64 s[10:11], -1
	s_and_b64 vcc, exec, s[6:7]
	v_or_b32_e32 v66, 0xc880, v0
	s_cbranch_vccnz .LBB0_740
	v_pk_mul_f32 v[78:79], v[148:149], v[70:71]
	v_lshl_add_u64 v[74:75], v[74:75], 1, s[2:3]
	s_nop 0
	s_nop 0
	v_cvt_pk_bf16_f32 v76, v78, v78
	v_cvt_pk_bf16_f32 v67, v79, v79
	v_lshrrev_b32_e32 v76, 16, v76
	v_and_or_b32 v67, v67, s28, v76
	global_store_dword v[74:75], v67, off
	v_mov_b32_e32 v74, v68
	v_mov_b32_e32 v75, v72
	v_mov_b32_e32 v67, v1
	v_pk_fma_f32 v[74:75], v[150:151], v[74:75], v[88:89]
	v_lshl_add_u64 v[78:79], v[66:67], 2, s[0:1]
	global_store_dwordx2 v[78:79], v[74:75], off
	v_pk_mul_f32 v[78:79], v[152:153], v[74:75]
	v_pk_mul_f32 v[70:71], v[70:71], v[70:71]
	v_and_b32_sdwa v80, v78, v178 dst_sel:DWORD dst_unused:UNUSED_PAD src0_sel:WORD_1 src1_sel:DWORD
	s_nop 0
	v_add3_u32 v78, v78, v80, s81
	v_cvt_pk_bf16_f32 v76, v79, v79
	v_lshrrev_b32_e32 v78, 16, v78
	v_pk_mul_f32 v[74:75], v[74:75], v[74:75]
	v_and_or_b32 v76, v76, s28, v78
	v_lshl_add_u64 v[78:79], v[66:67], 1, s[2:3]
	v_add_f32_e32 v67, v74, v75
	v_add_f32_e32 v70, v70, v71
	v_add_f32_e32 v67, v70, v67
	global_store_dword v[78:79], v76, off
	s_nop 0
	v_add_f32_dpp v67, v67, v67 quad_perm:[1,0,3,2] row_mask:0xf bank_mask:0xf bound_ctrl:1
	s_nop 1
	v_add_f32_dpp v67, v67, v67 quad_perm:[2,3,0,1] row_mask:0xf bank_mask:0xf bound_ctrl:1
	s_nop 1
	v_add_f32_dpp v67, v67, v67 row_half_mirror row_mask:0xf bank_mask:0xf bound_ctrl:1
	s_nop 1
	v_mov_b32_dpp v70, v67 row_mirror row_mask:0xf bank_mask:0xf bound_ctrl:1
	s_and_saveexec_b64 s[10:11], s[4:5]
	s_cbranch_execz .LBB0_739
	v_add_f32_e32 v67, v67, v70
	v_lshlrev_b32_e32 v70, 4, v163
	v_ashrrev_i32_e32 v71, 31, v70
	v_lshl_add_u64 v[70:71], v[70:71], 2, v[142:143]
	global_store_dword v[70:71], v67, off offset:3200

; __device__ __forceinline__ unsigned pack2(float a, float b) { return (unsigned)f2bf(a) | ((unsigned)f2bf(b) << 16); }
; __device__ __forceinline__ float dpp_row_sum16(float v) {
;   v += __int_as_float(__builtin_amdgcn_update_dpp(0, __float_as_int(v), 0xB1, 0xF, 0xF, true));
;   v += __int_as_float(__builtin_amdgcn_update_dpp(0, __float_as_int(v), 0x4E, 0xF, 0xF, true));
;   v += __int_as_float(__builtin_amdgcn_update_dpp(0, __float_as_int(v), 0x141, 0xF, 0xF, true));
;   v += __int_as_float(__builtin_amdgcn_update_dpp(0, __float_as_int(v), 0x140, 0xF, 0xF, true));
;   return v;
; }
; template <int EPI, bool HS = false>
; __device__ __forceinline__ void gemm_phase(const Params& p, const GemmCfg& g, char* shm, const int wave_s) {
;     ...
;             for (int bj = 0; bj < 2; ++bj) {
;               float2 xn;
;               xn.x = xv[j][bj].x + gt[bj][0] * acc[ai][bj][m][0][j];
;               xn.y = xv[j][bj].y + gt[bj][1] * acc[ai][bj][m][1][j];
;               const unsigned o = tb + (unsigned)((ai * 128 + m * 16 + j) * 1024 + bj * 128);
;               *(float2*)(xout_t + o) = xn;
;               if (g.has_next) *(unsigned*)(xg_t + o) = pack2(xn.x * gn[bj][0], xn.y * gn[bj][1]);
;               ss += xn.x * xn.x + xn.y * xn.y;
;             }
;             if (g.has_next) {
;               ss = dpp_row_sum16(ss);
;               if (fr == 0) rss_t[(wr * 64 + fq * 4 + ai * 128 + m * 16 + j) * 16] = ss;
;             }
.LBB0_742:
	v_or_b32_e32 v74, 0xcc00, v0
	v_mov_b32_e32 v80, v77
	v_mov_b32_e32 v75, v1
	s_waitcnt lgkmcnt(0)
	v_pk_fma_f32 v[70:71], v[154:155], v[80:81], v[82:83]
	v_lshl_add_u64 v[66:67], v[74:75], 2, s[0:1]
	global_store_dwordx2 v[66:67], v[70:71], off
	s_mov_b64 s[10:11], -1
	s_and_b64 vcc, exec, s[6:7]
	v_or_b32_e32 v66, 0xcc80, v0
	s_cbranch_vccnz .LBB0_746
	v_pk_mul_f32 v[76:77], v[148:149], v[70:71]
	v_lshl_add_u64 v[74:75], v[74:75], 1, s[2:3]
	s_nop 0
	s_nop 0
	v_cvt_pk_bf16_f32 v68, v76, v76
	v_cvt_pk_bf16_f32 v67, v77, v77
	v_lshrrev_b32_e32 v68, 16, v68
	v_and_or_b32 v67, v67, s28, v68
	global_store_dword v[74:75], v67, off
	v_mov_b32_e32 v72, v69
	v_mov_b32_e32 v67, v1
	v_pk_fma_f32 v[74:75], v[150:151], v[72:73], v[84:85]
	v_lshl_add_u64 v[76:77], v[66:67], 2, s[0:1]
	global_store_dwordx2 v[76:77], v[74:75], off
	v_pk_mul_f32 v[76:77], v[152:153], v[74:75]
	v_pk_mul_f32 v[70:71], v[70:71], v[70:71]
	s_nop 0
	s_nop 0
	v_cvt_pk_bf16_f32 v72, v76, v76
	v_cvt_pk_bf16_f32 v68, v77, v77
	v_lshrrev_b32_e32 v72, 16, v72
	v_and_or_b32 v68, v68, s28, v72
	v_lshl_add_u64 v[76:77], v[66:67], 1, s[2:3]
	v_pk_mul_f32 v[74:75], v[74:75], v[74:75]
	global_store_dword v[76:77], v68, off
	v_add_f32_e32 v67, v74, v75
	v_add_f32_e32 v68, v70, v71
	v_add_f32_e32 v67, v68, v67
	s_nop 1
	v_add_f32_dpp v67, v67, v67 quad_perm:[1,0,3,2] row_mask:0xf bank_mask:0xf bound_ctrl:1
	s_nop 1
	v_add_f32_dpp v67, v67, v67 quad_perm:[2,3,0,1] row_mask:0xf bank_mask:0xf bound_ctrl:1
	s_nop 1
	v_add_f32_dpp v67, v67, v67 row_half_mirror row_mask:0xf bank_mask:0xf bound_ctrl:1
	s_nop 1
	v_mov_b32_dpp v68, v67 row_mirror row_mask:0xf bank_mask:0xf bound_ctrl:1
	s_and_saveexec_b64 s[10:11], s[4:5]
	s_cbranch_execz .LBB0_745
	v_lshlrev_b32_e32 v70, 4, v163
	v_ashrrev_i32_e32 v71, 31, v70
	v_add_f32_e32 v67, v67, v68
	v_lshl_add_u64 v[70:71], v[70:71], 2, v[142:143]
	global_store_dword v[70:71], v67, off offset:3264

; __device__ __forceinline__ unsigned pack2(float a, float b) { return (unsigned)f2bf(a) | ((unsigned)f2bf(b) << 16); }
; #define WAIT_V(n) asm volatile("s_waitcnt vmcnt(" #n ")" ::: "memory")
; template <int EPI, bool HS = false>
; __device__ __forceinline__ void gemm_phase(const Params& p, const GemmCfg& g, char* shm, const int wave_s) {
;     ...
; #pragma unroll
;       for (int ai = 0; ai < 2; ++ai) {
; #pragma unroll
;         for (int i = 0; i < 16; ++i) {
;           const int r = wv_s * 16 + i;
;           glds_row(xin_t + (size_t)(ai * 128 + r) * 1024, (unsigned)lane * 16u, ldsb + (unsigned)(r * XROW));
;         }
;         WAIT_V(0);
;         __syncthreads();
; #pragma unroll
;         for (int m = 0; m < 4; ++m) {
;           float2 xv[4][2];
; #pragma unroll
;           for (int j = 0; j < 4; ++j)
; #pragma unroll
;             for (int bj = 0; bj < 2; ++bj) xv[j][bj] = *(const float2*)(xl + (m * 16 + j) * XROW + bj * 512);
; #pragma unroll
;           for (int j = 0; j < 4; ++j) {
;             float ss = 0.f;
; #pragma unroll
;             for (int bj = 0; bj < 2; ++bj) {
;               float2 xn;
;               xn.x = xv[j][bj].x + gt[bj][0] * acc[ai][bj][m][0][j];
;               xn.y = xv[j][bj].y + gt[bj][1] * acc[ai][bj][m][1][j];
;               const unsigned o = tb + (unsigned)((ai * 128 + m * 16 + j) * 1024 + bj * 128);
;               *(float2*)(xout_t + o) = xn;
;               if (g.has_next) *(unsigned*)(xg_t + o) = pack2(xn.x * gn[bj][0], xn.y * gn[bj][1]);
;               ss += xn.x * xn.x + xn.y * xn.y;
;             }
;             if (g.has_next) {
;               ss = dpp_row_sum16(ss);
;               if (fr == 0) rss_t[(wr * 64 + fq * 4 + ai * 128 + m * 16 + j) * 16] = ss;
;             }
.LBB0_748:
	s_lshl_b64 s[8:9], s[8:9], 12
	s_add_u32 s10, s71, s8
	s_addc_u32 s11, s72, s9
	s_add_u32 s8, s10, 0x80000
	s_addc_u32 s9, s11, 0
	s_waitcnt vmcnt(63) expcnt(7) lgkmcnt(15)
	s_barrier
	s_mov_b32 m0, s73
	s_nop 0
	global_load_lds_dwordx4 v167, s[8:9]
	s_add_u32 s8, s10, 0x81000
	s_addc_u32 s9, s11, 0
	s_mov_b32 m0, s74
	s_nop 0
	global_load_lds_dwordx4 v167, s[8:9]
	s_add_u32 s8, s10, 0x82000
	s_addc_u32 s9, s11, 0
	s_mov_b32 m0, s12
	s_nop 0
	global_load_lds_dwordx4 v167, s[8:9]
	s_add_u32 s8, s10, 0x83000
	s_addc_u32 s9, s11, 0
	s_mov_b32 m0, s13
	s_nop 0
	global_load_lds_dwordx4 v167, s[8:9]
	s_add_u32 s8, s10, 0x84000
	s_addc_u32 s9, s11, 0
	s_mov_b32 m0, s14
	s_nop 0
	global_load_lds_dwordx4 v167, s[8:9]
	s_add_u32 s8, s10, 0x85000
	s_addc_u32 s9, s11, 0
	s_mov_b32 m0, s15
	s_nop 0
	global_load_lds_dwordx4 v167, s[8:9]
	s_add_u32 s8, s10, 0x86000
	s_addc_u32 s9, s11, 0
	s_mov_b32 m0, s16
	s_nop 0
	global_load_lds_dwordx4 v167, s[8:9]
	s_add_u32 s8, s10, 0x87000
	s_addc_u32 s9, s11, 0
	s_mov_b32 m0, s17
	s_nop 0
	global_load_lds_dwordx4 v167, s[8:9]
	s_add_u32 s8, s10, 0x88000
	s_addc_u32 s9, s11, 0
	s_mov_b32 m0, s18
	s_nop 0
	global_load_lds_dwordx4 v167, s[8:9]
	s_add_u32 s8, s10, 0x89000
	s_addc_u32 s9, s11, 0
	s_mov_b32 m0, s19
	s_nop 0
	global_load_lds_dwordx4 v167, s[8:9]
	s_add_u32 s8, s10, 0x8a000
	s_addc_u32 s9, s11, 0
	s_mov_b32 m0, s20
	s_nop 0
	global_load_lds_dwordx4 v167, s[8:9]
	s_add_u32 s8, s10, 0x8b000
	s_addc_u32 s9, s11, 0
	s_mov_b32 m0, s21
	s_nop 0
	global_load_lds_dwordx4 v167, s[8:9]
	s_add_u32 s8, s10, 0x8c000
	s_addc_u32 s9, s11, 0
	s_mov_b32 m0, s22
	s_nop 0
	global_load_lds_dwordx4 v167, s[8:9]
	s_add_u32 s8, s10, 0x8d000
	s_addc_u32 s9, s11, 0
	s_mov_b32 m0, s23
	s_nop 0
	global_load_lds_dwordx4 v167, s[8:9]
	s_add_u32 s8, s10, 0x8e000
	s_addc_u32 s9, s11, 0
	s_mov_b32 m0, s24
	s_nop 0
	global_load_lds_dwordx4 v167, s[8:9]
	s_add_u32 s8, s10, 0x8f000
	s_addc_u32 s9, s11, 0
	s_mov_b32 m0, s25
	s_nop 0
	global_load_lds_dwordx4 v167, s[8:9]
	s_waitcnt vmcnt(0)
	s_barrier
	ds_read2st64_b64 v[78:81], v164 offset1:1
	ds_read2_b64 v[74:77], v164 offset0:130 offset1:194
	ds_read2st64_b64 v[70:73], v165 offset0:4 offset1:5
	ds_read2st64_b64 v[66:69], v166 offset0:6 offset1:7
	v_add_u32_e32 v84, 0x20000, v0
	v_mov_b32_e32 v82, v58
	v_mov_b32_e32 v83, v62
	v_mov_b32_e32 v85, v1
	s_waitcnt lgkmcnt(3)
	v_pk_fma_f32 v[82:83], v[154:155], v[82:83], v[78:79]
	v_lshl_add_u64 v[78:79], v[84:85], 2, s[0:1]
	global_store_dwordx2 v[78:79], v[82:83], off
	s_mov_b64 s[8:9], -1
	s_and_b64 vcc, exec, s[6:7]
	v_add_u32_e32 v78, 0x20080, v0
	s_cbranch_vccnz .LBB0_752
	v_pk_mul_f32 v[86:87], v[148:149], v[82:83]
	v_lshl_add_u64 v[84:85], v[84:85], 1, s[2:3]
	s_nop 0
	s_nop 0
	v_cvt_pk_bf16_f32 v62, v86, v86
	v_cvt_pk_bf16_f32 v58, v87, v87
	v_lshrrev_b32_e32 v62, 16, v62
	v_and_or_b32 v58, v58, s28, v62
	global_store_dword v[84:85], v58, off
	v_mov_b32_e32 v84, v50
	v_mov_b32_e32 v85, v54
	v_mov_b32_e32 v79, v1
	v_pk_fma_f32 v[84:85], v[150:151], v[84:85], v[80:81]
	v_lshl_add_u64 v[86:87], v[78:79], 2, s[0:1]
	global_store_dwordx2 v[86:87], v[84:85], off
	v_pk_mul_f32 v[86:87], v[152:153], v[84:85]
	v_pk_mul_f32 v[82:83], v[82:83], v[82:83]
	s_nop 0
	s_nop 0
	v_cvt_pk_bf16_f32 v62, v86, v86
	v_cvt_pk_bf16_f32 v58, v87, v87
	v_lshrrev_b32_e32 v62, 16, v62
	v_and_or_b32 v58, v58, s28, v62
	v_lshl_add_u64 v[86:87], v[78:79], 1, s[2:3]
	v_pk_mul_f32 v[84:85], v[84:85], v[84:85]
	global_store_dword v[86:87], v58, off
	v_add_f32_e32 v58, v84, v85
	v_add_f32_e32 v62, v82, v83
	v_add_f32_e32 v58, v62, v58
	s_nop 1
	v_add_f32_dpp v58, v58, v58 quad_perm:[1,0,3,2] row_mask:0xf bank_mask:0xf bound_ctrl:1
	s_nop 1
	v_add_f32_dpp v58, v58, v58 quad_perm:[2,3,0,1] row_mask:0xf bank_mask:0xf bound_ctrl:1
	s_nop 1
	v_add_f32_dpp v58, v58, v58 row_half_mirror row_mask:0xf bank_mask:0xf bound_ctrl:1
	s_nop 1
	v_mov_b32_dpp v62, v58 row_mirror row_mask:0xf bank_mask:0xf bound_ctrl:1
	s_and_saveexec_b64 s[8:9], s[4:5]
	s_cbranch_execz .LBB0_751
	v_add_f32_e32 v58, v58, v62
	v_mov_b32_e32 v62, 0x800
	v_lshl_add_u32 v82, v163, 4, v62
	v_ashrrev_i32_e32 v83, 31, v82
	v_lshl_add_u64 v[82:83], v[82:83], 2, v[142:143]
	global_store_dword v[82:83], v58, off

; __device__ __forceinline__ unsigned pack2(float a, float b) { return (unsigned)f2bf(a) | ((unsigned)f2bf(b) << 16); }
; __device__ __forceinline__ float dpp_row_sum16(float v) {
;   v += __int_as_float(__builtin_amdgcn_update_dpp(0, __float_as_int(v), 0xB1, 0xF, 0xF, true));
;   v += __int_as_float(__builtin_amdgcn_update_dpp(0, __float_as_int(v), 0x4E, 0xF, 0xF, true));
;   v += __int_as_float(__builtin_amdgcn_update_dpp(0, __float_as_int(v), 0x141, 0xF, 0xF, true));
;   v += __int_as_float(__builtin_amdgcn_update_dpp(0, __float_as_int(v), 0x140, 0xF, 0xF, true));
;   return v;
; }
; template <int EPI, bool HS = false>
; __device__ __forceinline__ void gemm_phase(const Params& p, const GemmCfg& g, char* shm, const int wave_s) {
;     ...
;             for (int bj = 0; bj < 2; ++bj) {
;               float2 xn;
;               xn.x = xv[j][bj].x + gt[bj][0] * acc[ai][bj][m][0][j];
;               xn.y = xv[j][bj].y + gt[bj][1] * acc[ai][bj][m][1][j];
;               const unsigned o = tb + (unsigned)((ai * 128 + m * 16 + j) * 1024 + bj * 128);
;               *(float2*)(xout_t + o) = xn;
;               if (g.has_next) *(unsigned*)(xg_t + o) = pack2(xn.x * gn[bj][0], xn.y * gn[bj][1]);
;               ss += xn.x * xn.x + xn.y * xn.y;
;             }
;             if (g.has_next) {
;               ss = dpp_row_sum16(ss);
;               if (fr == 0) rss_t[(wr * 64 + fq * 4 + ai * 128 + m * 16 + j) * 16] = ss;
;             }
.LBB0_754:
	v_add_u32_e32 v78, 0x20400, v0
	v_mov_b32_e32 v62, v59
	v_mov_b32_e32 v79, v1
	s_waitcnt lgkmcnt(2)
	v_pk_fma_f32 v[62:63], v[154:155], v[62:63], v[74:75]
	v_lshl_add_u64 v[58:59], v[78:79], 2, s[0:1]
	global_store_dwordx2 v[58:59], v[62:63], off
	s_mov_b64 s[8:9], -1
	s_and_b64 vcc, exec, s[6:7]
	v_add_u32_e32 v58, 0x20480, v0
	s_cbranch_vccnz .LBB0_758
	v_pk_mul_f32 v[74:75], v[148:149], v[62:63]
	v_mov_b32_e32 v59, v1
	s_nop 0
	s_nop 0
	v_cvt_pk_bf16_f32 v54, v74, v74
	v_cvt_pk_bf16_f32 v50, v75, v75
	v_lshrrev_b32_e32 v54, 16, v54
	v_and_or_b32 v50, v50, s28, v54
	v_lshl_add_u64 v[74:75], v[78:79], 1, s[2:3]
	v_mov_b32_e32 v54, v51
	global_store_dword v[74:75], v50, off
	v_pk_fma_f32 v[74:75], v[150:151], v[54:55], v[76:77]
	v_lshl_add_u64 v[78:79], v[58:59], 2, s[0:1]
	global_store_dwordx2 v[78:79], v[74:75], off
	v_pk_mul_f32 v[78:79], v[152:153], v[74:75]
	v_pk_mul_f32 v[62:63], v[62:63], v[62:63]
	s_nop 0
	s_nop 0
	v_cvt_pk_bf16_f32 v54, v78, v78
	v_cvt_pk_bf16_f32 v50, v79, v79
	v_lshrrev_b32_e32 v54, 16, v54
	v_and_or_b32 v50, v50, s28, v54
	v_lshl_add_u64 v[78:79], v[58:59], 1, s[2:3]
	v_pk_mul_f32 v[74:75], v[74:75], v[74:75]
	global_store_dword v[78:79], v50, off
	v_add_f32_e32 v50, v74, v75
	v_add_f32_e32 v54, v62, v63
	v_add_f32_e32 v50, v54, v50
	s_nop 1
	v_add_f32_dpp v50, v50, v50 quad_perm:[1,0,3,2] row_mask:0xf bank_mask:0xf bound_ctrl:1
	s_nop 1
	v_add_f32_dpp v50, v50, v50 quad_perm:[2,3,0,1] row_mask:0xf bank_mask:0xf bound_ctrl:1
	s_nop 1
	v_add_f32_dpp v50, v50, v50 row_half_mirror row_mask:0xf bank_mask:0xf bound_ctrl:1
	s_nop 1
	v_mov_b32_dpp v54, v50 row_mirror row_mask:0xf bank_mask:0xf bound_ctrl:1
	s_and_saveexec_b64 s[8:9], s[4:5]
	s_cbranch_execz .LBB0_757
	v_add_f32_e32 v50, v50, v54
	v_mov_b32_e32 v54, 0x810
	v_lshl_add_u32 v62, v163, 4, v54
	v_ashrrev_i32_e32 v63, 31, v62
	v_lshl_add_u64 v[62:63], v[62:63], 2, v[142:143]
	global_store_dword v[62:63], v50, off

; __device__ __forceinline__ unsigned pack2(float a, float b) { return (unsigned)f2bf(a) | ((unsigned)f2bf(b) << 16); }
; __device__ __forceinline__ float dpp_row_sum16(float v) {
;   v += __int_as_float(__builtin_amdgcn_update_dpp(0, __float_as_int(v), 0xB1, 0xF, 0xF, true));
;   v += __int_as_float(__builtin_amdgcn_update_dpp(0, __float_as_int(v), 0x4E, 0xF, 0xF, true));
;   v += __int_as_float(__builtin_amdgcn_update_dpp(0, __float_as_int(v), 0x141, 0xF, 0xF, true));
;   v += __int_as_float(__builtin_amdgcn_update_dpp(0, __float_as_int(v), 0x140, 0xF, 0xF, true));
;   return v;
; }
; template <int EPI, bool HS = false>
; __device__ __forceinline__ void gemm_phase(const Params& p, const GemmCfg& g, char* shm, const int wave_s) {
;     ...
;             for (int bj = 0; bj < 2; ++bj) {
;               float2 xn;
;               xn.x = xv[j][bj].x + gt[bj][0] * acc[ai][bj][m][0][j];
;               xn.y = xv[j][bj].y + gt[bj][1] * acc[ai][bj][m][1][j];
;               const unsigned o = tb + (unsigned)((ai * 128 + m * 16 + j) * 1024 + bj * 128);
;               *(float2*)(xout_t + o) = xn;
;               if (g.has_next) *(unsigned*)(xg_t + o) = pack2(xn.x * gn[bj][0], xn.y * gn[bj][1]);
;               ss += xn.x * xn.x + xn.y * xn.y;
;             }
;             if (g.has_next) {
;               ss = dpp_row_sum16(ss);
;               if (fr == 0) rss_t[(wr * 64 + fq * 4 + ai * 128 + m * 16 + j) * 16] = ss;
;             }
.LBB0_760:
	v_add_u32_e32 v58, 0x20800, v0
	v_mov_b32_e32 v50, v60
	v_mov_b32_e32 v51, v64
	v_mov_b32_e32 v59, v1
	s_waitcnt lgkmcnt(1)
	v_pk_fma_f32 v[54:55], v[154:155], v[50:51], v[70:71]
	v_lshl_add_u64 v[50:51], v[58:59], 2, s[0:1]
	global_store_dwordx2 v[50:51], v[54:55], off
	s_mov_b64 s[8:9], -1
	s_and_b64 vcc, exec, s[6:7]
	v_add_u32_e32 v50, 0x20880, v0
	s_cbranch_vccnz .LBB0_764
	v_pk_mul_f32 v[62:63], v[148:149], v[54:55]
	v_lshl_add_u64 v[58:59], v[58:59], 1, s[2:3]
	s_nop 0
	s_nop 0
	v_cvt_pk_bf16_f32 v60, v62, v62
	v_cvt_pk_bf16_f32 v51, v63, v63
	v_lshrrev_b32_e32 v60, 16, v60
	v_and_or_b32 v51, v51, s28, v60
	global_store_dword v[58:59], v51, off
	v_mov_b32_e32 v58, v52
	v_mov_b32_e32 v59, v56
	v_mov_b32_e32 v51, v1
	v_pk_fma_f32 v[58:59], v[150:151], v[58:59], v[72:73]
	v_lshl_add_u64 v[62:63], v[50:51], 2, s[0:1]
	global_store_dwordx2 v[62:63], v[58:59], off
	v_pk_mul_f32 v[62:63], v[152:153], v[58:59]
	v_pk_mul_f32 v[54:55], v[54:55], v[54:55]
	v_and_b32_sdwa v64, v62, v178 dst_sel:DWORD dst_unused:UNUSED_PAD src0_sel:WORD_1 src1_sel:DWORD
	s_nop 0
	v_add3_u32 v62, v62, v64, s81
	v_cvt_pk_bf16_f32 v60, v63, v63
	v_lshrrev_b32_e32 v62, 16, v62
	v_pk_mul_f32 v[58:59], v[58:59], v[58:59]
	v_and_or_b32 v60, v60, s28, v62
	v_lshl_add_u64 v[62:63], v[50:51], 1, s[2:3]
	v_add_f32_e32 v51, v58, v59
	v_add_f32_e32 v54, v54, v55
	v_add_f32_e32 v51, v54, v51
	global_store_dword v[62:63], v60, off
	s_nop 0
	v_add_f32_dpp v51, v51, v51 quad_perm:[1,0,3,2] row_mask:0xf bank_mask:0xf bound_ctrl:1
	s_nop 1
	v_add_f32_dpp v51, v51, v51 quad_perm:[2,3,0,1] row_mask:0xf bank_mask:0xf bound_ctrl:1
	s_nop 1
	v_add_f32_dpp v51, v51, v51 row_half_mirror row_mask:0xf bank_mask:0xf bound_ctrl:1
	s_nop 1
	v_mov_b32_dpp v54, v51 row_mirror row_mask:0xf bank_mask:0xf bound_ctrl:1
	s_and_saveexec_b64 s[8:9], s[4:5]
	s_cbranch_execz .LBB0_763
	v_add_f32_e32 v51, v51, v54
	v_mov_b32_e32 v54, 0x820
	v_lshl_add_u32 v54, v163, 4, v54
	v_ashrrev_i32_e32 v55, 31, v54
	v_lshl_add_u64 v[54:55], v[54:55], 2, v[142:143]
	global_store_dword v[54:55], v51, off

; __device__ __forceinline__ unsigned pack2(float a, float b) { return (unsigned)f2bf(a) | ((unsigned)f2bf(b) << 16); }
; __device__ __forceinline__ float dpp_row_sum16(float v) {
;   v += __int_as_float(__builtin_amdgcn_update_dpp(0, __float_as_int(v), 0xB1, 0xF, 0xF, true));
;   v += __int_as_float(__builtin_amdgcn_update_dpp(0, __float_as_int(v), 0x4E, 0xF, 0xF, true));
;   v += __int_as_float(__builtin_amdgcn_update_dpp(0, __float_as_int(v), 0x141, 0xF, 0xF, true));
;   v += __int_as_float(__builtin_amdgcn_update_dpp(0, __float_as_int(v), 0x140, 0xF, 0xF, true));
;   return v;
; }
; template <int EPI, bool HS = false>
; __device__ __forceinline__ void gemm_phase(const Params& p, const GemmCfg& g, char* shm, const int wave_s) {
;     ...
;             for (int bj = 0; bj < 2; ++bj) {
;               float2 xn;
;               xn.x = xv[j][bj].x + gt[bj][0] * acc[ai][bj][m][0][j];
;               xn.y = xv[j][bj].y + gt[bj][1] * acc[ai][bj][m][1][j];
;               const unsigned o = tb + (unsigned)((ai * 128 + m * 16 + j) * 1024 + bj * 128);
;               *(float2*)(xout_t + o) = xn;
;               if (g.has_next) *(unsigned*)(xg_t + o) = pack2(xn.x * gn[bj][0], xn.y * gn[bj][1]);
;               ss += xn.x * xn.x + xn.y * xn.y;
;             }
;             if (g.has_next) {
;               ss = dpp_row_sum16(ss);
;               if (fr == 0) rss_t[(wr * 64 + fq * 4 + ai * 128 + m * 16 + j) * 16] = ss;
;             }
.LBB0_766:
	v_add_u32_e32 v58, 0x20c00, v0
	v_mov_b32_e32 v64, v61
	v_mov_b32_e32 v59, v1
	s_waitcnt lgkmcnt(0)
	v_pk_fma_f32 v[54:55], v[154:155], v[64:65], v[66:67]
	v_lshl_add_u64 v[50:51], v[58:59], 2, s[0:1]
	global_store_dwordx2 v[50:51], v[54:55], off
	s_mov_b64 s[8:9], -1
	s_and_b64 vcc, exec, s[6:7]
	v_add_u32_e32 v50, 0x20c80, v0
	s_cbranch_vccnz .LBB0_770
	v_pk_mul_f32 v[60:61], v[148:149], v[54:55]
	v_lshl_add_u64 v[58:59], v[58:59], 1, s[2:3]
	s_nop 0
	s_nop 0
	v_cvt_pk_bf16_f32 v52, v60, v60
	v_cvt_pk_bf16_f32 v51, v61, v61
	v_lshrrev_b32_e32 v52, 16, v52
	v_and_or_b32 v51, v51, s28, v52
	global_store_dword v[58:59], v51, off
	v_mov_b32_e32 v56, v53
	v_mov_b32_e32 v51, v1
	v_pk_fma_f32 v[58:59], v[150:151], v[56:57], v[68:69]
	v_lshl_add_u64 v[60:61], v[50:51], 2, s[0:1]
	global_store_dwordx2 v[60:61], v[58:59], off
	v_pk_mul_f32 v[60:61], v[152:153], v[58:59]
	v_pk_mul_f32 v[54:55], v[54:55], v[54:55]
	s_nop 0
	s_nop 0
	v_cvt_pk_bf16_f32 v56, v60, v60
	v_cvt_pk_bf16_f32 v52, v61, v61
	v_lshrrev_b32_e32 v56, 16, v56
	v_and_or_b32 v52, v52, s28, v56
	v_lshl_add_u64 v[60:61], v[50:51], 1, s[2:3]
	v_pk_mul_f32 v[58:59], v[58:59], v[58:59]
	global_store_dword v[60:61], v52, off
	v_add_f32_e32 v51, v58, v59
	v_add_f32_e32 v52, v54, v55
	v_add_f32_e32 v51, v52, v51
	s_nop 1
	v_add_f32_dpp v51, v51, v51 quad_perm:[1,0,3,2] row_mask:0xf bank_mask:0xf bound_ctrl:1
	s_nop 1
	v_add_f32_dpp v51, v51, v51 quad_perm:[2,3,0,1] row_mask:0xf bank_mask:0xf bound_ctrl:1
	s_nop 1
	v_add_f32_dpp v51, v51, v51 row_half_mirror row_mask:0xf bank_mask:0xf bound_ctrl:1
	s_nop 1
	v_mov_b32_dpp v52, v51 row_mirror row_mask:0xf bank_mask:0xf bound_ctrl:1
	s_and_saveexec_b64 s[8:9], s[4:5]
	s_cbranch_execz .LBB0_769
	v_add_f32_e32 v51, v51, v52
	v_mov_b32_e32 v52, 0x830
	v_lshl_add_u32 v54, v163, 4, v52
	v_ashrrev_i32_e32 v55, 31, v54
	v_lshl_add_u64 v[54:55], v[54:55], 2, v[142:143]
	global_store_dword v[54:55], v51, off

; __device__ __forceinline__ unsigned pack2(float a, float b) { return (unsigned)f2bf(a) | ((unsigned)f2bf(b) << 16); }
; template <int EPI, bool HS = false>
; __device__ __forceinline__ void gemm_phase(const Params& p, const GemmCfg& g, char* shm, const int wave_s) {
;     ...
; #pragma unroll
;         for (int m = 0; m < 4; ++m) {
;           float2 xv[4][2];
; #pragma unroll
;           for (int j = 0; j < 4; ++j)
; #pragma unroll
;             for (int bj = 0; bj < 2; ++bj) xv[j][bj] = *(const float2*)(xl + (m * 16 + j) * XROW + bj * 512);
; #pragma unroll
;           for (int j = 0; j < 4; ++j) {
;             float ss = 0.f;
; #pragma unroll
;             for (int bj = 0; bj < 2; ++bj) {
;               float2 xn;
;               xn.x = xv[j][bj].x + gt[bj][0] * acc[ai][bj][m][0][j];
;               xn.y = xv[j][bj].y + gt[bj][1] * acc[ai][bj][m][1][j];
;               const unsigned o = tb + (unsigned)((ai * 128 + m * 16 + j) * 1024 + bj * 128);
;               *(float2*)(xout_t + o) = xn;
;               if (g.has_next) *(unsigned*)(xg_t + o) = pack2(xn.x * gn[bj][0], xn.y * gn[bj][1]);
;               ss += xn.x * xn.x + xn.y * xn.y;
;             }
;             if (g.has_next) {
;               ss = dpp_row_sum16(ss);
;               if (fr == 0) rss_t[(wr * 64 + fq * 4 + ai * 128 + m * 16 + j) * 16] = ss;
;             }
.LBB0_772:
	ds_read2st64_b64 v[62:65], v134 offset0:32 offset1:33
	ds_read2st64_b64 v[58:61], v135 offset0:34 offset1:35
	ds_read2st64_b64 v[54:57], v136 offset0:36 offset1:37
	ds_read2st64_b64 v[50:53], v137 offset0:38 offset1:39
	v_add_u32_e32 v68, 0x24000, v0
	v_mov_b32_e32 v66, v42
	v_mov_b32_e32 v67, v46
	v_mov_b32_e32 v69, v1
	s_waitcnt lgkmcnt(3)
	v_pk_fma_f32 v[66:67], v[154:155], v[66:67], v[62:63]
	v_lshl_add_u64 v[62:63], v[68:69], 2, s[0:1]
	global_store_dwordx2 v[62:63], v[66:67], off
	s_mov_b64 s[8:9], -1
	s_and_b64 vcc, exec, s[6:7]
	v_add_u32_e32 v62, 0x24080, v0
	s_cbranch_vccnz .LBB0_776
	v_pk_mul_f32 v[70:71], v[148:149], v[66:67]
	v_lshl_add_u64 v[68:69], v[68:69], 1, s[2:3]
	s_nop 0
	s_nop 0
	v_cvt_pk_bf16_f32 v46, v70, v70
	v_cvt_pk_bf16_f32 v42, v71, v71
	v_lshrrev_b32_e32 v46, 16, v46
	v_and_or_b32 v42, v42, s28, v46
	global_store_dword v[68:69], v42, off
	v_mov_b32_e32 v68, v34
	v_mov_b32_e32 v69, v38
	v_mov_b32_e32 v63, v1
	v_pk_fma_f32 v[68:69], v[150:151], v[68:69], v[64:65]
	v_lshl_add_u64 v[70:71], v[62:63], 2, s[0:1]
	global_store_dwordx2 v[70:71], v[68:69], off
	v_pk_mul_f32 v[70:71], v[152:153], v[68:69]
	v_pk_mul_f32 v[66:67], v[66:67], v[66:67]
	s_nop 0
	s_nop 0
	v_cvt_pk_bf16_f32 v46, v70, v70
	v_cvt_pk_bf16_f32 v42, v71, v71
	v_lshrrev_b32_e32 v46, 16, v46
	v_and_or_b32 v42, v42, s28, v46
	v_lshl_add_u64 v[70:71], v[62:63], 1, s[2:3]
	v_pk_mul_f32 v[68:69], v[68:69], v[68:69]
	global_store_dword v[70:71], v42, off
	v_add_f32_e32 v42, v68, v69
	v_add_f32_e32 v46, v66, v67
	v_add_f32_e32 v42, v46, v42
	s_nop 1
	v_add_f32_dpp v42, v42, v42 quad_perm:[1,0,3,2] row_mask:0xf bank_mask:0xf bound_ctrl:1
	s_nop 1
	v_add_f32_dpp v42, v42, v42 quad_perm:[2,3,0,1] row_mask:0xf bank_mask:0xf bound_ctrl:1
	s_nop 1
	v_add_f32_dpp v42, v42, v42 row_half_mirror row_mask:0xf bank_mask:0xf bound_ctrl:1
	s_nop 1
	v_mov_b32_dpp v46, v42 row_mirror row_mask:0xf bank_mask:0xf bound_ctrl:1
	s_and_saveexec_b64 s[8:9], s[4:5]
	s_cbranch_execz .LBB0_775
	v_add_f32_e32 v42, v42, v46
	v_mov_b32_e32 v46, 0x900
	v_lshl_add_u32 v66, v163, 4, v46
	v_ashrrev_i32_e32 v67, 31, v66
	v_lshl_add_u64 v[66:67], v[66:67], 2, v[142:143]
	global_store_dword v[66:67], v42, off

; __device__ __forceinline__ unsigned pack2(float a, float b) { return (unsigned)f2bf(a) | ((unsigned)f2bf(b) << 16); }
; __device__ __forceinline__ float dpp_row_sum16(float v) {
;   v += __int_as_float(__builtin_amdgcn_update_dpp(0, __float_as_int(v), 0xB1, 0xF, 0xF, true));
;   v += __int_as_float(__builtin_amdgcn_update_dpp(0, __float_as_int(v), 0x4E, 0xF, 0xF, true));
;   v += __int_as_float(__builtin_amdgcn_update_dpp(0, __float_as_int(v), 0x141, 0xF, 0xF, true));
;   v += __int_as_float(__builtin_amdgcn_update_dpp(0, __float_as_int(v), 0x140, 0xF, 0xF, true));
;   return v;
; }
; template <int EPI, bool HS = false>
; __device__ __forceinline__ void gemm_phase(const Params& p, const GemmCfg& g, char* shm, const int wave_s) {
;     ...
;             for (int bj = 0; bj < 2; ++bj) {
;               float2 xn;
;               xn.x = xv[j][bj].x + gt[bj][0] * acc[ai][bj][m][0][j];
;               xn.y = xv[j][bj].y + gt[bj][1] * acc[ai][bj][m][1][j];
;               const unsigned o = tb + (unsigned)((ai * 128 + m * 16 + j) * 1024 + bj * 128);
;               *(float2*)(xout_t + o) = xn;
;               if (g.has_next) *(unsigned*)(xg_t + o) = pack2(xn.x * gn[bj][0], xn.y * gn[bj][1]);
;               ss += xn.x * xn.x + xn.y * xn.y;
;             }
;             if (g.has_next) {
;               ss = dpp_row_sum16(ss);
;               if (fr == 0) rss_t[(wr * 64 + fq * 4 + ai * 128 + m * 16 + j) * 16] = ss;
;             }
.LBB0_778:
	v_add_u32_e32 v62, 0x24400, v0
	v_mov_b32_e32 v46, v43
	v_mov_b32_e32 v63, v1
	s_waitcnt lgkmcnt(2)
	v_pk_fma_f32 v[46:47], v[154:155], v[46:47], v[58:59]
	v_lshl_add_u64 v[42:43], v[62:63], 2, s[0:1]
	global_store_dwordx2 v[42:43], v[46:47], off
	s_mov_b64 s[8:9], -1
	s_and_b64 vcc, exec, s[6:7]
	v_add_u32_e32 v42, 0x24480, v0
	s_cbranch_vccnz .LBB0_782
	v_pk_mul_f32 v[58:59], v[148:149], v[46:47]
	v_mov_b32_e32 v43, v1
	s_nop 0
	s_nop 0
	v_cvt_pk_bf16_f32 v38, v58, v58
	v_cvt_pk_bf16_f32 v34, v59, v59
	v_lshrrev_b32_e32 v38, 16, v38
	v_and_or_b32 v34, v34, s28, v38
	v_lshl_add_u64 v[58:59], v[62:63], 1, s[2:3]
	v_mov_b32_e32 v38, v35
	global_store_dword v[58:59], v34, off
	v_pk_fma_f32 v[58:59], v[150:151], v[38:39], v[60:61]
	v_lshl_add_u64 v[62:63], v[42:43], 2, s[0:1]
	global_store_dwordx2 v[62:63], v[58:59], off
	v_pk_mul_f32 v[62:63], v[152:153], v[58:59]
	v_pk_mul_f32 v[46:47], v[46:47], v[46:47]
	s_nop 0
	s_nop 0
	v_cvt_pk_bf16_f32 v38, v62, v62
	v_cvt_pk_bf16_f32 v34, v63, v63
	v_lshrrev_b32_e32 v38, 16, v38
	v_and_or_b32 v34, v34, s28, v38
	v_lshl_add_u64 v[62:63], v[42:43], 1, s[2:3]
	v_pk_mul_f32 v[58:59], v[58:59], v[58:59]
	global_store_dword v[62:63], v34, off
	v_add_f32_e32 v34, v58, v59
	v_add_f32_e32 v38, v46, v47
	v_add_f32_e32 v34, v38, v34
	s_nop 1
	v_add_f32_dpp v34, v34, v34 quad_perm:[1,0,3,2] row_mask:0xf bank_mask:0xf bound_ctrl:1
	s_nop 1
	v_add_f32_dpp v34, v34, v34 quad_perm:[2,3,0,1] row_mask:0xf bank_mask:0xf bound_ctrl:1
	s_nop 1
	v_add_f32_dpp v34, v34, v34 row_half_mirror row_mask:0xf bank_mask:0xf bound_ctrl:1
	s_nop 1
	v_mov_b32_dpp v38, v34 row_mirror row_mask:0xf bank_mask:0xf bound_ctrl:1
	s_and_saveexec_b64 s[8:9], s[4:5]
	s_cbranch_execz .LBB0_781
	v_add_f32_e32 v34, v34, v38
	v_mov_b32_e32 v38, 0x910
	v_lshl_add_u32 v46, v163, 4, v38
	v_ashrrev_i32_e32 v47, 31, v46
	v_lshl_add_u64 v[46:47], v[46:47], 2, v[142:143]
	global_store_dword v[46:47], v34, off

; __device__ __forceinline__ unsigned pack2(float a, float b) { return (unsigned)f2bf(a) | ((unsigned)f2bf(b) << 16); }
; __device__ __forceinline__ float dpp_row_sum16(float v) {
;   v += __int_as_float(__builtin_amdgcn_update_dpp(0, __float_as_int(v), 0xB1, 0xF, 0xF, true));
;   v += __int_as_float(__builtin_amdgcn_update_dpp(0, __float_as_int(v), 0x4E, 0xF, 0xF, true));
;   v += __int_as_float(__builtin_amdgcn_update_dpp(0, __float_as_int(v), 0x141, 0xF, 0xF, true));
;   v += __int_as_float(__builtin_amdgcn_update_dpp(0, __float_as_int(v), 0x140, 0xF, 0xF, true));
;   return v;
; }
; template <int EPI, bool HS = false>
; __device__ __forceinline__ void gemm_phase(const Params& p, const GemmCfg& g, char* shm, const int wave_s) {
;     ...
;             for (int bj = 0; bj < 2; ++bj) {
;               float2 xn;
;               xn.x = xv[j][bj].x + gt[bj][0] * acc[ai][bj][m][0][j];
;               xn.y = xv[j][bj].y + gt[bj][1] * acc[ai][bj][m][1][j];
;               const unsigned o = tb + (unsigned)((ai * 128 + m * 16 + j) * 1024 + bj * 128);
;               *(float2*)(xout_t + o) = xn;
;               if (g.has_next) *(unsigned*)(xg_t + o) = pack2(xn.x * gn[bj][0], xn.y * gn[bj][1]);
;               ss += xn.x * xn.x + xn.y * xn.y;
;             }
;             if (g.has_next) {
;               ss = dpp_row_sum16(ss);
;               if (fr == 0) rss_t[(wr * 64 + fq * 4 + ai * 128 + m * 16 + j) * 16] = ss;
;             }
.LBB0_784:
	v_add_u32_e32 v42, 0x24800, v0
	v_mov_b32_e32 v34, v44
	v_mov_b32_e32 v35, v48
	v_mov_b32_e32 v43, v1
	s_waitcnt lgkmcnt(1)
	v_pk_fma_f32 v[38:39], v[154:155], v[34:35], v[54:55]
	v_lshl_add_u64 v[34:35], v[42:43], 2, s[0:1]
	global_store_dwordx2 v[34:35], v[38:39], off
	s_mov_b64 s[8:9], -1
	s_and_b64 vcc, exec, s[6:7]
	v_add_u32_e32 v34, 0x24880, v0
	s_cbranch_vccnz .LBB0_788
	v_pk_mul_f32 v[46:47], v[148:149], v[38:39]
	v_lshl_add_u64 v[42:43], v[42:43], 1, s[2:3]
	s_nop 0
	s_nop 0
	v_cvt_pk_bf16_f32 v44, v46, v46
	v_cvt_pk_bf16_f32 v35, v47, v47
	v_lshrrev_b32_e32 v44, 16, v44
	v_and_or_b32 v35, v35, s28, v44
	global_store_dword v[42:43], v35, off
	v_mov_b32_e32 v42, v36
	v_mov_b32_e32 v43, v40
	v_mov_b32_e32 v35, v1
	v_pk_fma_f32 v[42:43], v[150:151], v[42:43], v[56:57]
	v_lshl_add_u64 v[46:47], v[34:35], 2, s[0:1]
	global_store_dwordx2 v[46:47], v[42:43], off
	v_pk_mul_f32 v[46:47], v[152:153], v[42:43]
	v_pk_mul_f32 v[38:39], v[38:39], v[38:39]
	v_and_b32_sdwa v48, v46, v178 dst_sel:DWORD dst_unused:UNUSED_PAD src0_sel:WORD_1 src1_sel:DWORD
	s_nop 0
	v_add3_u32 v46, v46, v48, s81
	v_cvt_pk_bf16_f32 v44, v47, v47
	v_lshrrev_b32_e32 v46, 16, v46
	v_pk_mul_f32 v[42:43], v[42:43], v[42:43]
	v_and_or_b32 v44, v44, s28, v46
	v_lshl_add_u64 v[46:47], v[34:35], 1, s[2:3]
	v_add_f32_e32 v35, v42, v43
	v_add_f32_e32 v38, v38, v39
	v_add_f32_e32 v35, v38, v35
	global_store_dword v[46:47], v44, off
	s_nop 0
	v_add_f32_dpp v35, v35, v35 quad_perm:[1,0,3,2] row_mask:0xf bank_mask:0xf bound_ctrl:1
	s_nop 1
	v_add_f32_dpp v35, v35, v35 quad_perm:[2,3,0,1] row_mask:0xf bank_mask:0xf bound_ctrl:1
	s_nop 1
	v_add_f32_dpp v35, v35, v35 row_half_mirror row_mask:0xf bank_mask:0xf bound_ctrl:1
	s_nop 1
	v_mov_b32_dpp v38, v35 row_mirror row_mask:0xf bank_mask:0xf bound_ctrl:1
	s_and_saveexec_b64 s[8:9], s[4:5]
	s_cbranch_execz .LBB0_787
	v_add_f32_e32 v35, v35, v38
	v_mov_b32_e32 v38, 0x920
	v_lshl_add_u32 v38, v163, 4, v38
	v_ashrrev_i32_e32 v39, 31, v38
	v_lshl_add_u64 v[38:39], v[38:39], 2, v[142:143]
	global_store_dword v[38:39], v35, off

; __device__ __forceinline__ unsigned pack2(float a, float b) { return (unsigned)f2bf(a) | ((unsigned)f2bf(b) << 16); }
; __device__ __forceinline__ float dpp_row_sum16(float v) {
;   v += __int_as_float(__builtin_amdgcn_update_dpp(0, __float_as_int(v), 0xB1, 0xF, 0xF, true));
;   v += __int_as_float(__builtin_amdgcn_update_dpp(0, __float_as_int(v), 0x4E, 0xF, 0xF, true));
;   v += __int_as_float(__builtin_amdgcn_update_dpp(0, __float_as_int(v), 0x141, 0xF, 0xF, true));
;   v += __int_as_float(__builtin_amdgcn_update_dpp(0, __float_as_int(v), 0x140, 0xF, 0xF, true));
;   return v;
; }
; template <int EPI, bool HS = false>
; __device__ __forceinline__ void gemm_phase(const Params& p, const GemmCfg& g, char* shm, const int wave_s) {
;     ...
;             for (int bj = 0; bj < 2; ++bj) {
;               float2 xn;
;               xn.x = xv[j][bj].x + gt[bj][0] * acc[ai][bj][m][0][j];
;               xn.y = xv[j][bj].y + gt[bj][1] * acc[ai][bj][m][1][j];
;               const unsigned o = tb + (unsigned)((ai * 128 + m * 16 + j) * 1024 + bj * 128);
;               *(float2*)(xout_t + o) = xn;
;               if (g.has_next) *(unsigned*)(xg_t + o) = pack2(xn.x * gn[bj][0], xn.y * gn[bj][1]);
;               ss += xn.x * xn.x + xn.y * xn.y;
;             }
;             if (g.has_next) {
;               ss = dpp_row_sum16(ss);
;               if (fr == 0) rss_t[(wr * 64 + fq * 4 + ai * 128 + m * 16 + j) * 16] = ss;
;             }
.LBB0_790:
	v_add_u32_e32 v42, 0x24c00, v0
	v_mov_b32_e32 v48, v45
	v_mov_b32_e32 v43, v1
	s_waitcnt lgkmcnt(0)
	v_pk_fma_f32 v[38:39], v[154:155], v[48:49], v[50:51]
	v_lshl_add_u64 v[34:35], v[42:43], 2, s[0:1]
	global_store_dwordx2 v[34:35], v[38:39], off
	s_mov_b64 s[8:9], -1
	s_and_b64 vcc, exec, s[6:7]
	v_add_u32_e32 v34, 0x24c80, v0
	s_cbranch_vccnz .LBB0_794
	v_pk_mul_f32 v[44:45], v[148:149], v[38:39]
	v_lshl_add_u64 v[42:43], v[42:43], 1, s[2:3]
	s_nop 0
	s_nop 0
	v_cvt_pk_bf16_f32 v36, v44, v44
	v_cvt_pk_bf16_f32 v35, v45, v45
	v_lshrrev_b32_e32 v36, 16, v36
	v_and_or_b32 v35, v35, s28, v36
	global_store_dword v[42:43], v35, off
	v_mov_b32_e32 v40, v37
	v_mov_b32_e32 v35, v1
	v_pk_fma_f32 v[42:43], v[150:151], v[40:41], v[52:53]
	v_lshl_add_u64 v[44:45], v[34:35], 2, s[0:1]
	global_store_dwordx2 v[44:45], v[42:43], off
	v_pk_mul_f32 v[44:45], v[152:153], v[42:43]
	v_pk_mul_f32 v[38:39], v[38:39], v[38:39]
	s_nop 0
	s_nop 0
	v_cvt_pk_bf16_f32 v40, v44, v44
	v_cvt_pk_bf16_f32 v36, v45, v45
	v_lshrrev_b32_e32 v40, 16, v40
	v_and_or_b32 v36, v36, s28, v40
	v_lshl_add_u64 v[44:45], v[34:35], 1, s[2:3]
	v_pk_mul_f32 v[42:43], v[42:43], v[42:43]
	global_store_dword v[44:45], v36, off
	v_add_f32_e32 v35, v42, v43
	v_add_f32_e32 v36, v38, v39
	v_add_f32_e32 v35, v36, v35
	s_nop 1
	v_add_f32_dpp v35, v35, v35 quad_perm:[1,0,3,2] row_mask:0xf bank_mask:0xf bound_ctrl:1
	s_nop 1
	v_add_f32_dpp v35, v35, v35 quad_perm:[2,3,0,1] row_mask:0xf bank_mask:0xf bound_ctrl:1
	s_nop 1
	v_add_f32_dpp v35, v35, v35 row_half_mirror row_mask:0xf bank_mask:0xf bound_ctrl:1
	s_nop 1
	v_mov_b32_dpp v36, v35 row_mirror row_mask:0xf bank_mask:0xf bound_ctrl:1
	s_and_saveexec_b64 s[8:9], s[4:5]
	s_cbranch_execz .LBB0_793
	v_add_f32_e32 v35, v35, v36
	v_mov_b32_e32 v36, 0x930
	v_lshl_add_u32 v38, v163, 4, v36
	v_ashrrev_i32_e32 v39, 31, v38
	v_lshl_add_u64 v[38:39], v[38:39], 2, v[142:143]
	global_store_dword v[38:39], v35, off

; __device__ __forceinline__ unsigned pack2(float a, float b) { return (unsigned)f2bf(a) | ((unsigned)f2bf(b) << 16); }
; template <int EPI, bool HS = false>
; __device__ __forceinline__ void gemm_phase(const Params& p, const GemmCfg& g, char* shm, const int wave_s) {
;     ...
; #pragma unroll
;         for (int m = 0; m < 4; ++m) {
;           float2 xv[4][2];
; #pragma unroll
;           for (int j = 0; j < 4; ++j)
; #pragma unroll
;             for (int bj = 0; bj < 2; ++bj) xv[j][bj] = *(const float2*)(xl + (m * 16 + j) * XROW + bj * 512);
; #pragma unroll
;           for (int j = 0; j < 4; ++j) {
;             float ss = 0.f;
; #pragma unroll
;             for (int bj = 0; bj < 2; ++bj) {
;               float2 xn;
;               xn.x = xv[j][bj].x + gt[bj][0] * acc[ai][bj][m][0][j];
;               xn.y = xv[j][bj].y + gt[bj][1] * acc[ai][bj][m][1][j];
;               const unsigned o = tb + (unsigned)((ai * 128 + m * 16 + j) * 1024 + bj * 128);
;               *(float2*)(xout_t + o) = xn;
;               if (g.has_next) *(unsigned*)(xg_t + o) = pack2(xn.x * gn[bj][0], xn.y * gn[bj][1]);
;               ss += xn.x * xn.x + xn.y * xn.y;
;             }
;             if (g.has_next) {
;               ss = dpp_row_sum16(ss);
;               if (fr == 0) rss_t[(wr * 64 + fq * 4 + ai * 128 + m * 16 + j) * 16] = ss;
;             }
.LBB0_796:
	ds_read2st64_b64 v[46:49], v164 offset0:65 offset1:66
	ds_read2st64_b64 v[42:45], v118 offset0:67 offset1:68
	ds_read2st64_b64 v[38:41], v165 offset0:69 offset1:70
	ds_read2st64_b64 v[34:37], v166 offset0:71 offset1:72
	v_add_u32_e32 v52, 0x28000, v0
	v_mov_b32_e32 v50, v26
	v_mov_b32_e32 v51, v30
	v_mov_b32_e32 v53, v1
	s_waitcnt lgkmcnt(3)
	v_pk_fma_f32 v[50:51], v[154:155], v[50:51], v[46:47]
	v_lshl_add_u64 v[46:47], v[52:53], 2, s[0:1]
	global_store_dwordx2 v[46:47], v[50:51], off
	s_mov_b64 s[8:9], -1
	s_and_b64 vcc, exec, s[6:7]
	v_add_u32_e32 v46, 0x28080, v0
	s_cbranch_vccnz .LBB0_800
	v_pk_mul_f32 v[54:55], v[148:149], v[50:51]
	v_lshl_add_u64 v[52:53], v[52:53], 1, s[2:3]
	s_nop 0
	s_nop 0
	v_cvt_pk_bf16_f32 v30, v54, v54
	v_cvt_pk_bf16_f32 v26, v55, v55
	v_lshrrev_b32_e32 v30, 16, v30
	v_and_or_b32 v26, v26, s28, v30
	global_store_dword v[52:53], v26, off
	v_mov_b32_e32 v52, v18
	v_mov_b32_e32 v53, v22
	v_mov_b32_e32 v47, v1
	v_pk_fma_f32 v[52:53], v[150:151], v[52:53], v[48:49]
	v_lshl_add_u64 v[54:55], v[46:47], 2, s[0:1]
	global_store_dwordx2 v[54:55], v[52:53], off
	v_pk_mul_f32 v[54:55], v[152:153], v[52:53]
	v_pk_mul_f32 v[50:51], v[50:51], v[50:51]
	s_nop 0
	s_nop 0
	v_cvt_pk_bf16_f32 v30, v54, v54
	v_cvt_pk_bf16_f32 v26, v55, v55
	v_lshrrev_b32_e32 v30, 16, v30
	v_and_or_b32 v26, v26, s28, v30
	v_lshl_add_u64 v[54:55], v[46:47], 1, s[2:3]
	v_pk_mul_f32 v[52:53], v[52:53], v[52:53]
	global_store_dword v[54:55], v26, off
	v_add_f32_e32 v26, v52, v53
	v_add_f32_e32 v30, v50, v51
	v_add_f32_e32 v26, v30, v26
	s_nop 1
	v_add_f32_dpp v26, v26, v26 quad_perm:[1,0,3,2] row_mask:0xf bank_mask:0xf bound_ctrl:1
	s_nop 1
	v_add_f32_dpp v26, v26, v26 quad_perm:[2,3,0,1] row_mask:0xf bank_mask:0xf bound_ctrl:1
	s_nop 1
	v_add_f32_dpp v26, v26, v26 row_half_mirror row_mask:0xf bank_mask:0xf bound_ctrl:1
	s_nop 1
	v_mov_b32_dpp v30, v26 row_mirror row_mask:0xf bank_mask:0xf bound_ctrl:1
	s_and_saveexec_b64 s[8:9], s[4:5]
	s_cbranch_execz .LBB0_799
	v_add_f32_e32 v26, v26, v30
	v_mov_b32_e32 v30, 0xa00
	v_lshl_add_u32 v50, v163, 4, v30
	v_ashrrev_i32_e32 v51, 31, v50
	v_lshl_add_u64 v[50:51], v[50:51], 2, v[142:143]
	global_store_dword v[50:51], v26, off

; __device__ __forceinline__ unsigned pack2(float a, float b) { return (unsigned)f2bf(a) | ((unsigned)f2bf(b) << 16); }
; __device__ __forceinline__ float dpp_row_sum16(float v) {
;   v += __int_as_float(__builtin_amdgcn_update_dpp(0, __float_as_int(v), 0xB1, 0xF, 0xF, true));
;   v += __int_as_float(__builtin_amdgcn_update_dpp(0, __float_as_int(v), 0x4E, 0xF, 0xF, true));
;   v += __int_as_float(__builtin_amdgcn_update_dpp(0, __float_as_int(v), 0x141, 0xF, 0xF, true));
;   v += __int_as_float(__builtin_amdgcn_update_dpp(0, __float_as_int(v), 0x140, 0xF, 0xF, true));
;   return v;
; }
; template <int EPI, bool HS = false>
; __device__ __forceinline__ void gemm_phase(const Params& p, const GemmCfg& g, char* shm, const int wave_s) {
;     ...
;             for (int bj = 0; bj < 2; ++bj) {
;               float2 xn;
;               xn.x = xv[j][bj].x + gt[bj][0] * acc[ai][bj][m][0][j];
;               xn.y = xv[j][bj].y + gt[bj][1] * acc[ai][bj][m][1][j];
;               const unsigned o = tb + (unsigned)((ai * 128 + m * 16 + j) * 1024 + bj * 128);
;               *(float2*)(xout_t + o) = xn;
;               if (g.has_next) *(unsigned*)(xg_t + o) = pack2(xn.x * gn[bj][0], xn.y * gn[bj][1]);
;               ss += xn.x * xn.x + xn.y * xn.y;
;             }
;             if (g.has_next) {
;               ss = dpp_row_sum16(ss);
;               if (fr == 0) rss_t[(wr * 64 + fq * 4 + ai * 128 + m * 16 + j) * 16] = ss;
;             }
.LBB0_802:
	v_add_u32_e32 v46, 0x28400, v0
	v_mov_b32_e32 v30, v27
	v_mov_b32_e32 v47, v1
	s_waitcnt lgkmcnt(2)
	v_pk_fma_f32 v[30:31], v[154:155], v[30:31], v[42:43]
	v_lshl_add_u64 v[26:27], v[46:47], 2, s[0:1]
	global_store_dwordx2 v[26:27], v[30:31], off
	s_mov_b64 s[8:9], -1
	s_and_b64 vcc, exec, s[6:7]
	v_add_u32_e32 v26, 0x28480, v0
	s_cbranch_vccnz .LBB0_806
	v_pk_mul_f32 v[42:43], v[148:149], v[30:31]
	v_mov_b32_e32 v27, v1
	s_nop 0
	s_nop 0
	v_cvt_pk_bf16_f32 v22, v42, v42
	v_cvt_pk_bf16_f32 v18, v43, v43
	v_lshrrev_b32_e32 v22, 16, v22
	v_and_or_b32 v18, v18, s28, v22
	v_lshl_add_u64 v[42:43], v[46:47], 1, s[2:3]
	v_mov_b32_e32 v22, v19
	global_store_dword v[42:43], v18, off
	v_pk_fma_f32 v[42:43], v[150:151], v[22:23], v[44:45]
	v_lshl_add_u64 v[46:47], v[26:27], 2, s[0:1]
	global_store_dwordx2 v[46:47], v[42:43], off
	v_pk_mul_f32 v[46:47], v[152:153], v[42:43]
	v_pk_mul_f32 v[30:31], v[30:31], v[30:31]
	s_nop 0
	s_nop 0
	v_cvt_pk_bf16_f32 v22, v46, v46
	v_cvt_pk_bf16_f32 v18, v47, v47
	v_lshrrev_b32_e32 v22, 16, v22
	v_and_or_b32 v18, v18, s28, v22
	v_lshl_add_u64 v[46:47], v[26:27], 1, s[2:3]
	v_pk_mul_f32 v[42:43], v[42:43], v[42:43]
	global_store_dword v[46:47], v18, off
	v_add_f32_e32 v18, v42, v43
	v_add_f32_e32 v22, v30, v31
	v_add_f32_e32 v18, v22, v18
	s_nop 1
	v_add_f32_dpp v18, v18, v18 quad_perm:[1,0,3,2] row_mask:0xf bank_mask:0xf bound_ctrl:1
	s_nop 1
	v_add_f32_dpp v18, v18, v18 quad_perm:[2,3,0,1] row_mask:0xf bank_mask:0xf bound_ctrl:1
	s_nop 1
	v_add_f32_dpp v18, v18, v18 row_half_mirror row_mask:0xf bank_mask:0xf bound_ctrl:1
	s_nop 1
	v_mov_b32_dpp v22, v18 row_mirror row_mask:0xf bank_mask:0xf bound_ctrl:1
	s_and_saveexec_b64 s[8:9], s[4:5]
	s_cbranch_execz .LBB0_805
	v_add_f32_e32 v18, v18, v22
	v_mov_b32_e32 v22, 0xa10
	v_lshl_add_u32 v30, v163, 4, v22
	v_ashrrev_i32_e32 v31, 31, v30
	v_lshl_add_u64 v[30:31], v[30:31], 2, v[142:143]
	global_store_dword v[30:31], v18, off

; __device__ __forceinline__ unsigned pack2(float a, float b) { return (unsigned)f2bf(a) | ((unsigned)f2bf(b) << 16); }
; __device__ __forceinline__ float dpp_row_sum16(float v) {
;   v += __int_as_float(__builtin_amdgcn_update_dpp(0, __float_as_int(v), 0xB1, 0xF, 0xF, true));
;   v += __int_as_float(__builtin_amdgcn_update_dpp(0, __float_as_int(v), 0x4E, 0xF, 0xF, true));
;   v += __int_as_float(__builtin_amdgcn_update_dpp(0, __float_as_int(v), 0x141, 0xF, 0xF, true));
;   v += __int_as_float(__builtin_amdgcn_update_dpp(0, __float_as_int(v), 0x140, 0xF, 0xF, true));
;   return v;
; }
; template <int EPI, bool HS = false>
; __device__ __forceinline__ void gemm_phase(const Params& p, const GemmCfg& g, char* shm, const int wave_s) {
;     ...
;             for (int bj = 0; bj < 2; ++bj) {
;               float2 xn;
;               xn.x = xv[j][bj].x + gt[bj][0] * acc[ai][bj][m][0][j];
;               xn.y = xv[j][bj].y + gt[bj][1] * acc[ai][bj][m][1][j];
;               const unsigned o = tb + (unsigned)((ai * 128 + m * 16 + j) * 1024 + bj * 128);
;               *(float2*)(xout_t + o) = xn;
;               if (g.has_next) *(unsigned*)(xg_t + o) = pack2(xn.x * gn[bj][0], xn.y * gn[bj][1]);
;               ss += xn.x * xn.x + xn.y * xn.y;
;             }
;             if (g.has_next) {
;               ss = dpp_row_sum16(ss);
;               if (fr == 0) rss_t[(wr * 64 + fq * 4 + ai * 128 + m * 16 + j) * 16] = ss;
;             }
.LBB0_808:
	v_add_u32_e32 v26, 0x28800, v0
	v_mov_b32_e32 v18, v28
	v_mov_b32_e32 v19, v32
	v_mov_b32_e32 v27, v1
	s_waitcnt lgkmcnt(1)
	v_pk_fma_f32 v[22:23], v[154:155], v[18:19], v[38:39]
	v_lshl_add_u64 v[18:19], v[26:27], 2, s[0:1]
	global_store_dwordx2 v[18:19], v[22:23], off
	s_mov_b64 s[8:9], -1
	s_and_b64 vcc, exec, s[6:7]
	v_add_u32_e32 v18, 0x28880, v0
	s_cbranch_vccnz .LBB0_812
	v_pk_mul_f32 v[30:31], v[148:149], v[22:23]
	v_lshl_add_u64 v[26:27], v[26:27], 1, s[2:3]
	s_nop 0
	s_nop 0
	v_cvt_pk_bf16_f32 v28, v30, v30
	v_cvt_pk_bf16_f32 v19, v31, v31
	v_lshrrev_b32_e32 v28, 16, v28
	v_and_or_b32 v19, v19, s28, v28
	global_store_dword v[26:27], v19, off
	v_mov_b32_e32 v26, v20
	v_mov_b32_e32 v27, v24
	v_mov_b32_e32 v19, v1
	v_pk_fma_f32 v[26:27], v[150:151], v[26:27], v[40:41]
	v_lshl_add_u64 v[30:31], v[18:19], 2, s[0:1]
	global_store_dwordx2 v[30:31], v[26:27], off
	v_pk_mul_f32 v[30:31], v[152:153], v[26:27]
	v_pk_mul_f32 v[22:23], v[22:23], v[22:23]
	v_and_b32_sdwa v32, v30, v178 dst_sel:DWORD dst_unused:UNUSED_PAD src0_sel:WORD_1 src1_sel:DWORD
	s_nop 0
	v_add3_u32 v30, v30, v32, s81
	v_cvt_pk_bf16_f32 v28, v31, v31
	v_lshrrev_b32_e32 v30, 16, v30
	v_pk_mul_f32 v[26:27], v[26:27], v[26:27]
	v_and_or_b32 v28, v28, s28, v30
	v_lshl_add_u64 v[30:31], v[18:19], 1, s[2:3]
	v_add_f32_e32 v19, v26, v27
	v_add_f32_e32 v22, v22, v23
	v_add_f32_e32 v19, v22, v19
	global_store_dword v[30:31], v28, off
	s_nop 0
	v_add_f32_dpp v19, v19, v19 quad_perm:[1,0,3,2] row_mask:0xf bank_mask:0xf bound_ctrl:1
	s_nop 1
	v_add_f32_dpp v19, v19, v19 quad_perm:[2,3,0,1] row_mask:0xf bank_mask:0xf bound_ctrl:1
	s_nop 1
	v_add_f32_dpp v19, v19, v19 row_half_mirror row_mask:0xf bank_mask:0xf bound_ctrl:1
	s_nop 1
	v_mov_b32_dpp v22, v19 row_mirror row_mask:0xf bank_mask:0xf bound_ctrl:1
	s_and_saveexec_b64 s[8:9], s[4:5]
	s_cbranch_execz .LBB0_811
	v_add_f32_e32 v19, v19, v22
	v_mov_b32_e32 v22, 0xa20
	v_lshl_add_u32 v22, v163, 4, v22
	v_ashrrev_i32_e32 v23, 31, v22
	v_lshl_add_u64 v[22:23], v[22:23], 2, v[142:143]
	global_store_dword v[22:23], v19, off

; __device__ __forceinline__ unsigned pack2(float a, float b) { return (unsigned)f2bf(a) | ((unsigned)f2bf(b) << 16); }
; __device__ __forceinline__ float dpp_row_sum16(float v) {
;   v += __int_as_float(__builtin_amdgcn_update_dpp(0, __float_as_int(v), 0xB1, 0xF, 0xF, true));
;   v += __int_as_float(__builtin_amdgcn_update_dpp(0, __float_as_int(v), 0x4E, 0xF, 0xF, true));
;   v += __int_as_float(__builtin_amdgcn_update_dpp(0, __float_as_int(v), 0x141, 0xF, 0xF, true));
;   v += __int_as_float(__builtin_amdgcn_update_dpp(0, __float_as_int(v), 0x140, 0xF, 0xF, true));
;   return v;
; }
; template <int EPI, bool HS = false>
; __device__ __forceinline__ void gemm_phase(const Params& p, const GemmCfg& g, char* shm, const int wave_s) {
;     ...
;             for (int bj = 0; bj < 2; ++bj) {
;               float2 xn;
;               xn.x = xv[j][bj].x + gt[bj][0] * acc[ai][bj][m][0][j];
;               xn.y = xv[j][bj].y + gt[bj][1] * acc[ai][bj][m][1][j];
;               const unsigned o = tb + (unsigned)((ai * 128 + m * 16 + j) * 1024 + bj * 128);
;               *(float2*)(xout_t + o) = xn;
;               if (g.has_next) *(unsigned*)(xg_t + o) = pack2(xn.x * gn[bj][0], xn.y * gn[bj][1]);
;               ss += xn.x * xn.x + xn.y * xn.y;
;             }
;             if (g.has_next) {
;               ss = dpp_row_sum16(ss);
;               if (fr == 0) rss_t[(wr * 64 + fq * 4 + ai * 128 + m * 16 + j) * 16] = ss;
;             }
.LBB0_814:
	v_add_u32_e32 v26, 0x28c00, v0
	v_mov_b32_e32 v32, v29
	v_mov_b32_e32 v27, v1
	s_waitcnt lgkmcnt(0)
	v_pk_fma_f32 v[22:23], v[154:155], v[32:33], v[34:35]
	v_lshl_add_u64 v[18:19], v[26:27], 2, s[0:1]
	global_store_dwordx2 v[18:19], v[22:23], off
	s_mov_b64 s[8:9], -1
	s_and_b64 vcc, exec, s[6:7]
	v_add_u32_e32 v18, 0x28c80, v0
	s_cbranch_vccnz .LBB0_818
	v_pk_mul_f32 v[28:29], v[148:149], v[22:23]
	v_lshl_add_u64 v[26:27], v[26:27], 1, s[2:3]
	s_nop 0
	s_nop 0
	v_cvt_pk_bf16_f32 v20, v28, v28
	v_cvt_pk_bf16_f32 v19, v29, v29
	v_lshrrev_b32_e32 v20, 16, v20
	v_and_or_b32 v19, v19, s28, v20
	global_store_dword v[26:27], v19, off
	v_mov_b32_e32 v24, v21
	v_mov_b32_e32 v19, v1
	v_pk_fma_f32 v[26:27], v[150:151], v[24:25], v[36:37]
	v_lshl_add_u64 v[28:29], v[18:19], 2, s[0:1]
	global_store_dwordx2 v[28:29], v[26:27], off
	v_pk_mul_f32 v[28:29], v[152:153], v[26:27]
	v_pk_mul_f32 v[22:23], v[22:23], v[22:23]
	s_nop 0
	s_nop 0
	v_cvt_pk_bf16_f32 v24, v28, v28
	v_cvt_pk_bf16_f32 v20, v29, v29
	v_lshrrev_b32_e32 v24, 16, v24
	v_and_or_b32 v20, v20, s28, v24
	v_lshl_add_u64 v[28:29], v[18:19], 1, s[2:3]
	v_pk_mul_f32 v[26:27], v[26:27], v[26:27]
	global_store_dword v[28:29], v20, off
	v_add_f32_e32 v19, v26, v27
	v_add_f32_e32 v20, v22, v23
	v_add_f32_e32 v19, v20, v19
	s_nop 1
	v_add_f32_dpp v19, v19, v19 quad_perm:[1,0,3,2] row_mask:0xf bank_mask:0xf bound_ctrl:1
	s_nop 1
	v_add_f32_dpp v19, v19, v19 quad_perm:[2,3,0,1] row_mask:0xf bank_mask:0xf bound_ctrl:1
	s_nop 1
	v_add_f32_dpp v19, v19, v19 row_half_mirror row_mask:0xf bank_mask:0xf bound_ctrl:1
	s_nop 1
	v_mov_b32_dpp v20, v19 row_mirror row_mask:0xf bank_mask:0xf bound_ctrl:1
	s_and_saveexec_b64 s[8:9], s[4:5]
	s_cbranch_execz .LBB0_817
	v_add_f32_e32 v19, v19, v20
	v_mov_b32_e32 v20, 0xa30
	v_lshl_add_u32 v22, v163, 4, v20
	v_ashrrev_i32_e32 v23, 31, v22
	v_lshl_add_u64 v[22:23], v[22:23], 2, v[142:143]
	global_store_dword v[22:23], v19, off

; __device__ __forceinline__ unsigned pack2(float a, float b) { return (unsigned)f2bf(a) | ((unsigned)f2bf(b) << 16); }
; template <int EPI, bool HS = false>
; __device__ __forceinline__ void gemm_phase(const Params& p, const GemmCfg& g, char* shm, const int wave_s) {
;     ...
; #pragma unroll
;         for (int m = 0; m < 4; ++m) {
;           float2 xv[4][2];
; #pragma unroll
;           for (int j = 0; j < 4; ++j)
; #pragma unroll
;             for (int bj = 0; bj < 2; ++bj) xv[j][bj] = *(const float2*)(xl + (m * 16 + j) * XROW + bj * 512);
; #pragma unroll
;           for (int j = 0; j < 4; ++j) {
;             float ss = 0.f;
; #pragma unroll
;             for (int bj = 0; bj < 2; ++bj) {
;               float2 xn;
;               xn.x = xv[j][bj].x + gt[bj][0] * acc[ai][bj][m][0][j];
;               xn.y = xv[j][bj].y + gt[bj][1] * acc[ai][bj][m][1][j];
;               const unsigned o = tb + (unsigned)((ai * 128 + m * 16 + j) * 1024 + bj * 128);
;               *(float2*)(xout_t + o) = xn;
;               if (g.has_next) *(unsigned*)(xg_t + o) = pack2(xn.x * gn[bj][0], xn.y * gn[bj][1]);
;               ss += xn.x * xn.x + xn.y * xn.y;
;             }
;             if (g.has_next) {
;               ss = dpp_row_sum16(ss);
;               if (fr == 0) rss_t[(wr * 64 + fq * 4 + ai * 128 + m * 16 + j) * 16] = ss;
;             }
.LBB0_820:
	ds_read2st64_b64 v[30:33], v134 offset0:97 offset1:98
	ds_read2st64_b64 v[26:29], v135 offset0:99 offset1:100
	ds_read2st64_b64 v[22:25], v136 offset0:101 offset1:102
	ds_read2st64_b64 v[18:21], v137 offset0:103 offset1:104
	v_add_u32_e32 v36, 0x2c000, v0
	v_mov_b32_e32 v34, v10
	v_mov_b32_e32 v35, v14
	v_mov_b32_e32 v37, v1
	s_waitcnt lgkmcnt(3)
	v_pk_fma_f32 v[34:35], v[154:155], v[34:35], v[30:31]
	v_lshl_add_u64 v[30:31], v[36:37], 2, s[0:1]
	global_store_dwordx2 v[30:31], v[34:35], off
	s_mov_b64 s[8:9], -1
	s_and_b64 vcc, exec, s[6:7]
	v_add_u32_e32 v30, 0x2c080, v0
	s_cbranch_vccnz .LBB0_824
	v_pk_mul_f32 v[38:39], v[148:149], v[34:35]
	v_lshl_add_u64 v[36:37], v[36:37], 1, s[2:3]
	s_nop 0
	s_nop 0
	v_cvt_pk_bf16_f32 v14, v38, v38
	v_cvt_pk_bf16_f32 v10, v39, v39
	v_lshrrev_b32_e32 v14, 16, v14
	v_and_or_b32 v10, v10, s28, v14
	global_store_dword v[36:37], v10, off
	v_mov_b32_e32 v36, v2
	v_mov_b32_e32 v37, v6
	v_mov_b32_e32 v31, v1
	v_pk_fma_f32 v[36:37], v[150:151], v[36:37], v[32:33]
	v_lshl_add_u64 v[38:39], v[30:31], 2, s[0:1]
	global_store_dwordx2 v[38:39], v[36:37], off
	v_pk_mul_f32 v[38:39], v[152:153], v[36:37]
	v_pk_mul_f32 v[34:35], v[34:35], v[34:35]
	s_nop 0
	s_nop 0
	v_cvt_pk_bf16_f32 v14, v38, v38
	v_cvt_pk_bf16_f32 v10, v39, v39
	v_lshrrev_b32_e32 v14, 16, v14
	v_and_or_b32 v10, v10, s28, v14
	v_lshl_add_u64 v[38:39], v[30:31], 1, s[2:3]
	v_pk_mul_f32 v[36:37], v[36:37], v[36:37]
	global_store_dword v[38:39], v10, off
	v_add_f32_e32 v10, v36, v37
	v_add_f32_e32 v14, v34, v35
	v_add_f32_e32 v10, v14, v10
	s_nop 1
	v_add_f32_dpp v10, v10, v10 quad_perm:[1,0,3,2] row_mask:0xf bank_mask:0xf bound_ctrl:1
	s_nop 1
	v_add_f32_dpp v10, v10, v10 quad_perm:[2,3,0,1] row_mask:0xf bank_mask:0xf bound_ctrl:1
	s_nop 1
	v_add_f32_dpp v10, v10, v10 row_half_mirror row_mask:0xf bank_mask:0xf bound_ctrl:1
	s_nop 1
	v_mov_b32_dpp v14, v10 row_mirror row_mask:0xf bank_mask:0xf bound_ctrl:1
	s_and_saveexec_b64 s[8:9], s[4:5]
	s_cbranch_execz .LBB0_823
	v_add_f32_e32 v10, v10, v14
	v_mov_b32_e32 v14, 0xb00
	v_lshl_add_u32 v34, v163, 4, v14
	v_ashrrev_i32_e32 v35, 31, v34
	v_lshl_add_u64 v[34:35], v[34:35], 2, v[142:143]
	global_store_dword v[34:35], v10, off

; __device__ __forceinline__ unsigned pack2(float a, float b) { return (unsigned)f2bf(a) | ((unsigned)f2bf(b) << 16); }
; __device__ __forceinline__ float dpp_row_sum16(float v) {
;   v += __int_as_float(__builtin_amdgcn_update_dpp(0, __float_as_int(v), 0xB1, 0xF, 0xF, true));
;   v += __int_as_float(__builtin_amdgcn_update_dpp(0, __float_as_int(v), 0x4E, 0xF, 0xF, true));
;   v += __int_as_float(__builtin_amdgcn_update_dpp(0, __float_as_int(v), 0x141, 0xF, 0xF, true));
;   v += __int_as_float(__builtin_amdgcn_update_dpp(0, __float_as_int(v), 0x140, 0xF, 0xF, true));
;   return v;
; }
; template <int EPI, bool HS = false>
; __device__ __forceinline__ void gemm_phase(const Params& p, const GemmCfg& g, char* shm, const int wave_s) {
;     ...
;             for (int bj = 0; bj < 2; ++bj) {
;               float2 xn;
;               xn.x = xv[j][bj].x + gt[bj][0] * acc[ai][bj][m][0][j];
;               xn.y = xv[j][bj].y + gt[bj][1] * acc[ai][bj][m][1][j];
;               const unsigned o = tb + (unsigned)((ai * 128 + m * 16 + j) * 1024 + bj * 128);
;               *(float2*)(xout_t + o) = xn;
;               if (g.has_next) *(unsigned*)(xg_t + o) = pack2(xn.x * gn[bj][0], xn.y * gn[bj][1]);
;               ss += xn.x * xn.x + xn.y * xn.y;
;             }
;             if (g.has_next) {
;               ss = dpp_row_sum16(ss);
;               if (fr == 0) rss_t[(wr * 64 + fq * 4 + ai * 128 + m * 16 + j) * 16] = ss;
;             }
.LBB0_826:
	v_add_u32_e32 v30, 0x2c400, v0
	v_mov_b32_e32 v14, v11
	v_mov_b32_e32 v31, v1
	s_waitcnt lgkmcnt(2)
	v_pk_fma_f32 v[14:15], v[154:155], v[14:15], v[26:27]
	v_lshl_add_u64 v[10:11], v[30:31], 2, s[0:1]
	global_store_dwordx2 v[10:11], v[14:15], off
	s_mov_b64 s[8:9], -1
	s_and_b64 vcc, exec, s[6:7]
	v_add_u32_e32 v10, 0x2c480, v0
	s_cbranch_vccnz .LBB0_830
	v_pk_mul_f32 v[26:27], v[148:149], v[14:15]
	v_mov_b32_e32 v11, v1
	s_nop 0
	s_nop 0
	v_cvt_pk_bf16_f32 v6, v26, v26
	v_cvt_pk_bf16_f32 v2, v27, v27
	v_lshrrev_b32_e32 v6, 16, v6
	v_and_or_b32 v2, v2, s28, v6
	v_lshl_add_u64 v[26:27], v[30:31], 1, s[2:3]
	v_mov_b32_e32 v6, v3
	global_store_dword v[26:27], v2, off
	v_pk_fma_f32 v[26:27], v[150:151], v[6:7], v[28:29]
	v_lshl_add_u64 v[30:31], v[10:11], 2, s[0:1]
	global_store_dwordx2 v[30:31], v[26:27], off
	v_pk_mul_f32 v[30:31], v[152:153], v[26:27]
	v_pk_mul_f32 v[14:15], v[14:15], v[14:15]
	s_nop 0
	s_nop 0
	v_cvt_pk_bf16_f32 v6, v30, v30
	v_cvt_pk_bf16_f32 v2, v31, v31
	v_lshrrev_b32_e32 v6, 16, v6
	v_and_or_b32 v2, v2, s28, v6
	v_lshl_add_u64 v[30:31], v[10:11], 1, s[2:3]
	v_pk_mul_f32 v[26:27], v[26:27], v[26:27]
	global_store_dword v[30:31], v2, off
	v_add_f32_e32 v2, v26, v27
	v_add_f32_e32 v6, v14, v15
	v_add_f32_e32 v2, v6, v2
	s_nop 1
	v_add_f32_dpp v2, v2, v2 quad_perm:[1,0,3,2] row_mask:0xf bank_mask:0xf bound_ctrl:1
	s_nop 1
	v_add_f32_dpp v2, v2, v2 quad_perm:[2,3,0,1] row_mask:0xf bank_mask:0xf bound_ctrl:1
	s_nop 1
	v_add_f32_dpp v2, v2, v2 row_half_mirror row_mask:0xf bank_mask:0xf bound_ctrl:1
	s_nop 1
	v_mov_b32_dpp v6, v2 row_mirror row_mask:0xf bank_mask:0xf bound_ctrl:1
	s_and_saveexec_b64 s[8:9], s[4:5]
	s_cbranch_execz .LBB0_829
	v_add_f32_e32 v2, v2, v6
	v_mov_b32_e32 v6, 0xb10
	v_lshl_add_u32 v14, v163, 4, v6
	v_ashrrev_i32_e32 v15, 31, v14
	v_lshl_add_u64 v[14:15], v[14:15], 2, v[142:143]
	global_store_dword v[14:15], v2, off

; __device__ __forceinline__ unsigned pack2(float a, float b) { return (unsigned)f2bf(a) | ((unsigned)f2bf(b) << 16); }
; __device__ __forceinline__ float dpp_row_sum16(float v) {
;   v += __int_as_float(__builtin_amdgcn_update_dpp(0, __float_as_int(v), 0xB1, 0xF, 0xF, true));
;   v += __int_as_float(__builtin_amdgcn_update_dpp(0, __float_as_int(v), 0x4E, 0xF, 0xF, true));
;   v += __int_as_float(__builtin_amdgcn_update_dpp(0, __float_as_int(v), 0x141, 0xF, 0xF, true));
;   v += __int_as_float(__builtin_amdgcn_update_dpp(0, __float_as_int(v), 0x140, 0xF, 0xF, true));
;   return v;
; }
; template <int EPI, bool HS = false>
; __device__ __forceinline__ void gemm_phase(const Params& p, const GemmCfg& g, char* shm, const int wave_s) {
;     ...
;             for (int bj = 0; bj < 2; ++bj) {
;               float2 xn;
;               xn.x = xv[j][bj].x + gt[bj][0] * acc[ai][bj][m][0][j];
;               xn.y = xv[j][bj].y + gt[bj][1] * acc[ai][bj][m][1][j];
;               const unsigned o = tb + (unsigned)((ai * 128 + m * 16 + j) * 1024 + bj * 128);
;               *(float2*)(xout_t + o) = xn;
;               if (g.has_next) *(unsigned*)(xg_t + o) = pack2(xn.x * gn[bj][0], xn.y * gn[bj][1]);
;               ss += xn.x * xn.x + xn.y * xn.y;
;             }
;             if (g.has_next) {
;               ss = dpp_row_sum16(ss);
;               if (fr == 0) rss_t[(wr * 64 + fq * 4 + ai * 128 + m * 16 + j) * 16] = ss;
;             }
.LBB0_832:
	v_add_u32_e32 v10, 0x2c800, v0
	v_mov_b32_e32 v2, v12
	v_mov_b32_e32 v3, v16
	v_mov_b32_e32 v11, v1
	s_waitcnt lgkmcnt(1)
	v_pk_fma_f32 v[6:7], v[154:155], v[2:3], v[22:23]
	v_lshl_add_u64 v[2:3], v[10:11], 2, s[0:1]
	global_store_dwordx2 v[2:3], v[6:7], off
	s_mov_b64 s[8:9], -1
	s_and_b64 vcc, exec, s[6:7]
	v_add_u32_e32 v2, 0x2c880, v0
	s_cbranch_vccnz .LBB0_836
	v_pk_mul_f32 v[14:15], v[148:149], v[6:7]
	v_lshl_add_u64 v[10:11], v[10:11], 1, s[2:3]
	s_nop 0
	s_nop 0
	v_cvt_pk_bf16_f32 v12, v14, v14
	v_cvt_pk_bf16_f32 v3, v15, v15
	v_lshrrev_b32_e32 v12, 16, v12
	v_and_or_b32 v3, v3, s28, v12
	global_store_dword v[10:11], v3, off
	v_mov_b32_e32 v10, v4
	v_mov_b32_e32 v11, v8
	v_mov_b32_e32 v3, v1
	v_pk_fma_f32 v[10:11], v[150:151], v[10:11], v[24:25]
	v_lshl_add_u64 v[14:15], v[2:3], 2, s[0:1]
	global_store_dwordx2 v[14:15], v[10:11], off
	v_pk_mul_f32 v[14:15], v[152:153], v[10:11]
	v_pk_mul_f32 v[6:7], v[6:7], v[6:7]
	v_and_b32_sdwa v16, v14, v178 dst_sel:DWORD dst_unused:UNUSED_PAD src0_sel:WORD_1 src1_sel:DWORD
	s_nop 0
	v_add3_u32 v14, v14, v16, s81
	v_cvt_pk_bf16_f32 v12, v15, v15
	v_lshrrev_b32_e32 v14, 16, v14
	v_pk_mul_f32 v[10:11], v[10:11], v[10:11]
	v_and_or_b32 v12, v12, s28, v14
	v_lshl_add_u64 v[14:15], v[2:3], 1, s[2:3]
	v_add_f32_e32 v3, v10, v11
	v_add_f32_e32 v6, v6, v7
	v_add_f32_e32 v3, v6, v3
	global_store_dword v[14:15], v12, off
	s_nop 0
	v_add_f32_dpp v3, v3, v3 quad_perm:[1,0,3,2] row_mask:0xf bank_mask:0xf bound_ctrl:1
	s_nop 1
	v_add_f32_dpp v3, v3, v3 quad_perm:[2,3,0,1] row_mask:0xf bank_mask:0xf bound_ctrl:1
	s_nop 1
	v_add_f32_dpp v3, v3, v3 row_half_mirror row_mask:0xf bank_mask:0xf bound_ctrl:1
	s_nop 1
	v_mov_b32_dpp v6, v3 row_mirror row_mask:0xf bank_mask:0xf bound_ctrl:1
	s_and_saveexec_b64 s[8:9], s[4:5]
	s_cbranch_execz .LBB0_835
	v_add_f32_e32 v3, v3, v6
	v_mov_b32_e32 v6, 0xb20
	v_lshl_add_u32 v6, v163, 4, v6
	v_ashrrev_i32_e32 v7, 31, v6
	v_lshl_add_u64 v[6:7], v[6:7], 2, v[142:143]
	global_store_dword v[6:7], v3, off

; __device__ __forceinline__ unsigned pack2(float a, float b) { return (unsigned)f2bf(a) | ((unsigned)f2bf(b) << 16); }
; __device__ __forceinline__ float dpp_row_sum16(float v) {
;   v += __int_as_float(__builtin_amdgcn_update_dpp(0, __float_as_int(v), 0xB1, 0xF, 0xF, true));
;   v += __int_as_float(__builtin_amdgcn_update_dpp(0, __float_as_int(v), 0x4E, 0xF, 0xF, true));
;   v += __int_as_float(__builtin_amdgcn_update_dpp(0, __float_as_int(v), 0x141, 0xF, 0xF, true));
;   v += __int_as_float(__builtin_amdgcn_update_dpp(0, __float_as_int(v), 0x140, 0xF, 0xF, true));
;   return v;
; }
; template <int EPI, bool HS = false>
; __device__ __forceinline__ void gemm_phase(const Params& p, const GemmCfg& g, char* shm, const int wave_s) {
;     ...
;             for (int bj = 0; bj < 2; ++bj) {
;               float2 xn;
;               xn.x = xv[j][bj].x + gt[bj][0] * acc[ai][bj][m][0][j];
;               xn.y = xv[j][bj].y + gt[bj][1] * acc[ai][bj][m][1][j];
;               const unsigned o = tb + (unsigned)((ai * 128 + m * 16 + j) * 1024 + bj * 128);
;               *(float2*)(xout_t + o) = xn;
;               if (g.has_next) *(unsigned*)(xg_t + o) = pack2(xn.x * gn[bj][0], xn.y * gn[bj][1]);
;               ss += xn.x * xn.x + xn.y * xn.y;
;             }
;             if (g.has_next) {
;               ss = dpp_row_sum16(ss);
;               if (fr == 0) rss_t[(wr * 64 + fq * 4 + ai * 128 + m * 16 + j) * 16] = ss;
;             }
.LBB0_838:
	v_add_u32_e32 v6, 0x2cc00, v0
	v_mov_b32_e32 v16, v13
	v_mov_b32_e32 v7, v1
	s_waitcnt lgkmcnt(0)
	v_pk_fma_f32 v[2:3], v[154:155], v[16:17], v[18:19]
	v_lshl_add_u64 v[10:11], v[6:7], 2, s[0:1]
	s_mov_b64 s[8:9], -1
	s_and_b64 vcc, exec, s[6:7]
	v_add_u32_e32 v0, 0x2cc80, v0
	global_store_dwordx2 v[10:11], v[2:3], off
	s_cbranch_vccnz .LBB0_842
	v_pk_mul_f32 v[10:11], v[148:149], v[2:3]
	v_lshl_add_u64 v[6:7], v[6:7], 1, s[2:3]
	s_nop 0
	s_nop 0
	v_cvt_pk_bf16_f32 v8, v10, v10
	v_cvt_pk_bf16_f32 v4, v11, v11
	v_lshrrev_b32_e32 v8, 16, v8
	v_and_or_b32 v4, v4, s28, v8
	v_mov_b32_e32 v8, v5
	global_store_dword v[6:7], v4, off
	v_pk_fma_f32 v[6:7], v[150:151], v[8:9], v[20:21]
	v_lshl_add_u64 v[10:11], v[0:1], 2, s[0:1]
	global_store_dwordx2 v[10:11], v[6:7], off
	v_pk_mul_f32 v[10:11], v[152:153], v[6:7]
	v_pk_mul_f32 v[2:3], v[2:3], v[2:3]
	s_nop 0
	s_nop 0
	v_cvt_pk_bf16_f32 v8, v10, v10
	v_cvt_pk_bf16_f32 v4, v11, v11
	v_lshrrev_b32_e32 v8, 16, v8
	v_and_or_b32 v4, v4, s28, v8
	v_lshl_add_u64 v[10:11], v[0:1], 1, s[2:3]
	v_pk_mul_f32 v[6:7], v[6:7], v[6:7]
	global_store_dword v[10:11], v4, off
	v_add_f32_e32 v4, v6, v7
	v_add_f32_e32 v2, v2, v3
	v_add_f32_e32 v2, v2, v4
	s_nop 1
	v_add_f32_dpp v2, v2, v2 quad_perm:[1,0,3,2] row_mask:0xf bank_mask:0xf bound_ctrl:1
	s_nop 1
	v_add_f32_dpp v2, v2, v2 quad_perm:[2,3,0,1] row_mask:0xf bank_mask:0xf bound_ctrl:1
	s_nop 1
	v_add_f32_dpp v2, v2, v2 row_half_mirror row_mask:0xf bank_mask:0xf bound_ctrl:1
	s_nop 1
	v_mov_b32_dpp v3, v2 row_mirror row_mask:0xf bank_mask:0xf bound_ctrl:1
	s_and_saveexec_b64 s[2:3], s[4:5]
	s_cbranch_execz .LBB0_841
	v_add_f32_e32 v4, v2, v3
	v_mov_b32_e32 v2, 0xb30
	v_lshl_add_u32 v2, v163, 4, v2
	v_ashrrev_i32_e32 v3, 31, v2
	v_lshl_add_u64 v[2:3], v[2:3], 2, v[142:143]
	global_store_dword v[2:3], v4, off
